# every per-segment s_setprio deleted, one static s_setprio 1 for waves 4-7 at kernel entry
# speedup vs baseline: 1.0064x; 1.0064x over previous
; DI int half_() { return __builtin_amdgcn_readfirstlane((int)(threadIdx.x >> 8)); }
; DI int vbid() { return (int)blockIdx.x * 2 + half_(); }
; DI int vgrid() { return (int)gridDim.x * 2; }
; __global__ void __launch_bounds__(512, 2) mega(Params p_unused, int ph0, int ph1) {
;   __shared__ __attribute__((aligned(16))) unsigned char lds_all[LDS_BYTES];
;   unsigned char* ldsb = lds_all + half_() * LDS_HALF;
;   cg::grid_group grid = cg::this_grid();
;   for (int ph = ph0; ph < ph1; ++ph) {
;     const __attribute__((address_space(4))) Params* pp = (const __attribute__((address_space(4))) Params*)__builtin_amdgcn_kernarg_segment_ptr();
;     asm volatile("" : "+s"(pp));
;     PREF p = *pp;
;     if (ph1 < 0) grid.sync();
;     if (ph > ph0) grid_barrier(p.bar, (unsigned)(ph - ph0));
.LBB0_1:
	s_lshr_b32 s33, s0, 8
	v_readlane_b32 s0, v254, 1
	v_readlane_b32 s1, v254, 2
	s_add_u32 s2, s0, 0x1a8
	s_addc_u32 s3, s1, 0
	v_writelane_b32 v254, s2, 5
	v_lshrrev_b32_e32 v1, 20, v0
	v_lshrrev_b32_e32 v0, 10, v0
	v_writelane_b32 v254, s3, 6
	v_or_b32_e32 v0, v0, v1
	s_movk_i32 s2, 0x3ff
	v_and_or_b32 v0, v0, s2, v168
	v_readlane_b32 s8, v254, 3
	v_cmp_eq_u32_e64 s[2:3], 0, v0
	v_readlane_b32 s9, v254, 4
	s_load_dword s5, s[0:1], 0x1a8
	v_writelane_b32 v254, s2, 7
	s_cmp_lt_i32 s9, 0
	s_cselect_b64 s[0:1], -1, 0
	v_writelane_b32 v254, s3, 8
	v_cmp_eq_u32_e64 s[2:3], 0, v168
	s_waitcnt lgkmcnt(0)
	s_lshr_b32 s45, s5, 3
	s_mul_i32 s33, s33, 0x12400
	v_writelane_b32 v254, s2, 9
	v_cndmask_b32_e64 v0, 0, 1, s[0:1]
	v_cmp_ne_u32_e64 s[0:1], 1, v0
	v_writelane_b32 v254, s3, 10
	v_mbcnt_lo_u32_b32 v0, -1, 0
	v_readlane_b32 s4, v254, 0
	s_and_b32 s2, s4, 15
	s_xor_b32 s3, s2, 15
	s_add_i32 s3, s5, s3
	s_lshr_b32 s3, s3, 4
	s_lshl_b32 s2, s2, 6
	s_lshr_b32 s46, s4, 3
	s_cmpk_lt_u32 s4, 0x200
	v_writelane_b32 v254, s3, 11
	s_cselect_b64 s[6:7], -1, 0
	s_lshl_b32 s3, s4, 4
	s_and_b32 s47, s3, 0x70
	s_lshl_b32 s3, s4, 3
	s_lshl_b32 s48, s5, 3
	v_writelane_b32 v254, s6, 12
	s_cmpk_lt_i32 s4, 0x100
	s_mov_b32 s53, 0
	v_writelane_b32 v254, s7, 13
	s_cselect_b64 s[6:7], -1, 0
	v_writelane_b32 v254, s6, 14
	s_ashr_i32 s49, s48, 31
	s_lshl_b32 s64, s5, 9
	v_writelane_b32 v254, s7, 15
	s_add_i32 s6, s33, 0x12000
	v_writelane_b32 v254, s6, 16
	s_lshl_b32 s6, s4, 9
	v_writelane_b32 v254, s6, 17
	s_lshl_b64 s[6:7], s[48:49], 11
	v_writelane_b32 v254, s6, 18
	s_ashr_i32 s65, s64, 31
	s_lshl_b32 s70, s4, 1
	v_writelane_b32 v254, s7, 19
	v_writelane_b32 v254, s3, 20
	s_addk_i32 s3, 0x4000
	v_writelane_b32 v254, s3, 21
	s_lshl_b32 s3, s4, 8
	v_writelane_b32 v254, s3, 22
	s_lshl_b32 s3, s5, 8
	v_writelane_b32 v254, s3, 23
	s_add_i32 s3, s33, 0x4000
	v_writelane_b32 v254, s3, 24
	s_lshl_b32 s3, s4, 6
	v_writelane_b32 v254, s3, 25
	s_lshl_b64 s[6:7], s[64:65], 4
	v_writelane_b32 v254, s6, 26
	s_lshl_b32 s3, s5, 10
	s_lshl_b32 s71, s5, 1
	v_writelane_b32 v254, s7, 27
	s_lshl_b64 s[6:7], s[64:65], 5
	v_writelane_b32 v254, s6, 28
	s_lshl_b32 s81, s4, 7
	s_lshl_b32 s84, s5, 7
	v_writelane_b32 v254, s7, 29
	s_lshl_b64 s[6:7], s[48:49], 12
	v_writelane_b32 v254, s6, 30
	s_lshl_b32 s85, s5, 6
	s_movk_i32 s66, 0x200
	v_writelane_b32 v254, s7, 31
	v_writelane_b32 v254, s5, 32
	v_writelane_b32 v254, s3, 33
	s_lshl_b64 s[4:5], s[64:65], 2
	v_writelane_b32 v254, s4, 34
	v_and_b32_e32 v169, 0xff, v168
	s_movk_i32 s67, 0x100
	v_writelane_b32 v254, s5, 35
	v_writelane_b32 v254, s0, 36
	s_lshl_b64 s[72:73], s[64:65], 6
	v_mov_b32_e32 v1, 0
	v_writelane_b32 v254, s1, 37
	s_lshl_b32 s0, s2, 2
	v_writelane_b32 v254, s0, 38
	v_writelane_b32 v254, s45, 39
	v_writelane_b32 v254, s46, 40
	v_writelane_b32 v254, s47, 41
	s_mov_b32 s0, s48
	v_writelane_b32 v254, s0, 42
	s_mov_b32 s88, 0x10000
	v_mov_b32_e32 v170, 0x1000
	v_writelane_b32 v254, s1, 43
	s_mov_b32 s0, s64
	s_mov_b64 s[76:77], 0x80
	s_mov_b64 s[78:79], 0x40080
	s_mov_b64 s[42:43], 0x12b0100
	s_mov_b64 s[82:83], 0x100
	s_mov_b64 s[86:87], 0x40100
	s_mov_b64 s[90:91], 0x180
	s_movk_i32 s89, 0x180
	s_movk_i32 s92, 0x210
	s_movk_i32 s93, 0x80
	v_mov_b32_e32 v171, 0x3727c5ac
	s_mov_b32 s61, 0x800000
	s_movk_i32 s80, 0x1000
	s_mov_b64 s[50:51], 0x580100
	s_mov_b64 s[38:39], 0x980100
	s_mov_b64 s[4:5], 0x580180
	s_mov_b64 s[74:75], 0x980180
	s_movk_i32 s60, 0x1540
	s_movk_i32 s96, 0x300
	s_movk_i32 s97, 0x90
	s_mov_b32 s94, 0xff800000
	v_mbcnt_hi_u32_b32 v172, -1, v0
	v_mov_b32_e32 v163, 1.0
	s_mov_b64 s[2:3], 0xaa000
	v_mov_b32_e32 v173, 0x358637bd
	s_movk_i32 s95, 0x400
	s_mov_b64 s[6:7], 0x40180
	s_movk_i32 s58, 0xaa0
	s_movk_i32 s59, 0x600
	s_movk_i32 s54, 0x2a80
	v_mov_b32_e32 v174, 0x3c0881c4
	v_mov_b32_e32 v175, 0xbab64f3b
	v_mov_b32_e32 v176, 0xff800000
	v_mov_b32_e32 v177, 0x7f800000
	v_not_b32_e32 v178, 63
	v_not_b32_e32 v179, 31
	v_mov_b32_e32 v180, 0x7fc00000
	v_mov_b32_e32 v181, 0x37000000
	s_mov_b32 s34, s8
	v_writelane_b32 v254, s0, 44
	s_nop 1
	v_writelane_b32 v254, s1, 45
	v_readfirstlane_b32 s0, v168
	s_lshr_b32 s0, s0, 8
	s_cmp_eq_u32 s0, 0
	s_cbranch_scc1 .Lmy_prio_done
	s_setprio 1
.Lmy_prio_done:
	s_getreg_b32 s0, hwreg(HW_REG_XCC_ID, 0, 4)
	v_writelane_b32 v254, s0, 61
	s_mov_b32 s1, 0
	v_writelane_b32 v254, s1, 62
	v_writelane_b32 v254, s1, 63
	v_writelane_b32 v254, s1, 60
	s_nop 0
	v_readlane_b32 s1, v254, 0
	s_and_b32 s1, s1, 7
	s_cmp_lg_u32 s0, s1
	s_cselect_b32 s1, 0x10001, 1
	v_readlane_b32 s12, v254, 9
	v_readlane_b32 s13, v254, 10
	s_and_saveexec_b64 s[14:15], s[12:13]
	s_cbranch_execz .Lmy_xb_posted
	v_readlane_b32 s12, v254, 1
	v_readlane_b32 s13, v254, 2
	s_load_dwordx2 s[12:13], s[12:13], 0x198
	s_lshl_b32 s0, s0, 8
	s_addk_i32 s0, 0x400
	v_mov_b32_e32 v0, s0
	v_mov_b32_e32 v2, s1
	s_waitcnt lgkmcnt(0)
	global_atomic_add v0, v2, s[12:13]

; #define G_LDA(dst, b, h)                                                                                                  \
;   _Pragma("unroll") for (int m = 0; m < 4; ++m) _Pragma("unroll") for (int k = 0; k < 2; ++k)                             \
;       dst[m][k] = *(const bf16x8*)((const char*)G_SA(b, h) + ((wr * 4 + m) * 2 + k) * 1024 + rdo)
; #define G_LDB(dst, b, h)                                                                                                  \
;   _Pragma("unroll") for (int n = 0; n < 2; ++n) _Pragma("unroll") for (int k = 0; k < 2; ++k)                             \
;       dst[n][k] = *(const bf16x8*)((const char*)G_SB(b, h) + ((wc * 2 + n) * 2 + k) * 1024 + rdo)
; #define G_WAIT_L(n) asm volatile("s_waitcnt lgkmcnt(" #n ")" ::: "memory")
; #define G_BAR __builtin_amdgcn_s_barrier()
; #define G_SCHED __builtin_amdgcn_sched_barrier(0)
;     ...
;     G_LDB(B0, 0, 0); G_SCHED; G_LDA(At, 0, 0); G_STAGE(G_SA(1, 1), A, oa0, oa1, LDA, 128, KA(tt + 1));
;     G_WAIT_L(8); G_BAR; G_WAIT_L(0); G_MMA(0, 0, At, B0); G_BAR; G_SCHED;
;     G_LDB(B1, 0, 1); G_STAGE(G_SB(0, 0), B, ob0, ob1, LDB, 0, KB(tt + 2));
;     G_BAR; G_WAIT_L(0); G_MMA(0, 1, At, B1); G_BAR;
;     G_LDA(At, 0, 1); G_STAGE(G_SA(0, 0), A, oa0, oa1, LDA, 0, KA(tt + 2));
;     G_BAR; G_WAIT_L(0); G_MMA(1, 0, At, B0); G_BAR; G_SCHED;
.LBB0_40:
	ds_read_b128 v[164:167], v162
	ds_read_b128 v[182:185], v162 offset:1024
	ds_read_b128 v[186:189], v162 offset:2048
	ds_read_b128 v[190:193], v162 offset:3072
	v_lshl_add_u64 v[242:243], v[136:137], 0, s[20:21]
	v_readfirstlane_b32 s0, v161
	v_lshl_add_u64 v[226:227], v[242:243], 0, s[78:79]
	s_mov_b32 m0, s0
	v_lshl_add_u64 v[244:245], v[134:135], 0, s[20:21]
	v_readfirstlane_b32 s0, v160
	ds_read_b128 v[194:197], v142
	ds_read_b128 v[198:201], v142 offset:1024
	ds_read_b128 v[202:205], v142 offset:2048
	ds_read_b128 v[206:209], v142 offset:3072
	ds_read_b128 v[210:213], v142 offset:4096
	ds_read_b128 v[214:217], v142 offset:5120
	ds_read_b128 v[218:221], v142 offset:6144
	ds_read_b128 v[222:225], v142 offset:7168
	global_load_lds_dwordx4 v[226:227], off
	v_lshl_add_u64 v[226:227], v[244:245], 0, s[78:79]
	s_mov_b32 m0, s0
	s_nop 0
	global_load_lds_dwordx4 v[226:227], off
	s_waitcnt lgkmcnt(8)
	s_barrier
	s_waitcnt lgkmcnt(0)
	s_waitcnt lgkmcnt(0)
	v_mfma_f32_16x16x32_bf16 v[126:129], v[194:197], v[164:167], v[126:129]
	v_mfma_f32_16x16x32_bf16 v[122:125], v[194:197], v[186:189], v[122:125]
	v_mfma_f32_16x16x32_bf16 v[118:121], v[202:205], v[164:167], v[118:121]
	v_mfma_f32_16x16x32_bf16 v[114:117], v[202:205], v[186:189], v[114:117]
	v_mfma_f32_16x16x32_bf16 v[110:113], v[210:213], v[164:167], v[110:113]
	v_mfma_f32_16x16x32_bf16 v[106:109], v[210:213], v[186:189], v[106:109]
	v_mfma_f32_16x16x32_bf16 v[102:105], v[218:221], v[164:167], v[102:105]
	v_mfma_f32_16x16x32_bf16 v[98:101], v[218:221], v[186:189], v[98:101]
	v_mfma_f32_16x16x32_bf16 v[126:129], v[198:201], v[182:185], v[126:129]
	v_mfma_f32_16x16x32_bf16 v[122:125], v[198:201], v[190:193], v[122:125]
	v_mfma_f32_16x16x32_bf16 v[118:121], v[206:209], v[182:185], v[118:121]
	v_mfma_f32_16x16x32_bf16 v[114:117], v[206:209], v[190:193], v[114:117]
	v_mfma_f32_16x16x32_bf16 v[110:113], v[214:217], v[182:185], v[110:113]
	v_mfma_f32_16x16x32_bf16 v[106:109], v[214:217], v[190:193], v[106:109]
	v_mfma_f32_16x16x32_bf16 v[102:105], v[222:225], v[182:185], v[102:105]
	v_mfma_f32_16x16x32_bf16 v[98:101], v[222:225], v[190:193], v[98:101]
	s_barrier
	v_lshl_add_u64 v[246:247], v[140:141], 0, s[20:21]
	v_readfirstlane_b32 s0, v146
	v_lshl_add_u64 v[248:249], v[246:247], 0, s[42:43]
	s_mov_b32 m0, s0
	ds_read_b128 v[226:229], v159
	ds_read_b128 v[230:233], v159 offset:1024
	ds_read_b128 v[234:237], v159 offset:2048
	ds_read_b128 v[238:241], v159 offset:3072
	global_load_lds_dwordx4 v[248:249], off
	v_lshl_add_u64 v[248:249], v[138:139], 0, s[20:21]
	v_readfirstlane_b32 s0, v147
	v_lshl_add_u64 v[250:251], v[248:249], 0, s[42:43]
	s_mov_b32 m0, s0
	s_nop 0
	global_load_lds_dwordx4 v[250:251], off
	s_barrier
	s_waitcnt lgkmcnt(0)
	s_waitcnt lgkmcnt(0)
	v_mfma_f32_16x16x32_bf16 v[94:97], v[194:197], v[226:229], v[94:97]
	v_mfma_f32_16x16x32_bf16 v[78:81], v[194:197], v[234:237], v[78:81]
	v_mfma_f32_16x16x32_bf16 v[62:65], v[202:205], v[226:229], v[62:65]
	v_mfma_f32_16x16x32_bf16 v[54:57], v[202:205], v[234:237], v[54:57]
	v_mfma_f32_16x16x32_bf16 v[50:53], v[210:213], v[226:229], v[50:53]
	v_mfma_f32_16x16x32_bf16 v[46:49], v[210:213], v[234:237], v[46:49]
	v_mfma_f32_16x16x32_bf16 v[42:45], v[218:221], v[226:229], v[42:45]
	v_mfma_f32_16x16x32_bf16 v[38:41], v[218:221], v[234:237], v[38:41]
	v_mfma_f32_16x16x32_bf16 v[94:97], v[198:201], v[230:233], v[94:97]
	v_mfma_f32_16x16x32_bf16 v[78:81], v[198:201], v[238:241], v[78:81]
	v_mfma_f32_16x16x32_bf16 v[62:65], v[206:209], v[230:233], v[62:65]
	v_mfma_f32_16x16x32_bf16 v[54:57], v[206:209], v[238:241], v[54:57]
	v_mfma_f32_16x16x32_bf16 v[50:53], v[214:217], v[230:233], v[50:53]
	v_mfma_f32_16x16x32_bf16 v[46:49], v[214:217], v[238:241], v[46:49]
	v_mfma_f32_16x16x32_bf16 v[42:45], v[222:225], v[230:233], v[42:45]
	v_mfma_f32_16x16x32_bf16 v[38:41], v[222:225], v[238:241], v[38:41]
	v_readfirstlane_b32 s0, v143
	v_lshl_add_u64 v[250:251], v[242:243], 0, s[82:83]
	s_mov_b32 m0, s0
	v_readfirstlane_b32 s0, v144
	s_barrier
	ds_read_b128 v[194:197], v142 offset:16384
	ds_read_b128 v[198:201], v142 offset:17408
	ds_read_b128 v[202:205], v142 offset:18432
	ds_read_b128 v[206:209], v142 offset:19456
	ds_read_b128 v[210:213], v142 offset:20480
	ds_read_b128 v[214:217], v142 offset:21504
	ds_read_b128 v[218:221], v142 offset:22528
	ds_read_b128 v[222:225], v142 offset:23552
	global_load_lds_dwordx4 v[250:251], off
	v_lshl_add_u64 v[250:251], v[244:245], 0, s[82:83]
	s_mov_b32 m0, s0
	s_nop 0
	global_load_lds_dwordx4 v[250:251], off
	s_barrier
	s_waitcnt lgkmcnt(0)
	s_waitcnt lgkmcnt(0)
	v_mfma_f32_16x16x32_bf16 v[34:37], v[194:197], v[164:167], v[34:37]
	v_mfma_f32_16x16x32_bf16 v[30:33], v[194:197], v[186:189], v[30:33]
	v_mfma_f32_16x16x32_bf16 v[26:29], v[202:205], v[164:167], v[26:29]
	v_mfma_f32_16x16x32_bf16 v[22:25], v[202:205], v[186:189], v[22:25]
	v_mfma_f32_16x16x32_bf16 v[18:21], v[210:213], v[164:167], v[18:21]
	v_mfma_f32_16x16x32_bf16 v[14:17], v[210:213], v[186:189], v[14:17]
	v_mfma_f32_16x16x32_bf16 v[10:13], v[218:221], v[164:167], v[10:13]
	v_mfma_f32_16x16x32_bf16 v[6:9], v[218:221], v[186:189], v[6:9]
	v_mfma_f32_16x16x32_bf16 v[34:37], v[198:201], v[182:185], v[34:37]
	v_mfma_f32_16x16x32_bf16 v[30:33], v[198:201], v[190:193], v[30:33]
	v_mfma_f32_16x16x32_bf16 v[26:29], v[206:209], v[182:185], v[26:29]
	v_mfma_f32_16x16x32_bf16 v[22:25], v[206:209], v[190:193], v[22:25]
	v_mfma_f32_16x16x32_bf16 v[18:21], v[214:217], v[182:185], v[18:21]
	v_mfma_f32_16x16x32_bf16 v[14:17], v[214:217], v[190:193], v[14:17]
	v_mfma_f32_16x16x32_bf16 v[10:13], v[222:225], v[182:185], v[10:13]
	v_mfma_f32_16x16x32_bf16 v[6:9], v[222:225], v[190:193], v[6:9]
	s_barrier
; #define G_LDA(dst, b, h)                                                                                                  \
;   _Pragma("unroll") for (int m = 0; m < 4; ++m) _Pragma("unroll") for (int k = 0; k < 2; ++k)                             \
;       dst[m][k] = *(const bf16x8*)((const char*)G_SA(b, h) + ((wr * 4 + m) * 2 + k) * 1024 + rdo)
; #define G_LDB(dst, b, h)                                                                                                  \
;   _Pragma("unroll") for (int n = 0; n < 2; ++n) _Pragma("unroll") for (int k = 0; k < 2; ++k)                             \
;       dst[n][k] = *(const bf16x8*)((const char*)G_SB(b, h) + ((wc * 2 + n) * 2 + k) * 1024 + rdo)
; #define G_WAIT_V(n) asm volatile("s_waitcnt vmcnt(" #n ")" ::: "memory")
; #define G_WAIT_L(n) asm volatile("s_waitcnt lgkmcnt(" #n ")" ::: "memory")
; #define G_BAR __builtin_amdgcn_s_barrier()
; #define G_SCHED __builtin_amdgcn_sched_barrier(0)
;     ...
;     G_STAGE(G_SB(0, 1), B, ob0, ob1, LDB, 128, KB(tt + 2));
;     G_WAIT_V(6); G_BAR; G_MMA(1, 1, At, B1); G_BAR;
;     G_LDB(B0, 1, 0); G_SCHED; G_LDA(At, 1, 0); G_STAGE(G_SA(0, 1), A, oa0, oa1, LDA, 128, KA(tt + 2));
;     G_WAIT_L(8); G_BAR; G_WAIT_L(0); G_MMA(0, 0, At, B0); G_BAR; G_SCHED;
;     G_LDB(B1, 1, 1); G_STAGE(G_SB(1, 0), B, ob0, ob1, LDB, 0, KB(tt + 3));
;     G_BAR; G_WAIT_L(0); G_MMA(0, 1, At, B1); G_BAR;
;     G_LDA(At, 1, 1); G_STAGE(G_SA(1, 0), A, oa0, oa1, LDA, 0, KA(tt + 3));
	v_readfirstlane_b32 s0, v148
	v_lshl_add_u64 v[164:165], v[246:247], 0, s[24:25]
	s_mov_b32 m0, s0
	v_readfirstlane_b32 s0, v149
	global_load_lds_dwordx4 v[164:165], off
	v_lshl_add_u64 v[164:165], v[248:249], 0, s[24:25]
	s_mov_b32 m0, s0
	s_nop 0
	global_load_lds_dwordx4 v[164:165], off
	s_waitcnt vmcnt(6)
	s_barrier
	v_mfma_f32_16x16x32_bf16 v[2:5], v[194:197], v[226:229], v[2:5]
	v_mfma_f32_16x16x32_bf16 v[58:61], v[194:197], v[234:237], v[58:61]
	v_mfma_f32_16x16x32_bf16 v[66:69], v[202:205], v[226:229], v[66:69]
	v_mfma_f32_16x16x32_bf16 v[70:73], v[202:205], v[234:237], v[70:73]
	v_mfma_f32_16x16x32_bf16 v[74:77], v[210:213], v[226:229], v[74:77]
	v_mfma_f32_16x16x32_bf16 v[82:85], v[210:213], v[234:237], v[82:85]
	v_mfma_f32_16x16x32_bf16 v[86:89], v[218:221], v[226:229], v[86:89]
	v_mfma_f32_16x16x32_bf16 v[90:93], v[218:221], v[234:237], v[90:93]
	v_mfma_f32_16x16x32_bf16 v[2:5], v[198:201], v[230:233], v[2:5]
	v_mfma_f32_16x16x32_bf16 v[58:61], v[198:201], v[238:241], v[58:61]
	v_mfma_f32_16x16x32_bf16 v[66:69], v[206:209], v[230:233], v[66:69]
	v_mfma_f32_16x16x32_bf16 v[70:73], v[206:209], v[238:241], v[70:73]
	v_mfma_f32_16x16x32_bf16 v[74:77], v[214:217], v[230:233], v[74:77]
	v_mfma_f32_16x16x32_bf16 v[82:85], v[214:217], v[238:241], v[82:85]
	v_mfma_f32_16x16x32_bf16 v[86:89], v[222:225], v[230:233], v[86:89]
	v_mfma_f32_16x16x32_bf16 v[90:93], v[222:225], v[238:241], v[90:93]
	s_barrier
	ds_read_b128 v[164:167], v150
	ds_read_b128 v[182:185], v150 offset:1024
	ds_read_b128 v[186:189], v150 offset:2048
	ds_read_b128 v[190:193], v150 offset:3072
	v_readfirstlane_b32 s0, v151
	v_lshl_add_u64 v[226:227], v[242:243], 0, s[86:87]
	s_mov_b32 m0, s0
	v_readfirstlane_b32 s0, v152
	ds_read_b128 v[194:197], v142 offset:32768
	ds_read_b128 v[198:201], v142 offset:33792
	ds_read_b128 v[202:205], v142 offset:34816
	ds_read_b128 v[206:209], v142 offset:35840
	ds_read_b128 v[210:213], v142 offset:36864
	ds_read_b128 v[214:217], v142 offset:37888
	ds_read_b128 v[218:221], v142 offset:38912
	ds_read_b128 v[222:225], v142 offset:39936
	global_load_lds_dwordx4 v[226:227], off
	v_lshl_add_u64 v[226:227], v[244:245], 0, s[86:87]
	s_mov_b32 m0, s0
	s_nop 0
	global_load_lds_dwordx4 v[226:227], off
	s_waitcnt lgkmcnt(8)
	s_barrier
	s_waitcnt lgkmcnt(0)
	s_waitcnt lgkmcnt(0)
	v_mfma_f32_16x16x32_bf16 v[126:129], v[194:197], v[164:167], v[126:129]
	v_mfma_f32_16x16x32_bf16 v[122:125], v[194:197], v[186:189], v[122:125]
	v_mfma_f32_16x16x32_bf16 v[118:121], v[202:205], v[164:167], v[118:121]
	v_mfma_f32_16x16x32_bf16 v[114:117], v[202:205], v[186:189], v[114:117]
	v_mfma_f32_16x16x32_bf16 v[110:113], v[210:213], v[164:167], v[110:113]
	v_mfma_f32_16x16x32_bf16 v[106:109], v[210:213], v[186:189], v[106:109]
	v_mfma_f32_16x16x32_bf16 v[102:105], v[218:221], v[164:167], v[102:105]
	v_mfma_f32_16x16x32_bf16 v[98:101], v[218:221], v[186:189], v[98:101]
	v_mfma_f32_16x16x32_bf16 v[126:129], v[198:201], v[182:185], v[126:129]
	v_mfma_f32_16x16x32_bf16 v[122:125], v[198:201], v[190:193], v[122:125]
	v_mfma_f32_16x16x32_bf16 v[118:121], v[206:209], v[182:185], v[118:121]
	v_mfma_f32_16x16x32_bf16 v[114:117], v[206:209], v[190:193], v[114:117]
	v_mfma_f32_16x16x32_bf16 v[110:113], v[214:217], v[182:185], v[110:113]
	v_mfma_f32_16x16x32_bf16 v[106:109], v[214:217], v[190:193], v[106:109]
	v_mfma_f32_16x16x32_bf16 v[102:105], v[222:225], v[182:185], v[102:105]
	v_mfma_f32_16x16x32_bf16 v[98:101], v[222:225], v[190:193], v[98:101]
	s_barrier
	v_readfirstlane_b32 s0, v153
	v_lshl_add_u64 v[250:251], v[246:247], 0, s[36:37]
	s_mov_b32 m0, s0
	v_readfirstlane_b32 s0, v154
	ds_read_b128 v[226:229], v145
	ds_read_b128 v[230:233], v145 offset:1024
	ds_read_b128 v[234:237], v145 offset:2048
	ds_read_b128 v[238:241], v145 offset:3072
	global_load_lds_dwordx4 v[250:251], off
	v_lshl_add_u64 v[250:251], v[248:249], 0, s[36:37]
	s_mov_b32 m0, s0
	s_nop 0
	global_load_lds_dwordx4 v[250:251], off
	s_barrier
	s_waitcnt lgkmcnt(0)
	s_waitcnt lgkmcnt(0)
	v_mfma_f32_16x16x32_bf16 v[94:97], v[194:197], v[226:229], v[94:97]
	v_mfma_f32_16x16x32_bf16 v[78:81], v[194:197], v[234:237], v[78:81]
	v_mfma_f32_16x16x32_bf16 v[62:65], v[202:205], v[226:229], v[62:65]
	v_mfma_f32_16x16x32_bf16 v[54:57], v[202:205], v[234:237], v[54:57]
	v_mfma_f32_16x16x32_bf16 v[50:53], v[210:213], v[226:229], v[50:53]
	v_mfma_f32_16x16x32_bf16 v[46:49], v[210:213], v[234:237], v[46:49]
	v_mfma_f32_16x16x32_bf16 v[42:45], v[218:221], v[226:229], v[42:45]
	v_mfma_f32_16x16x32_bf16 v[38:41], v[218:221], v[234:237], v[38:41]
	v_mfma_f32_16x16x32_bf16 v[94:97], v[198:201], v[230:233], v[94:97]
	v_mfma_f32_16x16x32_bf16 v[78:81], v[198:201], v[238:241], v[78:81]
	v_mfma_f32_16x16x32_bf16 v[62:65], v[206:209], v[230:233], v[62:65]
	v_mfma_f32_16x16x32_bf16 v[54:57], v[206:209], v[238:241], v[54:57]
	v_mfma_f32_16x16x32_bf16 v[50:53], v[214:217], v[230:233], v[50:53]
	v_mfma_f32_16x16x32_bf16 v[46:49], v[214:217], v[238:241], v[46:49]
	v_mfma_f32_16x16x32_bf16 v[42:45], v[222:225], v[230:233], v[42:45]
	v_mfma_f32_16x16x32_bf16 v[38:41], v[222:225], v[238:241], v[38:41]
	v_readfirstlane_b32 s0, v155
	v_lshl_add_u64 v[242:243], v[242:243], 0, s[90:91]
	s_mov_b32 m0, s0
	v_readfirstlane_b32 s0, v156
	s_barrier
	ds_read_b128 v[194:197], v142 offset:49152
	ds_read_b128 v[198:201], v142 offset:50176
	ds_read_b128 v[202:205], v142 offset:51200
	ds_read_b128 v[206:209], v142 offset:52224
	ds_read_b128 v[210:213], v142 offset:53248
	ds_read_b128 v[214:217], v142 offset:54272
	ds_read_b128 v[218:221], v142 offset:55296
	ds_read_b128 v[222:225], v142 offset:56320
	global_load_lds_dwordx4 v[242:243], off
	v_lshl_add_u64 v[242:243], v[244:245], 0, s[90:91]
	s_mov_b32 m0, s0
	s_nop 0
	global_load_lds_dwordx4 v[242:243], off
	s_barrier
; #define G_LDA(dst, b, h)                                                                                                  \
;   _Pragma("unroll") for (int m = 0; m < 4; ++m) _Pragma("unroll") for (int k = 0; k < 2; ++k)                             \
;       dst[m][k] = *(const bf16x8*)((const char*)G_SA(b, h) + ((wr * 4 + m) * 2 + k) * 1024 + rdo)
; #define G_LDB(dst, b, h)                                                                                                  \
;   _Pragma("unroll") for (int n = 0; n < 2; ++n) _Pragma("unroll") for (int k = 0; k < 2; ++k)                             \
;       dst[n][k] = *(const bf16x8*)((const char*)G_SB(b, h) + ((wc * 2 + n) * 2 + k) * 1024 + rdo)
; #define G_WAIT_V(n) asm volatile("s_waitcnt vmcnt(" #n ")" ::: "memory")
; #define G_WAIT_L(n) asm volatile("s_waitcnt lgkmcnt(" #n ")" ::: "memory")
; #define G_BAR __builtin_amdgcn_s_barrier()
; #define G_SCHED __builtin_amdgcn_sched_barrier(0)
; DI void br_flush(PREF p, f32x4 (&acc)[2][2][4][2], int slot) { br_store(p, acc, slot); zero_acc256(acc); }
;     ...
;     G_BAR; G_WAIT_L(0); G_MMA(1, 0, At, B0); G_BAR; G_SCHED;
;     G_STAGE(G_SB(1, 1), B, ob0, ob1, LDB, 128, KB(tt + 3));
;     G_WAIT_V(6); G_BAR; G_MMA(1, 1, At, B1); G_BAR;
;     if (MODE && ((tt + 1) & 3) == 3) br_flush(p, acc, (tt + 1) >> 2);
;   }
;   {
;     G_LDB(B0, 0, 0); G_LDA(At, 0, 0); G_STAGE(G_SA(1, 1), A, oa0, oa1, LDA, 128, KA(nt - 1));
;     G_BAR; G_WAIT_L(0); G_MMA(0, 0, At, B0); G_BAR;
;     G_LDB(B1, 0, 1); G_BAR; G_WAIT_L(0); G_MMA(0, 1, At, B1); G_BAR;
	s_waitcnt lgkmcnt(0)
	s_waitcnt lgkmcnt(0)
	v_mfma_f32_16x16x32_bf16 v[34:37], v[194:197], v[164:167], v[34:37]
	v_mfma_f32_16x16x32_bf16 v[30:33], v[194:197], v[186:189], v[30:33]
	v_mfma_f32_16x16x32_bf16 v[26:29], v[202:205], v[164:167], v[26:29]
	v_mfma_f32_16x16x32_bf16 v[22:25], v[202:205], v[186:189], v[22:25]
	v_mfma_f32_16x16x32_bf16 v[18:21], v[210:213], v[164:167], v[18:21]
	v_mfma_f32_16x16x32_bf16 v[14:17], v[210:213], v[186:189], v[14:17]
	v_mfma_f32_16x16x32_bf16 v[10:13], v[218:221], v[164:167], v[10:13]
	v_mfma_f32_16x16x32_bf16 v[6:9], v[218:221], v[186:189], v[6:9]
	v_mfma_f32_16x16x32_bf16 v[34:37], v[198:201], v[182:185], v[34:37]
	v_mfma_f32_16x16x32_bf16 v[30:33], v[198:201], v[190:193], v[30:33]
	v_mfma_f32_16x16x32_bf16 v[26:29], v[206:209], v[182:185], v[26:29]
	v_mfma_f32_16x16x32_bf16 v[22:25], v[206:209], v[190:193], v[22:25]
	v_mfma_f32_16x16x32_bf16 v[18:21], v[214:217], v[182:185], v[18:21]
	v_mfma_f32_16x16x32_bf16 v[14:17], v[214:217], v[190:193], v[14:17]
	v_mfma_f32_16x16x32_bf16 v[10:13], v[222:225], v[182:185], v[10:13]
	v_mfma_f32_16x16x32_bf16 v[6:9], v[222:225], v[190:193], v[6:9]
	s_barrier
	v_readfirstlane_b32 s0, v157
	v_lshl_add_u64 v[164:165], v[246:247], 0, s[40:41]
	s_mov_b32 m0, s0
	v_readfirstlane_b32 s0, v158
	global_load_lds_dwordx4 v[164:165], off
	v_lshl_add_u64 v[164:165], v[248:249], 0, s[40:41]
	s_mov_b32 m0, s0
	s_nop 0
	global_load_lds_dwordx4 v[164:165], off
	s_waitcnt vmcnt(6)
	s_barrier
	v_mfma_f32_16x16x32_bf16 v[2:5], v[194:197], v[226:229], v[2:5]
	v_mfma_f32_16x16x32_bf16 v[58:61], v[194:197], v[234:237], v[58:61]
	v_mfma_f32_16x16x32_bf16 v[66:69], v[202:205], v[226:229], v[66:69]
	v_mfma_f32_16x16x32_bf16 v[70:73], v[202:205], v[234:237], v[70:73]
	v_mfma_f32_16x16x32_bf16 v[74:77], v[210:213], v[226:229], v[74:77]
	v_mfma_f32_16x16x32_bf16 v[82:85], v[210:213], v[234:237], v[82:85]
	v_mfma_f32_16x16x32_bf16 v[86:89], v[218:221], v[226:229], v[86:89]
	v_mfma_f32_16x16x32_bf16 v[90:93], v[218:221], v[234:237], v[90:93]
	v_mfma_f32_16x16x32_bf16 v[2:5], v[198:201], v[230:233], v[2:5]
	v_mfma_f32_16x16x32_bf16 v[58:61], v[198:201], v[238:241], v[58:61]
	v_mfma_f32_16x16x32_bf16 v[66:69], v[206:209], v[230:233], v[66:69]
	v_mfma_f32_16x16x32_bf16 v[70:73], v[206:209], v[238:241], v[70:73]
	v_mfma_f32_16x16x32_bf16 v[74:77], v[214:217], v[230:233], v[74:77]
	v_mfma_f32_16x16x32_bf16 v[82:85], v[214:217], v[238:241], v[82:85]
	v_mfma_f32_16x16x32_bf16 v[86:89], v[222:225], v[230:233], v[86:89]
	v_mfma_f32_16x16x32_bf16 v[90:93], v[222:225], v[238:241], v[90:93]
	s_add_i32 s22, s22, 2
	s_add_u32 s20, s20, 0x100
	s_addc_u32 s21, s21, 0
	s_cmp_lt_u32 s22, 12
	s_barrier
	s_cbranch_scc1 .LBB0_40
	s_add_u32 s0, s16, 0x40780
	s_addc_u32 s1, s17, 0
	v_readfirstlane_b32 s16, v161
	v_lshl_add_u64 v[132:133], v[132:133], 1, s[0:1]
	s_mov_b32 m0, s16
	v_lshl_add_u64 v[130:131], v[130:131], 1, s[0:1]
	v_readfirstlane_b32 s0, v160
	ds_read_b128 v[134:137], v162
	ds_read_b128 v[138:141], v162 offset:1024
	ds_read_b128 v[146:149], v162 offset:2048
	ds_read_b128 v[152:155], v162 offset:3072
	ds_read_b128 v[164:167], v142
	ds_read_b128 v[182:185], v142 offset:1024
	ds_read_b128 v[186:189], v142 offset:2048
	ds_read_b128 v[190:193], v142 offset:3072
	ds_read_b128 v[194:197], v142 offset:4096
	ds_read_b128 v[198:201], v142 offset:5120
	ds_read_b128 v[202:205], v142 offset:6144
	ds_read_b128 v[206:209], v142 offset:7168
	global_load_lds_dwordx4 v[132:133], off
	s_mov_b32 m0, s0
	s_nop 0
	global_load_lds_dwordx4 v[130:131], off
	s_barrier
	s_waitcnt lgkmcnt(0)
	s_waitcnt lgkmcnt(0)
	v_mfma_f32_16x16x32_bf16 v[126:129], v[164:167], v[134:137], v[126:129]
	v_mfma_f32_16x16x32_bf16 v[122:125], v[164:167], v[146:149], v[122:125]
	v_mfma_f32_16x16x32_bf16 v[110:113], v[194:197], v[134:137], v[110:113]
	v_mfma_f32_16x16x32_bf16 v[102:105], v[202:205], v[134:137], v[102:105]
	v_mfma_f32_16x16x32_bf16 v[126:129], v[182:185], v[138:141], v[126:129]
	v_mfma_f32_16x16x32_bf16 v[122:125], v[182:185], v[152:155], v[122:125]
	v_mfma_f32_16x16x32_bf16 v[118:121], v[186:189], v[134:137], v[118:121]
	v_mfma_f32_16x16x32_bf16 v[114:117], v[186:189], v[146:149], v[114:117]
	v_mfma_f32_16x16x32_bf16 v[110:113], v[198:201], v[138:141], v[110:113]
	v_mfma_f32_16x16x32_bf16 v[106:109], v[194:197], v[146:149], v[106:109]
	v_mfma_f32_16x16x32_bf16 v[102:105], v[206:209], v[138:141], v[102:105]
	v_mfma_f32_16x16x32_bf16 v[98:101], v[202:205], v[146:149], v[98:101]
	v_mfma_f32_16x16x32_bf16 v[130:133], v[190:193], v[138:141], v[118:121]
	v_mfma_f32_16x16x32_bf16 v[210:213], v[190:193], v[152:155], v[114:117]
	v_mfma_f32_16x16x32_bf16 v[214:217], v[198:201], v[152:155], v[106:109]
	v_mfma_f32_16x16x32_bf16 v[218:221], v[206:209], v[152:155], v[98:101]
	s_barrier
	s_nop 1
	s_nop 0
	ds_read_b128 v[98:101], v159
	ds_read_b128 v[106:109], v159 offset:1024
	ds_read_b128 v[114:117], v159 offset:2048
	ds_read_b128 v[118:121], v159 offset:3072
	s_barrier
	s_waitcnt lgkmcnt(0)
	s_waitcnt lgkmcnt(0)
	v_mfma_f32_16x16x32_bf16 v[94:97], v[164:167], v[98:101], v[94:97]
	v_mfma_f32_16x16x32_bf16 v[78:81], v[164:167], v[114:117], v[78:81]
	v_mfma_f32_16x16x32_bf16 v[62:65], v[186:189], v[98:101], v[62:65]
	v_mfma_f32_16x16x32_bf16 v[54:57], v[186:189], v[114:117], v[54:57]
	v_mfma_f32_16x16x32_bf16 v[50:53], v[194:197], v[98:101], v[50:53]
	v_mfma_f32_16x16x32_bf16 v[46:49], v[194:197], v[114:117], v[46:49]
	v_mfma_f32_16x16x32_bf16 v[42:45], v[202:205], v[98:101], v[42:45]
	v_mfma_f32_16x16x32_bf16 v[38:41], v[202:205], v[114:117], v[38:41]
	v_mfma_f32_16x16x32_bf16 v[94:97], v[182:185], v[106:109], v[94:97]
	v_mfma_f32_16x16x32_bf16 v[78:81], v[182:185], v[118:121], v[78:81]
	v_mfma_f32_16x16x32_bf16 v[62:65], v[190:193], v[106:109], v[62:65]
	v_mfma_f32_16x16x32_bf16 v[54:57], v[190:193], v[118:121], v[54:57]
	v_mfma_f32_16x16x32_bf16 v[50:53], v[198:201], v[106:109], v[50:53]
	v_mfma_f32_16x16x32_bf16 v[46:49], v[198:201], v[118:121], v[46:49]
	v_mfma_f32_16x16x32_bf16 v[42:45], v[206:209], v[106:109], v[42:45]
	v_mfma_f32_16x16x32_bf16 v[38:41], v[206:209], v[118:121], v[38:41]
	s_barrier
; #define G_LDA(dst, b, h)                                                                                                  \
;   _Pragma("unroll") for (int m = 0; m < 4; ++m) _Pragma("unroll") for (int k = 0; k < 2; ++k)                             \
;       dst[m][k] = *(const bf16x8*)((const char*)G_SA(b, h) + ((wr * 4 + m) * 2 + k) * 1024 + rdo)
; #define G_LDB(dst, b, h)                                                                                                  \
;   _Pragma("unroll") for (int n = 0; n < 2; ++n) _Pragma("unroll") for (int k = 0; k < 2; ++k)                             \
;       dst[n][k] = *(const bf16x8*)((const char*)G_SB(b, h) + ((wc * 2 + n) * 2 + k) * 1024 + rdo)
; #define G_WAIT_V(n) asm volatile("s_waitcnt vmcnt(" #n ")" ::: "memory")
; #define G_WAIT_L(n) asm volatile("s_waitcnt lgkmcnt(" #n ")" ::: "memory")
; #define G_BAR __builtin_amdgcn_s_barrier()
;     ...
;     G_LDA(At, 0, 1); G_WAIT_V(4); G_BAR; G_WAIT_L(0); G_MMA(1, 0, At, B0); G_MMA(1, 1, At, B1); G_BAR;
;   }
;   {
;     G_LDB(B0, 1, 0); G_LDA(At, 1, 0); G_WAIT_V(2); G_BAR; G_WAIT_L(0); G_MMA(0, 0, At, B0); G_BAR;
	ds_read_b128 v[156:159], v142 offset:16384
	ds_read_b128 v[164:167], v142 offset:17408
	ds_read_b128 v[182:185], v142 offset:18432
	ds_read_b128 v[186:189], v142 offset:19456
	ds_read_b128 v[190:193], v142 offset:20480
	ds_read_b128 v[194:197], v142 offset:21504
	ds_read_b128 v[198:201], v142 offset:22528
	ds_read_b128 v[202:205], v142 offset:23552
	s_waitcnt vmcnt(4)
	s_barrier
	s_waitcnt lgkmcnt(0)
	s_waitcnt lgkmcnt(0)
	v_mfma_f32_16x16x32_bf16 v[34:37], v[156:159], v[134:137], v[34:37]
	v_mfma_f32_16x16x32_bf16 v[30:33], v[156:159], v[146:149], v[30:33]
	v_mfma_f32_16x16x32_bf16 v[26:29], v[182:185], v[134:137], v[26:29]
	v_mfma_f32_16x16x32_bf16 v[22:25], v[182:185], v[146:149], v[22:25]
	v_mfma_f32_16x16x32_bf16 v[18:21], v[190:193], v[134:137], v[18:21]
	v_mfma_f32_16x16x32_bf16 v[14:17], v[190:193], v[146:149], v[14:17]
	v_mfma_f32_16x16x32_bf16 v[10:13], v[198:201], v[134:137], v[10:13]
	v_mfma_f32_16x16x32_bf16 v[6:9], v[198:201], v[146:149], v[6:9]
	v_mfma_f32_16x16x32_bf16 v[34:37], v[164:167], v[138:141], v[34:37]
	v_mfma_f32_16x16x32_bf16 v[30:33], v[164:167], v[152:155], v[30:33]
	v_mfma_f32_16x16x32_bf16 v[26:29], v[186:189], v[138:141], v[26:29]
	v_mfma_f32_16x16x32_bf16 v[22:25], v[186:189], v[152:155], v[22:25]
	v_mfma_f32_16x16x32_bf16 v[18:21], v[194:197], v[138:141], v[18:21]
	v_mfma_f32_16x16x32_bf16 v[14:17], v[194:197], v[152:155], v[14:17]
	v_mfma_f32_16x16x32_bf16 v[10:13], v[202:205], v[138:141], v[10:13]
	v_mfma_f32_16x16x32_bf16 v[6:9], v[202:205], v[152:155], v[6:9]
	v_mfma_f32_16x16x32_bf16 v[58:61], v[156:159], v[114:117], v[58:61]
	v_mfma_f32_16x16x32_bf16 v[134:137], v[164:167], v[118:121], v[58:61]
	v_mfma_f32_16x16x32_bf16 v[58:61], v[182:185], v[98:101], v[66:69]
	v_mfma_f32_16x16x32_bf16 v[138:141], v[186:189], v[106:109], v[58:61]
	v_mfma_f32_16x16x32_bf16 v[58:61], v[182:185], v[114:117], v[70:73]
	v_mfma_f32_16x16x32_bf16 v[146:149], v[186:189], v[118:121], v[58:61]
	v_mfma_f32_16x16x32_bf16 v[58:61], v[190:193], v[98:101], v[74:77]
	v_mfma_f32_16x16x32_bf16 v[152:155], v[194:197], v[106:109], v[58:61]
	v_mfma_f32_16x16x32_bf16 v[58:61], v[190:193], v[114:117], v[82:85]
	v_mfma_f32_16x16x32_bf16 v[2:5], v[156:159], v[98:101], v[2:5]
	v_mfma_f32_16x16x32_bf16 v[156:159], v[194:197], v[118:121], v[58:61]
	v_mfma_f32_16x16x32_bf16 v[58:61], v[198:201], v[98:101], v[86:89]
	v_mfma_f32_16x16x32_bf16 v[2:5], v[164:167], v[106:109], v[2:5]
	v_mfma_f32_16x16x32_bf16 v[164:167], v[202:205], v[106:109], v[58:61]
	v_mfma_f32_16x16x32_bf16 v[58:61], v[198:201], v[114:117], v[90:93]
	v_mfma_f32_16x16x32_bf16 v[182:185], v[202:205], v[118:121], v[58:61]
	s_barrier
	ds_read_b128 v[186:189], v150
	ds_read_b128 v[190:193], v150 offset:1024
	ds_read_b128 v[194:197], v150 offset:2048
	ds_read_b128 v[198:201], v150 offset:3072
	s_nop 0
	s_nop 0
	ds_read_b128 v[58:61], v142 offset:32768
	ds_read_b128 v[66:69], v142 offset:33792
	ds_read_b128 v[70:73], v142 offset:34816
	ds_read_b128 v[74:77], v142 offset:35840
	ds_read_b128 v[202:205], v142 offset:36864
	ds_read_b128 v[206:209], v142 offset:37888
	ds_read_b128 v[222:225], v142 offset:38912
	ds_read_b128 v[226:229], v142 offset:39936
	s_waitcnt vmcnt(2)
	s_barrier
	s_waitcnt lgkmcnt(0)
	s_waitcnt lgkmcnt(0)
	v_mfma_f32_16x16x32_bf16 v[82:85], v[58:61], v[186:189], v[126:129]
	v_mfma_f32_16x16x32_bf16 v[118:121], v[66:69], v[190:193], v[82:85]
	v_mfma_f32_16x16x32_bf16 v[82:85], v[58:61], v[194:197], v[122:125]
	v_mfma_f32_16x16x32_bf16 v[126:129], v[66:69], v[198:201], v[82:85]
	v_mfma_f32_16x16x32_bf16 v[82:85], v[70:73], v[186:189], v[130:133]
	v_mfma_f32_16x16x32_bf16 v[114:117], v[74:77], v[190:193], v[82:85]
	v_mfma_f32_16x16x32_bf16 v[82:85], v[70:73], v[194:197], v[210:213]
	v_mfma_f32_16x16x32_bf16 v[122:125], v[74:77], v[198:201], v[82:85]
	v_mfma_f32_16x16x32_bf16 v[82:85], v[202:205], v[186:189], v[110:113]
	v_mfma_f32_16x16x32_bf16 v[106:109], v[206:209], v[190:193], v[82:85]
	v_mfma_f32_16x16x32_bf16 v[82:85], v[202:205], v[194:197], v[214:217]
	v_mfma_f32_16x16x32_bf16 v[110:113], v[206:209], v[198:201], v[82:85]
	v_mfma_f32_16x16x32_bf16 v[82:85], v[222:225], v[186:189], v[102:105]
	v_mfma_f32_16x16x32_bf16 v[98:101], v[226:229], v[190:193], v[82:85]
	v_mfma_f32_16x16x32_bf16 v[82:85], v[222:225], v[194:197], v[218:221]
	v_mfma_f32_16x16x32_bf16 v[102:105], v[226:229], v[198:201], v[82:85]
	s_barrier
; #define G_LDA(dst, b, h)                                                                                                  \
;   _Pragma("unroll") for (int m = 0; m < 4; ++m) _Pragma("unroll") for (int k = 0; k < 2; ++k)                             \
;       dst[m][k] = *(const bf16x8*)((const char*)G_SA(b, h) + ((wr * 4 + m) * 2 + k) * 1024 + rdo)
; #define G_LDB(dst, b, h)                                                                                                  \
;   _Pragma("unroll") for (int n = 0; n < 2; ++n) _Pragma("unroll") for (int k = 0; k < 2; ++k)                             \
;       dst[n][k] = *(const bf16x8*)((const char*)G_SB(b, h) + ((wc * 2 + n) * 2 + k) * 1024 + rdo)
; #define G_WAIT_V(n) asm volatile("s_waitcnt vmcnt(" #n ")" ::: "memory")
; #define G_WAIT_L(n) asm volatile("s_waitcnt lgkmcnt(" #n ")" ::: "memory")
; #define G_BAR __builtin_amdgcn_s_barrier()
;     ...
;     G_LDB(B1, 1, 1); G_WAIT_V(0); G_BAR; G_WAIT_L(0); G_MMA(0, 1, At, B1); G_BAR;
;     G_LDA(At, 1, 1); G_BAR; G_WAIT_L(0); G_MMA(1, 0, At, B0); G_MMA(1, 1, At, B1); G_BAR;
;   }
;   if (wr == 0) G_BAR;
	ds_read_b128 v[130:133], v145
	ds_read_b128 v[210:213], v145 offset:1024
	ds_read_b128 v[214:217], v145 offset:2048
	ds_read_b128 v[218:221], v145 offset:3072
	s_waitcnt vmcnt(0)
	s_barrier
	s_waitcnt lgkmcnt(0)
	s_waitcnt lgkmcnt(0)
	v_mfma_f32_16x16x32_bf16 v[82:85], v[58:61], v[130:133], v[94:97]
	v_mfma_f32_16x16x32_bf16 v[58:61], v[58:61], v[214:217], v[78:81]
	v_mfma_f32_16x16x32_bf16 v[94:97], v[66:69], v[218:221], v[58:61]
	v_mfma_f32_16x16x32_bf16 v[58:61], v[70:73], v[130:133], v[62:65]
	v_mfma_f32_16x16x32_bf16 v[54:57], v[70:73], v[214:217], v[54:57]
	v_mfma_f32_16x16x32_bf16 v[50:53], v[202:205], v[130:133], v[50:53]
	v_mfma_f32_16x16x32_bf16 v[46:49], v[202:205], v[214:217], v[46:49]
	v_mfma_f32_16x16x32_bf16 v[42:45], v[222:225], v[130:133], v[42:45]
	v_mfma_f32_16x16x32_bf16 v[38:41], v[222:225], v[214:217], v[38:41]
	v_mfma_f32_16x16x32_bf16 v[86:89], v[66:69], v[210:213], v[82:85]
	v_mfma_f32_16x16x32_bf16 v[82:85], v[74:77], v[210:213], v[58:61]
	v_mfma_f32_16x16x32_bf16 v[90:93], v[74:77], v[218:221], v[54:57]
	v_mfma_f32_16x16x32_bf16 v[74:77], v[206:209], v[210:213], v[50:53]
	v_mfma_f32_16x16x32_bf16 v[78:81], v[206:209], v[218:221], v[46:49]
	v_mfma_f32_16x16x32_bf16 v[66:69], v[226:229], v[210:213], v[42:45]
	v_mfma_f32_16x16x32_bf16 v[70:73], v[226:229], v[218:221], v[38:41]
	s_barrier
	ds_read_b128 v[202:205], v142 offset:49152
	ds_read_b128 v[206:209], v142 offset:50176
	ds_read_b128 v[222:225], v142 offset:51200
	ds_read_b128 v[226:229], v142 offset:52224
	ds_read_b128 v[230:233], v142 offset:53248
	ds_read_b128 v[234:237], v142 offset:54272
	ds_read_b128 v[238:241], v142 offset:55296
	ds_read_b128 v[142:145], v142 offset:56320
	s_barrier
	s_waitcnt lgkmcnt(0)
	s_waitcnt lgkmcnt(0)
	v_mfma_f32_16x16x32_bf16 v[34:37], v[202:205], v[186:189], v[34:37]
	v_mfma_f32_16x16x32_bf16 v[30:33], v[202:205], v[194:197], v[30:33]
	v_mfma_f32_16x16x32_bf16 v[26:29], v[222:225], v[186:189], v[26:29]
	v_mfma_f32_16x16x32_bf16 v[22:25], v[222:225], v[194:197], v[22:25]
	v_mfma_f32_16x16x32_bf16 v[18:21], v[230:233], v[186:189], v[18:21]
	v_mfma_f32_16x16x32_bf16 v[14:17], v[230:233], v[194:197], v[14:17]
	v_mfma_f32_16x16x32_bf16 v[10:13], v[238:241], v[186:189], v[10:13]
	v_mfma_f32_16x16x32_bf16 v[6:9], v[238:241], v[194:197], v[6:9]
	v_mfma_f32_16x16x32_bf16 v[54:57], v[206:209], v[190:193], v[34:37]
	v_mfma_f32_16x16x32_bf16 v[62:65], v[206:209], v[198:201], v[30:33]
	v_mfma_f32_16x16x32_bf16 v[50:53], v[226:229], v[190:193], v[26:29]
	v_mfma_f32_16x16x32_bf16 v[58:61], v[226:229], v[198:201], v[22:25]
	v_mfma_f32_16x16x32_bf16 v[42:45], v[234:237], v[190:193], v[18:21]
	v_mfma_f32_16x16x32_bf16 v[46:49], v[234:237], v[198:201], v[14:17]
	v_mfma_f32_16x16x32_bf16 v[34:37], v[142:145], v[190:193], v[10:13]
	v_mfma_f32_16x16x32_bf16 v[38:41], v[142:145], v[198:201], v[6:9]
	v_mfma_f32_16x16x32_bf16 v[2:5], v[202:205], v[130:133], v[2:5]
	v_mfma_f32_16x16x32_bf16 v[22:25], v[206:209], v[210:213], v[2:5]
	v_mfma_f32_16x16x32_bf16 v[2:5], v[202:205], v[214:217], v[134:137]
	v_mfma_f32_16x16x32_bf16 v[30:33], v[206:209], v[218:221], v[2:5]
	v_mfma_f32_16x16x32_bf16 v[2:5], v[222:225], v[130:133], v[138:141]
	v_mfma_f32_16x16x32_bf16 v[18:21], v[226:229], v[210:213], v[2:5]
	v_mfma_f32_16x16x32_bf16 v[2:5], v[222:225], v[214:217], v[146:149]
	v_mfma_f32_16x16x32_bf16 v[26:29], v[226:229], v[218:221], v[2:5]
	v_mfma_f32_16x16x32_bf16 v[2:5], v[230:233], v[130:133], v[152:155]
	v_mfma_f32_16x16x32_bf16 v[10:13], v[234:237], v[210:213], v[2:5]
	v_mfma_f32_16x16x32_bf16 v[2:5], v[230:233], v[214:217], v[156:159]
	v_mfma_f32_16x16x32_bf16 v[14:17], v[234:237], v[218:221], v[2:5]
	v_mfma_f32_16x16x32_bf16 v[2:5], v[238:241], v[130:133], v[164:167]
	v_mfma_f32_16x16x32_bf16 v[6:9], v[238:241], v[214:217], v[182:185]
	v_mfma_f32_16x16x32_bf16 v[2:5], v[142:145], v[210:213], v[2:5]
	v_mfma_f32_16x16x32_bf16 v[6:9], v[142:145], v[218:221], v[6:9]
	v_cmp_gt_u32_e32 vcc, s67, v0
	s_barrier
	s_and_saveexec_b64 s[16:17], vcc
	s_cbranch_execz .LBB0_43
	s_barrier

; DI void lds_barrier() { asm volatile("s_waitcnt lgkmcnt(0)\n\ts_barrier" ::: "memory"); }
; DI int tid512() { int t = threadIdx.x; asm volatile("" : "+v"(t)); return t; }
; #define G_LDA(dst, b, h)                                                                                                  \
;   _Pragma("unroll") for (int m = 0; m < 4; ++m) _Pragma("unroll") for (int k = 0; k < 2; ++k)                             \
;       dst[m][k] = *(const bf16x8*)((const char*)G_SA(b, h) + ((wr * 4 + m) * 2 + k) * 1024 + rdo)
; #define G_LDB(dst, b, h)                                                                                                  \
;   _Pragma("unroll") for (int n = 0; n < 2; ++n) _Pragma("unroll") for (int k = 0; k < 2; ++k)                             \
;       dst[n][k] = *(const bf16x8*)((const char*)G_SB(b, h) + ((wc * 2 + n) * 2 + k) * 1024 + rdo)
; #define G_WAIT_V(n) asm volatile("s_waitcnt vmcnt(" #n ")" ::: "memory")
; #define G_WAIT_L(n) asm volatile("s_waitcnt lgkmcnt(" #n ")" ::: "memory")
; #define G_BAR __builtin_amdgcn_s_barrier()
;     ...
;   const int t = tid512();
;   const int wid = t >> 6, lane = t & 63, wr = wid >> 2, wc = wid & 3, fr = lane & 15, fq = lane >> 4;
;   int r0, c0, r1, c1;
;   g_stage_rc(t * 16, r0, c0); g_stage_rc(t * 16 + 8192, r1, c1);
;   const int oa0 = r0 * LDA + c0, oa1 = r1 * LDA + c1, ob0 = r0 * LDB + c0, ob1 = r1 * LDB + c1;
;   const int obr = fr * 64 + fq * 16, rdo = obr ^ (((obr >> 9) & 1) << 5);
;   bf16x8 At[4][2], B0[2][2], B1[2][2];
;   constexpr int nt = K / 64;
;   lds_barrier();
;   G_STAGE(G_SB(0, 0), B, ob0, ob1, LDB, 0, KB(0)); G_STAGE(G_SA(0, 0), A, oa0, oa1, LDA, 0, KA(0));
;   G_STAGE(G_SB(0, 1), B, ob0, ob1, LDB, 128, KB(0)); G_STAGE(G_SA(0, 1), A, oa0, oa1, LDA, 128, KA(0));
;   if (wr == 1) G_BAR;
;   G_WAIT_V(4); G_BAR;
;   G_STAGE(G_SB(1, 0), B, ob0, ob1, LDB, 0, KB(1)); G_STAGE(G_SA(1, 0), A, oa0, oa1, LDA, 0, KA(1)); G_STAGE(G_SB(1, 1), B, ob0, ob1, LDB, 128, KB(1));
;   G_WAIT_V(6); G_BAR;
;   for (int tt = 0; tt < nt - 2; tt += 2) {
;     G_LDB(B0, 0, 0); G_SCHED; G_LDA(At, 0, 0); G_STAGE(G_SA(1, 1), A, oa0, oa1, LDA, 128, KA(tt + 1));
;     G_WAIT_L(8); G_BAR; G_WAIT_L(0); G_MMA(0, 0, At, B0); G_BAR; G_SCHED;
;     G_LDB(B1, 0, 1); G_STAGE(G_SB(0, 0), B, ob0, ob1, LDB, 0, KB(tt + 2));
;     G_BAR; G_WAIT_L(0); G_MMA(0, 1, At, B1); G_BAR;
.LBB0_45:
	s_or_b64 exec, exec, s[22:23]
	v_add_u32_e32 v13, 0x18000, v18
	v_lshl_add_u64 v[24:25], v[6:7], 0, s[76:77]
	v_readfirstlane_b32 s37, v13
	v_add_u32_e32 v13, 0x1a000, v18
	s_mov_b32 m0, s37
	v_readfirstlane_b32 s40, v13
	v_add_u32_e32 v13, 0x8000, v18
	s_waitcnt vmcnt(4)
	s_barrier
	global_load_lds_dwordx4 v[24:25], off
	v_lshl_add_u64 v[24:25], v[8:9], 0, s[76:77]
	s_mov_b32 m0, s40
	v_readfirstlane_b32 s35, v13
	v_add_u32_e32 v13, 0xa000, v18
	global_load_lds_dwordx4 v[24:25], off
	v_lshl_add_u64 v[24:25], v[10:11], 0, s[76:77]
	s_mov_b32 m0, s35
	v_readfirstlane_b32 s36, v13
	s_add_u32 s0, s18, 0x10080
	v_add_u32_e32 v13, 0x1c000, v18
	global_load_lds_dwordx4 v[24:25], off
	v_lshl_add_u64 v[24:25], v[14:15], 0, s[76:77]
	s_mov_b32 m0, s36
	s_addc_u32 s1, s19, 0
	v_readfirstlane_b32 s22, v13
	v_add_u32_e32 v13, 0x1e000, v18
	global_load_lds_dwordx4 v[24:25], off
	v_lshl_add_u64 v[24:25], s[0:1], 0, v[2:3]
	s_mov_b32 m0, s22
	v_readfirstlane_b32 s23, v13
	global_load_lds_dwordx4 v[24:25], off
	v_lshl_add_u64 v[24:25], s[0:1], 0, v[4:5]
	s_mov_b32 m0, s23
	v_lshlrev_b32_e32 v26, 2, v0
	global_load_lds_dwordx4 v[24:25], off
	v_lshlrev_b32_e32 v24, 6, v0
	v_and_b32_e32 v13, 48, v0
	v_and_b32_e32 v25, 0x3c0, v24
	v_and_b32_e32 v41, 32, v26
	v_or_b32_e32 v40, v25, v13
	v_bitop3_b32 v13, v25, v41, v13 bitop3:0x36
	s_movk_i32 s0, 0x3000
	v_and_or_b32 v162, v24, s0, v13
	s_add_u32 s0, s20, 0x10080
	s_addc_u32 s1, s21, 0
	v_lshl_add_u64 v[72:73], s[0:1], 0, v[2:3]
	v_lshl_add_u64 v[74:75], s[0:1], 0, v[4:5]
	s_add_u32 s0, s18, 0x10100
	s_addc_u32 s1, s19, 0
	v_or_b32_e32 v230, 0x10000, v162
	v_or_b32_e32 v232, 0x10800, v162
	s_waitcnt vmcnt(6)
	s_barrier
	v_lshl_add_u64 v[160:161], s[0:1], 0, v[2:3]
	v_lshl_add_u64 v[194:195], s[0:1], 0, v[4:5]
	s_add_u32 s0, s20, 0x10100
	v_or_b32_e32 v231, 0x10400, v162
	ds_read_b128 v[24:27], v230
	ds_read_b128 v[28:31], v231
	v_or_b32_e32 v233, 0x10c00, v162
	ds_read_b128 v[32:35], v232
	ds_read_b128 v[36:39], v233
	s_addc_u32 s1, s21, 0
	v_lshl_add_u64 v[214:215], s[0:1], 0, v[2:3]
	v_lshl_add_u64 v[216:217], s[0:1], 0, v[4:5]
	s_add_u32 s0, s18, 0x10180
	s_addc_u32 s1, s19, 0
	v_lshlrev_b32_e32 v42, 13, v12
	v_lshl_add_u64 v[120:121], v[6:7], 0, s[82:83]
	v_lshl_add_u64 v[122:123], v[8:9], 0, s[82:83]
	v_lshl_add_u64 v[152:153], v[10:11], 0, s[82:83]
	v_lshl_add_u64 v[226:227], v[6:7], 0, s[90:91]
	v_lshl_add_u64 v[228:229], v[8:9], 0, s[90:91]
	v_lshl_add_u64 v[12:13], v[10:11], 0, s[90:91]
	v_lshl_add_u64 v[10:11], v[14:15], 0, s[90:91]
	v_lshl_add_u64 v[8:9], s[0:1], 0, v[2:3]
	v_lshl_add_u64 v[6:7], s[0:1], 0, v[4:5]
	v_lshl_add_u64 v[154:155], v[14:15], 0, s[82:83]
	v_add_u32_e32 v14, 0xc000, v18
	v_bitop3_b32 v242, v40, v42, v41 bitop3:0xde
	v_readfirstlane_b32 s19, v14
	v_add_u32_e32 v14, 0xe000, v18
	s_mov_b32 m0, s19
	v_readfirstlane_b32 s18, v14
	ds_read_b128 v[40:43], v242
	ds_read_b128 v[44:47], v242 offset:1024
	ds_read_b128 v[48:51], v242 offset:2048
	ds_read_b128 v[52:55], v242 offset:3072
	ds_read_b128 v[56:59], v242 offset:4096
	ds_read_b128 v[60:63], v242 offset:5120
	ds_read_b128 v[64:67], v242 offset:6144
	ds_read_b128 v[68:71], v242 offset:7168
	global_load_lds_dwordx4 v[72:73], off
	s_mov_b32 m0, s18
	s_nop 0
	global_load_lds_dwordx4 v[74:75], off
	s_waitcnt lgkmcnt(8)
	s_barrier
	s_waitcnt lgkmcnt(0)
	s_waitcnt lgkmcnt(0)
	v_mfma_f32_16x16x32_bf16 v[72:75], v[40:43], v[24:27], 0
	v_mfma_f32_16x16x32_bf16 v[76:79], v[40:43], v[32:35], 0
	v_mfma_f32_16x16x32_bf16 v[80:83], v[48:51], v[24:27], 0
	v_mfma_f32_16x16x32_bf16 v[84:87], v[48:51], v[32:35], 0
	v_mfma_f32_16x16x32_bf16 v[88:91], v[56:59], v[24:27], 0
	v_mfma_f32_16x16x32_bf16 v[92:95], v[56:59], v[32:35], 0
	v_mfma_f32_16x16x32_bf16 v[96:99], v[64:67], v[24:27], 0
	v_mfma_f32_16x16x32_bf16 v[100:103], v[64:67], v[32:35], 0
	v_mfma_f32_16x16x32_bf16 v[72:75], v[44:47], v[28:31], v[72:75]
	v_mfma_f32_16x16x32_bf16 v[76:79], v[44:47], v[36:39], v[76:79]
	v_mfma_f32_16x16x32_bf16 v[80:83], v[52:55], v[28:31], v[80:83]
	v_mfma_f32_16x16x32_bf16 v[84:87], v[52:55], v[36:39], v[84:87]
	v_mfma_f32_16x16x32_bf16 v[88:91], v[60:63], v[28:31], v[88:91]
	v_mfma_f32_16x16x32_bf16 v[92:95], v[60:63], v[36:39], v[92:95]
	v_mfma_f32_16x16x32_bf16 v[96:99], v[68:71], v[28:31], v[96:99]
	v_mfma_f32_16x16x32_bf16 v[100:103], v[68:71], v[36:39], v[100:103]
	s_barrier
	v_readfirstlane_b32 s0, v22
	v_or_b32_e32 v234, 0x14000, v162
	v_or_b32_e32 v236, 0x14800, v162
	s_mov_b32 m0, s0
	v_readfirstlane_b32 s0, v23
	v_or_b32_e32 v235, 0x14400, v162
	ds_read_b128 v[104:107], v234
	ds_read_b128 v[108:111], v235
	v_or_b32_e32 v237, 0x14c00, v162
	ds_read_b128 v[112:115], v236
	ds_read_b128 v[116:119], v237
	global_load_lds_dwordx4 v[120:121], off
	s_mov_b32 m0, s0
	s_nop 0
	global_load_lds_dwordx4 v[122:123], off
	s_barrier
	s_waitcnt lgkmcnt(0)
	s_waitcnt lgkmcnt(0)
	v_mfma_f32_16x16x32_bf16 v[120:123], v[40:43], v[104:107], 0
	v_mfma_f32_16x16x32_bf16 v[40:43], v[40:43], v[112:115], 0
	v_mfma_f32_16x16x32_bf16 v[120:123], v[44:47], v[108:111], v[120:123]
	v_mfma_f32_16x16x32_bf16 v[40:43], v[44:47], v[116:119], v[40:43]
	v_mfma_f32_16x16x32_bf16 v[44:47], v[48:51], v[104:107], 0
	v_mfma_f32_16x16x32_bf16 v[48:51], v[48:51], v[112:115], 0
	v_mfma_f32_16x16x32_bf16 v[44:47], v[52:55], v[108:111], v[44:47]
	v_mfma_f32_16x16x32_bf16 v[48:51], v[52:55], v[116:119], v[48:51]
	v_mfma_f32_16x16x32_bf16 v[52:55], v[56:59], v[104:107], 0
	v_mfma_f32_16x16x32_bf16 v[56:59], v[56:59], v[112:115], 0
	v_mfma_f32_16x16x32_bf16 v[52:55], v[60:63], v[108:111], v[52:55]
	v_mfma_f32_16x16x32_bf16 v[56:59], v[60:63], v[116:119], v[56:59]
	v_mfma_f32_16x16x32_bf16 v[60:63], v[64:67], v[104:107], 0
	v_mfma_f32_16x16x32_bf16 v[64:67], v[64:67], v[112:115], 0
	v_mfma_f32_16x16x32_bf16 v[60:63], v[68:71], v[108:111], v[60:63]
	v_mfma_f32_16x16x32_bf16 v[64:67], v[68:71], v[116:119], v[64:67]
	v_readfirstlane_b32 s0, v18
	s_mov_b32 m0, s0
	v_readfirstlane_b32 s0, v19
	s_barrier
; #define G_LDA(dst, b, h)                                                                                                  \
;   _Pragma("unroll") for (int m = 0; m < 4; ++m) _Pragma("unroll") for (int k = 0; k < 2; ++k)                             \
;       dst[m][k] = *(const bf16x8*)((const char*)G_SA(b, h) + ((wr * 4 + m) * 2 + k) * 1024 + rdo)
; #define G_LDB(dst, b, h)                                                                                                  \
;   _Pragma("unroll") for (int n = 0; n < 2; ++n) _Pragma("unroll") for (int k = 0; k < 2; ++k)                             \
;       dst[n][k] = *(const bf16x8*)((const char*)G_SB(b, h) + ((wc * 2 + n) * 2 + k) * 1024 + rdo)
; #define G_WAIT_V(n) asm volatile("s_waitcnt vmcnt(" #n ")" ::: "memory")
; #define G_WAIT_L(n) asm volatile("s_waitcnt lgkmcnt(" #n ")" ::: "memory")
; #define G_BAR __builtin_amdgcn_s_barrier()
; #define G_SCHED __builtin_amdgcn_sched_barrier(0)
;     ...
;     G_BAR; G_WAIT_L(0); G_MMA(0, 1, At, B1); G_BAR;
;     G_LDA(At, 0, 1); G_STAGE(G_SA(0, 0), A, oa0, oa1, LDA, 0, KA(tt + 2));
;     G_BAR; G_WAIT_L(0); G_MMA(1, 0, At, B0); G_BAR; G_SCHED;
;     G_STAGE(G_SB(0, 1), B, ob0, ob1, LDB, 128, KB(tt + 2));
;     G_WAIT_V(6); G_BAR; G_MMA(1, 1, At, B1); G_BAR;
;     G_LDB(B0, 1, 0); G_SCHED; G_LDA(At, 1, 0); G_STAGE(G_SA(0, 1), A, oa0, oa1, LDA, 128, KA(tt + 2));
;     G_WAIT_L(8); G_BAR; G_WAIT_L(0); G_MMA(0, 0, At, B0); G_BAR; G_SCHED;
;     G_LDB(B1, 1, 1); G_STAGE(G_SB(1, 0), B, ob0, ob1, LDB, 0, KB(tt + 3));
	ds_read_b128 v[68:71], v242 offset:16384
	ds_read_b128 v[124:127], v242 offset:17408
	ds_read_b128 v[128:131], v242 offset:18432
	ds_read_b128 v[132:135], v242 offset:19456
	ds_read_b128 v[136:139], v242 offset:20480
	ds_read_b128 v[140:143], v242 offset:21504
	ds_read_b128 v[144:147], v242 offset:22528
	ds_read_b128 v[148:151], v242 offset:23552
	global_load_lds_dwordx4 v[152:153], off
	s_mov_b32 m0, s0
	s_nop 0
	global_load_lds_dwordx4 v[154:155], off
	s_barrier
	s_waitcnt lgkmcnt(0)
	s_waitcnt lgkmcnt(0)
	v_mfma_f32_16x16x32_bf16 v[152:155], v[68:71], v[24:27], 0
	v_mfma_f32_16x16x32_bf16 v[164:167], v[128:131], v[24:27], 0
	v_mfma_f32_16x16x32_bf16 v[186:189], v[136:139], v[24:27], 0
	v_mfma_f32_16x16x32_bf16 v[22:25], v[144:147], v[24:27], 0
	v_mfma_f32_16x16x32_bf16 v[152:155], v[124:127], v[28:31], v[152:155]
	v_mfma_f32_16x16x32_bf16 v[164:167], v[132:135], v[28:31], v[164:167]
	v_mfma_f32_16x16x32_bf16 v[186:189], v[140:143], v[28:31], v[186:189]
	v_mfma_f32_16x16x32_bf16 v[22:25], v[148:151], v[28:31], v[22:25]
	v_mfma_f32_16x16x32_bf16 v[26:29], v[144:147], v[32:35], 0
	v_mfma_f32_16x16x32_bf16 v[156:159], v[68:71], v[32:35], 0
	v_mfma_f32_16x16x32_bf16 v[182:185], v[128:131], v[32:35], 0
	v_mfma_f32_16x16x32_bf16 v[190:193], v[136:139], v[32:35], 0
	v_mfma_f32_16x16x32_bf16 v[26:29], v[148:151], v[36:39], v[26:29]
	v_mfma_f32_16x16x32_bf16 v[156:159], v[124:127], v[36:39], v[156:159]
	v_mfma_f32_16x16x32_bf16 v[182:185], v[132:135], v[36:39], v[182:185]
	v_mfma_f32_16x16x32_bf16 v[190:193], v[140:143], v[36:39], v[190:193]
	s_barrier
	v_readfirstlane_b32 s0, v20
	s_mov_b32 m0, s0
	v_readfirstlane_b32 s0, v21
	global_load_lds_dwordx4 v[160:161], off
	s_mov_b32 m0, s0
	s_nop 0
	global_load_lds_dwordx4 v[194:195], off
	s_waitcnt vmcnt(6)
	s_barrier
	v_mfma_f32_16x16x32_bf16 v[18:21], v[68:71], v[104:107], 0
	v_mfma_f32_16x16x32_bf16 v[30:33], v[68:71], v[112:115], 0
	v_mfma_f32_16x16x32_bf16 v[18:21], v[124:127], v[108:111], v[18:21]
	v_mfma_f32_16x16x32_bf16 v[30:33], v[124:127], v[116:119], v[30:33]
	v_mfma_f32_16x16x32_bf16 v[34:37], v[128:131], v[104:107], 0
	v_mfma_f32_16x16x32_bf16 v[124:127], v[136:139], v[104:107], 0
	v_mfma_f32_16x16x32_bf16 v[104:107], v[144:147], v[104:107], 0
	v_mfma_f32_16x16x32_bf16 v[34:37], v[132:135], v[108:111], v[34:37]
	v_mfma_f32_16x16x32_bf16 v[68:71], v[128:131], v[112:115], 0
	v_mfma_f32_16x16x32_bf16 v[124:127], v[140:143], v[108:111], v[124:127]
	v_mfma_f32_16x16x32_bf16 v[128:131], v[136:139], v[112:115], 0
	v_mfma_f32_16x16x32_bf16 v[104:107], v[148:151], v[108:111], v[104:107]
	v_mfma_f32_16x16x32_bf16 v[108:111], v[144:147], v[112:115], 0
	v_mfma_f32_16x16x32_bf16 v[68:71], v[132:135], v[116:119], v[68:71]
	v_mfma_f32_16x16x32_bf16 v[128:131], v[140:143], v[116:119], v[128:131]
	v_mfma_f32_16x16x32_bf16 v[108:111], v[148:151], v[116:119], v[108:111]
	v_or_b32_e32 v160, 0x18000, v162
	v_or_b32_e32 v238, 0x18800, v162
	s_barrier
	v_or_b32_e32 v161, 0x18400, v162
	ds_read_b128 v[112:115], v160
	ds_read_b128 v[116:119], v161
	v_or_b32_e32 v239, 0x18c00, v162
	ds_read_b128 v[132:135], v238
	ds_read_b128 v[136:139], v239
	v_readfirstlane_b32 s0, v16
	s_mov_b32 m0, s0
	v_readfirstlane_b32 s0, v17
	ds_read_b128 v[140:143], v242 offset:32768
	ds_read_b128 v[144:147], v242 offset:33792
	ds_read_b128 v[148:151], v242 offset:34816
	ds_read_b128 v[194:197], v242 offset:35840
	ds_read_b128 v[198:201], v242 offset:36864
	ds_read_b128 v[202:205], v242 offset:37888
	ds_read_b128 v[206:209], v242 offset:38912
	ds_read_b128 v[210:213], v242 offset:39936
	global_load_lds_dwordx4 v[214:215], off
	s_mov_b32 m0, s0
	s_nop 0
	global_load_lds_dwordx4 v[216:217], off
	s_waitcnt lgkmcnt(8)
	s_barrier
	s_waitcnt lgkmcnt(0)
	s_waitcnt lgkmcnt(0)
	v_mfma_f32_16x16x32_bf16 v[14:17], v[140:143], v[112:115], v[72:75]
	v_mfma_f32_16x16x32_bf16 v[72:75], v[140:143], v[132:135], v[76:79]
	v_mfma_f32_16x16x32_bf16 v[76:79], v[148:151], v[112:115], v[80:83]
	v_mfma_f32_16x16x32_bf16 v[80:83], v[148:151], v[132:135], v[84:87]
	v_mfma_f32_16x16x32_bf16 v[84:87], v[198:201], v[112:115], v[88:91]
	v_mfma_f32_16x16x32_bf16 v[88:91], v[198:201], v[132:135], v[92:95]
	v_mfma_f32_16x16x32_bf16 v[92:95], v[206:209], v[112:115], v[96:99]
	v_mfma_f32_16x16x32_bf16 v[96:99], v[206:209], v[132:135], v[100:103]
	v_mfma_f32_16x16x32_bf16 v[14:17], v[144:147], v[116:119], v[14:17]
	v_mfma_f32_16x16x32_bf16 v[72:75], v[144:147], v[136:139], v[72:75]
	v_mfma_f32_16x16x32_bf16 v[76:79], v[194:197], v[116:119], v[76:79]
	v_mfma_f32_16x16x32_bf16 v[80:83], v[194:197], v[136:139], v[80:83]
	v_mfma_f32_16x16x32_bf16 v[84:87], v[202:205], v[116:119], v[84:87]
	v_mfma_f32_16x16x32_bf16 v[88:91], v[202:205], v[136:139], v[88:91]
	v_mfma_f32_16x16x32_bf16 v[92:95], v[210:213], v[116:119], v[92:95]
	v_mfma_f32_16x16x32_bf16 v[96:99], v[210:213], v[136:139], v[96:99]
	s_barrier
	v_or_b32_e32 v240, 0x1c000, v162
	v_or_b32_e32 v243, 0x1c800, v162
	s_mov_b32 m0, s37
	v_or_b32_e32 v241, 0x1c400, v162
	ds_read_b128 v[100:103], v240
	ds_read_b128 v[214:217], v241
	v_or_b32_e32 v162, 0x1cc00, v162
	ds_read_b128 v[218:221], v243
	ds_read_b128 v[222:225], v162
	global_load_lds_dwordx4 v[226:227], off
	s_mov_b32 m0, s40
	s_nop 0
	global_load_lds_dwordx4 v[228:229], off
	s_barrier
; #define G_LDA(dst, b, h)                                                                                                  \
;   _Pragma("unroll") for (int m = 0; m < 4; ++m) _Pragma("unroll") for (int k = 0; k < 2; ++k)                             \
;       dst[m][k] = *(const bf16x8*)((const char*)G_SA(b, h) + ((wr * 4 + m) * 2 + k) * 1024 + rdo)
; #define G_LDB(dst, b, h)                                                                                                  \
;   _Pragma("unroll") for (int n = 0; n < 2; ++n) _Pragma("unroll") for (int k = 0; k < 2; ++k)                             \
;       dst[n][k] = *(const bf16x8*)((const char*)G_SB(b, h) + ((wc * 2 + n) * 2 + k) * 1024 + rdo)
; #define G_WAIT_V(n) asm volatile("s_waitcnt vmcnt(" #n ")" ::: "memory")
; #define G_WAIT_L(n) asm volatile("s_waitcnt lgkmcnt(" #n ")" ::: "memory")
; #define G_BAR __builtin_amdgcn_s_barrier()
; #define G_SCHED __builtin_amdgcn_sched_barrier(0)
; DI void br_flush(PREF p, f32x4 (&acc)[2][2][4][2], int slot) { br_store(p, acc, slot); zero_acc256(acc); }
;     ...
;     G_LDB(B1, 1, 1); G_STAGE(G_SB(1, 0), B, ob0, ob1, LDB, 0, KB(tt + 3));
;     G_BAR; G_WAIT_L(0); G_MMA(0, 1, At, B1); G_BAR;
;     G_LDA(At, 1, 1); G_STAGE(G_SA(1, 0), A, oa0, oa1, LDA, 0, KA(tt + 3));
;     G_BAR; G_WAIT_L(0); G_MMA(1, 0, At, B0); G_BAR; G_SCHED;
;     G_STAGE(G_SB(1, 1), B, ob0, ob1, LDB, 128, KB(tt + 3));
;     G_WAIT_V(6); G_BAR; G_MMA(1, 1, At, B1); G_BAR;
;     if (MODE && ((tt + 1) & 3) == 3) br_flush(p, acc, (tt + 1) >> 2);
;   }
;   {
;     G_LDB(B0, 0, 0); G_LDA(At, 0, 0); G_STAGE(G_SA(1, 1), A, oa0, oa1, LDA, 128, KA(nt - 1));
;     G_BAR; G_WAIT_L(0); G_MMA(0, 0, At, B0); G_BAR;
	s_waitcnt lgkmcnt(0)
	s_waitcnt lgkmcnt(0)
	v_mfma_f32_16x16x32_bf16 v[120:123], v[140:143], v[100:103], v[120:123]
	v_mfma_f32_16x16x32_bf16 v[38:41], v[140:143], v[218:221], v[40:43]
	v_mfma_f32_16x16x32_bf16 v[42:45], v[148:151], v[100:103], v[44:47]
	v_mfma_f32_16x16x32_bf16 v[46:49], v[148:151], v[218:221], v[48:51]
	v_mfma_f32_16x16x32_bf16 v[50:53], v[198:201], v[100:103], v[52:55]
	v_mfma_f32_16x16x32_bf16 v[54:57], v[198:201], v[218:221], v[56:59]
	v_mfma_f32_16x16x32_bf16 v[58:61], v[206:209], v[100:103], v[60:63]
	v_mfma_f32_16x16x32_bf16 v[62:65], v[206:209], v[218:221], v[64:67]
	v_mfma_f32_16x16x32_bf16 v[120:123], v[144:147], v[214:217], v[120:123]
	v_mfma_f32_16x16x32_bf16 v[38:41], v[144:147], v[222:225], v[38:41]
	v_mfma_f32_16x16x32_bf16 v[42:45], v[194:197], v[214:217], v[42:45]
	v_mfma_f32_16x16x32_bf16 v[46:49], v[194:197], v[222:225], v[46:49]
	v_mfma_f32_16x16x32_bf16 v[50:53], v[202:205], v[214:217], v[50:53]
	v_mfma_f32_16x16x32_bf16 v[54:57], v[202:205], v[222:225], v[54:57]
	v_mfma_f32_16x16x32_bf16 v[58:61], v[210:213], v[214:217], v[58:61]
	v_mfma_f32_16x16x32_bf16 v[62:65], v[210:213], v[222:225], v[62:65]
	s_mov_b32 m0, s35
	s_barrier
	ds_read_b128 v[140:143], v242 offset:49152
	ds_read_b128 v[144:147], v242 offset:50176
	ds_read_b128 v[148:151], v242 offset:51200
	ds_read_b128 v[194:197], v242 offset:52224
	ds_read_b128 v[198:201], v242 offset:53248
	ds_read_b128 v[202:205], v242 offset:54272
	ds_read_b128 v[206:209], v242 offset:55296
	ds_read_b128 v[210:213], v242 offset:56320
	global_load_lds_dwordx4 v[12:13], off
	s_mov_b32 m0, s36
	s_nop 0
	global_load_lds_dwordx4 v[10:11], off
	s_barrier
	s_waitcnt lgkmcnt(0)
	s_waitcnt lgkmcnt(0)
	v_mfma_f32_16x16x32_bf16 v[10:13], v[140:143], v[112:115], v[152:155]
	v_mfma_f32_16x16x32_bf16 v[22:25], v[206:209], v[112:115], v[22:25]
	v_mfma_f32_16x16x32_bf16 v[26:29], v[206:209], v[132:135], v[26:29]
	v_mfma_f32_16x16x32_bf16 v[10:13], v[144:147], v[116:119], v[10:13]
	v_mfma_f32_16x16x32_bf16 v[152:155], v[140:143], v[132:135], v[156:159]
	v_mfma_f32_16x16x32_bf16 v[156:159], v[148:151], v[112:115], v[164:167]
	v_mfma_f32_16x16x32_bf16 v[164:167], v[148:151], v[132:135], v[182:185]
	v_mfma_f32_16x16x32_bf16 v[182:185], v[198:201], v[112:115], v[186:189]
	v_mfma_f32_16x16x32_bf16 v[186:189], v[198:201], v[132:135], v[190:193]
	v_mfma_f32_16x16x32_bf16 v[22:25], v[210:213], v[116:119], v[22:25]
	v_mfma_f32_16x16x32_bf16 v[26:29], v[210:213], v[136:139], v[26:29]
	v_mfma_f32_16x16x32_bf16 v[152:155], v[144:147], v[136:139], v[152:155]
	v_mfma_f32_16x16x32_bf16 v[156:159], v[194:197], v[116:119], v[156:159]
	v_mfma_f32_16x16x32_bf16 v[164:167], v[194:197], v[136:139], v[164:167]
	v_mfma_f32_16x16x32_bf16 v[182:185], v[202:205], v[116:119], v[182:185]
	v_mfma_f32_16x16x32_bf16 v[186:189], v[202:205], v[136:139], v[186:189]
	s_barrier
	s_mov_b32 m0, s22
	s_nop 0
	global_load_lds_dwordx4 v[8:9], off
	s_mov_b32 m0, s23
	s_nop 0
	global_load_lds_dwordx4 v[6:7], off
	s_waitcnt vmcnt(6)
	s_barrier
	v_mfma_f32_16x16x32_bf16 v[6:9], v[140:143], v[100:103], v[18:21]
	v_mfma_f32_16x16x32_bf16 v[18:21], v[140:143], v[218:221], v[30:33]
	v_mfma_f32_16x16x32_bf16 v[30:33], v[148:151], v[100:103], v[34:37]
	v_mfma_f32_16x16x32_bf16 v[34:37], v[148:151], v[218:221], v[68:71]
	v_mfma_f32_16x16x32_bf16 v[66:69], v[198:201], v[100:103], v[124:127]
	v_mfma_f32_16x16x32_bf16 v[100:103], v[206:209], v[100:103], v[104:107]
	v_mfma_f32_16x16x32_bf16 v[104:107], v[206:209], v[218:221], v[108:111]
	v_mfma_f32_16x16x32_bf16 v[6:9], v[144:147], v[214:217], v[6:9]
	v_mfma_f32_16x16x32_bf16 v[18:21], v[144:147], v[222:225], v[18:21]
	v_mfma_f32_16x16x32_bf16 v[30:33], v[194:197], v[214:217], v[30:33]
	v_mfma_f32_16x16x32_bf16 v[34:37], v[194:197], v[222:225], v[34:37]
	v_mfma_f32_16x16x32_bf16 v[66:69], v[202:205], v[214:217], v[66:69]
	v_mfma_f32_16x16x32_bf16 v[112:115], v[198:201], v[218:221], v[128:131]
	v_mfma_f32_16x16x32_bf16 v[100:103], v[210:213], v[214:217], v[100:103]
	v_mfma_f32_16x16x32_bf16 v[104:107], v[210:213], v[222:225], v[104:107]
	v_mfma_f32_16x16x32_bf16 v[112:115], v[202:205], v[222:225], v[112:115]
	s_add_u32 s0, s20, 0x10180
	s_addc_u32 s1, s21, 0
	s_mov_b32 m0, s19
	v_lshl_add_u64 v[2:3], s[0:1], 0, v[2:3]
	s_barrier
	ds_read_b128 v[108:111], v230
	ds_read_b128 v[116:119], v231
	ds_read_b128 v[124:127], v232
	ds_read_b128 v[128:131], v233
	ds_read_b128 v[132:135], v242
	ds_read_b128 v[136:139], v242 offset:1024
	ds_read_b128 v[140:143], v242 offset:2048
	ds_read_b128 v[144:147], v242 offset:3072
	ds_read_b128 v[148:151], v242 offset:4096
	ds_read_b128 v[190:193], v242 offset:5120
	ds_read_b128 v[194:197], v242 offset:6144
	ds_read_b128 v[198:201], v242 offset:7168
	global_load_lds_dwordx4 v[2:3], off
	v_lshl_add_u64 v[2:3], s[0:1], 0, v[4:5]
	s_mov_b32 m0, s18
	s_nop 0
	global_load_lds_dwordx4 v[2:3], off
	s_barrier
	s_waitcnt lgkmcnt(0)
	s_waitcnt lgkmcnt(0)
	v_mfma_f32_16x16x32_bf16 v[2:5], v[132:135], v[108:111], v[14:17]
	v_mfma_f32_16x16x32_bf16 v[14:17], v[132:135], v[124:127], v[72:75]
	v_mfma_f32_16x16x32_bf16 v[70:73], v[140:143], v[108:111], v[76:79]
	v_mfma_f32_16x16x32_bf16 v[74:77], v[140:143], v[124:127], v[80:83]
	v_mfma_f32_16x16x32_bf16 v[78:81], v[148:151], v[108:111], v[84:87]
	v_mfma_f32_16x16x32_bf16 v[82:85], v[148:151], v[124:127], v[88:91]
	v_mfma_f32_16x16x32_bf16 v[86:89], v[194:197], v[108:111], v[92:95]
	v_mfma_f32_16x16x32_bf16 v[90:93], v[194:197], v[124:127], v[96:99]
	v_mfma_f32_16x16x32_bf16 v[2:5], v[136:139], v[116:119], v[2:5]
	v_mfma_f32_16x16x32_bf16 v[14:17], v[136:139], v[128:131], v[14:17]
	v_mfma_f32_16x16x32_bf16 v[70:73], v[144:147], v[116:119], v[70:73]
	v_mfma_f32_16x16x32_bf16 v[74:77], v[144:147], v[128:131], v[74:77]
	v_mfma_f32_16x16x32_bf16 v[78:81], v[190:193], v[116:119], v[78:81]
	v_mfma_f32_16x16x32_bf16 v[82:85], v[190:193], v[128:131], v[82:85]
	v_mfma_f32_16x16x32_bf16 v[86:89], v[198:201], v[116:119], v[86:89]
	v_mfma_f32_16x16x32_bf16 v[90:93], v[198:201], v[128:131], v[90:93]
	s_barrier
; #define G_LDA(dst, b, h)                                                                                                  \
;   _Pragma("unroll") for (int m = 0; m < 4; ++m) _Pragma("unroll") for (int k = 0; k < 2; ++k)                             \
;       dst[m][k] = *(const bf16x8*)((const char*)G_SA(b, h) + ((wr * 4 + m) * 2 + k) * 1024 + rdo)
; #define G_LDB(dst, b, h)                                                                                                  \
;   _Pragma("unroll") for (int n = 0; n < 2; ++n) _Pragma("unroll") for (int k = 0; k < 2; ++k)                             \
;       dst[n][k] = *(const bf16x8*)((const char*)G_SB(b, h) + ((wc * 2 + n) * 2 + k) * 1024 + rdo)
; #define G_WAIT_V(n) asm volatile("s_waitcnt vmcnt(" #n ")" ::: "memory")
; #define G_WAIT_L(n) asm volatile("s_waitcnt lgkmcnt(" #n ")" ::: "memory")
; #define G_BAR __builtin_amdgcn_s_barrier()
;     ...
;     G_LDB(B1, 0, 1); G_BAR; G_WAIT_L(0); G_MMA(0, 1, At, B1); G_BAR;
;     G_LDA(At, 0, 1); G_WAIT_V(4); G_BAR; G_WAIT_L(0); G_MMA(1, 0, At, B0); G_MMA(1, 1, At, B1); G_BAR;
;   }
;   {
;     G_LDB(B0, 1, 0); G_LDA(At, 1, 0); G_WAIT_V(2); G_BAR; G_WAIT_L(0); G_MMA(0, 0, At, B0); G_BAR;
	ds_read_b128 v[94:97], v234
	ds_read_b128 v[202:205], v235
	ds_read_b128 v[206:209], v236
	ds_read_b128 v[210:213], v237
	s_barrier
	s_waitcnt lgkmcnt(0)
	s_waitcnt lgkmcnt(0)
	v_mfma_f32_16x16x32_bf16 v[38:41], v[132:135], v[206:209], v[38:41]
	v_mfma_f32_16x16x32_bf16 v[42:45], v[140:143], v[94:97], v[42:45]
	v_mfma_f32_16x16x32_bf16 v[46:49], v[140:143], v[206:209], v[46:49]
	v_mfma_f32_16x16x32_bf16 v[50:53], v[148:151], v[94:97], v[50:53]
	v_mfma_f32_16x16x32_bf16 v[54:57], v[148:151], v[206:209], v[54:57]
	v_mfma_f32_16x16x32_bf16 v[58:61], v[194:197], v[94:97], v[58:61]
	v_mfma_f32_16x16x32_bf16 v[62:65], v[194:197], v[206:209], v[62:65]
	v_mfma_f32_16x16x32_bf16 v[120:123], v[132:135], v[94:97], v[120:123]
	v_mfma_f32_16x16x32_bf16 v[38:41], v[136:139], v[210:213], v[38:41]
	v_mfma_f32_16x16x32_bf16 v[42:45], v[144:147], v[202:205], v[42:45]
	v_mfma_f32_16x16x32_bf16 v[46:49], v[144:147], v[210:213], v[46:49]
	v_mfma_f32_16x16x32_bf16 v[50:53], v[190:193], v[202:205], v[50:53]
	v_mfma_f32_16x16x32_bf16 v[54:57], v[190:193], v[210:213], v[54:57]
	v_mfma_f32_16x16x32_bf16 v[58:61], v[198:201], v[202:205], v[58:61]
	v_mfma_f32_16x16x32_bf16 v[62:65], v[198:201], v[210:213], v[62:65]
	v_mfma_f32_16x16x32_bf16 v[214:217], v[136:139], v[202:205], v[120:123]
	s_barrier
	s_nop 0
	ds_read_b128 v[120:123], v242 offset:16384
	ds_read_b128 v[132:135], v242 offset:17408
	ds_read_b128 v[136:139], v242 offset:18432
	ds_read_b128 v[140:143], v242 offset:19456
	ds_read_b128 v[144:147], v242 offset:20480
	ds_read_b128 v[148:151], v242 offset:21504
	ds_read_b128 v[190:193], v242 offset:22528
	ds_read_b128 v[194:197], v242 offset:23552
	s_waitcnt vmcnt(4)
	s_barrier
	s_waitcnt lgkmcnt(0)
	s_waitcnt lgkmcnt(0)
	v_mfma_f32_16x16x32_bf16 v[10:13], v[120:123], v[108:111], v[10:13]
	v_mfma_f32_16x16x32_bf16 v[22:25], v[190:193], v[108:111], v[22:25]
	v_mfma_f32_16x16x32_bf16 v[26:29], v[190:193], v[124:127], v[26:29]
	v_mfma_f32_16x16x32_bf16 v[10:13], v[132:135], v[116:119], v[10:13]
	v_mfma_f32_16x16x32_bf16 v[152:155], v[120:123], v[124:127], v[152:155]
	v_mfma_f32_16x16x32_bf16 v[156:159], v[136:139], v[108:111], v[156:159]
	v_mfma_f32_16x16x32_bf16 v[164:167], v[136:139], v[124:127], v[164:167]
	v_mfma_f32_16x16x32_bf16 v[182:185], v[144:147], v[108:111], v[182:185]
	v_mfma_f32_16x16x32_bf16 v[186:189], v[144:147], v[124:127], v[186:189]
	v_mfma_f32_16x16x32_bf16 v[22:25], v[194:197], v[116:119], v[22:25]
	v_mfma_f32_16x16x32_bf16 v[26:29], v[194:197], v[128:131], v[26:29]
	v_mfma_f32_16x16x32_bf16 v[152:155], v[132:135], v[128:131], v[152:155]
	v_mfma_f32_16x16x32_bf16 v[156:159], v[140:143], v[116:119], v[156:159]
	v_mfma_f32_16x16x32_bf16 v[164:167], v[140:143], v[128:131], v[164:167]
	v_mfma_f32_16x16x32_bf16 v[182:185], v[148:151], v[116:119], v[182:185]
	v_mfma_f32_16x16x32_bf16 v[186:189], v[148:151], v[128:131], v[186:189]
	v_mfma_f32_16x16x32_bf16 v[30:33], v[136:139], v[94:97], v[30:33]
	v_mfma_f32_16x16x32_bf16 v[126:129], v[140:143], v[202:205], v[30:33]
	v_mfma_f32_16x16x32_bf16 v[30:33], v[136:139], v[206:209], v[34:37]
	v_mfma_f32_16x16x32_bf16 v[198:201], v[140:143], v[210:213], v[30:33]
	v_mfma_f32_16x16x32_bf16 v[30:33], v[144:147], v[94:97], v[66:69]
	v_mfma_f32_16x16x32_bf16 v[218:221], v[148:151], v[202:205], v[30:33]
	v_mfma_f32_16x16x32_bf16 v[30:33], v[144:147], v[206:209], v[112:115]
	v_mfma_f32_16x16x32_bf16 v[6:9], v[120:123], v[94:97], v[6:9]
	v_mfma_f32_16x16x32_bf16 v[18:21], v[120:123], v[206:209], v[18:21]
	v_mfma_f32_16x16x32_bf16 v[110:113], v[148:151], v[210:213], v[30:33]
	v_mfma_f32_16x16x32_bf16 v[30:33], v[190:193], v[94:97], v[100:103]
	v_mfma_f32_16x16x32_bf16 v[6:9], v[132:135], v[202:205], v[6:9]
	v_mfma_f32_16x16x32_bf16 v[18:21], v[132:135], v[210:213], v[18:21]
	v_mfma_f32_16x16x32_bf16 v[114:117], v[194:197], v[202:205], v[30:33]
	v_mfma_f32_16x16x32_bf16 v[30:33], v[190:193], v[206:209], v[104:107]
	v_mfma_f32_16x16x32_bf16 v[102:105], v[194:197], v[210:213], v[30:33]
	s_barrier
	s_nop 4
	s_nop 0
	ds_read_b128 v[30:33], v160
	ds_read_b128 v[34:37], v161
	ds_read_b128 v[146:149], v238
	ds_read_b128 v[190:193], v239
	ds_read_b128 v[66:69], v242 offset:32768
	ds_read_b128 v[94:97], v242 offset:33792
	ds_read_b128 v[194:197], v242 offset:34816
	ds_read_b128 v[202:205], v242 offset:35840
	ds_read_b128 v[206:209], v242 offset:36864
	ds_read_b128 v[210:213], v242 offset:37888
	ds_read_b128 v[222:225], v242 offset:38912
	ds_read_b128 v[226:229], v242 offset:39936
	s_waitcnt vmcnt(2)
	s_barrier
; #define G_LDA(dst, b, h)                                                                                                  \
;   _Pragma("unroll") for (int m = 0; m < 4; ++m) _Pragma("unroll") for (int k = 0; k < 2; ++k)                             \
;       dst[m][k] = *(const bf16x8*)((const char*)G_SA(b, h) + ((wr * 4 + m) * 2 + k) * 1024 + rdo)
; #define G_LDB(dst, b, h)                                                                                                  \
;   _Pragma("unroll") for (int n = 0; n < 2; ++n) _Pragma("unroll") for (int k = 0; k < 2; ++k)                             \
;       dst[n][k] = *(const bf16x8*)((const char*)G_SB(b, h) + ((wc * 2 + n) * 2 + k) * 1024 + rdo)
; #define G_WAIT_V(n) asm volatile("s_waitcnt vmcnt(" #n ")" ::: "memory")
; #define G_WAIT_L(n) asm volatile("s_waitcnt lgkmcnt(" #n ")" ::: "memory")
; #define G_BAR __builtin_amdgcn_s_barrier()
;     ...
;     G_LDB(B0, 1, 0); G_LDA(At, 1, 0); G_WAIT_V(2); G_BAR; G_WAIT_L(0); G_MMA(0, 0, At, B0); G_BAR;
;     G_LDB(B1, 1, 1); G_WAIT_V(0); G_BAR; G_WAIT_L(0); G_MMA(0, 1, At, B1); G_BAR;
;     G_LDA(At, 1, 1); G_BAR; G_WAIT_L(0); G_MMA(1, 0, At, B0); G_MMA(1, 1, At, B1); G_BAR;
;   }
;   if (wr == 0) G_BAR;
	s_waitcnt lgkmcnt(0)
	s_waitcnt lgkmcnt(0)
	v_mfma_f32_16x16x32_bf16 v[2:5], v[66:69], v[30:33], v[2:5]
	v_mfma_f32_16x16x32_bf16 v[134:137], v[94:97], v[34:37], v[2:5]
	v_mfma_f32_16x16x32_bf16 v[2:5], v[66:69], v[146:149], v[14:17]
	v_mfma_f32_16x16x32_bf16 v[142:145], v[94:97], v[190:193], v[2:5]
	v_mfma_f32_16x16x32_bf16 v[2:5], v[194:197], v[30:33], v[70:73]
	v_mfma_f32_16x16x32_bf16 v[130:133], v[202:205], v[34:37], v[2:5]
	v_mfma_f32_16x16x32_bf16 v[2:5], v[194:197], v[146:149], v[74:77]
	v_mfma_f32_16x16x32_bf16 v[138:141], v[202:205], v[190:193], v[2:5]
	v_mfma_f32_16x16x32_bf16 v[2:5], v[206:209], v[30:33], v[78:81]
	v_mfma_f32_16x16x32_bf16 v[118:121], v[210:213], v[34:37], v[2:5]
	v_mfma_f32_16x16x32_bf16 v[2:5], v[206:209], v[146:149], v[82:85]
	v_mfma_f32_16x16x32_bf16 v[122:125], v[210:213], v[190:193], v[2:5]
	v_mfma_f32_16x16x32_bf16 v[2:5], v[222:225], v[30:33], v[86:89]
	v_mfma_f32_16x16x32_bf16 v[98:101], v[226:229], v[34:37], v[2:5]
	v_mfma_f32_16x16x32_bf16 v[2:5], v[222:225], v[146:149], v[90:93]
	v_mfma_f32_16x16x32_bf16 v[106:109], v[226:229], v[190:193], v[2:5]
	s_barrier
	s_nop 4
	s_nop 0
	ds_read_b128 v[2:5], v240
	ds_read_b128 v[230:233], v241
	ds_read_b128 v[234:237], v243
	ds_read_b128 v[238:241], v162
	s_waitcnt vmcnt(0)
	s_barrier
	s_waitcnt lgkmcnt(0)
	s_waitcnt lgkmcnt(0)
	v_mfma_f32_16x16x32_bf16 v[14:17], v[66:69], v[2:5], v[214:217]
	v_mfma_f32_16x16x32_bf16 v[86:89], v[94:97], v[230:233], v[14:17]
	v_mfma_f32_16x16x32_bf16 v[14:17], v[66:69], v[234:237], v[38:41]
	v_mfma_f32_16x16x32_bf16 v[94:97], v[94:97], v[238:241], v[14:17]
	v_mfma_f32_16x16x32_bf16 v[14:17], v[194:197], v[2:5], v[42:45]
	v_mfma_f32_16x16x32_bf16 v[82:85], v[202:205], v[230:233], v[14:17]
	v_mfma_f32_16x16x32_bf16 v[14:17], v[194:197], v[234:237], v[46:49]
	v_mfma_f32_16x16x32_bf16 v[90:93], v[202:205], v[238:241], v[14:17]
	v_mfma_f32_16x16x32_bf16 v[14:17], v[206:209], v[2:5], v[50:53]
	v_mfma_f32_16x16x32_bf16 v[74:77], v[210:213], v[230:233], v[14:17]
	v_mfma_f32_16x16x32_bf16 v[14:17], v[206:209], v[234:237], v[54:57]
	v_mfma_f32_16x16x32_bf16 v[78:81], v[210:213], v[238:241], v[14:17]
	v_mfma_f32_16x16x32_bf16 v[14:17], v[222:225], v[2:5], v[58:61]
	v_mfma_f32_16x16x32_bf16 v[66:69], v[226:229], v[230:233], v[14:17]
	v_mfma_f32_16x16x32_bf16 v[14:17], v[222:225], v[234:237], v[62:65]
	v_mfma_f32_16x16x32_bf16 v[70:73], v[226:229], v[238:241], v[14:17]
	s_barrier
	s_nop 4
	s_nop 0
	ds_read_b128 v[14:17], v242 offset:49152
	ds_read_b128 v[194:197], v242 offset:50176
	ds_read_b128 v[202:205], v242 offset:51200
	ds_read_b128 v[206:209], v242 offset:52224
	ds_read_b128 v[210:213], v242 offset:53248
	ds_read_b128 v[214:217], v242 offset:54272
	ds_read_b128 v[222:225], v242 offset:55296
	ds_read_b128 v[226:229], v242 offset:56320
	s_barrier
	s_waitcnt lgkmcnt(0)
	s_waitcnt lgkmcnt(0)
	v_mfma_f32_16x16x32_bf16 v[10:13], v[14:17], v[30:33], v[10:13]
	v_mfma_f32_16x16x32_bf16 v[54:57], v[194:197], v[34:37], v[10:13]
	v_mfma_f32_16x16x32_bf16 v[10:13], v[14:17], v[146:149], v[152:155]
	v_mfma_f32_16x16x32_bf16 v[62:65], v[194:197], v[190:193], v[10:13]
	v_mfma_f32_16x16x32_bf16 v[10:13], v[202:205], v[30:33], v[156:159]
	v_mfma_f32_16x16x32_bf16 v[50:53], v[206:209], v[34:37], v[10:13]
	v_mfma_f32_16x16x32_bf16 v[10:13], v[202:205], v[146:149], v[164:167]
	v_mfma_f32_16x16x32_bf16 v[58:61], v[206:209], v[190:193], v[10:13]
	v_mfma_f32_16x16x32_bf16 v[10:13], v[210:213], v[30:33], v[182:185]
	v_mfma_f32_16x16x32_bf16 v[42:45], v[214:217], v[34:37], v[10:13]
	v_mfma_f32_16x16x32_bf16 v[10:13], v[210:213], v[146:149], v[186:189]
	v_mfma_f32_16x16x32_bf16 v[46:49], v[214:217], v[190:193], v[10:13]
	v_mfma_f32_16x16x32_bf16 v[10:13], v[222:225], v[30:33], v[22:25]
	v_mfma_f32_16x16x32_bf16 v[34:37], v[226:229], v[34:37], v[10:13]
	v_mfma_f32_16x16x32_bf16 v[10:13], v[222:225], v[146:149], v[26:29]
	v_mfma_f32_16x16x32_bf16 v[38:41], v[226:229], v[190:193], v[10:13]
	v_mfma_f32_16x16x32_bf16 v[6:9], v[14:17], v[2:5], v[6:9]
	v_mfma_f32_16x16x32_bf16 v[22:25], v[194:197], v[230:233], v[6:9]
	v_mfma_f32_16x16x32_bf16 v[6:9], v[14:17], v[234:237], v[18:21]
	v_mfma_f32_16x16x32_bf16 v[30:33], v[194:197], v[238:241], v[6:9]
	v_mfma_f32_16x16x32_bf16 v[6:9], v[202:205], v[2:5], v[126:129]
	v_mfma_f32_16x16x32_bf16 v[18:21], v[206:209], v[230:233], v[6:9]
	v_mfma_f32_16x16x32_bf16 v[6:9], v[202:205], v[234:237], v[198:201]
	v_mfma_f32_16x16x32_bf16 v[26:29], v[206:209], v[238:241], v[6:9]
	v_mfma_f32_16x16x32_bf16 v[6:9], v[210:213], v[2:5], v[218:221]
	v_mfma_f32_16x16x32_bf16 v[10:13], v[214:217], v[230:233], v[6:9]
	v_mfma_f32_16x16x32_bf16 v[6:9], v[210:213], v[234:237], v[110:113]
	v_mfma_f32_16x16x32_bf16 v[14:17], v[214:217], v[238:241], v[6:9]
	v_mfma_f32_16x16x32_bf16 v[2:5], v[222:225], v[2:5], v[114:117]
	v_mfma_f32_16x16x32_bf16 v[6:9], v[222:225], v[234:237], v[102:105]
	v_mfma_f32_16x16x32_bf16 v[2:5], v[226:229], v[230:233], v[2:5]
	v_mfma_f32_16x16x32_bf16 v[6:9], v[226:229], v[238:241], v[6:9]
	v_cmp_gt_u32_e32 vcc, s67, v0
	s_barrier
	s_and_saveexec_b64 s[18:19], vcc
	s_cbranch_execz .LBB0_36
	s_barrier
	s_branch .LBB0_36

; #define G_LDA(dst, b, h)                                                                                                  \
;   _Pragma("unroll") for (int m = 0; m < 4; ++m) _Pragma("unroll") for (int k = 0; k < 2; ++k)                             \
;       dst[m][k] = *(const bf16x8*)((const char*)G_SA(b, h) + ((wr * 4 + m) * 2 + k) * 1024 + rdo)
; #define G_LDB(dst, b, h)                                                                                                  \
;   _Pragma("unroll") for (int n = 0; n < 2; ++n) _Pragma("unroll") for (int k = 0; k < 2; ++k)                             \
;       dst[n][k] = *(const bf16x8*)((const char*)G_SB(b, h) + ((wc * 2 + n) * 2 + k) * 1024 + rdo)
; #define G_WAIT_V(n) asm volatile("s_waitcnt vmcnt(" #n ")" ::: "memory")
; #define G_WAIT_L(n) asm volatile("s_waitcnt lgkmcnt(" #n ")" ::: "memory")
; #define G_BAR __builtin_amdgcn_s_barrier()
; #define G_SCHED __builtin_amdgcn_sched_barrier(0)
;     ...
;   for (int tt = 0; tt < nt - 2; tt += 2) {
;     G_LDB(B0, 0, 0); G_SCHED; G_LDA(At, 0, 0); G_STAGE(G_SA(1, 1), A, oa0, oa1, LDA, 128, KA(tt + 1));
;     G_WAIT_L(8); G_BAR; G_WAIT_L(0); G_MMA(0, 0, At, B0); G_BAR; G_SCHED;
;     G_LDB(B1, 0, 1); G_STAGE(G_SB(0, 0), B, ob0, ob1, LDB, 0, KB(tt + 2));
;     G_BAR; G_WAIT_L(0); G_MMA(0, 1, At, B1); G_BAR;
;     G_LDA(At, 0, 1); G_STAGE(G_SA(0, 0), A, oa0, oa1, LDA, 0, KA(tt + 2));
;     G_BAR; G_WAIT_L(0); G_MMA(1, 0, At, B0); G_BAR; G_SCHED;
;     G_STAGE(G_SB(0, 1), B, ob0, ob1, LDB, 128, KB(tt + 2));
;     G_WAIT_V(6); G_BAR; G_MMA(1, 1, At, B1); G_BAR;
.LBB0_66:
	ds_read_b128 v[164:167], v160
	ds_read_b128 v[182:185], v160 offset:1024
	ds_read_b128 v[186:189], v160 offset:2048
	ds_read_b128 v[190:193], v160 offset:3072
	v_add_u32_e32 v161, 0xc000, v143
	v_lshl_add_u64 v[242:243], v[136:137], 0, s[22:23]
	v_readfirstlane_b32 s0, v161
	v_add_u32_e32 v162, 0xe000, v143
	v_lshl_add_u64 v[226:227], v[242:243], 0, s[78:79]
	s_mov_b32 m0, s0
	v_lshl_add_u64 v[244:245], v[134:135], 0, s[22:23]
	v_readfirstlane_b32 s0, v162
	ds_read_b128 v[194:197], v142
	ds_read_b128 v[198:201], v142 offset:1024
	ds_read_b128 v[202:205], v142 offset:2048
	ds_read_b128 v[206:209], v142 offset:3072
	ds_read_b128 v[210:213], v142 offset:4096
	ds_read_b128 v[214:217], v142 offset:5120
	ds_read_b128 v[218:221], v142 offset:6144
	ds_read_b128 v[222:225], v142 offset:7168
	global_load_lds_dwordx4 v[226:227], off
	v_lshl_add_u64 v[226:227], v[244:245], 0, s[78:79]
	s_mov_b32 m0, s0
	s_nop 0
	global_load_lds_dwordx4 v[226:227], off
	s_waitcnt lgkmcnt(8)
	s_barrier
	s_waitcnt lgkmcnt(0)
	s_waitcnt lgkmcnt(0)
	v_mfma_f32_16x16x32_bf16 v[126:129], v[194:197], v[164:167], v[126:129]
	v_mfma_f32_16x16x32_bf16 v[122:125], v[194:197], v[186:189], v[122:125]
	v_mfma_f32_16x16x32_bf16 v[118:121], v[202:205], v[164:167], v[118:121]
	v_mfma_f32_16x16x32_bf16 v[114:117], v[202:205], v[186:189], v[114:117]
	v_mfma_f32_16x16x32_bf16 v[110:113], v[210:213], v[164:167], v[110:113]
	v_mfma_f32_16x16x32_bf16 v[106:109], v[210:213], v[186:189], v[106:109]
	v_mfma_f32_16x16x32_bf16 v[102:105], v[218:221], v[164:167], v[102:105]
	v_mfma_f32_16x16x32_bf16 v[98:101], v[218:221], v[186:189], v[98:101]
	v_mfma_f32_16x16x32_bf16 v[126:129], v[198:201], v[182:185], v[126:129]
	v_mfma_f32_16x16x32_bf16 v[122:125], v[198:201], v[190:193], v[122:125]
	v_mfma_f32_16x16x32_bf16 v[118:121], v[206:209], v[182:185], v[118:121]
	v_mfma_f32_16x16x32_bf16 v[114:117], v[206:209], v[190:193], v[114:117]
	v_mfma_f32_16x16x32_bf16 v[110:113], v[214:217], v[182:185], v[110:113]
	v_mfma_f32_16x16x32_bf16 v[106:109], v[214:217], v[190:193], v[106:109]
	v_mfma_f32_16x16x32_bf16 v[102:105], v[222:225], v[182:185], v[102:105]
	v_mfma_f32_16x16x32_bf16 v[98:101], v[222:225], v[190:193], v[98:101]
	s_barrier
	v_lshl_add_u64 v[246:247], v[140:141], 0, s[22:23]
	v_readfirstlane_b32 s0, v146
	v_lshl_add_u64 v[248:249], v[246:247], 0, s[48:49]
	s_mov_b32 m0, s0
	ds_read_b128 v[226:229], v158
	ds_read_b128 v[230:233], v158 offset:1024
	ds_read_b128 v[234:237], v158 offset:2048
	ds_read_b128 v[238:241], v158 offset:3072
	global_load_lds_dwordx4 v[248:249], off
	v_lshl_add_u64 v[248:249], v[138:139], 0, s[22:23]
	v_readfirstlane_b32 s0, v147
	v_lshl_add_u64 v[250:251], v[248:249], 0, s[48:49]
	s_mov_b32 m0, s0
	s_nop 0
	global_load_lds_dwordx4 v[250:251], off
	s_barrier
	s_waitcnt lgkmcnt(0)
	s_waitcnt lgkmcnt(0)
	v_mfma_f32_16x16x32_bf16 v[94:97], v[194:197], v[226:229], v[94:97]
	v_mfma_f32_16x16x32_bf16 v[90:93], v[194:197], v[234:237], v[90:93]
	v_mfma_f32_16x16x32_bf16 v[86:89], v[202:205], v[226:229], v[86:89]
	v_mfma_f32_16x16x32_bf16 v[82:85], v[202:205], v[234:237], v[82:85]
	v_mfma_f32_16x16x32_bf16 v[78:81], v[210:213], v[226:229], v[78:81]
	v_mfma_f32_16x16x32_bf16 v[74:77], v[210:213], v[234:237], v[74:77]
	v_mfma_f32_16x16x32_bf16 v[70:73], v[218:221], v[226:229], v[70:73]
	v_mfma_f32_16x16x32_bf16 v[66:69], v[218:221], v[234:237], v[66:69]
	v_mfma_f32_16x16x32_bf16 v[94:97], v[198:201], v[230:233], v[94:97]
	v_mfma_f32_16x16x32_bf16 v[90:93], v[198:201], v[238:241], v[90:93]
	v_mfma_f32_16x16x32_bf16 v[86:89], v[206:209], v[230:233], v[86:89]
	v_mfma_f32_16x16x32_bf16 v[82:85], v[206:209], v[238:241], v[82:85]
	v_mfma_f32_16x16x32_bf16 v[78:81], v[214:217], v[230:233], v[78:81]
	v_mfma_f32_16x16x32_bf16 v[74:77], v[214:217], v[238:241], v[74:77]
	v_mfma_f32_16x16x32_bf16 v[70:73], v[222:225], v[230:233], v[70:73]
	v_mfma_f32_16x16x32_bf16 v[66:69], v[222:225], v[238:241], v[66:69]
	v_readfirstlane_b32 s0, v143
	v_lshl_add_u64 v[250:251], v[242:243], 0, s[82:83]
	s_mov_b32 m0, s0
	v_readfirstlane_b32 s0, v144
	s_barrier
	ds_read_b128 v[194:197], v142 offset:16384
	ds_read_b128 v[198:201], v142 offset:17408
	ds_read_b128 v[202:205], v142 offset:18432
	ds_read_b128 v[206:209], v142 offset:19456
	ds_read_b128 v[210:213], v142 offset:20480
	ds_read_b128 v[214:217], v142 offset:21504
	ds_read_b128 v[218:221], v142 offset:22528
	ds_read_b128 v[222:225], v142 offset:23552
	global_load_lds_dwordx4 v[250:251], off
	v_lshl_add_u64 v[250:251], v[244:245], 0, s[82:83]
	s_mov_b32 m0, s0
	s_nop 0
	global_load_lds_dwordx4 v[250:251], off
	s_barrier
	s_waitcnt lgkmcnt(0)
	s_waitcnt lgkmcnt(0)
	v_mfma_f32_16x16x32_bf16 v[62:65], v[194:197], v[164:167], v[62:65]
	v_mfma_f32_16x16x32_bf16 v[58:61], v[194:197], v[186:189], v[58:61]
	v_mfma_f32_16x16x32_bf16 v[54:57], v[202:205], v[164:167], v[54:57]
	v_mfma_f32_16x16x32_bf16 v[50:53], v[202:205], v[186:189], v[50:53]
	v_mfma_f32_16x16x32_bf16 v[46:49], v[210:213], v[164:167], v[46:49]
	v_mfma_f32_16x16x32_bf16 v[42:45], v[210:213], v[186:189], v[42:45]
	v_mfma_f32_16x16x32_bf16 v[38:41], v[218:221], v[164:167], v[38:41]
	v_mfma_f32_16x16x32_bf16 v[34:37], v[218:221], v[186:189], v[34:37]
	v_mfma_f32_16x16x32_bf16 v[62:65], v[198:201], v[182:185], v[62:65]
	v_mfma_f32_16x16x32_bf16 v[58:61], v[198:201], v[190:193], v[58:61]
	v_mfma_f32_16x16x32_bf16 v[54:57], v[206:209], v[182:185], v[54:57]
	v_mfma_f32_16x16x32_bf16 v[50:53], v[206:209], v[190:193], v[50:53]
	v_mfma_f32_16x16x32_bf16 v[46:49], v[214:217], v[182:185], v[46:49]
	v_mfma_f32_16x16x32_bf16 v[42:45], v[214:217], v[190:193], v[42:45]
	v_mfma_f32_16x16x32_bf16 v[38:41], v[222:225], v[182:185], v[38:41]
	v_mfma_f32_16x16x32_bf16 v[34:37], v[222:225], v[190:193], v[34:37]
	s_barrier
; #define G_LDA(dst, b, h)                                                                                                  \
;   _Pragma("unroll") for (int m = 0; m < 4; ++m) _Pragma("unroll") for (int k = 0; k < 2; ++k)                             \
;       dst[m][k] = *(const bf16x8*)((const char*)G_SA(b, h) + ((wr * 4 + m) * 2 + k) * 1024 + rdo)
; #define G_LDB(dst, b, h)                                                                                                  \
;   _Pragma("unroll") for (int n = 0; n < 2; ++n) _Pragma("unroll") for (int k = 0; k < 2; ++k)                             \
;       dst[n][k] = *(const bf16x8*)((const char*)G_SB(b, h) + ((wc * 2 + n) * 2 + k) * 1024 + rdo)
; #define G_WAIT_V(n) asm volatile("s_waitcnt vmcnt(" #n ")" ::: "memory")
; #define G_WAIT_L(n) asm volatile("s_waitcnt lgkmcnt(" #n ")" ::: "memory")
; #define G_BAR __builtin_amdgcn_s_barrier()
; #define G_SCHED __builtin_amdgcn_sched_barrier(0)
;     ...
;     G_WAIT_V(6); G_BAR; G_MMA(1, 1, At, B1); G_BAR;
;     G_LDB(B0, 1, 0); G_SCHED; G_LDA(At, 1, 0); G_STAGE(G_SA(0, 1), A, oa0, oa1, LDA, 128, KA(tt + 2));
;     G_WAIT_L(8); G_BAR; G_WAIT_L(0); G_MMA(0, 0, At, B0); G_BAR; G_SCHED;
;     G_LDB(B1, 1, 1); G_STAGE(G_SB(1, 0), B, ob0, ob1, LDB, 0, KB(tt + 3));
;     G_BAR; G_WAIT_L(0); G_MMA(0, 1, At, B1); G_BAR;
;     G_LDA(At, 1, 1); G_STAGE(G_SA(1, 0), A, oa0, oa1, LDA, 0, KA(tt + 3));
;     G_BAR; G_WAIT_L(0); G_MMA(1, 0, At, B0); G_BAR; G_SCHED;
;     G_STAGE(G_SB(1, 1), B, ob0, ob1, LDB, 128, KB(tt + 3));
;     G_WAIT_V(6); G_BAR; G_MMA(1, 1, At, B1); G_BAR;
	v_readfirstlane_b32 s0, v148
	v_lshl_add_u64 v[164:165], v[246:247], 0, s[24:25]
	s_mov_b32 m0, s0
	v_readfirstlane_b32 s0, v150
	global_load_lds_dwordx4 v[164:165], off
	v_lshl_add_u64 v[164:165], v[248:249], 0, s[24:25]
	s_mov_b32 m0, s0
	s_nop 0
	global_load_lds_dwordx4 v[164:165], off
	s_waitcnt vmcnt(6)
	s_barrier
	v_mfma_f32_16x16x32_bf16 v[30:33], v[194:197], v[226:229], v[30:33]
	v_mfma_f32_16x16x32_bf16 v[26:29], v[194:197], v[234:237], v[26:29]
	v_mfma_f32_16x16x32_bf16 v[22:25], v[202:205], v[226:229], v[22:25]
	v_mfma_f32_16x16x32_bf16 v[18:21], v[202:205], v[234:237], v[18:21]
	v_mfma_f32_16x16x32_bf16 v[14:17], v[210:213], v[226:229], v[14:17]
	v_mfma_f32_16x16x32_bf16 v[10:13], v[210:213], v[234:237], v[10:13]
	v_mfma_f32_16x16x32_bf16 v[6:9], v[218:221], v[226:229], v[6:9]
	v_mfma_f32_16x16x32_bf16 v[2:5], v[218:221], v[234:237], v[2:5]
	v_mfma_f32_16x16x32_bf16 v[30:33], v[198:201], v[230:233], v[30:33]
	v_mfma_f32_16x16x32_bf16 v[26:29], v[198:201], v[238:241], v[26:29]
	v_mfma_f32_16x16x32_bf16 v[22:25], v[206:209], v[230:233], v[22:25]
	v_mfma_f32_16x16x32_bf16 v[18:21], v[206:209], v[238:241], v[18:21]
	v_mfma_f32_16x16x32_bf16 v[14:17], v[214:217], v[230:233], v[14:17]
	v_mfma_f32_16x16x32_bf16 v[10:13], v[214:217], v[238:241], v[10:13]
	v_mfma_f32_16x16x32_bf16 v[6:9], v[222:225], v[230:233], v[6:9]
	v_mfma_f32_16x16x32_bf16 v[2:5], v[222:225], v[238:241], v[2:5]
	s_barrier
	ds_read_b128 v[164:167], v149
	ds_read_b128 v[182:185], v149 offset:1024
	ds_read_b128 v[186:189], v149 offset:2048
	ds_read_b128 v[190:193], v149 offset:3072
	v_readfirstlane_b32 s0, v151
	v_lshl_add_u64 v[226:227], v[242:243], 0, s[86:87]
	s_mov_b32 m0, s0
	v_readfirstlane_b32 s0, v152
	ds_read_b128 v[194:197], v142 offset:32768
	ds_read_b128 v[198:201], v142 offset:33792
	ds_read_b128 v[202:205], v142 offset:34816
	ds_read_b128 v[206:209], v142 offset:35840
	ds_read_b128 v[210:213], v142 offset:36864
	ds_read_b128 v[214:217], v142 offset:37888
	ds_read_b128 v[218:221], v142 offset:38912
	ds_read_b128 v[222:225], v142 offset:39936
	global_load_lds_dwordx4 v[226:227], off
	v_lshl_add_u64 v[226:227], v[244:245], 0, s[86:87]
	s_mov_b32 m0, s0
	s_nop 0
	global_load_lds_dwordx4 v[226:227], off
	s_waitcnt lgkmcnt(8)
	s_barrier
	s_waitcnt lgkmcnt(0)
	s_waitcnt lgkmcnt(0)
	v_mfma_f32_16x16x32_bf16 v[126:129], v[194:197], v[164:167], v[126:129]
	v_mfma_f32_16x16x32_bf16 v[122:125], v[194:197], v[186:189], v[122:125]
	v_mfma_f32_16x16x32_bf16 v[118:121], v[202:205], v[164:167], v[118:121]
	v_mfma_f32_16x16x32_bf16 v[114:117], v[202:205], v[186:189], v[114:117]
	v_mfma_f32_16x16x32_bf16 v[110:113], v[210:213], v[164:167], v[110:113]
	v_mfma_f32_16x16x32_bf16 v[106:109], v[210:213], v[186:189], v[106:109]
	v_mfma_f32_16x16x32_bf16 v[102:105], v[218:221], v[164:167], v[102:105]
	v_mfma_f32_16x16x32_bf16 v[98:101], v[218:221], v[186:189], v[98:101]
	v_mfma_f32_16x16x32_bf16 v[126:129], v[198:201], v[182:185], v[126:129]
	v_mfma_f32_16x16x32_bf16 v[122:125], v[198:201], v[190:193], v[122:125]
	v_mfma_f32_16x16x32_bf16 v[118:121], v[206:209], v[182:185], v[118:121]
	v_mfma_f32_16x16x32_bf16 v[114:117], v[206:209], v[190:193], v[114:117]
	v_mfma_f32_16x16x32_bf16 v[110:113], v[214:217], v[182:185], v[110:113]
	v_mfma_f32_16x16x32_bf16 v[106:109], v[214:217], v[190:193], v[106:109]
	v_mfma_f32_16x16x32_bf16 v[102:105], v[222:225], v[182:185], v[102:105]
	v_mfma_f32_16x16x32_bf16 v[98:101], v[222:225], v[190:193], v[98:101]
	s_barrier
	v_readfirstlane_b32 s0, v153
	v_lshl_add_u64 v[250:251], v[246:247], 0, s[26:27]
	s_mov_b32 m0, s0
	v_readfirstlane_b32 s0, v154
	ds_read_b128 v[226:229], v145
	ds_read_b128 v[230:233], v145 offset:1024
	ds_read_b128 v[234:237], v145 offset:2048
	ds_read_b128 v[238:241], v145 offset:3072
	global_load_lds_dwordx4 v[250:251], off
	v_lshl_add_u64 v[250:251], v[248:249], 0, s[26:27]
	s_mov_b32 m0, s0
	s_nop 0
	global_load_lds_dwordx4 v[250:251], off
	s_barrier
	s_waitcnt lgkmcnt(0)
	s_waitcnt lgkmcnt(0)
	v_mfma_f32_16x16x32_bf16 v[94:97], v[194:197], v[226:229], v[94:97]
	v_mfma_f32_16x16x32_bf16 v[90:93], v[194:197], v[234:237], v[90:93]
	v_mfma_f32_16x16x32_bf16 v[86:89], v[202:205], v[226:229], v[86:89]
	v_mfma_f32_16x16x32_bf16 v[82:85], v[202:205], v[234:237], v[82:85]
	v_mfma_f32_16x16x32_bf16 v[78:81], v[210:213], v[226:229], v[78:81]
	v_mfma_f32_16x16x32_bf16 v[74:77], v[210:213], v[234:237], v[74:77]
	v_mfma_f32_16x16x32_bf16 v[70:73], v[218:221], v[226:229], v[70:73]
	v_mfma_f32_16x16x32_bf16 v[66:69], v[218:221], v[234:237], v[66:69]
	v_mfma_f32_16x16x32_bf16 v[94:97], v[198:201], v[230:233], v[94:97]
	v_mfma_f32_16x16x32_bf16 v[90:93], v[198:201], v[238:241], v[90:93]
	v_mfma_f32_16x16x32_bf16 v[86:89], v[206:209], v[230:233], v[86:89]
	v_mfma_f32_16x16x32_bf16 v[82:85], v[206:209], v[238:241], v[82:85]
	v_mfma_f32_16x16x32_bf16 v[78:81], v[214:217], v[230:233], v[78:81]
	v_mfma_f32_16x16x32_bf16 v[74:77], v[214:217], v[238:241], v[74:77]
	v_mfma_f32_16x16x32_bf16 v[70:73], v[222:225], v[230:233], v[70:73]
	v_mfma_f32_16x16x32_bf16 v[66:69], v[222:225], v[238:241], v[66:69]
	v_readfirstlane_b32 s0, v155
	v_lshl_add_u64 v[242:243], v[242:243], 0, s[90:91]
	s_mov_b32 m0, s0
	v_readfirstlane_b32 s0, v156
	s_barrier
	ds_read_b128 v[194:197], v142 offset:49152
	ds_read_b128 v[198:201], v142 offset:50176
	ds_read_b128 v[202:205], v142 offset:51200
	ds_read_b128 v[206:209], v142 offset:52224
	ds_read_b128 v[210:213], v142 offset:53248
	ds_read_b128 v[214:217], v142 offset:54272
	ds_read_b128 v[218:221], v142 offset:55296
	ds_read_b128 v[222:225], v142 offset:56320
	global_load_lds_dwordx4 v[242:243], off
	v_lshl_add_u64 v[242:243], v[244:245], 0, s[90:91]
	s_mov_b32 m0, s0
	s_nop 0
	global_load_lds_dwordx4 v[242:243], off
	s_barrier
; #define G_LDA(dst, b, h)                                                                                                  \
;   _Pragma("unroll") for (int m = 0; m < 4; ++m) _Pragma("unroll") for (int k = 0; k < 2; ++k)                             \
;       dst[m][k] = *(const bf16x8*)((const char*)G_SA(b, h) + ((wr * 4 + m) * 2 + k) * 1024 + rdo)
; #define G_LDB(dst, b, h)                                                                                                  \
;   _Pragma("unroll") for (int n = 0; n < 2; ++n) _Pragma("unroll") for (int k = 0; k < 2; ++k)                             \
;       dst[n][k] = *(const bf16x8*)((const char*)G_SB(b, h) + ((wc * 2 + n) * 2 + k) * 1024 + rdo)
; #define G_WAIT_V(n) asm volatile("s_waitcnt vmcnt(" #n ")" ::: "memory")
; #define G_WAIT_L(n) asm volatile("s_waitcnt lgkmcnt(" #n ")" ::: "memory")
; #define G_BAR __builtin_amdgcn_s_barrier()
; #define G_SCHED __builtin_amdgcn_sched_barrier(0)
; DI void br_flush(PREF p, f32x4 (&acc)[2][2][4][2], int slot) { br_store(p, acc, slot); zero_acc256(acc); }
;     ...
;     G_BAR; G_WAIT_L(0); G_MMA(1, 0, At, B0); G_BAR; G_SCHED;
;     G_STAGE(G_SB(1, 1), B, ob0, ob1, LDB, 128, KB(tt + 3));
;     G_WAIT_V(6); G_BAR; G_MMA(1, 1, At, B1); G_BAR;
;     if (MODE && ((tt + 1) & 3) == 3) br_flush(p, acc, (tt + 1) >> 2);
;   }
;   {
;     G_LDB(B0, 0, 0); G_LDA(At, 0, 0); G_STAGE(G_SA(1, 1), A, oa0, oa1, LDA, 128, KA(nt - 1));
;     G_BAR; G_WAIT_L(0); G_MMA(0, 0, At, B0); G_BAR;
;     G_LDB(B1, 0, 1); G_BAR; G_WAIT_L(0); G_MMA(0, 1, At, B1); G_BAR;
;     G_LDA(At, 0, 1); G_WAIT_V(4); G_BAR; G_WAIT_L(0); G_MMA(1, 0, At, B0); G_MMA(1, 1, At, B1); G_BAR;
	s_waitcnt lgkmcnt(0)
	s_waitcnt lgkmcnt(0)
	v_mfma_f32_16x16x32_bf16 v[62:65], v[194:197], v[164:167], v[62:65]
	v_mfma_f32_16x16x32_bf16 v[58:61], v[194:197], v[186:189], v[58:61]
	v_mfma_f32_16x16x32_bf16 v[54:57], v[202:205], v[164:167], v[54:57]
	v_mfma_f32_16x16x32_bf16 v[50:53], v[202:205], v[186:189], v[50:53]
	v_mfma_f32_16x16x32_bf16 v[46:49], v[210:213], v[164:167], v[46:49]
	v_mfma_f32_16x16x32_bf16 v[42:45], v[210:213], v[186:189], v[42:45]
	v_mfma_f32_16x16x32_bf16 v[38:41], v[218:221], v[164:167], v[38:41]
	v_mfma_f32_16x16x32_bf16 v[34:37], v[218:221], v[186:189], v[34:37]
	v_mfma_f32_16x16x32_bf16 v[62:65], v[198:201], v[182:185], v[62:65]
	v_mfma_f32_16x16x32_bf16 v[58:61], v[198:201], v[190:193], v[58:61]
	v_mfma_f32_16x16x32_bf16 v[54:57], v[206:209], v[182:185], v[54:57]
	v_mfma_f32_16x16x32_bf16 v[50:53], v[206:209], v[190:193], v[50:53]
	v_mfma_f32_16x16x32_bf16 v[46:49], v[214:217], v[182:185], v[46:49]
	v_mfma_f32_16x16x32_bf16 v[42:45], v[214:217], v[190:193], v[42:45]
	v_mfma_f32_16x16x32_bf16 v[38:41], v[222:225], v[182:185], v[38:41]
	v_mfma_f32_16x16x32_bf16 v[34:37], v[222:225], v[190:193], v[34:37]
	s_barrier
	v_readfirstlane_b32 s0, v157
	v_lshl_add_u64 v[164:165], v[246:247], 0, s[36:37]
	s_mov_b32 m0, s0
	v_readfirstlane_b32 s0, v159
	global_load_lds_dwordx4 v[164:165], off
	v_lshl_add_u64 v[164:165], v[248:249], 0, s[36:37]
	s_mov_b32 m0, s0
	s_nop 0
	global_load_lds_dwordx4 v[164:165], off
	s_waitcnt vmcnt(6)
	s_barrier
	v_mfma_f32_16x16x32_bf16 v[30:33], v[194:197], v[226:229], v[30:33]
	v_mfma_f32_16x16x32_bf16 v[26:29], v[194:197], v[234:237], v[26:29]
	v_mfma_f32_16x16x32_bf16 v[22:25], v[202:205], v[226:229], v[22:25]
	v_mfma_f32_16x16x32_bf16 v[18:21], v[202:205], v[234:237], v[18:21]
	v_mfma_f32_16x16x32_bf16 v[14:17], v[210:213], v[226:229], v[14:17]
	v_mfma_f32_16x16x32_bf16 v[10:13], v[210:213], v[234:237], v[10:13]
	v_mfma_f32_16x16x32_bf16 v[6:9], v[218:221], v[226:229], v[6:9]
	v_mfma_f32_16x16x32_bf16 v[2:5], v[218:221], v[234:237], v[2:5]
	v_mfma_f32_16x16x32_bf16 v[30:33], v[198:201], v[230:233], v[30:33]
	v_mfma_f32_16x16x32_bf16 v[26:29], v[198:201], v[238:241], v[26:29]
	v_mfma_f32_16x16x32_bf16 v[22:25], v[206:209], v[230:233], v[22:25]
	v_mfma_f32_16x16x32_bf16 v[18:21], v[206:209], v[238:241], v[18:21]
	v_mfma_f32_16x16x32_bf16 v[14:17], v[214:217], v[230:233], v[14:17]
	v_mfma_f32_16x16x32_bf16 v[10:13], v[214:217], v[238:241], v[10:13]
	v_mfma_f32_16x16x32_bf16 v[6:9], v[222:225], v[230:233], v[6:9]
	v_mfma_f32_16x16x32_bf16 v[2:5], v[222:225], v[238:241], v[2:5]
	s_add_i32 s9, s9, 2
	s_add_u32 s22, s22, 0x100
	s_addc_u32 s23, s23, 0
	s_cmp_lt_u32 s9, 12
	s_barrier
	s_cbranch_scc1 .LBB0_66
	s_add_u32 s0, s20, 0x40780
	s_addc_u32 s1, s21, 0
	v_readfirstlane_b32 s9, v161
	v_lshl_add_u64 v[132:133], v[132:133], 1, s[0:1]
	s_mov_b32 m0, s9
	v_lshl_add_u64 v[130:131], v[130:131], 1, s[0:1]
	v_readfirstlane_b32 s0, v162
	ds_read_b128 v[134:137], v160
	ds_read_b128 v[138:141], v160 offset:1024
	ds_read_b128 v[150:153], v160 offset:2048
	ds_read_b128 v[154:157], v160 offset:3072
	ds_read_b128 v[164:167], v142
	ds_read_b128 v[182:185], v142 offset:1024
	ds_read_b128 v[186:189], v142 offset:2048
	ds_read_b128 v[190:193], v142 offset:3072
	ds_read_b128 v[194:197], v142 offset:4096
	ds_read_b128 v[198:201], v142 offset:5120
	ds_read_b128 v[202:205], v142 offset:6144
	ds_read_b128 v[206:209], v142 offset:7168
	global_load_lds_dwordx4 v[132:133], off
	s_mov_b32 m0, s0
	s_nop 0
	global_load_lds_dwordx4 v[130:131], off
	s_barrier
	s_waitcnt lgkmcnt(0)
	s_waitcnt lgkmcnt(0)
	v_mfma_f32_16x16x32_bf16 v[126:129], v[164:167], v[134:137], v[126:129]
	v_mfma_f32_16x16x32_bf16 v[122:125], v[164:167], v[150:153], v[122:125]
	v_mfma_f32_16x16x32_bf16 v[110:113], v[194:197], v[134:137], v[110:113]
	v_mfma_f32_16x16x32_bf16 v[102:105], v[202:205], v[134:137], v[102:105]
	v_mfma_f32_16x16x32_bf16 v[126:129], v[182:185], v[138:141], v[126:129]
	v_mfma_f32_16x16x32_bf16 v[122:125], v[182:185], v[154:157], v[122:125]
	v_mfma_f32_16x16x32_bf16 v[118:121], v[186:189], v[134:137], v[118:121]
	v_mfma_f32_16x16x32_bf16 v[114:117], v[186:189], v[150:153], v[114:117]
	v_mfma_f32_16x16x32_bf16 v[110:113], v[198:201], v[138:141], v[110:113]
	v_mfma_f32_16x16x32_bf16 v[106:109], v[194:197], v[150:153], v[106:109]
	v_mfma_f32_16x16x32_bf16 v[102:105], v[206:209], v[138:141], v[102:105]
	v_mfma_f32_16x16x32_bf16 v[98:101], v[202:205], v[150:153], v[98:101]
	v_mfma_f32_16x16x32_bf16 v[130:133], v[190:193], v[138:141], v[118:121]
	v_mfma_f32_16x16x32_bf16 v[210:213], v[190:193], v[154:157], v[114:117]
	v_mfma_f32_16x16x32_bf16 v[214:217], v[198:201], v[154:157], v[106:109]
	v_mfma_f32_16x16x32_bf16 v[218:221], v[206:209], v[154:157], v[98:101]
	s_barrier
	s_nop 1
	s_nop 0
	ds_read_b128 v[98:101], v158
	ds_read_b128 v[106:109], v158 offset:1024
	ds_read_b128 v[114:117], v158 offset:2048
	ds_read_b128 v[118:121], v158 offset:3072
	s_barrier
	s_waitcnt lgkmcnt(0)
	s_waitcnt lgkmcnt(0)
	v_mfma_f32_16x16x32_bf16 v[94:97], v[164:167], v[98:101], v[94:97]
	v_mfma_f32_16x16x32_bf16 v[90:93], v[164:167], v[114:117], v[90:93]
	v_mfma_f32_16x16x32_bf16 v[78:81], v[194:197], v[98:101], v[78:81]
	v_mfma_f32_16x16x32_bf16 v[70:73], v[202:205], v[98:101], v[70:73]
	v_mfma_f32_16x16x32_bf16 v[94:97], v[182:185], v[106:109], v[94:97]
	v_mfma_f32_16x16x32_bf16 v[90:93], v[182:185], v[118:121], v[90:93]
	v_mfma_f32_16x16x32_bf16 v[86:89], v[186:189], v[98:101], v[86:89]
	v_mfma_f32_16x16x32_bf16 v[82:85], v[186:189], v[114:117], v[82:85]
	v_mfma_f32_16x16x32_bf16 v[78:81], v[198:201], v[106:109], v[78:81]
	v_mfma_f32_16x16x32_bf16 v[74:77], v[194:197], v[114:117], v[74:77]
	v_mfma_f32_16x16x32_bf16 v[70:73], v[206:209], v[106:109], v[70:73]
	v_mfma_f32_16x16x32_bf16 v[66:69], v[202:205], v[114:117], v[66:69]
	v_mfma_f32_16x16x32_bf16 v[158:161], v[190:193], v[106:109], v[86:89]
	v_mfma_f32_16x16x32_bf16 v[164:167], v[190:193], v[118:121], v[82:85]
	v_mfma_f32_16x16x32_bf16 v[182:185], v[198:201], v[118:121], v[74:77]
	v_mfma_f32_16x16x32_bf16 v[186:189], v[206:209], v[118:121], v[66:69]
	s_barrier
; #define G_LDA(dst, b, h)                                                                                                  \
;   _Pragma("unroll") for (int m = 0; m < 4; ++m) _Pragma("unroll") for (int k = 0; k < 2; ++k)                             \
;       dst[m][k] = *(const bf16x8*)((const char*)G_SA(b, h) + ((wr * 4 + m) * 2 + k) * 1024 + rdo)
; #define G_LDB(dst, b, h)                                                                                                  \
;   _Pragma("unroll") for (int n = 0; n < 2; ++n) _Pragma("unroll") for (int k = 0; k < 2; ++k)                             \
;       dst[n][k] = *(const bf16x8*)((const char*)G_SB(b, h) + ((wc * 2 + n) * 2 + k) * 1024 + rdo)
; #define G_WAIT_V(n) asm volatile("s_waitcnt vmcnt(" #n ")" ::: "memory")
; #define G_WAIT_L(n) asm volatile("s_waitcnt lgkmcnt(" #n ")" ::: "memory")
; #define G_BAR __builtin_amdgcn_s_barrier()
;     ...
;     G_LDA(At, 0, 1); G_WAIT_V(4); G_BAR; G_WAIT_L(0); G_MMA(1, 0, At, B0); G_MMA(1, 1, At, B1); G_BAR;
;   }
;   {
;     G_LDB(B0, 1, 0); G_LDA(At, 1, 0); G_WAIT_V(2); G_BAR; G_WAIT_L(0); G_MMA(0, 0, At, B0); G_BAR;
	s_nop 1
	s_nop 0
	ds_read_b128 v[66:69], v142 offset:16384
	ds_read_b128 v[74:77], v142 offset:17408
	ds_read_b128 v[82:85], v142 offset:18432
	ds_read_b128 v[86:89], v142 offset:19456
	ds_read_b128 v[190:193], v142 offset:20480
	ds_read_b128 v[194:197], v142 offset:21504
	ds_read_b128 v[198:201], v142 offset:22528
	ds_read_b128 v[202:205], v142 offset:23552
	s_waitcnt vmcnt(4)
	s_barrier
	s_waitcnt lgkmcnt(0)
	s_waitcnt lgkmcnt(0)
	v_mfma_f32_16x16x32_bf16 v[62:65], v[66:69], v[134:137], v[62:65]
	v_mfma_f32_16x16x32_bf16 v[58:61], v[66:69], v[150:153], v[58:61]
	v_mfma_f32_16x16x32_bf16 v[46:49], v[190:193], v[134:137], v[46:49]
	v_mfma_f32_16x16x32_bf16 v[38:41], v[198:201], v[134:137], v[38:41]
	v_mfma_f32_16x16x32_bf16 v[62:65], v[74:77], v[138:141], v[62:65]
	v_mfma_f32_16x16x32_bf16 v[58:61], v[74:77], v[154:157], v[58:61]
	v_mfma_f32_16x16x32_bf16 v[54:57], v[82:85], v[134:137], v[54:57]
	v_mfma_f32_16x16x32_bf16 v[50:53], v[82:85], v[150:153], v[50:53]
	v_mfma_f32_16x16x32_bf16 v[46:49], v[194:197], v[138:141], v[46:49]
	v_mfma_f32_16x16x32_bf16 v[42:45], v[190:193], v[150:153], v[42:45]
	v_mfma_f32_16x16x32_bf16 v[38:41], v[202:205], v[138:141], v[38:41]
	v_mfma_f32_16x16x32_bf16 v[34:37], v[198:201], v[150:153], v[34:37]
	v_mfma_f32_16x16x32_bf16 v[206:209], v[86:89], v[138:141], v[54:57]
	v_mfma_f32_16x16x32_bf16 v[222:225], v[86:89], v[154:157], v[50:53]
	v_mfma_f32_16x16x32_bf16 v[226:229], v[194:197], v[154:157], v[42:45]
	v_mfma_f32_16x16x32_bf16 v[134:137], v[202:205], v[154:157], v[34:37]
	v_mfma_f32_16x16x32_bf16 v[30:33], v[66:69], v[98:101], v[30:33]
	v_mfma_f32_16x16x32_bf16 v[26:29], v[66:69], v[114:117], v[26:29]
	v_mfma_f32_16x16x32_bf16 v[14:17], v[190:193], v[98:101], v[14:17]
	v_mfma_f32_16x16x32_bf16 v[6:9], v[198:201], v[98:101], v[6:9]
	v_mfma_f32_16x16x32_bf16 v[30:33], v[74:77], v[106:109], v[30:33]
	v_mfma_f32_16x16x32_bf16 v[26:29], v[74:77], v[118:121], v[26:29]
	v_mfma_f32_16x16x32_bf16 v[22:25], v[82:85], v[98:101], v[22:25]
	v_mfma_f32_16x16x32_bf16 v[18:21], v[82:85], v[114:117], v[18:21]
	v_mfma_f32_16x16x32_bf16 v[14:17], v[194:197], v[106:109], v[14:17]
	v_mfma_f32_16x16x32_bf16 v[10:13], v[190:193], v[114:117], v[10:13]
	v_mfma_f32_16x16x32_bf16 v[6:9], v[202:205], v[106:109], v[6:9]
	v_mfma_f32_16x16x32_bf16 v[2:5], v[198:201], v[114:117], v[2:5]
	v_mfma_f32_16x16x32_bf16 v[138:141], v[86:89], v[106:109], v[22:25]
	v_mfma_f32_16x16x32_bf16 v[150:153], v[86:89], v[118:121], v[18:21]
	v_mfma_f32_16x16x32_bf16 v[154:157], v[194:197], v[118:121], v[10:13]
	v_mfma_f32_16x16x32_bf16 v[190:193], v[202:205], v[118:121], v[2:5]
	s_barrier
	s_nop 1
	s_nop 0
	ds_read_b128 v[2:5], v149
	ds_read_b128 v[10:13], v149 offset:1024
	ds_read_b128 v[18:21], v149 offset:2048
	ds_read_b128 v[22:25], v149 offset:3072
	ds_read_b128 v[34:37], v142 offset:32768
	ds_read_b128 v[42:45], v142 offset:33792
	ds_read_b128 v[50:53], v142 offset:34816
	ds_read_b128 v[54:57], v142 offset:35840
	ds_read_b128 v[66:69], v142 offset:36864
	ds_read_b128 v[146:149], v142 offset:37888
	ds_read_b128 v[194:197], v142 offset:38912
	ds_read_b128 v[198:201], v142 offset:39936
	s_waitcnt vmcnt(2)
	s_barrier
	s_waitcnt lgkmcnt(0)
	s_waitcnt lgkmcnt(0)
	v_mfma_f32_16x16x32_bf16 v[74:77], v[34:37], v[2:5], v[126:129]
	v_mfma_f32_16x16x32_bf16 v[118:121], v[42:45], v[10:13], v[74:77]
	v_mfma_f32_16x16x32_bf16 v[74:77], v[34:37], v[18:21], v[122:125]
	v_mfma_f32_16x16x32_bf16 v[126:129], v[42:45], v[22:25], v[74:77]
	v_mfma_f32_16x16x32_bf16 v[74:77], v[50:53], v[2:5], v[130:133]
	v_mfma_f32_16x16x32_bf16 v[114:117], v[54:57], v[10:13], v[74:77]
	v_mfma_f32_16x16x32_bf16 v[74:77], v[50:53], v[18:21], v[210:213]
	v_mfma_f32_16x16x32_bf16 v[122:125], v[54:57], v[22:25], v[74:77]
	v_mfma_f32_16x16x32_bf16 v[74:77], v[66:69], v[2:5], v[110:113]
	v_mfma_f32_16x16x32_bf16 v[106:109], v[146:149], v[10:13], v[74:77]
	v_mfma_f32_16x16x32_bf16 v[74:77], v[66:69], v[18:21], v[214:217]
	v_mfma_f32_16x16x32_bf16 v[110:113], v[146:149], v[22:25], v[74:77]
	v_mfma_f32_16x16x32_bf16 v[74:77], v[194:197], v[2:5], v[102:105]
	v_mfma_f32_16x16x32_bf16 v[98:101], v[198:201], v[10:13], v[74:77]
	v_mfma_f32_16x16x32_bf16 v[74:77], v[194:197], v[18:21], v[218:221]
	v_mfma_f32_16x16x32_bf16 v[102:105], v[198:201], v[22:25], v[74:77]
	s_barrier
; #define G_LDA(dst, b, h)                                                                                                  \
;   _Pragma("unroll") for (int m = 0; m < 4; ++m) _Pragma("unroll") for (int k = 0; k < 2; ++k)                             \
;       dst[m][k] = *(const bf16x8*)((const char*)G_SA(b, h) + ((wr * 4 + m) * 2 + k) * 1024 + rdo)
; #define G_LDB(dst, b, h)                                                                                                  \
;   _Pragma("unroll") for (int n = 0; n < 2; ++n) _Pragma("unroll") for (int k = 0; k < 2; ++k)                             \
;       dst[n][k] = *(const bf16x8*)((const char*)G_SB(b, h) + ((wc * 2 + n) * 2 + k) * 1024 + rdo)
; #define G_WAIT_V(n) asm volatile("s_waitcnt vmcnt(" #n ")" ::: "memory")
; #define G_WAIT_L(n) asm volatile("s_waitcnt lgkmcnt(" #n ")" ::: "memory")
; #define G_BAR __builtin_amdgcn_s_barrier()
;     ...
;     G_LDB(B0, 1, 0); G_LDA(At, 1, 0); G_WAIT_V(2); G_BAR; G_WAIT_L(0); G_MMA(0, 0, At, B0); G_BAR;
;     G_LDB(B1, 1, 1); G_WAIT_V(0); G_BAR; G_WAIT_L(0); G_MMA(0, 1, At, B1); G_BAR;
;     G_LDA(At, 1, 1); G_BAR; G_WAIT_L(0); G_MMA(1, 0, At, B0); G_MMA(1, 1, At, B1); G_BAR;
;   }
;   if (wr == 0) G_BAR;
	ds_read_b128 v[130:133], v145
	ds_read_b128 v[202:205], v145 offset:1024
	ds_read_b128 v[210:213], v145 offset:2048
	ds_read_b128 v[214:217], v145 offset:3072
	s_waitcnt vmcnt(0)
	s_barrier
	s_waitcnt lgkmcnt(0)
	s_waitcnt lgkmcnt(0)
	v_mfma_f32_16x16x32_bf16 v[74:77], v[34:37], v[130:133], v[94:97]
	v_mfma_f32_16x16x32_bf16 v[34:37], v[34:37], v[210:213], v[90:93]
	v_mfma_f32_16x16x32_bf16 v[94:97], v[42:45], v[214:217], v[34:37]
	v_mfma_f32_16x16x32_bf16 v[34:37], v[50:53], v[130:133], v[158:161]
	v_mfma_f32_16x16x32_bf16 v[82:85], v[54:57], v[202:205], v[34:37]
	v_mfma_f32_16x16x32_bf16 v[34:37], v[50:53], v[210:213], v[164:167]
	v_mfma_f32_16x16x32_bf16 v[90:93], v[54:57], v[214:217], v[34:37]
	v_mfma_f32_16x16x32_bf16 v[34:37], v[66:69], v[130:133], v[78:81]
	v_mfma_f32_16x16x32_bf16 v[86:89], v[42:45], v[202:205], v[74:77]
	v_mfma_f32_16x16x32_bf16 v[74:77], v[146:149], v[202:205], v[34:37]
	v_mfma_f32_16x16x32_bf16 v[34:37], v[66:69], v[210:213], v[182:185]
	v_mfma_f32_16x16x32_bf16 v[78:81], v[146:149], v[214:217], v[34:37]
	v_mfma_f32_16x16x32_bf16 v[34:37], v[194:197], v[130:133], v[70:73]
	v_mfma_f32_16x16x32_bf16 v[66:69], v[198:201], v[202:205], v[34:37]
	v_mfma_f32_16x16x32_bf16 v[34:37], v[194:197], v[210:213], v[186:189]
	v_mfma_f32_16x16x32_bf16 v[70:73], v[198:201], v[214:217], v[34:37]
	s_barrier
	ds_read_b128 v[144:147], v142 offset:49152
	ds_read_b128 v[158:161], v142 offset:50176
	ds_read_b128 v[164:167], v142 offset:51200
	ds_read_b128 v[182:185], v142 offset:52224
	ds_read_b128 v[186:189], v142 offset:53248
	ds_read_b128 v[194:197], v142 offset:54272
	ds_read_b128 v[198:201], v142 offset:55296
	ds_read_b128 v[218:221], v142 offset:56320
	s_barrier
	s_waitcnt lgkmcnt(0)
	s_waitcnt lgkmcnt(0)
	v_mfma_f32_16x16x32_bf16 v[34:37], v[144:147], v[2:5], v[62:65]
	v_mfma_f32_16x16x32_bf16 v[54:57], v[158:161], v[10:13], v[34:37]
	v_mfma_f32_16x16x32_bf16 v[34:37], v[144:147], v[18:21], v[58:61]
	v_mfma_f32_16x16x32_bf16 v[62:65], v[158:161], v[22:25], v[34:37]
	v_mfma_f32_16x16x32_bf16 v[34:37], v[164:167], v[2:5], v[206:209]
	v_mfma_f32_16x16x32_bf16 v[50:53], v[182:185], v[10:13], v[34:37]
	v_mfma_f32_16x16x32_bf16 v[34:37], v[164:167], v[18:21], v[222:225]
	v_mfma_f32_16x16x32_bf16 v[58:61], v[182:185], v[22:25], v[34:37]
	v_mfma_f32_16x16x32_bf16 v[34:37], v[186:189], v[2:5], v[46:49]
	v_mfma_f32_16x16x32_bf16 v[42:45], v[194:197], v[10:13], v[34:37]
	v_mfma_f32_16x16x32_bf16 v[34:37], v[186:189], v[18:21], v[226:229]
	v_mfma_f32_16x16x32_bf16 v[2:5], v[198:201], v[2:5], v[38:41]
	v_mfma_f32_16x16x32_bf16 v[46:49], v[194:197], v[22:25], v[34:37]
	v_mfma_f32_16x16x32_bf16 v[34:37], v[218:221], v[10:13], v[2:5]
	v_mfma_f32_16x16x32_bf16 v[2:5], v[198:201], v[18:21], v[134:137]
	v_mfma_f32_16x16x32_bf16 v[38:41], v[218:221], v[22:25], v[2:5]
	v_mfma_f32_16x16x32_bf16 v[2:5], v[144:147], v[130:133], v[30:33]
	v_mfma_f32_16x16x32_bf16 v[22:25], v[158:161], v[202:205], v[2:5]
	v_mfma_f32_16x16x32_bf16 v[2:5], v[144:147], v[210:213], v[26:29]
	v_mfma_f32_16x16x32_bf16 v[30:33], v[158:161], v[214:217], v[2:5]
	v_mfma_f32_16x16x32_bf16 v[2:5], v[164:167], v[130:133], v[138:141]
	v_mfma_f32_16x16x32_bf16 v[18:21], v[182:185], v[202:205], v[2:5]
	v_mfma_f32_16x16x32_bf16 v[2:5], v[164:167], v[210:213], v[150:153]
	v_mfma_f32_16x16x32_bf16 v[26:29], v[182:185], v[214:217], v[2:5]
	v_mfma_f32_16x16x32_bf16 v[2:5], v[186:189], v[130:133], v[14:17]
	v_mfma_f32_16x16x32_bf16 v[10:13], v[194:197], v[202:205], v[2:5]
	v_mfma_f32_16x16x32_bf16 v[2:5], v[186:189], v[210:213], v[154:157]
	v_mfma_f32_16x16x32_bf16 v[14:17], v[194:197], v[214:217], v[2:5]
	v_mfma_f32_16x16x32_bf16 v[2:5], v[198:201], v[130:133], v[6:9]
	v_mfma_f32_16x16x32_bf16 v[6:9], v[198:201], v[210:213], v[190:193]
	v_mfma_f32_16x16x32_bf16 v[2:5], v[218:221], v[202:205], v[2:5]
	v_mfma_f32_16x16x32_bf16 v[6:9], v[218:221], v[214:217], v[6:9]
	v_cmp_gt_u32_e32 vcc, s67, v0
	s_barrier
	s_and_saveexec_b64 s[20:21], vcc
	s_cbranch_execz .LBB0_69
	s_barrier

; #define G_LDA(dst, b, h)                                                                                                  \
;   _Pragma("unroll") for (int m = 0; m < 4; ++m) _Pragma("unroll") for (int k = 0; k < 2; ++k)                             \
;       dst[m][k] = *(const bf16x8*)((const char*)G_SA(b, h) + ((wr * 4 + m) * 2 + k) * 1024 + rdo)
; #define G_LDB(dst, b, h)                                                                                                  \
;   _Pragma("unroll") for (int n = 0; n < 2; ++n) _Pragma("unroll") for (int k = 0; k < 2; ++k)                             \
;       dst[n][k] = *(const bf16x8*)((const char*)G_SB(b, h) + ((wc * 2 + n) * 2 + k) * 1024 + rdo)
; #define G_WAIT_V(n) asm volatile("s_waitcnt vmcnt(" #n ")" ::: "memory")
; #define G_WAIT_L(n) asm volatile("s_waitcnt lgkmcnt(" #n ")" ::: "memory")
; #define G_BAR __builtin_amdgcn_s_barrier()
; #define G_SCHED __builtin_amdgcn_sched_barrier(0)
;     ...
;   for (int tt = 0; tt < nt - 2; tt += 2) {
;     G_LDB(B0, 0, 0); G_SCHED; G_LDA(At, 0, 0); G_STAGE(G_SA(1, 1), A, oa0, oa1, LDA, 128, KA(tt + 1));
;     G_WAIT_L(8); G_BAR; G_WAIT_L(0); G_MMA(0, 0, At, B0); G_BAR; G_SCHED;
;     G_LDB(B1, 0, 1); G_STAGE(G_SB(0, 0), B, ob0, ob1, LDB, 0, KB(tt + 2));
;     G_BAR; G_WAIT_L(0); G_MMA(0, 1, At, B1); G_BAR;
;     G_LDA(At, 0, 1); G_STAGE(G_SA(0, 0), A, oa0, oa1, LDA, 0, KA(tt + 2));
;     G_BAR; G_WAIT_L(0); G_MMA(1, 0, At, B0); G_BAR; G_SCHED;
;     G_STAGE(G_SB(0, 1), B, ob0, ob1, LDB, 128, KB(tt + 2));
;     G_WAIT_V(6); G_BAR; G_MMA(1, 1, At, B1); G_BAR;
.LBB0_96:
	ds_read_b128 v[182:185], v151
	ds_read_b128 v[186:189], v151 offset:1024
	ds_read_b128 v[190:193], v151 offset:2048
	ds_read_b128 v[194:197], v151 offset:3072
	v_add_u32_e32 v162, 0xc000, v147
	v_lshl_add_u64 v[166:167], s[30:31], 0, v[140:141]
	v_readfirstlane_b32 s0, v162
	v_lshl_add_u64 v[164:165], v[166:167], 0, s[78:79]
	s_mov_b32 m0, s0
	ds_read_b128 v[198:201], v143
	ds_read_b128 v[202:205], v143 offset:1024
	ds_read_b128 v[206:209], v143 offset:2048
	ds_read_b128 v[210:213], v143 offset:3072
	ds_read_b128 v[214:217], v143 offset:4096
	ds_read_b128 v[218:221], v143 offset:5120
	ds_read_b128 v[222:225], v143 offset:6144
	ds_read_b128 v[226:229], v143 offset:7168
	global_load_lds_dwordx4 v[164:165], off
	v_add_u32_e32 v164, 0xe000, v147
	v_lshl_add_u64 v[246:247], s[30:31], 0, v[138:139]
	v_readfirstlane_b32 s0, v164
	v_lshl_add_u64 v[230:231], v[246:247], 0, s[78:79]
	s_mov_b32 m0, s0
	s_add_i32 s34, s13, -1
	global_load_lds_dwordx4 v[230:231], off
	s_waitcnt lgkmcnt(8)
	s_barrier
	s_waitcnt lgkmcnt(0)
	s_waitcnt lgkmcnt(0)
	v_mfma_f32_16x16x32_bf16 v[126:129], v[198:201], v[182:185], v[126:129]
	v_mfma_f32_16x16x32_bf16 v[122:125], v[198:201], v[190:193], v[122:125]
	v_mfma_f32_16x16x32_bf16 v[118:121], v[206:209], v[182:185], v[118:121]
	v_mfma_f32_16x16x32_bf16 v[114:117], v[206:209], v[190:193], v[114:117]
	v_mfma_f32_16x16x32_bf16 v[110:113], v[214:217], v[182:185], v[110:113]
	v_mfma_f32_16x16x32_bf16 v[106:109], v[214:217], v[190:193], v[106:109]
	v_mfma_f32_16x16x32_bf16 v[102:105], v[222:225], v[182:185], v[102:105]
	v_mfma_f32_16x16x32_bf16 v[98:101], v[222:225], v[190:193], v[98:101]
	v_mfma_f32_16x16x32_bf16 v[126:129], v[202:205], v[186:189], v[126:129]
	v_mfma_f32_16x16x32_bf16 v[122:125], v[202:205], v[194:197], v[122:125]
	v_mfma_f32_16x16x32_bf16 v[118:121], v[210:213], v[186:189], v[118:121]
	v_mfma_f32_16x16x32_bf16 v[114:117], v[210:213], v[194:197], v[114:117]
	v_mfma_f32_16x16x32_bf16 v[110:113], v[218:221], v[186:189], v[110:113]
	v_mfma_f32_16x16x32_bf16 v[106:109], v[218:221], v[194:197], v[106:109]
	v_mfma_f32_16x16x32_bf16 v[102:105], v[226:229], v[186:189], v[102:105]
	v_mfma_f32_16x16x32_bf16 v[98:101], v[226:229], v[194:197], v[98:101]
	s_barrier
	s_add_i32 s0, s25, 0xffff0000
	s_sub_i32 s1, s23, 64
	s_and_b32 s0, s0, 0x1c0000
	s_and_b32 s1, s1, 0x80
	s_or_b32 s0, s0, s1
	s_lshl_b32 s35, s0, 1
	s_add_u32 s0, s26, s35
	s_addc_u32 s1, s27, 0
	v_readfirstlane_b32 s36, v149
	v_lshl_add_u64 v[248:249], s[0:1], 0, v[134:135]
	s_mov_b32 m0, s36
	ds_read_b128 v[230:233], v146
	ds_read_b128 v[234:237], v146 offset:1024
	ds_read_b128 v[238:241], v146 offset:2048
	ds_read_b128 v[242:245], v146 offset:3072
	global_load_lds_dwordx4 v[248:249], off
	v_lshl_add_u64 v[248:249], s[0:1], 0, v[136:137]
	v_readfirstlane_b32 s0, v150
	s_mov_b32 m0, s0
	s_nop 0
	global_load_lds_dwordx4 v[248:249], off
	s_barrier
	s_waitcnt lgkmcnt(0)
	s_waitcnt lgkmcnt(0)
	v_mfma_f32_16x16x32_bf16 v[94:97], v[198:201], v[230:233], v[94:97]
	v_mfma_f32_16x16x32_bf16 v[90:93], v[198:201], v[238:241], v[90:93]
	v_mfma_f32_16x16x32_bf16 v[86:89], v[206:209], v[230:233], v[86:89]
	v_mfma_f32_16x16x32_bf16 v[82:85], v[206:209], v[238:241], v[82:85]
	v_mfma_f32_16x16x32_bf16 v[78:81], v[214:217], v[230:233], v[78:81]
	v_mfma_f32_16x16x32_bf16 v[74:77], v[214:217], v[238:241], v[74:77]
	v_mfma_f32_16x16x32_bf16 v[70:73], v[222:225], v[230:233], v[70:73]
	v_mfma_f32_16x16x32_bf16 v[66:69], v[222:225], v[238:241], v[66:69]
	v_mfma_f32_16x16x32_bf16 v[94:97], v[202:205], v[234:237], v[94:97]
	v_mfma_f32_16x16x32_bf16 v[90:93], v[202:205], v[242:245], v[90:93]
	v_mfma_f32_16x16x32_bf16 v[86:89], v[210:213], v[234:237], v[86:89]
	v_mfma_f32_16x16x32_bf16 v[82:85], v[210:213], v[242:245], v[82:85]
	v_mfma_f32_16x16x32_bf16 v[78:81], v[218:221], v[234:237], v[78:81]
	v_mfma_f32_16x16x32_bf16 v[74:77], v[218:221], v[242:245], v[74:77]
	v_mfma_f32_16x16x32_bf16 v[70:73], v[226:229], v[234:237], v[70:73]
	v_mfma_f32_16x16x32_bf16 v[66:69], v[226:229], v[242:245], v[66:69]
	v_readfirstlane_b32 s0, v147
	v_lshl_add_u64 v[248:249], v[166:167], 0, s[82:83]
	s_mov_b32 m0, s0
	v_readfirstlane_b32 s0, v148
	s_barrier
	ds_read_b128 v[198:201], v143 offset:16384
	ds_read_b128 v[202:205], v143 offset:17408
	ds_read_b128 v[206:209], v143 offset:18432
	ds_read_b128 v[210:213], v143 offset:19456
	ds_read_b128 v[214:217], v143 offset:20480
	ds_read_b128 v[218:221], v143 offset:21504
	ds_read_b128 v[222:225], v143 offset:22528
	ds_read_b128 v[226:229], v143 offset:23552
	global_load_lds_dwordx4 v[248:249], off
	v_lshl_add_u64 v[248:249], v[246:247], 0, s[82:83]
	s_mov_b32 m0, s0
	s_nop 0
	global_load_lds_dwordx4 v[248:249], off
	s_barrier
	s_waitcnt lgkmcnt(0)
	s_waitcnt lgkmcnt(0)
	v_mfma_f32_16x16x32_bf16 v[62:65], v[198:201], v[182:185], v[62:65]
	v_mfma_f32_16x16x32_bf16 v[58:61], v[198:201], v[190:193], v[58:61]
	v_mfma_f32_16x16x32_bf16 v[54:57], v[206:209], v[182:185], v[54:57]
	v_mfma_f32_16x16x32_bf16 v[50:53], v[206:209], v[190:193], v[50:53]
	v_mfma_f32_16x16x32_bf16 v[46:49], v[214:217], v[182:185], v[46:49]
	v_mfma_f32_16x16x32_bf16 v[42:45], v[214:217], v[190:193], v[42:45]
	v_mfma_f32_16x16x32_bf16 v[38:41], v[222:225], v[182:185], v[38:41]
	v_mfma_f32_16x16x32_bf16 v[34:37], v[222:225], v[190:193], v[34:37]
	v_mfma_f32_16x16x32_bf16 v[62:65], v[202:205], v[186:189], v[62:65]
	v_mfma_f32_16x16x32_bf16 v[58:61], v[202:205], v[194:197], v[58:61]
	v_mfma_f32_16x16x32_bf16 v[54:57], v[210:213], v[186:189], v[54:57]
	v_mfma_f32_16x16x32_bf16 v[50:53], v[210:213], v[194:197], v[50:53]
	v_mfma_f32_16x16x32_bf16 v[46:49], v[218:221], v[186:189], v[46:49]
	v_mfma_f32_16x16x32_bf16 v[42:45], v[218:221], v[194:197], v[42:45]
	v_mfma_f32_16x16x32_bf16 v[38:41], v[226:229], v[186:189], v[38:41]
	v_mfma_f32_16x16x32_bf16 v[34:37], v[226:229], v[194:197], v[34:37]
	s_barrier
; #define G_LDA(dst, b, h)                                                                                                  \
;   _Pragma("unroll") for (int m = 0; m < 4; ++m) _Pragma("unroll") for (int k = 0; k < 2; ++k)                             \
;       dst[m][k] = *(const bf16x8*)((const char*)G_SA(b, h) + ((wr * 4 + m) * 2 + k) * 1024 + rdo)
; #define G_LDB(dst, b, h)                                                                                                  \
;   _Pragma("unroll") for (int n = 0; n < 2; ++n) _Pragma("unroll") for (int k = 0; k < 2; ++k)                             \
;       dst[n][k] = *(const bf16x8*)((const char*)G_SB(b, h) + ((wc * 2 + n) * 2 + k) * 1024 + rdo)
; #define G_WAIT_V(n) asm volatile("s_waitcnt vmcnt(" #n ")" ::: "memory")
; #define G_WAIT_L(n) asm volatile("s_waitcnt lgkmcnt(" #n ")" ::: "memory")
; #define G_BAR __builtin_amdgcn_s_barrier()
; #define G_SCHED __builtin_amdgcn_sched_barrier(0)
;     ...
;     G_WAIT_V(6); G_BAR; G_MMA(1, 1, At, B1); G_BAR;
;     G_LDB(B0, 1, 0); G_SCHED; G_LDA(At, 1, 0); G_STAGE(G_SA(0, 1), A, oa0, oa1, LDA, 128, KA(tt + 2));
;     G_WAIT_L(8); G_BAR; G_WAIT_L(0); G_MMA(0, 0, At, B0); G_BAR; G_SCHED;
;     G_LDB(B1, 1, 1); G_STAGE(G_SB(1, 0), B, ob0, ob1, LDB, 0, KB(tt + 3));
;     G_BAR; G_WAIT_L(0); G_MMA(0, 1, At, B1); G_BAR;
;     G_LDA(At, 1, 1); G_STAGE(G_SA(1, 0), A, oa0, oa1, LDA, 0, KA(tt + 3));
;     G_BAR; G_WAIT_L(0); G_MMA(1, 0, At, B0); G_BAR; G_SCHED;
	s_add_u32 s0, s28, s35
	s_addc_u32 s1, s29, 0
	v_readfirstlane_b32 s35, v152
	v_lshl_add_u64 v[182:183], s[0:1], 0, v[134:135]
	s_mov_b32 m0, s35
	s_nop 0
	global_load_lds_dwordx4 v[182:183], off
	v_lshl_add_u64 v[182:183], s[0:1], 0, v[136:137]
	v_readfirstlane_b32 s0, v153
	s_mov_b32 m0, s0
	s_nop 0
	global_load_lds_dwordx4 v[182:183], off
	s_waitcnt vmcnt(6)
	s_barrier
	v_mfma_f32_16x16x32_bf16 v[30:33], v[198:201], v[230:233], v[30:33]
	v_mfma_f32_16x16x32_bf16 v[26:29], v[198:201], v[238:241], v[26:29]
	v_mfma_f32_16x16x32_bf16 v[22:25], v[206:209], v[230:233], v[22:25]
	v_mfma_f32_16x16x32_bf16 v[18:21], v[206:209], v[238:241], v[18:21]
	v_mfma_f32_16x16x32_bf16 v[14:17], v[214:217], v[230:233], v[14:17]
	v_mfma_f32_16x16x32_bf16 v[10:13], v[214:217], v[238:241], v[10:13]
	v_mfma_f32_16x16x32_bf16 v[6:9], v[222:225], v[230:233], v[6:9]
	v_mfma_f32_16x16x32_bf16 v[2:5], v[222:225], v[238:241], v[2:5]
	v_mfma_f32_16x16x32_bf16 v[30:33], v[202:205], v[234:237], v[30:33]
	v_mfma_f32_16x16x32_bf16 v[26:29], v[202:205], v[242:245], v[26:29]
	v_mfma_f32_16x16x32_bf16 v[22:25], v[210:213], v[234:237], v[22:25]
	v_mfma_f32_16x16x32_bf16 v[18:21], v[210:213], v[242:245], v[18:21]
	v_mfma_f32_16x16x32_bf16 v[14:17], v[218:221], v[234:237], v[14:17]
	v_mfma_f32_16x16x32_bf16 v[10:13], v[218:221], v[242:245], v[10:13]
	v_mfma_f32_16x16x32_bf16 v[6:9], v[226:229], v[234:237], v[6:9]
	v_mfma_f32_16x16x32_bf16 v[2:5], v[226:229], v[242:245], v[2:5]
	s_barrier
	ds_read_b128 v[182:185], v145
	ds_read_b128 v[186:189], v145 offset:1024
	ds_read_b128 v[190:193], v145 offset:2048
	ds_read_b128 v[194:197], v145 offset:3072
	v_readfirstlane_b32 s0, v154
	v_lshl_add_u64 v[230:231], v[166:167], 0, s[86:87]
	s_mov_b32 m0, s0
	v_readfirstlane_b32 s0, v155
	ds_read_b128 v[198:201], v143 offset:32768
	ds_read_b128 v[202:205], v143 offset:33792
	ds_read_b128 v[206:209], v143 offset:34816
	ds_read_b128 v[210:213], v143 offset:35840
	ds_read_b128 v[214:217], v143 offset:36864
	ds_read_b128 v[218:221], v143 offset:37888
	ds_read_b128 v[222:225], v143 offset:38912
	ds_read_b128 v[226:229], v143 offset:39936
	global_load_lds_dwordx4 v[230:231], off
	v_lshl_add_u64 v[230:231], v[246:247], 0, s[86:87]
	s_mov_b32 m0, s0
	s_nop 0
	global_load_lds_dwordx4 v[230:231], off
	s_waitcnt lgkmcnt(8)
	s_barrier
	s_waitcnt lgkmcnt(0)
	s_waitcnt lgkmcnt(0)
	v_mfma_f32_16x16x32_bf16 v[126:129], v[198:201], v[182:185], v[126:129]
	v_mfma_f32_16x16x32_bf16 v[122:125], v[198:201], v[190:193], v[122:125]
	v_mfma_f32_16x16x32_bf16 v[118:121], v[206:209], v[182:185], v[118:121]
	v_mfma_f32_16x16x32_bf16 v[114:117], v[206:209], v[190:193], v[114:117]
	v_mfma_f32_16x16x32_bf16 v[110:113], v[214:217], v[182:185], v[110:113]
	v_mfma_f32_16x16x32_bf16 v[106:109], v[214:217], v[190:193], v[106:109]
	v_mfma_f32_16x16x32_bf16 v[102:105], v[222:225], v[182:185], v[102:105]
	v_mfma_f32_16x16x32_bf16 v[98:101], v[222:225], v[190:193], v[98:101]
	v_mfma_f32_16x16x32_bf16 v[126:129], v[202:205], v[186:189], v[126:129]
	v_mfma_f32_16x16x32_bf16 v[122:125], v[202:205], v[194:197], v[122:125]
	v_mfma_f32_16x16x32_bf16 v[118:121], v[210:213], v[186:189], v[118:121]
	v_mfma_f32_16x16x32_bf16 v[114:117], v[210:213], v[194:197], v[114:117]
	v_mfma_f32_16x16x32_bf16 v[110:113], v[218:221], v[186:189], v[110:113]
	v_mfma_f32_16x16x32_bf16 v[106:109], v[218:221], v[194:197], v[106:109]
	v_mfma_f32_16x16x32_bf16 v[102:105], v[226:229], v[186:189], v[102:105]
	v_mfma_f32_16x16x32_bf16 v[98:101], v[226:229], v[194:197], v[98:101]
	s_barrier
	s_and_b32 s0, s25, 0x1c0000
	s_and_b32 s1, s23, 0xc0
	s_or_b32 s0, s0, s1
	s_lshl_b32 s35, s0, 1
	s_add_u32 s0, s26, s35
	s_addc_u32 s1, s27, 0
	v_readfirstlane_b32 s36, v156
	v_lshl_add_u64 v[248:249], s[0:1], 0, v[134:135]
	s_mov_b32 m0, s36
	ds_read_b128 v[230:233], v144
	ds_read_b128 v[234:237], v144 offset:1024
	ds_read_b128 v[238:241], v144 offset:2048
	ds_read_b128 v[242:245], v144 offset:3072
	global_load_lds_dwordx4 v[248:249], off
	v_lshl_add_u64 v[248:249], s[0:1], 0, v[136:137]
	v_readfirstlane_b32 s0, v157
	s_mov_b32 m0, s0
	s_nop 0
	global_load_lds_dwordx4 v[248:249], off
	s_barrier
	s_waitcnt lgkmcnt(0)
	s_waitcnt lgkmcnt(0)
	v_mfma_f32_16x16x32_bf16 v[94:97], v[198:201], v[230:233], v[94:97]
	v_mfma_f32_16x16x32_bf16 v[90:93], v[198:201], v[238:241], v[90:93]
	v_mfma_f32_16x16x32_bf16 v[86:89], v[206:209], v[230:233], v[86:89]
	v_mfma_f32_16x16x32_bf16 v[82:85], v[206:209], v[238:241], v[82:85]
	v_mfma_f32_16x16x32_bf16 v[78:81], v[214:217], v[230:233], v[78:81]
	v_mfma_f32_16x16x32_bf16 v[74:77], v[214:217], v[238:241], v[74:77]
	v_mfma_f32_16x16x32_bf16 v[70:73], v[222:225], v[230:233], v[70:73]
	v_mfma_f32_16x16x32_bf16 v[66:69], v[222:225], v[238:241], v[66:69]
	v_mfma_f32_16x16x32_bf16 v[94:97], v[202:205], v[234:237], v[94:97]
	v_mfma_f32_16x16x32_bf16 v[90:93], v[202:205], v[242:245], v[90:93]
	v_mfma_f32_16x16x32_bf16 v[86:89], v[210:213], v[234:237], v[86:89]
	v_mfma_f32_16x16x32_bf16 v[82:85], v[210:213], v[242:245], v[82:85]
	v_mfma_f32_16x16x32_bf16 v[78:81], v[218:221], v[234:237], v[78:81]
	v_mfma_f32_16x16x32_bf16 v[74:77], v[218:221], v[242:245], v[74:77]
	v_mfma_f32_16x16x32_bf16 v[70:73], v[226:229], v[234:237], v[70:73]
	v_mfma_f32_16x16x32_bf16 v[66:69], v[226:229], v[242:245], v[66:69]
	v_readfirstlane_b32 s0, v158
	v_lshl_add_u64 v[166:167], v[166:167], 0, s[90:91]
	s_mov_b32 m0, s0
	v_readfirstlane_b32 s0, v159
	s_barrier
; DI unsigned pack2(float a, float b) { unsigned r; asm("v_cvt_pk_bf16_f32 %0, %1, %2\n\ts_nop 1" : "=v"(r) : "v"(a), "v"(b)); return r; }
; #define G_WAIT_V(n) asm volatile("s_waitcnt vmcnt(" #n ")" ::: "memory")
; #define G_WAIT_L(n) asm volatile("s_waitcnt lgkmcnt(" #n ")" ::: "memory")
; #define G_BAR __builtin_amdgcn_s_barrier()
; #define G_SCHED __builtin_amdgcn_sched_barrier(0)
; DI u32x4* merge_scratch(PREF p, int region) { const int t = tid512(); return (u32x4*)p.fbuf + (size_t)blockIdx.x * 40960 + region * 8192 + (t >> 6) * 1024 + (t & 63); }
;     ...
;     G_BAR; G_WAIT_L(0); G_MMA(1, 0, At, B0); G_BAR; G_SCHED;
;     G_STAGE(G_SB(1, 1), B, ob0, ob1, LDB, 128, KB(tt + 3));
;     G_WAIT_V(6); G_BAR; G_MMA(1, 1, At, B1); G_BAR;
;     if (MODE && ((tt + 1) & 3) == 3) br_flush(p, acc, (tt + 1) >> 2);
; DI void br_store(PREF p, const f32x4 (&acc)[2][2][4][2], int slot) {
;   u32x4* sb = merge_scratch(p, slot);
; #pragma unroll
;   for (int ai = 0; ai < 2; ++ai)
; #pragma unroll
;     for (int bj = 0; bj < 2; ++bj)
; #pragma unroll
;       for (int m = 0; m < 4; ++m) {
;         u32x4 o;
;         o.x = pack2(acc[ai][bj][m][0][0], acc[ai][bj][m][0][1]); o.y = pack2(acc[ai][bj][m][0][2], acc[ai][bj][m][0][3]);
;         o.z = pack2(acc[ai][bj][m][1][0], acc[ai][bj][m][1][1]); o.w = pack2(acc[ai][bj][m][1][2], acc[ai][bj][m][1][3]);
;         sb[((ai * 2 + bj) * 4 + m) * 64] = o;
;       }
; }
; DI void br_flush(PREF p, f32x4 (&acc)[2][2][4][2], int slot) { br_store(p, acc, slot); zero_acc256(acc); }
	ds_read_b128 v[198:201], v143 offset:49152
	ds_read_b128 v[202:205], v143 offset:50176
	ds_read_b128 v[206:209], v143 offset:51200
	ds_read_b128 v[210:213], v143 offset:52224
	ds_read_b128 v[214:217], v143 offset:53248
	ds_read_b128 v[218:221], v143 offset:54272
	ds_read_b128 v[222:225], v143 offset:55296
	ds_read_b128 v[226:229], v143 offset:56320
	global_load_lds_dwordx4 v[166:167], off
	v_lshl_add_u64 v[166:167], v[246:247], 0, s[90:91]
	s_mov_b32 m0, s0
	s_nop 0
	global_load_lds_dwordx4 v[166:167], off
	s_barrier
	s_waitcnt lgkmcnt(0)
	s_waitcnt lgkmcnt(0)
	v_mfma_f32_16x16x32_bf16 v[62:65], v[198:201], v[182:185], v[62:65]
	v_mfma_f32_16x16x32_bf16 v[58:61], v[198:201], v[190:193], v[58:61]
	v_mfma_f32_16x16x32_bf16 v[54:57], v[206:209], v[182:185], v[54:57]
	v_mfma_f32_16x16x32_bf16 v[50:53], v[206:209], v[190:193], v[50:53]
	v_mfma_f32_16x16x32_bf16 v[46:49], v[214:217], v[182:185], v[46:49]
	v_mfma_f32_16x16x32_bf16 v[42:45], v[214:217], v[190:193], v[42:45]
	v_mfma_f32_16x16x32_bf16 v[38:41], v[222:225], v[182:185], v[38:41]
	v_mfma_f32_16x16x32_bf16 v[34:37], v[222:225], v[190:193], v[34:37]
	v_mfma_f32_16x16x32_bf16 v[62:65], v[202:205], v[186:189], v[62:65]
	v_mfma_f32_16x16x32_bf16 v[58:61], v[202:205], v[194:197], v[58:61]
	v_mfma_f32_16x16x32_bf16 v[54:57], v[210:213], v[186:189], v[54:57]
	v_mfma_f32_16x16x32_bf16 v[50:53], v[210:213], v[194:197], v[50:53]
	v_mfma_f32_16x16x32_bf16 v[46:49], v[218:221], v[186:189], v[46:49]
	v_mfma_f32_16x16x32_bf16 v[42:45], v[218:221], v[194:197], v[42:45]
	v_mfma_f32_16x16x32_bf16 v[38:41], v[226:229], v[186:189], v[38:41]
	v_mfma_f32_16x16x32_bf16 v[34:37], v[226:229], v[194:197], v[34:37]
	s_barrier
	s_add_u32 s0, s28, s35
	s_addc_u32 s1, s29, 0
	v_readfirstlane_b32 s35, v160
	v_lshl_add_u64 v[166:167], s[0:1], 0, v[134:135]
	s_mov_b32 m0, s35
	s_nop 0
	global_load_lds_dwordx4 v[166:167], off
	v_lshl_add_u64 v[166:167], s[0:1], 0, v[136:137]
	v_readfirstlane_b32 s0, v161
	s_mov_b32 m0, s0
	s_nop 0
	global_load_lds_dwordx4 v[166:167], off
	s_waitcnt vmcnt(6)
	s_barrier
	v_mfma_f32_16x16x32_bf16 v[30:33], v[198:201], v[230:233], v[30:33]
	v_mfma_f32_16x16x32_bf16 v[26:29], v[198:201], v[238:241], v[26:29]
	v_mfma_f32_16x16x32_bf16 v[22:25], v[206:209], v[230:233], v[22:25]
	v_mfma_f32_16x16x32_bf16 v[18:21], v[206:209], v[238:241], v[18:21]
	v_mfma_f32_16x16x32_bf16 v[14:17], v[214:217], v[230:233], v[14:17]
	v_mfma_f32_16x16x32_bf16 v[10:13], v[214:217], v[238:241], v[10:13]
	v_mfma_f32_16x16x32_bf16 v[6:9], v[222:225], v[230:233], v[6:9]
	v_mfma_f32_16x16x32_bf16 v[2:5], v[222:225], v[238:241], v[2:5]
	v_mfma_f32_16x16x32_bf16 v[30:33], v[202:205], v[234:237], v[30:33]
	v_mfma_f32_16x16x32_bf16 v[26:29], v[202:205], v[242:245], v[26:29]
	v_mfma_f32_16x16x32_bf16 v[22:25], v[210:213], v[234:237], v[22:25]
	v_mfma_f32_16x16x32_bf16 v[18:21], v[210:213], v[242:245], v[18:21]
	v_mfma_f32_16x16x32_bf16 v[14:17], v[218:221], v[234:237], v[14:17]
	v_mfma_f32_16x16x32_bf16 v[10:13], v[218:221], v[242:245], v[10:13]
	v_mfma_f32_16x16x32_bf16 v[6:9], v[226:229], v[234:237], v[6:9]
	v_mfma_f32_16x16x32_bf16 v[2:5], v[226:229], v[242:245], v[2:5]
	s_and_b32 s0, s34, 3
	s_cmp_eq_u32 s0, 3
	s_barrier
	s_cbranch_scc0 .LBB0_95
	v_mov_b32_e32 v0, v168
	s_and_b32 s0, s12, 0x6000
	s_lshl_b32 s0, s0, 4
	v_lshlrev_b32_e32 v165, 4, v0
	s_add_u32 s0, s63, s0
	v_and_b32_e32 v166, 0xfffffc00, v165
	s_addc_u32 s1, s64, 0
	v_ashrrev_i32_e32 v167, 31, v166
	v_and_b32_e32 v0, 63, v0
	v_lshl_add_u64 v[166:167], v[166:167], 4, s[0:1]
	v_lshlrev_b32_e32 v0, 4, v0
	v_lshl_add_u64 v[166:167], v[166:167], 0, v[0:1]
	v_cvt_pk_bf16_f32 v94, v94, v95
	v_cvt_pk_bf16_f32 v95, v96, v97
	v_cvt_pk_bf16_f32 v96, v90, v91
	v_add_co_u32_e32 v90, vcc, s80, v166
	v_cvt_pk_bf16_f32 v97, v92, v93
	s_movk_i32 s0, 0x3000
	s_nop 0
	v_addc_co_u32_e32 v91, vcc, 0, v167, vcc
	v_add_co_u32_e32 v92, vcc, s40, v166
	v_cvt_pk_bf16_f32 v30, v30, v31
	v_cvt_pk_bf16_f32 v31, v32, v33
	v_cvt_pk_bf16_f32 v32, v26, v27
	v_cvt_pk_bf16_f32 v126, v126, v127
	s_nop 1
	v_addc_co_u32_e32 v93, vcc, 0, v167, vcc
	v_add_co_u32_e32 v26, vcc, s0, v166
	v_cvt_pk_bf16_f32 v127, v128, v129
	v_cvt_pk_bf16_f32 v128, v122, v123
	v_cvt_pk_bf16_f32 v129, v124, v125
	v_cvt_pk_bf16_f32 v118, v118, v119
	v_cvt_pk_bf16_f32 v119, v120, v121
	v_cvt_pk_bf16_f32 v120, v114, v115
	v_cvt_pk_bf16_f32 v121, v116, v117
	v_cvt_pk_bf16_f32 v110, v110, v111
	v_cvt_pk_bf16_f32 v111, v112, v113
	v_cvt_pk_bf16_f32 v112, v106, v107
	v_cvt_pk_bf16_f32 v113, v108, v109
	v_cvt_pk_bf16_f32 v102, v102, v103
	v_cvt_pk_bf16_f32 v103, v104, v105
	v_cvt_pk_bf16_f32 v104, v98, v99
	v_cvt_pk_bf16_f32 v105, v100, v101
	v_cvt_pk_bf16_f32 v86, v86, v87
	v_cvt_pk_bf16_f32 v87, v88, v89
	v_cvt_pk_bf16_f32 v88, v82, v83
	v_cvt_pk_bf16_f32 v89, v84, v85
	v_cvt_pk_bf16_f32 v78, v78, v79
	v_cvt_pk_bf16_f32 v79, v80, v81
	v_cvt_pk_bf16_f32 v80, v74, v75
	v_cvt_pk_bf16_f32 v81, v76, v77
	v_cvt_pk_bf16_f32 v70, v70, v71
	v_cvt_pk_bf16_f32 v71, v72, v73
	v_cvt_pk_bf16_f32 v72, v66, v67
	v_cvt_pk_bf16_f32 v73, v68, v69
	v_cvt_pk_bf16_f32 v62, v62, v63
	v_cvt_pk_bf16_f32 v63, v64, v65
	v_cvt_pk_bf16_f32 v64, v58, v59
	v_cvt_pk_bf16_f32 v65, v60, v61
	v_cvt_pk_bf16_f32 v54, v54, v55
	v_cvt_pk_bf16_f32 v55, v56, v57
	v_cvt_pk_bf16_f32 v56, v50, v51
	v_cvt_pk_bf16_f32 v57, v52, v53
	v_cvt_pk_bf16_f32 v46, v46, v47
	v_cvt_pk_bf16_f32 v47, v48, v49
	v_cvt_pk_bf16_f32 v48, v42, v43
	v_cvt_pk_bf16_f32 v49, v44, v45
	v_cvt_pk_bf16_f32 v38, v38, v39
	v_cvt_pk_bf16_f32 v39, v40, v41
	v_cvt_pk_bf16_f32 v40, v34, v35
	v_cvt_pk_bf16_f32 v41, v36, v37
	v_cvt_pk_bf16_f32 v33, v28, v29
	s_nop 1
	v_addc_co_u32_e32 v27, vcc, 0, v167, vcc
; DI unsigned pack2(float a, float b) { unsigned r; asm("v_cvt_pk_bf16_f32 %0, %1, %2\n\ts_nop 1" : "=v"(r) : "v"(a), "v"(b)); return r; }
; DI void zero_acc256(f32x4 (&a)[2][2][4][2]) {
; #pragma unroll
;   for (int i = 0; i < 2; ++i)
; #pragma unroll
;     for (int j = 0; j < 2; ++j)
; #pragma unroll
;       for (int m = 0; m < 4; ++m)
; #pragma unroll
;         for (int n = 0; n < 2; ++n)
; #pragma unroll
;           for (int e = 0; e < 4; ++e) a[i][j][m][n][e] = 0.f;
; }
; DI void br_store(PREF p, const f32x4 (&acc)[2][2][4][2], int slot) {
;     ...
;         u32x4 o;
;         o.x = pack2(acc[ai][bj][m][0][0], acc[ai][bj][m][0][1]); o.y = pack2(acc[ai][bj][m][0][2], acc[ai][bj][m][0][3]);
;         o.z = pack2(acc[ai][bj][m][1][0], acc[ai][bj][m][1][1]); o.w = pack2(acc[ai][bj][m][1][2], acc[ai][bj][m][1][3]);
;         sb[((ai * 2 + bj) * 4 + m) * 64] = o;
;       }
; }
; DI void br_flush(PREF p, f32x4 (&acc)[2][2][4][2], int slot) { br_store(p, acc, slot); zero_acc256(acc); }
	v_cvt_pk_bf16_f32 v22, v22, v23
	v_cvt_pk_bf16_f32 v23, v24, v25
	v_cvt_pk_bf16_f32 v24, v18, v19
	v_cvt_pk_bf16_f32 v25, v20, v21
	v_cvt_pk_bf16_f32 v14, v14, v15
	v_cvt_pk_bf16_f32 v15, v16, v17
	v_cvt_pk_bf16_f32 v16, v10, v11
	v_cvt_pk_bf16_f32 v17, v12, v13
	v_cvt_pk_bf16_f32 v6, v6, v7
	v_cvt_pk_bf16_f32 v7, v8, v9
	v_cvt_pk_bf16_f32 v8, v2, v3
	v_cvt_pk_bf16_f32 v9, v4, v5
	v_mov_b32_e32 v2, 0
	global_store_dwordx4 v[166:167], v[126:129], off
	global_store_dwordx4 v[166:167], v[118:121], off offset:1024
	global_store_dwordx4 v[166:167], v[110:113], off offset:2048
	global_store_dwordx4 v[166:167], v[102:105], off offset:3072
	global_store_dwordx4 v[92:93], v[94:97], off offset:-4096
	global_store_dwordx4 v[90:91], v[86:89], off offset:1024
	global_store_dwordx4 v[90:91], v[78:81], off offset:2048
	global_store_dwordx4 v[90:91], v[70:73], off offset:3072
	global_store_dwordx4 v[92:93], v[62:65], off
	global_store_dwordx4 v[92:93], v[54:57], off offset:1024
	global_store_dwordx4 v[92:93], v[46:49], off offset:2048
	global_store_dwordx4 v[92:93], v[38:41], off offset:3072
	global_store_dwordx4 v[26:27], v[30:33], off
	global_store_dwordx4 v[26:27], v[22:25], off offset:1024
	global_store_dwordx4 v[26:27], v[14:17], off offset:2048
	global_store_dwordx4 v[26:27], v[6:9], off offset:3072
	v_mov_b32_e32 v3, v2
	v_mov_b32_e32 v4, v2
	v_mov_b32_e32 v5, v2
	v_mov_b32_e32 v6, v2
	v_mov_b32_e32 v7, v2
	v_mov_b32_e32 v8, v2
	v_mov_b32_e32 v9, v2
	v_mov_b32_e32 v10, v2
	v_mov_b32_e32 v11, v2
	v_mov_b32_e32 v12, v2
	v_mov_b32_e32 v13, v2
	v_mov_b32_e32 v14, v2
	v_mov_b32_e32 v15, v2
	v_mov_b32_e32 v16, v2
	v_mov_b32_e32 v17, v2
	v_mov_b32_e32 v18, v2
	v_mov_b32_e32 v19, v2
	v_mov_b32_e32 v20, v2
	v_mov_b32_e32 v21, v2
	v_mov_b32_e32 v22, v2
	v_mov_b32_e32 v23, v2
	v_mov_b32_e32 v24, v2
	v_mov_b32_e32 v25, v2
	v_mov_b32_e32 v26, v2
	v_mov_b32_e32 v27, v2
	v_mov_b32_e32 v28, v2
	v_mov_b32_e32 v29, v2
	v_mov_b32_e32 v30, v2
	v_mov_b32_e32 v31, v2
	v_mov_b32_e32 v32, v2
	v_mov_b32_e32 v33, v2
	v_mov_b32_e32 v34, v2
	v_mov_b32_e32 v35, v2
	v_mov_b32_e32 v36, v2
	v_mov_b32_e32 v37, v2
	v_mov_b32_e32 v38, v2
	v_mov_b32_e32 v39, v2
	v_mov_b32_e32 v40, v2
	v_mov_b32_e32 v41, v2
	v_mov_b32_e32 v42, v2
	v_mov_b32_e32 v43, v2
	v_mov_b32_e32 v44, v2
	v_mov_b32_e32 v45, v2
	v_mov_b32_e32 v46, v2
	v_mov_b32_e32 v47, v2
	v_mov_b32_e32 v48, v2
	v_mov_b32_e32 v49, v2
	v_mov_b32_e32 v50, v2
	v_mov_b32_e32 v51, v2
	v_mov_b32_e32 v52, v2
	v_mov_b32_e32 v53, v2
	v_mov_b32_e32 v54, v2
	v_mov_b32_e32 v55, v2
	v_mov_b32_e32 v56, v2
	v_mov_b32_e32 v57, v2
	v_mov_b32_e32 v58, v2
	v_mov_b32_e32 v59, v2
	v_mov_b32_e32 v60, v2
	v_mov_b32_e32 v61, v2
	v_mov_b32_e32 v62, v2
	v_mov_b32_e32 v63, v2
	v_mov_b32_e32 v64, v2
	v_mov_b32_e32 v65, v2
	v_mov_b32_e32 v66, v2
	v_mov_b32_e32 v67, v2
	v_mov_b32_e32 v68, v2
	v_mov_b32_e32 v69, v2
	v_mov_b32_e32 v70, v2
	v_mov_b32_e32 v71, v2
	v_mov_b32_e32 v72, v2
	v_mov_b32_e32 v73, v2
	v_mov_b32_e32 v74, v2
	v_mov_b32_e32 v75, v2
	v_mov_b32_e32 v76, v2
	v_mov_b32_e32 v77, v2
	v_mov_b32_e32 v78, v2
	v_mov_b32_e32 v79, v2
	v_mov_b32_e32 v80, v2
	v_mov_b32_e32 v81, v2
	v_mov_b32_e32 v82, v2
	v_mov_b32_e32 v83, v2
	v_mov_b32_e32 v84, v2
	v_mov_b32_e32 v85, v2
	v_mov_b32_e32 v86, v2
	v_mov_b32_e32 v87, v2
	v_mov_b32_e32 v88, v2
	v_mov_b32_e32 v89, v2
	v_mov_b32_e32 v90, v2
	v_mov_b32_e32 v91, v2
	v_mov_b32_e32 v92, v2
	v_mov_b32_e32 v93, v2
	v_mov_b32_e32 v94, v2
	v_mov_b32_e32 v95, v2
	v_mov_b32_e32 v96, v2
	v_mov_b32_e32 v97, v2
	v_mov_b32_e32 v98, v2
	v_mov_b32_e32 v99, v2
	v_mov_b32_e32 v100, v2
	v_mov_b32_e32 v101, v2
	v_mov_b32_e32 v102, v2
	v_mov_b32_e32 v103, v2
	v_mov_b32_e32 v104, v2
	v_mov_b32_e32 v105, v2
	v_mov_b32_e32 v106, v2
	v_mov_b32_e32 v107, v2
	v_mov_b32_e32 v108, v2
	v_mov_b32_e32 v109, v2
	v_mov_b32_e32 v110, v2
	v_mov_b32_e32 v111, v2
	v_mov_b32_e32 v112, v2
	v_mov_b32_e32 v113, v2
	v_mov_b32_e32 v114, v2
	v_mov_b32_e32 v115, v2
	v_mov_b32_e32 v116, v2
	v_mov_b32_e32 v117, v2
	v_mov_b32_e32 v118, v2
	v_mov_b32_e32 v119, v2
	v_mov_b32_e32 v120, v2
	v_mov_b32_e32 v121, v2
	v_mov_b32_e32 v122, v2
	v_mov_b32_e32 v123, v2
	v_mov_b32_e32 v124, v2
	v_mov_b32_e32 v125, v2
	v_mov_b32_e32 v126, v2
	v_mov_b32_e32 v127, v2
	v_mov_b32_e32 v128, v2
	v_mov_b32_e32 v129, v2
	s_branch .LBB0_95
; #define G_LDA(dst, b, h)                                                                                                  \
;   _Pragma("unroll") for (int m = 0; m < 4; ++m) _Pragma("unroll") for (int k = 0; k < 2; ++k)                             \
;       dst[m][k] = *(const bf16x8*)((const char*)G_SA(b, h) + ((wr * 4 + m) * 2 + k) * 1024 + rdo)
; #define G_LDB(dst, b, h)                                                                                                  \
;   _Pragma("unroll") for (int n = 0; n < 2; ++n) _Pragma("unroll") for (int k = 0; k < 2; ++k)                             \
;       dst[n][k] = *(const bf16x8*)((const char*)G_SB(b, h) + ((wc * 2 + n) * 2 + k) * 1024 + rdo)
; #define G_WAIT_V(n) asm volatile("s_waitcnt vmcnt(" #n ")" ::: "memory")
; #define G_WAIT_L(n) asm volatile("s_waitcnt lgkmcnt(" #n ")" ::: "memory")
; #define G_BAR __builtin_amdgcn_s_barrier()
;     ...
;     G_LDB(B0, 0, 0); G_LDA(At, 0, 0); G_STAGE(G_SA(1, 1), A, oa0, oa1, LDA, 128, KA(nt - 1));
;     G_BAR; G_WAIT_L(0); G_MMA(0, 0, At, B0); G_BAR;
;     G_LDB(B1, 0, 1); G_BAR; G_WAIT_L(0); G_MMA(0, 1, At, B1); G_BAR;
;     G_LDA(At, 0, 1); G_WAIT_V(4); G_BAR; G_WAIT_L(0); G_MMA(1, 0, At, B0); G_MMA(1, 1, At, B1); G_BAR;
;   }
;   {
;     G_LDB(B0, 1, 0); G_LDA(At, 1, 0); G_WAIT_V(2); G_BAR; G_WAIT_L(0); G_MMA(0, 0, At, B0); G_BAR;
.LBB0_98:
	s_add_u32 s0, s10, 0x40780
	s_addc_u32 s1, s11, 0
	v_readfirstlane_b32 s10, v162
	v_lshl_add_u64 v[132:133], v[132:133], 1, s[0:1]
	s_mov_b32 m0, s10
	v_lshl_add_u64 v[130:131], v[130:131], 1, s[0:1]
	v_readfirstlane_b32 s0, v164
	ds_read_b128 v[134:137], v151
	ds_read_b128 v[138:141], v151 offset:1024
	ds_read_b128 v[152:155], v151 offset:2048
	ds_read_b128 v[148:151], v151 offset:3072
	ds_read_b128 v[156:159], v143
	ds_read_b128 v[182:185], v143 offset:1024
	ds_read_b128 v[186:189], v143 offset:2048
	ds_read_b128 v[190:193], v143 offset:3072
	ds_read_b128 v[194:197], v143 offset:4096
	ds_read_b128 v[198:201], v143 offset:5120
	ds_read_b128 v[202:205], v143 offset:6144
	ds_read_b128 v[206:209], v143 offset:7168
	global_load_lds_dwordx4 v[132:133], off
	s_mov_b32 m0, s0
	s_nop 0
	global_load_lds_dwordx4 v[130:131], off
	s_barrier
	s_waitcnt lgkmcnt(0)
	s_waitcnt lgkmcnt(0)
	v_mfma_f32_16x16x32_bf16 v[126:129], v[156:159], v[134:137], v[126:129]
	v_mfma_f32_16x16x32_bf16 v[122:125], v[156:159], v[152:155], v[122:125]
	v_mfma_f32_16x16x32_bf16 v[118:121], v[186:189], v[134:137], v[118:121]
	v_mfma_f32_16x16x32_bf16 v[114:117], v[186:189], v[152:155], v[114:117]
	v_mfma_f32_16x16x32_bf16 v[110:113], v[194:197], v[134:137], v[110:113]
	v_mfma_f32_16x16x32_bf16 v[106:109], v[194:197], v[152:155], v[106:109]
	v_mfma_f32_16x16x32_bf16 v[102:105], v[202:205], v[134:137], v[102:105]
	v_mfma_f32_16x16x32_bf16 v[98:101], v[202:205], v[152:155], v[98:101]
	v_mfma_f32_16x16x32_bf16 v[126:129], v[182:185], v[138:141], v[126:129]
	v_mfma_f32_16x16x32_bf16 v[122:125], v[182:185], v[148:151], v[122:125]
	v_mfma_f32_16x16x32_bf16 v[118:121], v[190:193], v[138:141], v[118:121]
	v_mfma_f32_16x16x32_bf16 v[114:117], v[190:193], v[148:151], v[114:117]
	v_mfma_f32_16x16x32_bf16 v[110:113], v[198:201], v[138:141], v[110:113]
	v_mfma_f32_16x16x32_bf16 v[106:109], v[198:201], v[148:151], v[106:109]
	v_mfma_f32_16x16x32_bf16 v[102:105], v[206:209], v[138:141], v[102:105]
	v_mfma_f32_16x16x32_bf16 v[98:101], v[206:209], v[148:151], v[98:101]
	s_barrier
	ds_read_b128 v[130:133], v146
	ds_read_b128 v[164:167], v146 offset:1024
	ds_read_b128 v[210:213], v146 offset:2048
	ds_read_b128 v[214:217], v146 offset:3072
	s_barrier
	s_waitcnt lgkmcnt(0)
	s_waitcnt lgkmcnt(0)
	v_mfma_f32_16x16x32_bf16 v[90:93], v[156:159], v[210:213], v[90:93]
	v_mfma_f32_16x16x32_bf16 v[86:89], v[186:189], v[130:133], v[86:89]
	v_mfma_f32_16x16x32_bf16 v[82:85], v[186:189], v[210:213], v[82:85]
	v_mfma_f32_16x16x32_bf16 v[78:81], v[194:197], v[130:133], v[78:81]
	v_mfma_f32_16x16x32_bf16 v[74:77], v[194:197], v[210:213], v[74:77]
	v_mfma_f32_16x16x32_bf16 v[70:73], v[202:205], v[130:133], v[70:73]
	v_mfma_f32_16x16x32_bf16 v[94:97], v[156:159], v[130:133], v[94:97]
	v_mfma_f32_16x16x32_bf16 v[90:93], v[182:185], v[214:217], v[90:93]
	v_mfma_f32_16x16x32_bf16 v[86:89], v[190:193], v[164:167], v[86:89]
	v_mfma_f32_16x16x32_bf16 v[82:85], v[190:193], v[214:217], v[82:85]
	v_mfma_f32_16x16x32_bf16 v[78:81], v[198:201], v[164:167], v[78:81]
	v_mfma_f32_16x16x32_bf16 v[74:77], v[198:201], v[214:217], v[74:77]
	v_mfma_f32_16x16x32_bf16 v[70:73], v[206:209], v[164:167], v[70:73]
	v_mfma_f32_16x16x32_bf16 v[66:69], v[202:205], v[210:213], v[66:69]
	v_mfma_f32_16x16x32_bf16 v[218:221], v[182:185], v[164:167], v[94:97]
	v_mfma_f32_16x16x32_bf16 v[156:159], v[206:209], v[214:217], v[66:69]
	s_barrier
	s_nop 3
	s_nop 0
	ds_read_b128 v[66:69], v143 offset:16384
	ds_read_b128 v[94:97], v143 offset:17408
	ds_read_b128 v[182:185], v143 offset:18432
	ds_read_b128 v[186:189], v143 offset:19456
	ds_read_b128 v[190:193], v143 offset:20480
	ds_read_b128 v[194:197], v143 offset:21504
	ds_read_b128 v[198:201], v143 offset:22528
	ds_read_b128 v[202:205], v143 offset:23552
	s_waitcnt vmcnt(4)
	s_barrier
	s_waitcnt lgkmcnt(0)
	s_waitcnt lgkmcnt(0)
	v_mfma_f32_16x16x32_bf16 v[62:65], v[66:69], v[134:137], v[62:65]
	v_mfma_f32_16x16x32_bf16 v[54:57], v[182:185], v[134:137], v[54:57]
	v_mfma_f32_16x16x32_bf16 v[50:53], v[182:185], v[152:155], v[50:53]
	v_mfma_f32_16x16x32_bf16 v[46:49], v[190:193], v[134:137], v[46:49]
	v_mfma_f32_16x16x32_bf16 v[42:45], v[190:193], v[152:155], v[42:45]
	v_mfma_f32_16x16x32_bf16 v[38:41], v[198:201], v[134:137], v[38:41]
	v_mfma_f32_16x16x32_bf16 v[34:37], v[198:201], v[152:155], v[34:37]
	v_mfma_f32_16x16x32_bf16 v[62:65], v[94:97], v[138:141], v[62:65]
	v_mfma_f32_16x16x32_bf16 v[58:61], v[66:69], v[152:155], v[58:61]
	v_mfma_f32_16x16x32_bf16 v[54:57], v[186:189], v[138:141], v[54:57]
	v_mfma_f32_16x16x32_bf16 v[50:53], v[186:189], v[148:151], v[50:53]
	v_mfma_f32_16x16x32_bf16 v[46:49], v[194:197], v[138:141], v[46:49]
	v_mfma_f32_16x16x32_bf16 v[42:45], v[194:197], v[148:151], v[42:45]
	v_mfma_f32_16x16x32_bf16 v[38:41], v[202:205], v[138:141], v[38:41]
	v_mfma_f32_16x16x32_bf16 v[34:37], v[202:205], v[148:151], v[34:37]
	v_mfma_f32_16x16x32_bf16 v[206:209], v[94:97], v[148:151], v[58:61]
	v_mfma_f32_16x16x32_bf16 v[30:33], v[66:69], v[130:133], v[30:33]
	v_mfma_f32_16x16x32_bf16 v[26:29], v[66:69], v[210:213], v[26:29]
	v_mfma_f32_16x16x32_bf16 v[22:25], v[182:185], v[130:133], v[22:25]
	v_mfma_f32_16x16x32_bf16 v[18:21], v[182:185], v[210:213], v[18:21]
	v_mfma_f32_16x16x32_bf16 v[14:17], v[190:193], v[130:133], v[14:17]
	v_mfma_f32_16x16x32_bf16 v[10:13], v[190:193], v[210:213], v[10:13]
	v_mfma_f32_16x16x32_bf16 v[6:9], v[198:201], v[130:133], v[6:9]
	v_mfma_f32_16x16x32_bf16 v[2:5], v[198:201], v[210:213], v[2:5]
	v_mfma_f32_16x16x32_bf16 v[30:33], v[94:97], v[164:167], v[30:33]
	v_mfma_f32_16x16x32_bf16 v[26:29], v[94:97], v[214:217], v[26:29]
	v_mfma_f32_16x16x32_bf16 v[22:25], v[186:189], v[164:167], v[22:25]
	v_mfma_f32_16x16x32_bf16 v[18:21], v[186:189], v[214:217], v[18:21]
	v_mfma_f32_16x16x32_bf16 v[14:17], v[194:197], v[164:167], v[14:17]
	v_mfma_f32_16x16x32_bf16 v[10:13], v[194:197], v[214:217], v[10:13]
	v_mfma_f32_16x16x32_bf16 v[6:9], v[202:205], v[164:167], v[6:9]
	v_mfma_f32_16x16x32_bf16 v[2:5], v[202:205], v[214:217], v[2:5]
	s_barrier
; #define G_LDA(dst, b, h)                                                                                                  \
;   _Pragma("unroll") for (int m = 0; m < 4; ++m) _Pragma("unroll") for (int k = 0; k < 2; ++k)                             \
;       dst[m][k] = *(const bf16x8*)((const char*)G_SA(b, h) + ((wr * 4 + m) * 2 + k) * 1024 + rdo)
; #define G_LDB(dst, b, h)                                                                                                  \
;   _Pragma("unroll") for (int n = 0; n < 2; ++n) _Pragma("unroll") for (int k = 0; k < 2; ++k)                             \
;       dst[n][k] = *(const bf16x8*)((const char*)G_SB(b, h) + ((wc * 2 + n) * 2 + k) * 1024 + rdo)
; #define G_WAIT_V(n) asm volatile("s_waitcnt vmcnt(" #n ")" ::: "memory")
; #define G_WAIT_L(n) asm volatile("s_waitcnt lgkmcnt(" #n ")" ::: "memory")
; #define G_BAR __builtin_amdgcn_s_barrier()
;     ...
;     G_LDB(B0, 1, 0); G_LDA(At, 1, 0); G_WAIT_V(2); G_BAR; G_WAIT_L(0); G_MMA(0, 0, At, B0); G_BAR;
;     G_LDB(B1, 1, 1); G_WAIT_V(0); G_BAR; G_WAIT_L(0); G_MMA(0, 1, At, B1); G_BAR;
;     G_LDA(At, 1, 1); G_BAR; G_WAIT_L(0); G_MMA(1, 0, At, B0); G_MMA(1, 1, At, B1); G_BAR;
;   }
;   if (wr == 0) G_BAR;
	ds_read_b128 v[130:133], v145
	ds_read_b128 v[134:137], v145 offset:1024
	ds_read_b128 v[138:141], v145 offset:2048
	ds_read_b128 v[146:149], v145 offset:3072
	ds_read_b128 v[58:61], v143 offset:32768
	ds_read_b128 v[66:69], v143 offset:33792
	ds_read_b128 v[150:153], v143 offset:34816
	ds_read_b128 v[164:167], v143 offset:35840
	ds_read_b128 v[182:185], v143 offset:36864
	ds_read_b128 v[186:189], v143 offset:37888
	ds_read_b128 v[190:193], v143 offset:38912
	ds_read_b128 v[194:197], v143 offset:39936
	s_waitcnt vmcnt(2)
	s_barrier
	s_waitcnt lgkmcnt(0)
	s_waitcnt lgkmcnt(0)
	v_mfma_f32_16x16x32_bf16 v[94:97], v[58:61], v[130:133], v[126:129]
	v_mfma_f32_16x16x32_bf16 v[126:129], v[66:69], v[134:137], v[94:97]
	v_mfma_f32_16x16x32_bf16 v[94:97], v[58:61], v[138:141], v[122:125]
	v_mfma_f32_16x16x32_bf16 v[122:125], v[66:69], v[146:149], v[94:97]
	v_mfma_f32_16x16x32_bf16 v[94:97], v[150:153], v[130:133], v[118:121]
	v_mfma_f32_16x16x32_bf16 v[118:121], v[164:167], v[134:137], v[94:97]
	v_mfma_f32_16x16x32_bf16 v[94:97], v[150:153], v[138:141], v[114:117]
	v_mfma_f32_16x16x32_bf16 v[114:117], v[164:167], v[146:149], v[94:97]
	v_mfma_f32_16x16x32_bf16 v[94:97], v[182:185], v[130:133], v[110:113]
	v_mfma_f32_16x16x32_bf16 v[110:113], v[186:189], v[134:137], v[94:97]
	v_mfma_f32_16x16x32_bf16 v[94:97], v[182:185], v[138:141], v[106:109]
	v_mfma_f32_16x16x32_bf16 v[106:109], v[186:189], v[146:149], v[94:97]
	v_mfma_f32_16x16x32_bf16 v[94:97], v[190:193], v[130:133], v[102:105]
	v_mfma_f32_16x16x32_bf16 v[102:105], v[194:197], v[134:137], v[94:97]
	v_mfma_f32_16x16x32_bf16 v[94:97], v[190:193], v[138:141], v[98:101]
	v_mfma_f32_16x16x32_bf16 v[94:97], v[194:197], v[146:149], v[94:97]
	s_barrier
	ds_read_b128 v[198:201], v144
	ds_read_b128 v[202:205], v144 offset:1024
	ds_read_b128 v[210:213], v144 offset:2048
	ds_read_b128 v[214:217], v144 offset:3072
	s_waitcnt vmcnt(0)
	s_barrier
	s_waitcnt lgkmcnt(0)
	s_waitcnt lgkmcnt(0)
	v_mfma_f32_16x16x32_bf16 v[98:101], v[58:61], v[198:201], v[218:221]
	v_mfma_f32_16x16x32_bf16 v[58:61], v[58:61], v[210:213], v[90:93]
	v_mfma_f32_16x16x32_bf16 v[90:93], v[66:69], v[214:217], v[58:61]
	v_mfma_f32_16x16x32_bf16 v[58:61], v[150:153], v[198:201], v[86:89]
	v_mfma_f32_16x16x32_bf16 v[86:89], v[164:167], v[202:205], v[58:61]
	v_mfma_f32_16x16x32_bf16 v[58:61], v[150:153], v[210:213], v[82:85]
	v_mfma_f32_16x16x32_bf16 v[82:85], v[164:167], v[214:217], v[58:61]
	v_mfma_f32_16x16x32_bf16 v[58:61], v[182:185], v[198:201], v[78:81]
	v_mfma_f32_16x16x32_bf16 v[78:81], v[186:189], v[202:205], v[58:61]
	v_mfma_f32_16x16x32_bf16 v[58:61], v[182:185], v[210:213], v[74:77]
	v_mfma_f32_16x16x32_bf16 v[74:77], v[186:189], v[214:217], v[58:61]
	v_mfma_f32_16x16x32_bf16 v[58:61], v[190:193], v[198:201], v[70:73]
	v_mfma_f32_16x16x32_bf16 v[98:101], v[66:69], v[202:205], v[98:101]
	v_mfma_f32_16x16x32_bf16 v[66:69], v[194:197], v[202:205], v[58:61]
	v_mfma_f32_16x16x32_bf16 v[58:61], v[190:193], v[210:213], v[156:159]
	v_mfma_f32_16x16x32_bf16 v[58:61], v[194:197], v[214:217], v[58:61]
	s_barrier
	ds_read_b128 v[150:153], v143 offset:49152
	ds_read_b128 v[154:157], v143 offset:50176
	ds_read_b128 v[158:161], v143 offset:51200
	ds_read_b128 v[164:167], v143 offset:52224
	ds_read_b128 v[182:185], v143 offset:53248
	ds_read_b128 v[186:189], v143 offset:54272
	ds_read_b128 v[190:193], v143 offset:55296
	ds_read_b128 v[194:197], v143 offset:56320
	s_barrier
	s_waitcnt lgkmcnt(0)
	s_waitcnt lgkmcnt(0)
	v_mfma_f32_16x16x32_bf16 v[62:65], v[150:153], v[130:133], v[62:65]
	v_mfma_f32_16x16x32_bf16 v[70:73], v[154:157], v[134:137], v[62:65]
	v_mfma_f32_16x16x32_bf16 v[62:65], v[150:153], v[138:141], v[206:209]
	v_mfma_f32_16x16x32_bf16 v[54:57], v[158:161], v[130:133], v[54:57]
	v_mfma_f32_16x16x32_bf16 v[50:53], v[158:161], v[138:141], v[50:53]
	v_mfma_f32_16x16x32_bf16 v[46:49], v[182:185], v[130:133], v[46:49]
	v_mfma_f32_16x16x32_bf16 v[42:45], v[182:185], v[138:141], v[42:45]
	v_mfma_f32_16x16x32_bf16 v[38:41], v[190:193], v[130:133], v[38:41]
	v_mfma_f32_16x16x32_bf16 v[34:37], v[190:193], v[138:141], v[34:37]
	v_mfma_f32_16x16x32_bf16 v[62:65], v[154:157], v[146:149], v[62:65]
	v_mfma_f32_16x16x32_bf16 v[54:57], v[164:167], v[134:137], v[54:57]
	v_mfma_f32_16x16x32_bf16 v[50:53], v[164:167], v[146:149], v[50:53]
	v_mfma_f32_16x16x32_bf16 v[46:49], v[186:189], v[134:137], v[46:49]
	v_mfma_f32_16x16x32_bf16 v[42:45], v[186:189], v[146:149], v[42:45]
	v_mfma_f32_16x16x32_bf16 v[38:41], v[194:197], v[134:137], v[38:41]
	v_mfma_f32_16x16x32_bf16 v[34:37], v[194:197], v[146:149], v[34:37]
	v_mfma_f32_16x16x32_bf16 v[30:33], v[150:153], v[198:201], v[30:33]
	v_mfma_f32_16x16x32_bf16 v[26:29], v[150:153], v[210:213], v[26:29]
	v_mfma_f32_16x16x32_bf16 v[22:25], v[158:161], v[198:201], v[22:25]
	v_mfma_f32_16x16x32_bf16 v[18:21], v[158:161], v[210:213], v[18:21]
	v_mfma_f32_16x16x32_bf16 v[14:17], v[182:185], v[198:201], v[14:17]
	v_mfma_f32_16x16x32_bf16 v[10:13], v[182:185], v[210:213], v[10:13]
	v_mfma_f32_16x16x32_bf16 v[6:9], v[190:193], v[198:201], v[6:9]
	v_mfma_f32_16x16x32_bf16 v[2:5], v[190:193], v[210:213], v[2:5]
	v_mfma_f32_16x16x32_bf16 v[30:33], v[154:157], v[202:205], v[30:33]
	v_mfma_f32_16x16x32_bf16 v[26:29], v[154:157], v[214:217], v[26:29]
	v_mfma_f32_16x16x32_bf16 v[22:25], v[164:167], v[202:205], v[22:25]
	v_mfma_f32_16x16x32_bf16 v[18:21], v[164:167], v[214:217], v[18:21]
	v_mfma_f32_16x16x32_bf16 v[14:17], v[186:189], v[202:205], v[14:17]
	v_mfma_f32_16x16x32_bf16 v[10:13], v[186:189], v[214:217], v[10:13]
	v_mfma_f32_16x16x32_bf16 v[6:9], v[194:197], v[202:205], v[6:9]
	v_mfma_f32_16x16x32_bf16 v[2:5], v[194:197], v[214:217], v[2:5]
	v_cmp_gt_u32_e32 vcc, s67, v142
	s_barrier
	s_and_saveexec_b64 s[10:11], vcc
	s_cbranch_execz .LBB0_100
	s_barrier

; #define G_LDA(dst, b, h)                                                                                                  \
;   _Pragma("unroll") for (int m = 0; m < 4; ++m) _Pragma("unroll") for (int k = 0; k < 2; ++k)                             \
;       dst[m][k] = *(const bf16x8*)((const char*)G_SA(b, h) + ((wr * 4 + m) * 2 + k) * 1024 + rdo)
; #define G_LDB(dst, b, h)                                                                                                  \
;   _Pragma("unroll") for (int n = 0; n < 2; ++n) _Pragma("unroll") for (int k = 0; k < 2; ++k)                             \
;       dst[n][k] = *(const bf16x8*)((const char*)G_SB(b, h) + ((wc * 2 + n) * 2 + k) * 1024 + rdo)
; #define G_WAIT_V(n) asm volatile("s_waitcnt vmcnt(" #n ")" ::: "memory")
; #define G_WAIT_L(n) asm volatile("s_waitcnt lgkmcnt(" #n ")" ::: "memory")
; #define G_BAR __builtin_amdgcn_s_barrier()
; #define G_SCHED __builtin_amdgcn_sched_barrier(0)
;     ...
;   for (int tt = 0; tt < nt - 2; tt += 2) {
;     G_LDB(B0, 0, 0); G_SCHED; G_LDA(At, 0, 0); G_STAGE(G_SA(1, 1), A, oa0, oa1, LDA, 128, KA(tt + 1));
;     G_WAIT_L(8); G_BAR; G_WAIT_L(0); G_MMA(0, 0, At, B0); G_BAR; G_SCHED;
;     G_LDB(B1, 0, 1); G_STAGE(G_SB(0, 0), B, ob0, ob1, LDB, 0, KB(tt + 2));
;     G_BAR; G_WAIT_L(0); G_MMA(0, 1, At, B1); G_BAR;
;     G_LDA(At, 0, 1); G_STAGE(G_SA(0, 0), A, oa0, oa1, LDA, 0, KA(tt + 2));
;     G_BAR; G_WAIT_L(0); G_MMA(1, 0, At, B0); G_BAR; G_SCHED;
;     G_STAGE(G_SB(0, 1), B, ob0, ob1, LDB, 128, KB(tt + 2));
;     G_WAIT_V(6); G_BAR; G_MMA(1, 1, At, B1); G_BAR;
.LBB0_105:
	ds_read_b128 v[164:167], v160
	ds_read_b128 v[182:185], v160 offset:1024
	ds_read_b128 v[186:189], v160 offset:2048
	ds_read_b128 v[190:193], v160 offset:3072
	v_add_u32_e32 v161, 0xc000, v143
	v_lshl_add_u64 v[242:243], v[136:137], 0, s[8:9]
	v_readfirstlane_b32 s0, v161
	v_add_u32_e32 v162, 0xe000, v143
	v_lshl_add_u64 v[226:227], v[242:243], 0, s[78:79]
	s_mov_b32 m0, s0
	v_lshl_add_u64 v[244:245], v[134:135], 0, s[8:9]
	v_readfirstlane_b32 s0, v162
	ds_read_b128 v[194:197], v142
	ds_read_b128 v[198:201], v142 offset:1024
	ds_read_b128 v[202:205], v142 offset:2048
	ds_read_b128 v[206:209], v142 offset:3072
	ds_read_b128 v[210:213], v142 offset:4096
	ds_read_b128 v[214:217], v142 offset:5120
	ds_read_b128 v[218:221], v142 offset:6144
	ds_read_b128 v[222:225], v142 offset:7168
	global_load_lds_dwordx4 v[226:227], off
	v_lshl_add_u64 v[226:227], v[244:245], 0, s[78:79]
	s_mov_b32 m0, s0
	s_nop 0
	global_load_lds_dwordx4 v[226:227], off
	s_waitcnt lgkmcnt(8)
	s_barrier
	s_waitcnt lgkmcnt(0)
	s_waitcnt lgkmcnt(0)
	v_mfma_f32_16x16x32_bf16 v[126:129], v[194:197], v[164:167], v[126:129]
	v_mfma_f32_16x16x32_bf16 v[122:125], v[194:197], v[186:189], v[122:125]
	v_mfma_f32_16x16x32_bf16 v[118:121], v[202:205], v[164:167], v[118:121]
	v_mfma_f32_16x16x32_bf16 v[114:117], v[202:205], v[186:189], v[114:117]
	v_mfma_f32_16x16x32_bf16 v[110:113], v[210:213], v[164:167], v[110:113]
	v_mfma_f32_16x16x32_bf16 v[106:109], v[210:213], v[186:189], v[106:109]
	v_mfma_f32_16x16x32_bf16 v[102:105], v[218:221], v[164:167], v[102:105]
	v_mfma_f32_16x16x32_bf16 v[98:101], v[218:221], v[186:189], v[98:101]
	v_mfma_f32_16x16x32_bf16 v[126:129], v[198:201], v[182:185], v[126:129]
	v_mfma_f32_16x16x32_bf16 v[122:125], v[198:201], v[190:193], v[122:125]
	v_mfma_f32_16x16x32_bf16 v[118:121], v[206:209], v[182:185], v[118:121]
	v_mfma_f32_16x16x32_bf16 v[114:117], v[206:209], v[190:193], v[114:117]
	v_mfma_f32_16x16x32_bf16 v[110:113], v[214:217], v[182:185], v[110:113]
	v_mfma_f32_16x16x32_bf16 v[106:109], v[214:217], v[190:193], v[106:109]
	v_mfma_f32_16x16x32_bf16 v[102:105], v[222:225], v[182:185], v[102:105]
	v_mfma_f32_16x16x32_bf16 v[98:101], v[222:225], v[190:193], v[98:101]
	s_barrier
	v_lshl_add_u64 v[246:247], v[140:141], 0, s[8:9]
	v_readfirstlane_b32 s0, v146
	v_lshl_add_u64 v[248:249], v[246:247], 0, s[50:51]
	s_mov_b32 m0, s0
	ds_read_b128 v[226:229], v158
	ds_read_b128 v[230:233], v158 offset:1024
	ds_read_b128 v[234:237], v158 offset:2048
	ds_read_b128 v[238:241], v158 offset:3072
	global_load_lds_dwordx4 v[248:249], off
	v_lshl_add_u64 v[248:249], v[138:139], 0, s[8:9]
	v_readfirstlane_b32 s0, v147
	v_lshl_add_u64 v[250:251], v[248:249], 0, s[50:51]
	s_mov_b32 m0, s0
	s_nop 0
	global_load_lds_dwordx4 v[250:251], off
	s_barrier
	s_waitcnt lgkmcnt(0)
	s_waitcnt lgkmcnt(0)
	v_mfma_f32_16x16x32_bf16 v[94:97], v[194:197], v[226:229], v[94:97]
	v_mfma_f32_16x16x32_bf16 v[90:93], v[194:197], v[234:237], v[90:93]
	v_mfma_f32_16x16x32_bf16 v[86:89], v[202:205], v[226:229], v[86:89]
	v_mfma_f32_16x16x32_bf16 v[82:85], v[202:205], v[234:237], v[82:85]
	v_mfma_f32_16x16x32_bf16 v[78:81], v[210:213], v[226:229], v[78:81]
	v_mfma_f32_16x16x32_bf16 v[74:77], v[210:213], v[234:237], v[74:77]
	v_mfma_f32_16x16x32_bf16 v[70:73], v[218:221], v[226:229], v[70:73]
	v_mfma_f32_16x16x32_bf16 v[66:69], v[218:221], v[234:237], v[66:69]
	v_mfma_f32_16x16x32_bf16 v[94:97], v[198:201], v[230:233], v[94:97]
	v_mfma_f32_16x16x32_bf16 v[90:93], v[198:201], v[238:241], v[90:93]
	v_mfma_f32_16x16x32_bf16 v[86:89], v[206:209], v[230:233], v[86:89]
	v_mfma_f32_16x16x32_bf16 v[82:85], v[206:209], v[238:241], v[82:85]
	v_mfma_f32_16x16x32_bf16 v[78:81], v[214:217], v[230:233], v[78:81]
	v_mfma_f32_16x16x32_bf16 v[74:77], v[214:217], v[238:241], v[74:77]
	v_mfma_f32_16x16x32_bf16 v[70:73], v[222:225], v[230:233], v[70:73]
	v_mfma_f32_16x16x32_bf16 v[66:69], v[222:225], v[238:241], v[66:69]
	v_readfirstlane_b32 s0, v143
	v_lshl_add_u64 v[250:251], v[242:243], 0, s[82:83]
	s_mov_b32 m0, s0
	v_readfirstlane_b32 s0, v144
	s_barrier
	ds_read_b128 v[194:197], v142 offset:16384
	ds_read_b128 v[198:201], v142 offset:17408
	ds_read_b128 v[202:205], v142 offset:18432
	ds_read_b128 v[206:209], v142 offset:19456
	ds_read_b128 v[210:213], v142 offset:20480
	ds_read_b128 v[214:217], v142 offset:21504
	ds_read_b128 v[218:221], v142 offset:22528
	ds_read_b128 v[222:225], v142 offset:23552
	global_load_lds_dwordx4 v[250:251], off
	v_lshl_add_u64 v[250:251], v[244:245], 0, s[82:83]
	s_mov_b32 m0, s0
	s_nop 0
	global_load_lds_dwordx4 v[250:251], off
	s_barrier
	s_waitcnt lgkmcnt(0)
	s_waitcnt lgkmcnt(0)
	v_mfma_f32_16x16x32_bf16 v[62:65], v[194:197], v[164:167], v[62:65]
	v_mfma_f32_16x16x32_bf16 v[58:61], v[194:197], v[186:189], v[58:61]
	v_mfma_f32_16x16x32_bf16 v[54:57], v[202:205], v[164:167], v[54:57]
	v_mfma_f32_16x16x32_bf16 v[50:53], v[202:205], v[186:189], v[50:53]
	v_mfma_f32_16x16x32_bf16 v[46:49], v[210:213], v[164:167], v[46:49]
	v_mfma_f32_16x16x32_bf16 v[42:45], v[210:213], v[186:189], v[42:45]
	v_mfma_f32_16x16x32_bf16 v[38:41], v[218:221], v[164:167], v[38:41]
	v_mfma_f32_16x16x32_bf16 v[34:37], v[218:221], v[186:189], v[34:37]
	v_mfma_f32_16x16x32_bf16 v[62:65], v[198:201], v[182:185], v[62:65]
	v_mfma_f32_16x16x32_bf16 v[58:61], v[198:201], v[190:193], v[58:61]
	v_mfma_f32_16x16x32_bf16 v[54:57], v[206:209], v[182:185], v[54:57]
	v_mfma_f32_16x16x32_bf16 v[50:53], v[206:209], v[190:193], v[50:53]
	v_mfma_f32_16x16x32_bf16 v[46:49], v[214:217], v[182:185], v[46:49]
	v_mfma_f32_16x16x32_bf16 v[42:45], v[214:217], v[190:193], v[42:45]
	v_mfma_f32_16x16x32_bf16 v[38:41], v[222:225], v[182:185], v[38:41]
	v_mfma_f32_16x16x32_bf16 v[34:37], v[222:225], v[190:193], v[34:37]
	s_barrier
; #define G_LDA(dst, b, h)                                                                                                  \
;   _Pragma("unroll") for (int m = 0; m < 4; ++m) _Pragma("unroll") for (int k = 0; k < 2; ++k)                             \
;       dst[m][k] = *(const bf16x8*)((const char*)G_SA(b, h) + ((wr * 4 + m) * 2 + k) * 1024 + rdo)
; #define G_LDB(dst, b, h)                                                                                                  \
;   _Pragma("unroll") for (int n = 0; n < 2; ++n) _Pragma("unroll") for (int k = 0; k < 2; ++k)                             \
;       dst[n][k] = *(const bf16x8*)((const char*)G_SB(b, h) + ((wc * 2 + n) * 2 + k) * 1024 + rdo)
; #define G_WAIT_V(n) asm volatile("s_waitcnt vmcnt(" #n ")" ::: "memory")
; #define G_WAIT_L(n) asm volatile("s_waitcnt lgkmcnt(" #n ")" ::: "memory")
; #define G_BAR __builtin_amdgcn_s_barrier()
; #define G_SCHED __builtin_amdgcn_sched_barrier(0)
;     ...
;     G_WAIT_V(6); G_BAR; G_MMA(1, 1, At, B1); G_BAR;
;     G_LDB(B0, 1, 0); G_SCHED; G_LDA(At, 1, 0); G_STAGE(G_SA(0, 1), A, oa0, oa1, LDA, 128, KA(tt + 2));
;     G_WAIT_L(8); G_BAR; G_WAIT_L(0); G_MMA(0, 0, At, B0); G_BAR; G_SCHED;
;     G_LDB(B1, 1, 1); G_STAGE(G_SB(1, 0), B, ob0, ob1, LDB, 0, KB(tt + 3));
;     G_BAR; G_WAIT_L(0); G_MMA(0, 1, At, B1); G_BAR;
;     G_LDA(At, 1, 1); G_STAGE(G_SA(1, 0), A, oa0, oa1, LDA, 0, KA(tt + 3));
;     G_BAR; G_WAIT_L(0); G_MMA(1, 0, At, B0); G_BAR; G_SCHED;
;     G_STAGE(G_SB(1, 1), B, ob0, ob1, LDB, 128, KB(tt + 3));
;     G_WAIT_V(6); G_BAR; G_MMA(1, 1, At, B1); G_BAR;
	v_readfirstlane_b32 s0, v149
	v_lshl_add_u64 v[164:165], v[246:247], 0, s[38:39]
	s_mov_b32 m0, s0
	v_readfirstlane_b32 s0, v150
	global_load_lds_dwordx4 v[164:165], off
	v_lshl_add_u64 v[164:165], v[248:249], 0, s[38:39]
	s_mov_b32 m0, s0
	s_nop 0
	global_load_lds_dwordx4 v[164:165], off
	s_waitcnt vmcnt(6)
	s_barrier
	v_mfma_f32_16x16x32_bf16 v[30:33], v[194:197], v[226:229], v[30:33]
	v_mfma_f32_16x16x32_bf16 v[26:29], v[194:197], v[234:237], v[26:29]
	v_mfma_f32_16x16x32_bf16 v[22:25], v[202:205], v[226:229], v[22:25]
	v_mfma_f32_16x16x32_bf16 v[18:21], v[202:205], v[234:237], v[18:21]
	v_mfma_f32_16x16x32_bf16 v[14:17], v[210:213], v[226:229], v[14:17]
	v_mfma_f32_16x16x32_bf16 v[10:13], v[210:213], v[234:237], v[10:13]
	v_mfma_f32_16x16x32_bf16 v[6:9], v[218:221], v[226:229], v[6:9]
	v_mfma_f32_16x16x32_bf16 v[2:5], v[218:221], v[234:237], v[2:5]
	v_mfma_f32_16x16x32_bf16 v[30:33], v[198:201], v[230:233], v[30:33]
	v_mfma_f32_16x16x32_bf16 v[26:29], v[198:201], v[238:241], v[26:29]
	v_mfma_f32_16x16x32_bf16 v[22:25], v[206:209], v[230:233], v[22:25]
	v_mfma_f32_16x16x32_bf16 v[18:21], v[206:209], v[238:241], v[18:21]
	v_mfma_f32_16x16x32_bf16 v[14:17], v[214:217], v[230:233], v[14:17]
	v_mfma_f32_16x16x32_bf16 v[10:13], v[214:217], v[238:241], v[10:13]
	v_mfma_f32_16x16x32_bf16 v[6:9], v[222:225], v[230:233], v[6:9]
	v_mfma_f32_16x16x32_bf16 v[2:5], v[222:225], v[238:241], v[2:5]
	s_barrier
	ds_read_b128 v[164:167], v148
	ds_read_b128 v[182:185], v148 offset:1024
	ds_read_b128 v[186:189], v148 offset:2048
	ds_read_b128 v[190:193], v148 offset:3072
	v_readfirstlane_b32 s0, v151
	v_lshl_add_u64 v[226:227], v[242:243], 0, s[86:87]
	s_mov_b32 m0, s0
	v_readfirstlane_b32 s0, v152
	ds_read_b128 v[194:197], v142 offset:32768
	ds_read_b128 v[198:201], v142 offset:33792
	ds_read_b128 v[202:205], v142 offset:34816
	ds_read_b128 v[206:209], v142 offset:35840
	ds_read_b128 v[210:213], v142 offset:36864
	ds_read_b128 v[214:217], v142 offset:37888
	ds_read_b128 v[218:221], v142 offset:38912
	ds_read_b128 v[222:225], v142 offset:39936
	global_load_lds_dwordx4 v[226:227], off
	v_lshl_add_u64 v[226:227], v[244:245], 0, s[86:87]
	s_mov_b32 m0, s0
	s_nop 0
	global_load_lds_dwordx4 v[226:227], off
	s_waitcnt lgkmcnt(8)
	s_barrier
	s_waitcnt lgkmcnt(0)
	s_waitcnt lgkmcnt(0)
	v_mfma_f32_16x16x32_bf16 v[126:129], v[194:197], v[164:167], v[126:129]
	v_mfma_f32_16x16x32_bf16 v[122:125], v[194:197], v[186:189], v[122:125]
	v_mfma_f32_16x16x32_bf16 v[118:121], v[202:205], v[164:167], v[118:121]
	v_mfma_f32_16x16x32_bf16 v[114:117], v[202:205], v[186:189], v[114:117]
	v_mfma_f32_16x16x32_bf16 v[110:113], v[210:213], v[164:167], v[110:113]
	v_mfma_f32_16x16x32_bf16 v[106:109], v[210:213], v[186:189], v[106:109]
	v_mfma_f32_16x16x32_bf16 v[102:105], v[218:221], v[164:167], v[102:105]
	v_mfma_f32_16x16x32_bf16 v[98:101], v[218:221], v[186:189], v[98:101]
	v_mfma_f32_16x16x32_bf16 v[126:129], v[198:201], v[182:185], v[126:129]
	v_mfma_f32_16x16x32_bf16 v[122:125], v[198:201], v[190:193], v[122:125]
	v_mfma_f32_16x16x32_bf16 v[118:121], v[206:209], v[182:185], v[118:121]
	v_mfma_f32_16x16x32_bf16 v[114:117], v[206:209], v[190:193], v[114:117]
	v_mfma_f32_16x16x32_bf16 v[110:113], v[214:217], v[182:185], v[110:113]
	v_mfma_f32_16x16x32_bf16 v[106:109], v[214:217], v[190:193], v[106:109]
	v_mfma_f32_16x16x32_bf16 v[102:105], v[222:225], v[182:185], v[102:105]
	v_mfma_f32_16x16x32_bf16 v[98:101], v[222:225], v[190:193], v[98:101]
	s_barrier
	v_readfirstlane_b32 s0, v153
	v_lshl_add_u64 v[250:251], v[246:247], 0, s[4:5]
	s_mov_b32 m0, s0
	v_readfirstlane_b32 s0, v154
	ds_read_b128 v[226:229], v145
	ds_read_b128 v[230:233], v145 offset:1024
	ds_read_b128 v[234:237], v145 offset:2048
	ds_read_b128 v[238:241], v145 offset:3072
	global_load_lds_dwordx4 v[250:251], off
	v_lshl_add_u64 v[250:251], v[248:249], 0, s[4:5]
	s_mov_b32 m0, s0
	s_nop 0
	global_load_lds_dwordx4 v[250:251], off
	s_barrier
	s_waitcnt lgkmcnt(0)
	s_waitcnt lgkmcnt(0)
	v_mfma_f32_16x16x32_bf16 v[94:97], v[194:197], v[226:229], v[94:97]
	v_mfma_f32_16x16x32_bf16 v[90:93], v[194:197], v[234:237], v[90:93]
	v_mfma_f32_16x16x32_bf16 v[86:89], v[202:205], v[226:229], v[86:89]
	v_mfma_f32_16x16x32_bf16 v[82:85], v[202:205], v[234:237], v[82:85]
	v_mfma_f32_16x16x32_bf16 v[78:81], v[210:213], v[226:229], v[78:81]
	v_mfma_f32_16x16x32_bf16 v[74:77], v[210:213], v[234:237], v[74:77]
	v_mfma_f32_16x16x32_bf16 v[70:73], v[218:221], v[226:229], v[70:73]
	v_mfma_f32_16x16x32_bf16 v[66:69], v[218:221], v[234:237], v[66:69]
	v_mfma_f32_16x16x32_bf16 v[94:97], v[198:201], v[230:233], v[94:97]
	v_mfma_f32_16x16x32_bf16 v[90:93], v[198:201], v[238:241], v[90:93]
	v_mfma_f32_16x16x32_bf16 v[86:89], v[206:209], v[230:233], v[86:89]
	v_mfma_f32_16x16x32_bf16 v[82:85], v[206:209], v[238:241], v[82:85]
	v_mfma_f32_16x16x32_bf16 v[78:81], v[214:217], v[230:233], v[78:81]
	v_mfma_f32_16x16x32_bf16 v[74:77], v[214:217], v[238:241], v[74:77]
	v_mfma_f32_16x16x32_bf16 v[70:73], v[222:225], v[230:233], v[70:73]
	v_mfma_f32_16x16x32_bf16 v[66:69], v[222:225], v[238:241], v[66:69]
	v_readfirstlane_b32 s0, v155
	v_lshl_add_u64 v[242:243], v[242:243], 0, s[90:91]
	s_mov_b32 m0, s0
	v_readfirstlane_b32 s0, v156
	s_barrier
	ds_read_b128 v[194:197], v142 offset:49152
	ds_read_b128 v[198:201], v142 offset:50176
	ds_read_b128 v[202:205], v142 offset:51200
	ds_read_b128 v[206:209], v142 offset:52224
	ds_read_b128 v[210:213], v142 offset:53248
	ds_read_b128 v[214:217], v142 offset:54272
	ds_read_b128 v[218:221], v142 offset:55296
	ds_read_b128 v[222:225], v142 offset:56320
	global_load_lds_dwordx4 v[242:243], off
	v_lshl_add_u64 v[242:243], v[244:245], 0, s[90:91]
	s_mov_b32 m0, s0
	s_nop 0
	global_load_lds_dwordx4 v[242:243], off
	s_barrier
; #define G_LDA(dst, b, h)                                                                                                  \
;   _Pragma("unroll") for (int m = 0; m < 4; ++m) _Pragma("unroll") for (int k = 0; k < 2; ++k)                             \
;       dst[m][k] = *(const bf16x8*)((const char*)G_SA(b, h) + ((wr * 4 + m) * 2 + k) * 1024 + rdo)
; #define G_LDB(dst, b, h)                                                                                                  \
;   _Pragma("unroll") for (int n = 0; n < 2; ++n) _Pragma("unroll") for (int k = 0; k < 2; ++k)                             \
;       dst[n][k] = *(const bf16x8*)((const char*)G_SB(b, h) + ((wc * 2 + n) * 2 + k) * 1024 + rdo)
; #define G_WAIT_V(n) asm volatile("s_waitcnt vmcnt(" #n ")" ::: "memory")
; #define G_WAIT_L(n) asm volatile("s_waitcnt lgkmcnt(" #n ")" ::: "memory")
; #define G_BAR __builtin_amdgcn_s_barrier()
; #define G_SCHED __builtin_amdgcn_sched_barrier(0)
; DI void br_flush(PREF p, f32x4 (&acc)[2][2][4][2], int slot) { br_store(p, acc, slot); zero_acc256(acc); }
;     ...
;     G_BAR; G_WAIT_L(0); G_MMA(1, 0, At, B0); G_BAR; G_SCHED;
;     G_STAGE(G_SB(1, 1), B, ob0, ob1, LDB, 128, KB(tt + 3));
;     G_WAIT_V(6); G_BAR; G_MMA(1, 1, At, B1); G_BAR;
;     if (MODE && ((tt + 1) & 3) == 3) br_flush(p, acc, (tt + 1) >> 2);
;   }
;   {
;     G_LDB(B0, 0, 0); G_LDA(At, 0, 0); G_STAGE(G_SA(1, 1), A, oa0, oa1, LDA, 128, KA(nt - 1));
;     G_BAR; G_WAIT_L(0); G_MMA(0, 0, At, B0); G_BAR;
;     G_LDB(B1, 0, 1); G_BAR; G_WAIT_L(0); G_MMA(0, 1, At, B1); G_BAR;
;     G_LDA(At, 0, 1); G_WAIT_V(4); G_BAR; G_WAIT_L(0); G_MMA(1, 0, At, B0); G_MMA(1, 1, At, B1); G_BAR;
	s_waitcnt lgkmcnt(0)
	s_waitcnt lgkmcnt(0)
	v_mfma_f32_16x16x32_bf16 v[62:65], v[194:197], v[164:167], v[62:65]
	v_mfma_f32_16x16x32_bf16 v[58:61], v[194:197], v[186:189], v[58:61]
	v_mfma_f32_16x16x32_bf16 v[54:57], v[202:205], v[164:167], v[54:57]
	v_mfma_f32_16x16x32_bf16 v[50:53], v[202:205], v[186:189], v[50:53]
	v_mfma_f32_16x16x32_bf16 v[46:49], v[210:213], v[164:167], v[46:49]
	v_mfma_f32_16x16x32_bf16 v[42:45], v[210:213], v[186:189], v[42:45]
	v_mfma_f32_16x16x32_bf16 v[38:41], v[218:221], v[164:167], v[38:41]
	v_mfma_f32_16x16x32_bf16 v[34:37], v[218:221], v[186:189], v[34:37]
	v_mfma_f32_16x16x32_bf16 v[62:65], v[198:201], v[182:185], v[62:65]
	v_mfma_f32_16x16x32_bf16 v[58:61], v[198:201], v[190:193], v[58:61]
	v_mfma_f32_16x16x32_bf16 v[54:57], v[206:209], v[182:185], v[54:57]
	v_mfma_f32_16x16x32_bf16 v[50:53], v[206:209], v[190:193], v[50:53]
	v_mfma_f32_16x16x32_bf16 v[46:49], v[214:217], v[182:185], v[46:49]
	v_mfma_f32_16x16x32_bf16 v[42:45], v[214:217], v[190:193], v[42:45]
	v_mfma_f32_16x16x32_bf16 v[38:41], v[222:225], v[182:185], v[38:41]
	v_mfma_f32_16x16x32_bf16 v[34:37], v[222:225], v[190:193], v[34:37]
	s_barrier
	v_readfirstlane_b32 s0, v157
	v_lshl_add_u64 v[164:165], v[246:247], 0, s[74:75]
	s_mov_b32 m0, s0
	v_readfirstlane_b32 s0, v159
	global_load_lds_dwordx4 v[164:165], off
	v_lshl_add_u64 v[164:165], v[248:249], 0, s[74:75]
	s_mov_b32 m0, s0
	s_nop 0
	global_load_lds_dwordx4 v[164:165], off
	s_waitcnt vmcnt(6)
	s_barrier
	v_mfma_f32_16x16x32_bf16 v[30:33], v[194:197], v[226:229], v[30:33]
	v_mfma_f32_16x16x32_bf16 v[26:29], v[194:197], v[234:237], v[26:29]
	v_mfma_f32_16x16x32_bf16 v[22:25], v[202:205], v[226:229], v[22:25]
	v_mfma_f32_16x16x32_bf16 v[18:21], v[202:205], v[234:237], v[18:21]
	v_mfma_f32_16x16x32_bf16 v[14:17], v[210:213], v[226:229], v[14:17]
	v_mfma_f32_16x16x32_bf16 v[10:13], v[210:213], v[234:237], v[10:13]
	v_mfma_f32_16x16x32_bf16 v[6:9], v[218:221], v[226:229], v[6:9]
	v_mfma_f32_16x16x32_bf16 v[2:5], v[218:221], v[234:237], v[2:5]
	v_mfma_f32_16x16x32_bf16 v[30:33], v[198:201], v[230:233], v[30:33]
	v_mfma_f32_16x16x32_bf16 v[26:29], v[198:201], v[238:241], v[26:29]
	v_mfma_f32_16x16x32_bf16 v[22:25], v[206:209], v[230:233], v[22:25]
	v_mfma_f32_16x16x32_bf16 v[18:21], v[206:209], v[238:241], v[18:21]
	v_mfma_f32_16x16x32_bf16 v[14:17], v[214:217], v[230:233], v[14:17]
	v_mfma_f32_16x16x32_bf16 v[10:13], v[214:217], v[238:241], v[10:13]
	v_mfma_f32_16x16x32_bf16 v[6:9], v[222:225], v[230:233], v[6:9]
	v_mfma_f32_16x16x32_bf16 v[2:5], v[222:225], v[238:241], v[2:5]
	s_add_i32 s10, s10, 2
	s_add_u32 s8, s8, 0x100
	s_addc_u32 s9, s9, 0
	s_cmp_lt_u32 s10, 12
	s_barrier
	s_cbranch_scc1 .LBB0_105
	v_readfirstlane_b32 s0, v161
	v_lshl_add_u64 v[132:133], v[132:133], 1, s[34:35]
	s_mov_b32 m0, s0
	v_readfirstlane_b32 s0, v162
	ds_read_b128 v[134:137], v160
	ds_read_b128 v[138:141], v160 offset:1024
	ds_read_b128 v[150:153], v160 offset:2048
	ds_read_b128 v[154:157], v160 offset:3072
	ds_read_b128 v[164:167], v142
	ds_read_b128 v[182:185], v142 offset:1024
	ds_read_b128 v[186:189], v142 offset:2048
	ds_read_b128 v[190:193], v142 offset:3072
	ds_read_b128 v[194:197], v142 offset:4096
	ds_read_b128 v[198:201], v142 offset:5120
	ds_read_b128 v[202:205], v142 offset:6144
	ds_read_b128 v[206:209], v142 offset:7168
	global_load_lds_dwordx4 v[132:133], off
	v_lshl_add_u64 v[130:131], v[130:131], 1, s[34:35]
	s_mov_b32 m0, s0
	s_nop 0
	global_load_lds_dwordx4 v[130:131], off
	s_lshl_b32 s1, s23, 8
	s_add_u32 s98, s25, s1
	s_addc_u32 s99, s48, 0
	v_bfe_u32 v251, v168, 6, 2
	v_lshlrev_b32_e32 v248, 6, v251
	v_and_b32_e32 v250, 15, v168
	v_lshl_or_b32 v248, v250, 2, v248
	global_load_dword v170, v248, s[98:99]
	s_add_u32 s98, s98, 0x1000
	s_addc_u32 s99, s99, 0
	global_load_dword v252, v248, s[98:99]
	s_add_u32 s98, s98, 0x1000
	s_addc_u32 s99, s99, 0
	global_load_dword v253, v248, s[98:99]
	s_add_u32 s98, s98, 0x1000
	s_addc_u32 s99, s99, 0
	global_load_dword v162, v248, s[98:99]
	s_lshl_b32 s1, s23, 1
	v_lshrrev_b32_e32 v249, 1, v251
	v_add_u32_e32 v249, s1, v249
	v_and_b32_e32 v249, 3, v249
	v_lshrrev_b32_e32 v250, 8, v168
	v_lshl_add_u32 v249, v250, 2, v249
	v_lshlrev_b32_e32 v249, 14, v249
	v_and_b32_e32 v250, 63, v168
	v_lshl_or_b32 v249, v250, 4, v249
	v_and_b32_e32 v250, 1, v251
	v_lshl_or_b32 v249, v250, 3, v249
	s_lshr_b32 s1, s23, 1
	s_lshl_b32 s1, s1, 12
	s_add_u32 s20, s63, s1
	s_addc_u32 s21, s64, 0
	global_load_dwordx2 v[230:231], v249, s[20:21] offset:0
	global_load_dwordx2 v[238:239], v249, s[20:21] offset:1024
	s_add_u32 s20, s20, 0x20000
	s_addc_u32 s21, s21, 0
	global_load_dwordx2 v[232:233], v249, s[20:21] offset:0
	global_load_dwordx2 v[240:241], v249, s[20:21] offset:1024
	s_add_u32 s20, s20, 0x20000
	s_addc_u32 s21, s21, 0
	global_load_dwordx2 v[234:235], v249, s[20:21] offset:0
	global_load_dwordx2 v[242:243], v249, s[20:21] offset:1024
	s_add_u32 s20, s20, 0x20000
	s_addc_u32 s21, s21, 0
	global_load_dwordx2 v[236:237], v249, s[20:21] offset:0
	global_load_dwordx2 v[244:245], v249, s[20:21] offset:1024
	s_barrier
; #define G_LDA(dst, b, h)                                                                                                  \
;   _Pragma("unroll") for (int m = 0; m < 4; ++m) _Pragma("unroll") for (int k = 0; k < 2; ++k)                             \
;       dst[m][k] = *(const bf16x8*)((const char*)G_SA(b, h) + ((wr * 4 + m) * 2 + k) * 1024 + rdo)
; #define G_LDB(dst, b, h)                                                                                                  \
;   _Pragma("unroll") for (int n = 0; n < 2; ++n) _Pragma("unroll") for (int k = 0; k < 2; ++k)                             \
;       dst[n][k] = *(const bf16x8*)((const char*)G_SB(b, h) + ((wc * 2 + n) * 2 + k) * 1024 + rdo)
; #define G_WAIT_V(n) asm volatile("s_waitcnt vmcnt(" #n ")" ::: "memory")
; #define G_WAIT_L(n) asm volatile("s_waitcnt lgkmcnt(" #n ")" ::: "memory")
; #define G_BAR __builtin_amdgcn_s_barrier()
;     ...
;     G_LDB(B0, 0, 0); G_LDA(At, 0, 0); G_STAGE(G_SA(1, 1), A, oa0, oa1, LDA, 128, KA(nt - 1));
;     G_BAR; G_WAIT_L(0); G_MMA(0, 0, At, B0); G_BAR;
;     G_LDB(B1, 0, 1); G_BAR; G_WAIT_L(0); G_MMA(0, 1, At, B1); G_BAR;
;     G_LDA(At, 0, 1); G_WAIT_V(4); G_BAR; G_WAIT_L(0); G_MMA(1, 0, At, B0); G_MMA(1, 1, At, B1); G_BAR;
;   }
;   {
;     G_LDB(B0, 1, 0); G_LDA(At, 1, 0); G_WAIT_V(2); G_BAR; G_WAIT_L(0); G_MMA(0, 0, At, B0); G_BAR;
	s_waitcnt lgkmcnt(0)
	s_waitcnt lgkmcnt(0)
	v_mfma_f32_16x16x32_bf16 v[126:129], v[164:167], v[134:137], v[126:129]
	v_mfma_f32_16x16x32_bf16 v[122:125], v[164:167], v[150:153], v[122:125]
	v_mfma_f32_16x16x32_bf16 v[114:117], v[186:189], v[150:153], v[114:117]
	v_mfma_f32_16x16x32_bf16 v[110:113], v[194:197], v[134:137], v[110:113]
	v_mfma_f32_16x16x32_bf16 v[106:109], v[194:197], v[150:153], v[106:109]
	v_mfma_f32_16x16x32_bf16 v[102:105], v[202:205], v[134:137], v[102:105]
	v_mfma_f32_16x16x32_bf16 v[98:101], v[202:205], v[150:153], v[98:101]
	v_mfma_f32_16x16x32_bf16 v[126:129], v[182:185], v[138:141], v[126:129]
	v_mfma_f32_16x16x32_bf16 v[122:125], v[182:185], v[154:157], v[122:125]
	v_mfma_f32_16x16x32_bf16 v[118:121], v[186:189], v[134:137], v[118:121]
	v_mfma_f32_16x16x32_bf16 v[114:117], v[190:193], v[154:157], v[114:117]
	v_mfma_f32_16x16x32_bf16 v[110:113], v[198:201], v[138:141], v[110:113]
	v_mfma_f32_16x16x32_bf16 v[106:109], v[198:201], v[154:157], v[106:109]
	v_mfma_f32_16x16x32_bf16 v[102:105], v[206:209], v[138:141], v[102:105]
	v_mfma_f32_16x16x32_bf16 v[98:101], v[206:209], v[154:157], v[98:101]
	v_mfma_f32_16x16x32_bf16 v[118:121], v[190:193], v[138:141], v[118:121]
	s_barrier
	ds_read_b128 v[130:133], v158
	ds_read_b128 v[210:213], v158 offset:1024
	ds_read_b128 v[214:217], v158 offset:2048
	ds_read_b128 v[158:161], v158 offset:3072
	s_barrier
	s_waitcnt lgkmcnt(0)
	s_waitcnt lgkmcnt(0)
	v_mfma_f32_16x16x32_bf16 v[94:97], v[164:167], v[130:133], v[94:97]
	v_mfma_f32_16x16x32_bf16 v[90:93], v[164:167], v[214:217], v[90:93]
	v_mfma_f32_16x16x32_bf16 v[86:89], v[186:189], v[130:133], v[86:89]
	v_mfma_f32_16x16x32_bf16 v[82:85], v[186:189], v[214:217], v[82:85]
	v_mfma_f32_16x16x32_bf16 v[78:81], v[194:197], v[130:133], v[78:81]
	v_mfma_f32_16x16x32_bf16 v[74:77], v[194:197], v[214:217], v[74:77]
	v_mfma_f32_16x16x32_bf16 v[70:73], v[202:205], v[130:133], v[70:73]
	v_mfma_f32_16x16x32_bf16 v[66:69], v[202:205], v[214:217], v[66:69]
	v_mfma_f32_16x16x32_bf16 v[94:97], v[182:185], v[210:213], v[94:97]
	v_mfma_f32_16x16x32_bf16 v[90:93], v[182:185], v[158:161], v[90:93]
	v_mfma_f32_16x16x32_bf16 v[86:89], v[190:193], v[210:213], v[86:89]
	v_mfma_f32_16x16x32_bf16 v[82:85], v[190:193], v[158:161], v[82:85]
	v_mfma_f32_16x16x32_bf16 v[78:81], v[198:201], v[210:213], v[78:81]
	v_mfma_f32_16x16x32_bf16 v[74:77], v[198:201], v[158:161], v[74:77]
	v_mfma_f32_16x16x32_bf16 v[70:73], v[206:209], v[210:213], v[70:73]
	v_mfma_f32_16x16x32_bf16 v[66:69], v[206:209], v[158:161], v[66:69]
	s_barrier
	ds_read_b128 v[164:167], v142 offset:16384
	ds_read_b128 v[182:185], v142 offset:17408
	ds_read_b128 v[186:189], v142 offset:18432
	ds_read_b128 v[190:193], v142 offset:19456
	ds_read_b128 v[194:197], v142 offset:20480
	ds_read_b128 v[198:201], v142 offset:21504
	ds_read_b128 v[202:205], v142 offset:22528
	ds_read_b128 v[206:209], v142 offset:23552
	s_waitcnt vmcnt(16)
	s_barrier
	s_waitcnt lgkmcnt(0)
	s_waitcnt lgkmcnt(0)
	v_mfma_f32_16x16x32_bf16 v[62:65], v[164:167], v[134:137], v[62:65]
	v_mfma_f32_16x16x32_bf16 v[58:61], v[164:167], v[150:153], v[58:61]
	v_mfma_f32_16x16x32_bf16 v[54:57], v[186:189], v[134:137], v[54:57]
	v_mfma_f32_16x16x32_bf16 v[50:53], v[186:189], v[150:153], v[50:53]
	v_mfma_f32_16x16x32_bf16 v[46:49], v[194:197], v[134:137], v[46:49]
	v_mfma_f32_16x16x32_bf16 v[38:41], v[202:205], v[134:137], v[38:41]
	v_mfma_f32_16x16x32_bf16 v[34:37], v[202:205], v[150:153], v[34:37]
	v_mfma_f32_16x16x32_bf16 v[62:65], v[182:185], v[138:141], v[62:65]
	v_mfma_f32_16x16x32_bf16 v[58:61], v[182:185], v[154:157], v[58:61]
	v_mfma_f32_16x16x32_bf16 v[54:57], v[190:193], v[138:141], v[54:57]
	v_mfma_f32_16x16x32_bf16 v[50:53], v[190:193], v[154:157], v[50:53]
	v_mfma_f32_16x16x32_bf16 v[46:49], v[198:201], v[138:141], v[46:49]
	v_mfma_f32_16x16x32_bf16 v[42:45], v[194:197], v[150:153], v[42:45]
	v_mfma_f32_16x16x32_bf16 v[38:41], v[206:209], v[138:141], v[38:41]
	v_mfma_f32_16x16x32_bf16 v[34:37], v[206:209], v[154:157], v[34:37]
	v_mfma_f32_16x16x32_bf16 v[42:45], v[198:201], v[154:157], v[42:45]
	v_mfma_f32_16x16x32_bf16 v[26:29], v[164:167], v[214:217], v[26:29]
	v_mfma_f32_16x16x32_bf16 v[22:25], v[186:189], v[130:133], v[22:25]
	v_mfma_f32_16x16x32_bf16 v[14:17], v[194:197], v[130:133], v[14:17]
	v_mfma_f32_16x16x32_bf16 v[10:13], v[194:197], v[214:217], v[10:13]
	v_mfma_f32_16x16x32_bf16 v[2:5], v[202:205], v[214:217], v[2:5]
	v_mfma_f32_16x16x32_bf16 v[30:33], v[164:167], v[130:133], v[30:33]
	v_mfma_f32_16x16x32_bf16 v[26:29], v[182:185], v[158:161], v[26:29]
	v_mfma_f32_16x16x32_bf16 v[22:25], v[190:193], v[210:213], v[22:25]
	v_mfma_f32_16x16x32_bf16 v[18:21], v[186:189], v[214:217], v[18:21]
	v_mfma_f32_16x16x32_bf16 v[14:17], v[198:201], v[210:213], v[14:17]
	v_mfma_f32_16x16x32_bf16 v[10:13], v[198:201], v[158:161], v[10:13]
	v_mfma_f32_16x16x32_bf16 v[6:9], v[202:205], v[130:133], v[6:9]
	v_mfma_f32_16x16x32_bf16 v[2:5], v[206:209], v[158:161], v[2:5]
	v_mfma_f32_16x16x32_bf16 v[30:33], v[182:185], v[210:213], v[30:33]
	v_mfma_f32_16x16x32_bf16 v[18:21], v[190:193], v[158:161], v[18:21]
	v_mfma_f32_16x16x32_bf16 v[6:9], v[206:209], v[210:213], v[6:9]
	s_barrier
	ds_read_b128 v[130:133], v148
	ds_read_b128 v[154:157], v148 offset:1024
	ds_read_b128 v[164:167], v148 offset:2048
	ds_read_b128 v[182:185], v148 offset:3072
	ds_read_b128 v[186:189], v142 offset:32768
	ds_read_b128 v[190:193], v142 offset:33792
	ds_read_b128 v[194:197], v142 offset:34816
	ds_read_b128 v[198:201], v142 offset:35840
	ds_read_b128 v[202:205], v142 offset:36864
	ds_read_b128 v[206:209], v142 offset:37888
	ds_read_b128 v[210:213], v142 offset:38912
	ds_read_b128 v[214:217], v142 offset:39936
	s_waitcnt vmcnt(14)
	s_barrier
; #define G_LDA(dst, b, h)                                                                                                  \
;   _Pragma("unroll") for (int m = 0; m < 4; ++m) _Pragma("unroll") for (int k = 0; k < 2; ++k)                             \
;       dst[m][k] = *(const bf16x8*)((const char*)G_SA(b, h) + ((wr * 4 + m) * 2 + k) * 1024 + rdo)
; #define G_LDB(dst, b, h)                                                                                                  \
;   _Pragma("unroll") for (int n = 0; n < 2; ++n) _Pragma("unroll") for (int k = 0; k < 2; ++k)                             \
;       dst[n][k] = *(const bf16x8*)((const char*)G_SB(b, h) + ((wc * 2 + n) * 2 + k) * 1024 + rdo)
; #define G_WAIT_V(n) asm volatile("s_waitcnt vmcnt(" #n ")" ::: "memory")
; #define G_WAIT_L(n) asm volatile("s_waitcnt lgkmcnt(" #n ")" ::: "memory")
; #define G_BAR __builtin_amdgcn_s_barrier()
;     ...
;     G_LDB(B0, 1, 0); G_LDA(At, 1, 0); G_WAIT_V(2); G_BAR; G_WAIT_L(0); G_MMA(0, 0, At, B0); G_BAR;
;     G_LDB(B1, 1, 1); G_WAIT_V(0); G_BAR; G_WAIT_L(0); G_MMA(0, 1, At, B1); G_BAR;
;     G_LDA(At, 1, 1); G_BAR; G_WAIT_L(0); G_MMA(1, 0, At, B0); G_MMA(1, 1, At, B1); G_BAR;
;   }
;   if (wr == 0) G_BAR;
	s_waitcnt lgkmcnt(0)
	s_waitcnt lgkmcnt(0)
	v_mfma_f32_16x16x32_bf16 v[126:129], v[186:189], v[130:133], v[126:129]
	v_mfma_f32_16x16x32_bf16 v[122:125], v[186:189], v[164:167], v[122:125]
	v_mfma_f32_16x16x32_bf16 v[118:121], v[194:197], v[130:133], v[118:121]
	v_mfma_f32_16x16x32_bf16 v[114:117], v[194:197], v[164:167], v[114:117]
	v_mfma_f32_16x16x32_bf16 v[110:113], v[202:205], v[130:133], v[110:113]
	v_mfma_f32_16x16x32_bf16 v[106:109], v[202:205], v[164:167], v[106:109]
	v_mfma_f32_16x16x32_bf16 v[102:105], v[210:213], v[130:133], v[102:105]
	v_mfma_f32_16x16x32_bf16 v[98:101], v[210:213], v[164:167], v[98:101]
	v_mfma_f32_16x16x32_bf16 v[158:161], v[190:193], v[154:157], v[126:129]
	v_mfma_f32_16x16x32_bf16 v[150:153], v[190:193], v[182:185], v[122:125]
	v_mfma_f32_16x16x32_bf16 v[146:149], v[198:201], v[154:157], v[118:121]
	v_mfma_f32_16x16x32_bf16 v[138:141], v[198:201], v[182:185], v[114:117]
	v_mfma_f32_16x16x32_bf16 v[134:137], v[206:209], v[154:157], v[110:113]
	v_mfma_f32_16x16x32_bf16 v[126:129], v[206:209], v[182:185], v[106:109]
	v_mfma_f32_16x16x32_bf16 v[122:125], v[214:217], v[154:157], v[102:105]
	v_mfma_f32_16x16x32_bf16 v[114:117], v[214:217], v[182:185], v[98:101]
	s_barrier
	ds_read_b128 v[118:121], v145
	ds_read_b128 v[218:221], v145 offset:1024
	ds_read_b128 v[222:225], v145 offset:2048
	ds_read_b128 v[226:229], v145 offset:3072
	s_waitcnt vmcnt(12)
	s_barrier
	s_waitcnt lgkmcnt(0)
	s_waitcnt lgkmcnt(0)
	v_mfma_f32_16x16x32_bf16 v[94:97], v[186:189], v[118:121], v[94:97]
	v_mfma_f32_16x16x32_bf16 v[90:93], v[186:189], v[222:225], v[90:93]
	v_mfma_f32_16x16x32_bf16 v[86:89], v[194:197], v[118:121], v[86:89]
	v_mfma_f32_16x16x32_bf16 v[82:85], v[194:197], v[222:225], v[82:85]
	v_mfma_f32_16x16x32_bf16 v[78:81], v[202:205], v[118:121], v[78:81]
	v_mfma_f32_16x16x32_bf16 v[74:77], v[202:205], v[222:225], v[74:77]
	v_mfma_f32_16x16x32_bf16 v[70:73], v[210:213], v[118:121], v[70:73]
	v_mfma_f32_16x16x32_bf16 v[66:69], v[210:213], v[222:225], v[66:69]
	v_mfma_f32_16x16x32_bf16 v[110:113], v[190:193], v[218:221], v[94:97]
	v_mfma_f32_16x16x32_bf16 v[106:109], v[190:193], v[226:229], v[90:93]
	v_mfma_f32_16x16x32_bf16 v[102:105], v[198:201], v[218:221], v[86:89]
	v_mfma_f32_16x16x32_bf16 v[98:101], v[198:201], v[226:229], v[82:85]
	v_mfma_f32_16x16x32_bf16 v[94:97], v[206:209], v[218:221], v[78:81]
	v_mfma_f32_16x16x32_bf16 v[90:93], v[206:209], v[226:229], v[74:77]
	v_mfma_f32_16x16x32_bf16 v[86:89], v[214:217], v[218:221], v[70:73]
	v_mfma_f32_16x16x32_bf16 v[82:85], v[214:217], v[226:229], v[66:69]
	s_barrier
	ds_read_b128 v[186:189], v142 offset:49152
	ds_read_b128 v[190:193], v142 offset:50176
	ds_read_b128 v[194:197], v142 offset:51200
	ds_read_b128 v[198:201], v142 offset:52224
	ds_read_b128 v[202:205], v142 offset:53248
	ds_read_b128 v[206:209], v142 offset:54272
	ds_read_b128 v[210:213], v142 offset:55296
	ds_read_b128 v[142:145], v142 offset:56320
	s_barrier
	s_waitcnt lgkmcnt(0)
	s_waitcnt lgkmcnt(0)
	v_mfma_f32_16x16x32_bf16 v[62:65], v[186:189], v[130:133], v[62:65]
	v_mfma_f32_16x16x32_bf16 v[58:61], v[186:189], v[164:167], v[58:61]
	v_mfma_f32_16x16x32_bf16 v[54:57], v[194:197], v[130:133], v[54:57]
	v_mfma_f32_16x16x32_bf16 v[50:53], v[194:197], v[164:167], v[50:53]
	v_mfma_f32_16x16x32_bf16 v[46:49], v[202:205], v[130:133], v[46:49]
	v_mfma_f32_16x16x32_bf16 v[42:45], v[202:205], v[164:167], v[42:45]
	v_mfma_f32_16x16x32_bf16 v[38:41], v[210:213], v[130:133], v[38:41]
	v_mfma_f32_16x16x32_bf16 v[34:37], v[210:213], v[164:167], v[34:37]
	v_mfma_f32_16x16x32_bf16 v[78:81], v[190:193], v[154:157], v[62:65]
	v_mfma_f32_16x16x32_bf16 v[74:77], v[190:193], v[182:185], v[58:61]
	v_mfma_f32_16x16x32_bf16 v[70:73], v[198:201], v[154:157], v[54:57]
	v_mfma_f32_16x16x32_bf16 v[66:69], v[198:201], v[182:185], v[50:53]
	v_mfma_f32_16x16x32_bf16 v[62:65], v[206:209], v[154:157], v[46:49]
	v_mfma_f32_16x16x32_bf16 v[58:61], v[206:209], v[182:185], v[42:45]
	v_mfma_f32_16x16x32_bf16 v[54:57], v[142:145], v[154:157], v[38:41]
	v_mfma_f32_16x16x32_bf16 v[50:53], v[142:145], v[182:185], v[34:37]
	v_mfma_f32_16x16x32_bf16 v[30:33], v[186:189], v[118:121], v[30:33]
	v_mfma_f32_16x16x32_bf16 v[26:29], v[186:189], v[222:225], v[26:29]
	v_mfma_f32_16x16x32_bf16 v[22:25], v[194:197], v[118:121], v[22:25]
	v_mfma_f32_16x16x32_bf16 v[18:21], v[194:197], v[222:225], v[18:21]
	v_mfma_f32_16x16x32_bf16 v[14:17], v[202:205], v[118:121], v[14:17]
	v_mfma_f32_16x16x32_bf16 v[10:13], v[202:205], v[222:225], v[10:13]
	v_mfma_f32_16x16x32_bf16 v[6:9], v[210:213], v[118:121], v[6:9]
	v_mfma_f32_16x16x32_bf16 v[2:5], v[210:213], v[222:225], v[2:5]
	v_mfma_f32_16x16x32_bf16 v[46:49], v[190:193], v[218:221], v[30:33]
	v_mfma_f32_16x16x32_bf16 v[38:41], v[190:193], v[226:229], v[26:29]
	v_mfma_f32_16x16x32_bf16 v[34:37], v[198:201], v[218:221], v[22:25]
	v_mfma_f32_16x16x32_bf16 v[26:29], v[198:201], v[226:229], v[18:21]
	v_mfma_f32_16x16x32_bf16 v[22:25], v[206:209], v[218:221], v[14:17]
	v_mfma_f32_16x16x32_bf16 v[14:17], v[206:209], v[226:229], v[10:13]
	v_mfma_f32_16x16x32_bf16 v[10:13], v[142:145], v[218:221], v[6:9]
	v_mfma_f32_16x16x32_bf16 v[2:5], v[142:145], v[226:229], v[2:5]
	v_cmp_gt_u32_e32 vcc, s67, v0
	s_barrier
	s_and_saveexec_b64 s[8:9], vcc
	s_cbranch_execz .LBB0_108
	s_barrier

; DI void lds_barrier() { asm volatile("s_waitcnt lgkmcnt(0)\n\ts_barrier" ::: "memory"); }
; #define G_LDA(dst, b, h)                                                                                                  \
;   _Pragma("unroll") for (int m = 0; m < 4; ++m) _Pragma("unroll") for (int k = 0; k < 2; ++k)                             \
;       dst[m][k] = *(const bf16x8*)((const char*)G_SA(b, h) + ((wr * 4 + m) * 2 + k) * 1024 + rdo)
; #define G_LDB(dst, b, h)                                                                                                  \
;   _Pragma("unroll") for (int n = 0; n < 2; ++n) _Pragma("unroll") for (int k = 0; k < 2; ++k)                             \
;       dst[n][k] = *(const bf16x8*)((const char*)G_SB(b, h) + ((wc * 2 + n) * 2 + k) * 1024 + rdo)
; #define G_WAIT_V(n) asm volatile("s_waitcnt vmcnt(" #n ")" ::: "memory")
; #define G_WAIT_L(n) asm volatile("s_waitcnt lgkmcnt(" #n ")" ::: "memory")
; #define G_BAR __builtin_amdgcn_s_barrier()
; #define G_SCHED __builtin_amdgcn_sched_barrier(0)
;     ...
;   lds_barrier();
;   G_STAGE(G_SB(0, 0), B, ob0, ob1, LDB, 0, KB(0)); G_STAGE(G_SA(0, 0), A, oa0, oa1, LDA, 0, KA(0));
;   G_STAGE(G_SB(0, 1), B, ob0, ob1, LDB, 128, KB(0)); G_STAGE(G_SA(0, 1), A, oa0, oa1, LDA, 128, KA(0));
;   if (wr == 1) G_BAR;
;   G_WAIT_V(4); G_BAR;
;   G_STAGE(G_SB(1, 0), B, ob0, ob1, LDB, 0, KB(1)); G_STAGE(G_SA(1, 0), A, oa0, oa1, LDA, 0, KA(1)); G_STAGE(G_SB(1, 1), B, ob0, ob1, LDB, 128, KB(1));
;   G_WAIT_V(6); G_BAR;
;   for (int tt = 0; tt < nt - 2; tt += 2) {
;     G_LDB(B0, 0, 0); G_SCHED; G_LDA(At, 0, 0); G_STAGE(G_SA(1, 1), A, oa0, oa1, LDA, 128, KA(tt + 1));
;     G_WAIT_L(8); G_BAR; G_WAIT_L(0); G_MMA(0, 0, At, B0); G_BAR; G_SCHED;
;     G_LDB(B1, 0, 1); G_STAGE(G_SB(0, 0), B, ob0, ob1, LDB, 0, KB(tt + 2));
;     G_BAR; G_WAIT_L(0); G_MMA(0, 1, At, B1); G_BAR;
.LBB0_217:
	s_or_b64 exec, exec, s[20:21]
	v_add_u32_e32 v13, 0x18000, v18
	v_lshl_add_u64 v[24:25], v[6:7], 0, s[76:77]
	v_readfirstlane_b32 s27, v13
	v_add_u32_e32 v13, 0x1a000, v18
	s_mov_b32 m0, s27
	v_readfirstlane_b32 s28, v13
	v_add_u32_e32 v13, 0x8000, v18
	s_waitcnt vmcnt(4)
	s_barrier
	global_load_lds_dwordx4 v[24:25], off
	v_lshl_add_u64 v[24:25], v[8:9], 0, s[76:77]
	s_mov_b32 m0, s28
	v_readfirstlane_b32 s21, v13
	v_add_u32_e32 v13, 0xa000, v18
	global_load_lds_dwordx4 v[24:25], off
	v_lshl_add_u64 v[24:25], v[10:11], 0, s[76:77]
	s_mov_b32 m0, s21
	v_readfirstlane_b32 s26, v13
	s_add_u32 s0, s18, 0x10080
	v_add_u32_e32 v13, 0x1c000, v18
	global_load_lds_dwordx4 v[24:25], off
	v_lshl_add_u64 v[24:25], v[14:15], 0, s[76:77]
	s_mov_b32 m0, s26
	s_addc_u32 s1, s19, 0
	v_readfirstlane_b32 s15, v13
	v_add_u32_e32 v13, 0x1e000, v18
	global_load_lds_dwordx4 v[24:25], off
	v_lshl_add_u64 v[24:25], s[0:1], 0, v[2:3]
	s_mov_b32 m0, s15
	v_readfirstlane_b32 s20, v13
	global_load_lds_dwordx4 v[24:25], off
	v_lshl_add_u64 v[24:25], s[0:1], 0, v[4:5]
	s_mov_b32 m0, s20
	v_lshlrev_b32_e32 v26, 2, v0
	global_load_lds_dwordx4 v[24:25], off
	v_lshlrev_b32_e32 v24, 6, v0
	v_and_b32_e32 v13, 48, v0
	v_and_b32_e32 v25, 0x3c0, v24
	v_and_b32_e32 v41, 32, v26
	v_or_b32_e32 v40, v25, v13
	v_bitop3_b32 v13, v25, v41, v13 bitop3:0x36
	s_movk_i32 s0, 0x3000
	v_and_or_b32 v162, v24, s0, v13
	s_add_u32 s0, s16, 0x10080
	s_addc_u32 s1, s17, 0
	v_lshl_add_u64 v[72:73], s[0:1], 0, v[2:3]
	v_lshl_add_u64 v[74:75], s[0:1], 0, v[4:5]
	s_add_u32 s0, s18, 0x10100
	s_addc_u32 s1, s19, 0
	v_or_b32_e32 v230, 0x10000, v162
	v_or_b32_e32 v232, 0x10800, v162
	s_waitcnt vmcnt(6)
	s_barrier
	v_lshl_add_u64 v[160:161], s[0:1], 0, v[2:3]
	v_lshl_add_u64 v[194:195], s[0:1], 0, v[4:5]
	s_add_u32 s0, s16, 0x10100
	v_or_b32_e32 v231, 0x10400, v162
	ds_read_b128 v[24:27], v230
	ds_read_b128 v[28:31], v231
	v_or_b32_e32 v233, 0x10c00, v162
	ds_read_b128 v[32:35], v232
	ds_read_b128 v[36:39], v233
	s_addc_u32 s1, s17, 0
	v_lshl_add_u64 v[214:215], s[0:1], 0, v[2:3]
	v_lshl_add_u64 v[216:217], s[0:1], 0, v[4:5]
	s_add_u32 s0, s18, 0x10180
	s_addc_u32 s1, s19, 0
	v_lshlrev_b32_e32 v42, 13, v12
	v_lshl_add_u64 v[120:121], v[6:7], 0, s[82:83]
	v_lshl_add_u64 v[122:123], v[8:9], 0, s[82:83]
	v_lshl_add_u64 v[152:153], v[10:11], 0, s[82:83]
	v_lshl_add_u64 v[226:227], v[6:7], 0, s[90:91]
	v_lshl_add_u64 v[228:229], v[8:9], 0, s[90:91]
	v_lshl_add_u64 v[12:13], v[10:11], 0, s[90:91]
	v_lshl_add_u64 v[10:11], v[14:15], 0, s[90:91]
	v_lshl_add_u64 v[8:9], s[0:1], 0, v[2:3]
	v_lshl_add_u64 v[6:7], s[0:1], 0, v[4:5]
	v_lshl_add_u64 v[154:155], v[14:15], 0, s[82:83]
	v_add_u32_e32 v14, 0xc000, v18
	v_bitop3_b32 v242, v40, v42, v41 bitop3:0xde
	v_readfirstlane_b32 s19, v14
	v_add_u32_e32 v14, 0xe000, v18
	s_mov_b32 m0, s19
	v_readfirstlane_b32 s18, v14
	ds_read_b128 v[40:43], v242
	ds_read_b128 v[44:47], v242 offset:1024
	ds_read_b128 v[48:51], v242 offset:2048
	ds_read_b128 v[52:55], v242 offset:3072
	ds_read_b128 v[56:59], v242 offset:4096
	ds_read_b128 v[60:63], v242 offset:5120
	ds_read_b128 v[64:67], v242 offset:6144
	ds_read_b128 v[68:71], v242 offset:7168
	global_load_lds_dwordx4 v[72:73], off
	s_mov_b32 m0, s18
	s_nop 0
	global_load_lds_dwordx4 v[74:75], off
	s_waitcnt lgkmcnt(8)
	s_barrier
	s_waitcnt lgkmcnt(0)
	s_waitcnt lgkmcnt(0)
	v_mfma_f32_16x16x32_bf16 v[72:75], v[40:43], v[24:27], 0
	v_mfma_f32_16x16x32_bf16 v[76:79], v[40:43], v[32:35], 0
	v_mfma_f32_16x16x32_bf16 v[80:83], v[48:51], v[24:27], 0
	v_mfma_f32_16x16x32_bf16 v[84:87], v[48:51], v[32:35], 0
	v_mfma_f32_16x16x32_bf16 v[88:91], v[56:59], v[24:27], 0
	v_mfma_f32_16x16x32_bf16 v[92:95], v[56:59], v[32:35], 0
	v_mfma_f32_16x16x32_bf16 v[96:99], v[64:67], v[24:27], 0
	v_mfma_f32_16x16x32_bf16 v[100:103], v[64:67], v[32:35], 0
	v_mfma_f32_16x16x32_bf16 v[72:75], v[44:47], v[28:31], v[72:75]
	v_mfma_f32_16x16x32_bf16 v[76:79], v[44:47], v[36:39], v[76:79]
	v_mfma_f32_16x16x32_bf16 v[80:83], v[52:55], v[28:31], v[80:83]
	v_mfma_f32_16x16x32_bf16 v[84:87], v[52:55], v[36:39], v[84:87]
	v_mfma_f32_16x16x32_bf16 v[88:91], v[60:63], v[28:31], v[88:91]
	v_mfma_f32_16x16x32_bf16 v[92:95], v[60:63], v[36:39], v[92:95]
	v_mfma_f32_16x16x32_bf16 v[96:99], v[68:71], v[28:31], v[96:99]
	v_mfma_f32_16x16x32_bf16 v[100:103], v[68:71], v[36:39], v[100:103]
	s_barrier
	v_readfirstlane_b32 s0, v22
	v_or_b32_e32 v234, 0x14000, v162
	v_or_b32_e32 v236, 0x14800, v162
	s_mov_b32 m0, s0
	v_readfirstlane_b32 s0, v23
	v_or_b32_e32 v235, 0x14400, v162
	ds_read_b128 v[104:107], v234
	ds_read_b128 v[108:111], v235
	v_or_b32_e32 v237, 0x14c00, v162
	ds_read_b128 v[112:115], v236
	ds_read_b128 v[116:119], v237
	global_load_lds_dwordx4 v[120:121], off
	s_mov_b32 m0, s0
	s_nop 0
	global_load_lds_dwordx4 v[122:123], off
	s_barrier
	s_waitcnt lgkmcnt(0)
	s_waitcnt lgkmcnt(0)
	v_mfma_f32_16x16x32_bf16 v[120:123], v[40:43], v[104:107], 0
	v_mfma_f32_16x16x32_bf16 v[40:43], v[40:43], v[112:115], 0
	v_mfma_f32_16x16x32_bf16 v[120:123], v[44:47], v[108:111], v[120:123]
	v_mfma_f32_16x16x32_bf16 v[40:43], v[44:47], v[116:119], v[40:43]
	v_mfma_f32_16x16x32_bf16 v[44:47], v[48:51], v[104:107], 0
	v_mfma_f32_16x16x32_bf16 v[48:51], v[48:51], v[112:115], 0
	v_mfma_f32_16x16x32_bf16 v[44:47], v[52:55], v[108:111], v[44:47]
	v_mfma_f32_16x16x32_bf16 v[48:51], v[52:55], v[116:119], v[48:51]
	v_mfma_f32_16x16x32_bf16 v[52:55], v[56:59], v[104:107], 0
	v_mfma_f32_16x16x32_bf16 v[56:59], v[56:59], v[112:115], 0
	v_mfma_f32_16x16x32_bf16 v[52:55], v[60:63], v[108:111], v[52:55]
	v_mfma_f32_16x16x32_bf16 v[56:59], v[60:63], v[116:119], v[56:59]
	v_mfma_f32_16x16x32_bf16 v[60:63], v[64:67], v[104:107], 0
	v_mfma_f32_16x16x32_bf16 v[64:67], v[64:67], v[112:115], 0
	v_mfma_f32_16x16x32_bf16 v[60:63], v[68:71], v[108:111], v[60:63]
	v_mfma_f32_16x16x32_bf16 v[64:67], v[68:71], v[116:119], v[64:67]
	v_readfirstlane_b32 s0, v18
	s_mov_b32 m0, s0
	v_readfirstlane_b32 s0, v19
	s_barrier
; #define G_LDA(dst, b, h)                                                                                                  \
;   _Pragma("unroll") for (int m = 0; m < 4; ++m) _Pragma("unroll") for (int k = 0; k < 2; ++k)                             \
;       dst[m][k] = *(const bf16x8*)((const char*)G_SA(b, h) + ((wr * 4 + m) * 2 + k) * 1024 + rdo)
; #define G_LDB(dst, b, h)                                                                                                  \
;   _Pragma("unroll") for (int n = 0; n < 2; ++n) _Pragma("unroll") for (int k = 0; k < 2; ++k)                             \
;       dst[n][k] = *(const bf16x8*)((const char*)G_SB(b, h) + ((wc * 2 + n) * 2 + k) * 1024 + rdo)
; #define G_WAIT_V(n) asm volatile("s_waitcnt vmcnt(" #n ")" ::: "memory")
; #define G_WAIT_L(n) asm volatile("s_waitcnt lgkmcnt(" #n ")" ::: "memory")
; #define G_BAR __builtin_amdgcn_s_barrier()
; #define G_SCHED __builtin_amdgcn_sched_barrier(0)
;     ...
;     G_BAR; G_WAIT_L(0); G_MMA(0, 1, At, B1); G_BAR;
;     G_LDA(At, 0, 1); G_STAGE(G_SA(0, 0), A, oa0, oa1, LDA, 0, KA(tt + 2));
;     G_BAR; G_WAIT_L(0); G_MMA(1, 0, At, B0); G_BAR; G_SCHED;
;     G_STAGE(G_SB(0, 1), B, ob0, ob1, LDB, 128, KB(tt + 2));
;     G_WAIT_V(6); G_BAR; G_MMA(1, 1, At, B1); G_BAR;
;     G_LDB(B0, 1, 0); G_SCHED; G_LDA(At, 1, 0); G_STAGE(G_SA(0, 1), A, oa0, oa1, LDA, 128, KA(tt + 2));
;     G_WAIT_L(8); G_BAR; G_WAIT_L(0); G_MMA(0, 0, At, B0); G_BAR; G_SCHED;
;     G_LDB(B1, 1, 1); G_STAGE(G_SB(1, 0), B, ob0, ob1, LDB, 0, KB(tt + 3));
;     G_BAR; G_WAIT_L(0); G_MMA(0, 1, At, B1); G_BAR;
	ds_read_b128 v[68:71], v242 offset:16384
	ds_read_b128 v[124:127], v242 offset:17408
	ds_read_b128 v[128:131], v242 offset:18432
	ds_read_b128 v[132:135], v242 offset:19456
	ds_read_b128 v[136:139], v242 offset:20480
	ds_read_b128 v[140:143], v242 offset:21504
	ds_read_b128 v[144:147], v242 offset:22528
	ds_read_b128 v[148:151], v242 offset:23552
	global_load_lds_dwordx4 v[152:153], off
	s_mov_b32 m0, s0
	s_nop 0
	global_load_lds_dwordx4 v[154:155], off
	s_barrier
	s_waitcnt lgkmcnt(0)
	s_waitcnt lgkmcnt(0)
	v_mfma_f32_16x16x32_bf16 v[152:155], v[68:71], v[24:27], 0
	v_mfma_f32_16x16x32_bf16 v[164:167], v[128:131], v[24:27], 0
	v_mfma_f32_16x16x32_bf16 v[186:189], v[136:139], v[24:27], 0
	v_mfma_f32_16x16x32_bf16 v[22:25], v[144:147], v[24:27], 0
	v_mfma_f32_16x16x32_bf16 v[152:155], v[124:127], v[28:31], v[152:155]
	v_mfma_f32_16x16x32_bf16 v[164:167], v[132:135], v[28:31], v[164:167]
	v_mfma_f32_16x16x32_bf16 v[186:189], v[140:143], v[28:31], v[186:189]
	v_mfma_f32_16x16x32_bf16 v[22:25], v[148:151], v[28:31], v[22:25]
	v_mfma_f32_16x16x32_bf16 v[26:29], v[144:147], v[32:35], 0
	v_mfma_f32_16x16x32_bf16 v[156:159], v[68:71], v[32:35], 0
	v_mfma_f32_16x16x32_bf16 v[182:185], v[128:131], v[32:35], 0
	v_mfma_f32_16x16x32_bf16 v[190:193], v[136:139], v[32:35], 0
	v_mfma_f32_16x16x32_bf16 v[26:29], v[148:151], v[36:39], v[26:29]
	v_mfma_f32_16x16x32_bf16 v[156:159], v[124:127], v[36:39], v[156:159]
	v_mfma_f32_16x16x32_bf16 v[182:185], v[132:135], v[36:39], v[182:185]
	v_mfma_f32_16x16x32_bf16 v[190:193], v[140:143], v[36:39], v[190:193]
	s_barrier
	v_readfirstlane_b32 s0, v20
	s_mov_b32 m0, s0
	v_readfirstlane_b32 s0, v21
	global_load_lds_dwordx4 v[160:161], off
	s_mov_b32 m0, s0
	s_nop 0
	global_load_lds_dwordx4 v[194:195], off
	s_waitcnt vmcnt(6)
	s_barrier
	v_mfma_f32_16x16x32_bf16 v[18:21], v[68:71], v[104:107], 0
	v_mfma_f32_16x16x32_bf16 v[30:33], v[68:71], v[112:115], 0
	v_mfma_f32_16x16x32_bf16 v[18:21], v[124:127], v[108:111], v[18:21]
	v_mfma_f32_16x16x32_bf16 v[30:33], v[124:127], v[116:119], v[30:33]
	v_mfma_f32_16x16x32_bf16 v[34:37], v[128:131], v[104:107], 0
	v_mfma_f32_16x16x32_bf16 v[124:127], v[136:139], v[104:107], 0
	v_mfma_f32_16x16x32_bf16 v[104:107], v[144:147], v[104:107], 0
	v_mfma_f32_16x16x32_bf16 v[34:37], v[132:135], v[108:111], v[34:37]
	v_mfma_f32_16x16x32_bf16 v[68:71], v[128:131], v[112:115], 0
	v_mfma_f32_16x16x32_bf16 v[124:127], v[140:143], v[108:111], v[124:127]
	v_mfma_f32_16x16x32_bf16 v[128:131], v[136:139], v[112:115], 0
	v_mfma_f32_16x16x32_bf16 v[104:107], v[148:151], v[108:111], v[104:107]
	v_mfma_f32_16x16x32_bf16 v[108:111], v[144:147], v[112:115], 0
	v_mfma_f32_16x16x32_bf16 v[68:71], v[132:135], v[116:119], v[68:71]
	v_mfma_f32_16x16x32_bf16 v[128:131], v[140:143], v[116:119], v[128:131]
	v_mfma_f32_16x16x32_bf16 v[108:111], v[148:151], v[116:119], v[108:111]
	v_or_b32_e32 v160, 0x18000, v162
	v_or_b32_e32 v238, 0x18800, v162
	s_barrier
	v_or_b32_e32 v161, 0x18400, v162
	ds_read_b128 v[112:115], v160
	ds_read_b128 v[116:119], v161
	v_or_b32_e32 v239, 0x18c00, v162
	ds_read_b128 v[132:135], v238
	ds_read_b128 v[136:139], v239
	v_readfirstlane_b32 s0, v16
	s_mov_b32 m0, s0
	v_readfirstlane_b32 s0, v17
	ds_read_b128 v[140:143], v242 offset:32768
	ds_read_b128 v[144:147], v242 offset:33792
	ds_read_b128 v[148:151], v242 offset:34816
	ds_read_b128 v[194:197], v242 offset:35840
	ds_read_b128 v[198:201], v242 offset:36864
	ds_read_b128 v[202:205], v242 offset:37888
	ds_read_b128 v[206:209], v242 offset:38912
	ds_read_b128 v[210:213], v242 offset:39936
	global_load_lds_dwordx4 v[214:215], off
	s_mov_b32 m0, s0
	s_nop 0
	global_load_lds_dwordx4 v[216:217], off
	s_waitcnt lgkmcnt(8)
	s_barrier
	s_waitcnt lgkmcnt(0)
	s_waitcnt lgkmcnt(0)
	v_mfma_f32_16x16x32_bf16 v[14:17], v[140:143], v[112:115], v[72:75]
	v_mfma_f32_16x16x32_bf16 v[72:75], v[140:143], v[132:135], v[76:79]
	v_mfma_f32_16x16x32_bf16 v[76:79], v[148:151], v[112:115], v[80:83]
	v_mfma_f32_16x16x32_bf16 v[80:83], v[148:151], v[132:135], v[84:87]
	v_mfma_f32_16x16x32_bf16 v[84:87], v[198:201], v[112:115], v[88:91]
	v_mfma_f32_16x16x32_bf16 v[88:91], v[198:201], v[132:135], v[92:95]
	v_mfma_f32_16x16x32_bf16 v[92:95], v[206:209], v[112:115], v[96:99]
	v_mfma_f32_16x16x32_bf16 v[96:99], v[206:209], v[132:135], v[100:103]
	v_mfma_f32_16x16x32_bf16 v[14:17], v[144:147], v[116:119], v[14:17]
	v_mfma_f32_16x16x32_bf16 v[72:75], v[144:147], v[136:139], v[72:75]
	v_mfma_f32_16x16x32_bf16 v[76:79], v[194:197], v[116:119], v[76:79]
	v_mfma_f32_16x16x32_bf16 v[80:83], v[194:197], v[136:139], v[80:83]
	v_mfma_f32_16x16x32_bf16 v[84:87], v[202:205], v[116:119], v[84:87]
	v_mfma_f32_16x16x32_bf16 v[88:91], v[202:205], v[136:139], v[88:91]
	v_mfma_f32_16x16x32_bf16 v[92:95], v[210:213], v[116:119], v[92:95]
	v_mfma_f32_16x16x32_bf16 v[96:99], v[210:213], v[136:139], v[96:99]
	s_barrier
	v_or_b32_e32 v240, 0x1c000, v162
	v_or_b32_e32 v243, 0x1c800, v162
	s_mov_b32 m0, s27
	v_or_b32_e32 v241, 0x1c400, v162
	ds_read_b128 v[100:103], v240
	ds_read_b128 v[214:217], v241
	v_or_b32_e32 v162, 0x1cc00, v162
	ds_read_b128 v[218:221], v243
	ds_read_b128 v[222:225], v162
	global_load_lds_dwordx4 v[226:227], off
	s_mov_b32 m0, s28
	s_nop 0
	global_load_lds_dwordx4 v[228:229], off
	s_barrier
; #define G_LDA(dst, b, h)                                                                                                  \
;   _Pragma("unroll") for (int m = 0; m < 4; ++m) _Pragma("unroll") for (int k = 0; k < 2; ++k)                             \
;       dst[m][k] = *(const bf16x8*)((const char*)G_SA(b, h) + ((wr * 4 + m) * 2 + k) * 1024 + rdo)
; #define G_LDB(dst, b, h)                                                                                                  \
;   _Pragma("unroll") for (int n = 0; n < 2; ++n) _Pragma("unroll") for (int k = 0; k < 2; ++k)                             \
;       dst[n][k] = *(const bf16x8*)((const char*)G_SB(b, h) + ((wc * 2 + n) * 2 + k) * 1024 + rdo)
; #define G_WAIT_V(n) asm volatile("s_waitcnt vmcnt(" #n ")" ::: "memory")
; #define G_WAIT_L(n) asm volatile("s_waitcnt lgkmcnt(" #n ")" ::: "memory")
; #define G_BAR __builtin_amdgcn_s_barrier()
; #define G_SCHED __builtin_amdgcn_sched_barrier(0)
; DI void br_flush(PREF p, f32x4 (&acc)[2][2][4][2], int slot) { br_store(p, acc, slot); zero_acc256(acc); }
;     ...
;     G_BAR; G_WAIT_L(0); G_MMA(0, 1, At, B1); G_BAR;
;     G_LDA(At, 1, 1); G_STAGE(G_SA(1, 0), A, oa0, oa1, LDA, 0, KA(tt + 3));
;     G_BAR; G_WAIT_L(0); G_MMA(1, 0, At, B0); G_BAR; G_SCHED;
;     G_STAGE(G_SB(1, 1), B, ob0, ob1, LDB, 128, KB(tt + 3));
;     G_WAIT_V(6); G_BAR; G_MMA(1, 1, At, B1); G_BAR;
;     if (MODE && ((tt + 1) & 3) == 3) br_flush(p, acc, (tt + 1) >> 2);
;   }
;   {
;     G_LDB(B0, 0, 0); G_LDA(At, 0, 0); G_STAGE(G_SA(1, 1), A, oa0, oa1, LDA, 128, KA(nt - 1));
;     G_BAR; G_WAIT_L(0); G_MMA(0, 0, At, B0); G_BAR;
;     G_LDB(B1, 0, 1); G_BAR; G_WAIT_L(0); G_MMA(0, 1, At, B1); G_BAR;
;     G_LDA(At, 0, 1); G_WAIT_V(4); G_BAR; G_WAIT_L(0); G_MMA(1, 0, At, B0); G_MMA(1, 1, At, B1); G_BAR;
	s_waitcnt lgkmcnt(0)
	s_waitcnt lgkmcnt(0)
	v_mfma_f32_16x16x32_bf16 v[120:123], v[140:143], v[100:103], v[120:123]
	v_mfma_f32_16x16x32_bf16 v[38:41], v[140:143], v[218:221], v[40:43]
	v_mfma_f32_16x16x32_bf16 v[42:45], v[148:151], v[100:103], v[44:47]
	v_mfma_f32_16x16x32_bf16 v[46:49], v[148:151], v[218:221], v[48:51]
	v_mfma_f32_16x16x32_bf16 v[50:53], v[198:201], v[100:103], v[52:55]
	v_mfma_f32_16x16x32_bf16 v[54:57], v[198:201], v[218:221], v[56:59]
	v_mfma_f32_16x16x32_bf16 v[58:61], v[206:209], v[100:103], v[60:63]
	v_mfma_f32_16x16x32_bf16 v[62:65], v[206:209], v[218:221], v[64:67]
	v_mfma_f32_16x16x32_bf16 v[120:123], v[144:147], v[214:217], v[120:123]
	v_mfma_f32_16x16x32_bf16 v[38:41], v[144:147], v[222:225], v[38:41]
	v_mfma_f32_16x16x32_bf16 v[42:45], v[194:197], v[214:217], v[42:45]
	v_mfma_f32_16x16x32_bf16 v[46:49], v[194:197], v[222:225], v[46:49]
	v_mfma_f32_16x16x32_bf16 v[50:53], v[202:205], v[214:217], v[50:53]
	v_mfma_f32_16x16x32_bf16 v[54:57], v[202:205], v[222:225], v[54:57]
	v_mfma_f32_16x16x32_bf16 v[58:61], v[210:213], v[214:217], v[58:61]
	v_mfma_f32_16x16x32_bf16 v[62:65], v[210:213], v[222:225], v[62:65]
	s_mov_b32 m0, s21
	s_barrier
	ds_read_b128 v[140:143], v242 offset:49152
	ds_read_b128 v[144:147], v242 offset:50176
	ds_read_b128 v[148:151], v242 offset:51200
	ds_read_b128 v[194:197], v242 offset:52224
	ds_read_b128 v[198:201], v242 offset:53248
	ds_read_b128 v[202:205], v242 offset:54272
	ds_read_b128 v[206:209], v242 offset:55296
	ds_read_b128 v[210:213], v242 offset:56320
	global_load_lds_dwordx4 v[12:13], off
	s_mov_b32 m0, s26
	s_nop 0
	global_load_lds_dwordx4 v[10:11], off
	s_barrier
	s_waitcnt lgkmcnt(0)
	s_waitcnt lgkmcnt(0)
	v_mfma_f32_16x16x32_bf16 v[10:13], v[140:143], v[112:115], v[152:155]
	v_mfma_f32_16x16x32_bf16 v[22:25], v[206:209], v[112:115], v[22:25]
	v_mfma_f32_16x16x32_bf16 v[26:29], v[206:209], v[132:135], v[26:29]
	v_mfma_f32_16x16x32_bf16 v[10:13], v[144:147], v[116:119], v[10:13]
	v_mfma_f32_16x16x32_bf16 v[152:155], v[140:143], v[132:135], v[156:159]
	v_mfma_f32_16x16x32_bf16 v[156:159], v[148:151], v[112:115], v[164:167]
	v_mfma_f32_16x16x32_bf16 v[164:167], v[148:151], v[132:135], v[182:185]
	v_mfma_f32_16x16x32_bf16 v[182:185], v[198:201], v[112:115], v[186:189]
	v_mfma_f32_16x16x32_bf16 v[186:189], v[198:201], v[132:135], v[190:193]
	v_mfma_f32_16x16x32_bf16 v[22:25], v[210:213], v[116:119], v[22:25]
	v_mfma_f32_16x16x32_bf16 v[26:29], v[210:213], v[136:139], v[26:29]
	v_mfma_f32_16x16x32_bf16 v[152:155], v[144:147], v[136:139], v[152:155]
	v_mfma_f32_16x16x32_bf16 v[156:159], v[194:197], v[116:119], v[156:159]
	v_mfma_f32_16x16x32_bf16 v[164:167], v[194:197], v[136:139], v[164:167]
	v_mfma_f32_16x16x32_bf16 v[182:185], v[202:205], v[116:119], v[182:185]
	v_mfma_f32_16x16x32_bf16 v[186:189], v[202:205], v[136:139], v[186:189]
	s_barrier
	s_mov_b32 m0, s15
	s_nop 0
	global_load_lds_dwordx4 v[8:9], off
	s_mov_b32 m0, s20
	s_nop 0
	global_load_lds_dwordx4 v[6:7], off
	s_waitcnt vmcnt(6)
	s_barrier
	v_mfma_f32_16x16x32_bf16 v[6:9], v[140:143], v[100:103], v[18:21]
	v_mfma_f32_16x16x32_bf16 v[18:21], v[140:143], v[218:221], v[30:33]
	v_mfma_f32_16x16x32_bf16 v[30:33], v[148:151], v[100:103], v[34:37]
	v_mfma_f32_16x16x32_bf16 v[34:37], v[148:151], v[218:221], v[68:71]
	v_mfma_f32_16x16x32_bf16 v[66:69], v[198:201], v[100:103], v[124:127]
	v_mfma_f32_16x16x32_bf16 v[112:115], v[198:201], v[218:221], v[128:131]
	v_mfma_f32_16x16x32_bf16 v[100:103], v[206:209], v[100:103], v[104:107]
	v_mfma_f32_16x16x32_bf16 v[104:107], v[206:209], v[218:221], v[108:111]
	v_mfma_f32_16x16x32_bf16 v[6:9], v[144:147], v[214:217], v[6:9]
	v_mfma_f32_16x16x32_bf16 v[18:21], v[144:147], v[222:225], v[18:21]
	v_mfma_f32_16x16x32_bf16 v[30:33], v[194:197], v[214:217], v[30:33]
	v_mfma_f32_16x16x32_bf16 v[34:37], v[194:197], v[222:225], v[34:37]
	v_mfma_f32_16x16x32_bf16 v[66:69], v[202:205], v[214:217], v[66:69]
	v_mfma_f32_16x16x32_bf16 v[112:115], v[202:205], v[222:225], v[112:115]
	v_mfma_f32_16x16x32_bf16 v[100:103], v[210:213], v[214:217], v[100:103]
	v_mfma_f32_16x16x32_bf16 v[104:107], v[210:213], v[222:225], v[104:107]
	s_add_u32 s0, s16, 0x10180
	s_addc_u32 s1, s17, 0
	s_mov_b32 m0, s19
	v_lshl_add_u64 v[2:3], s[0:1], 0, v[2:3]
	s_barrier
	ds_read_b128 v[108:111], v230
	ds_read_b128 v[116:119], v231
	ds_read_b128 v[124:127], v232
	ds_read_b128 v[128:131], v233
	ds_read_b128 v[132:135], v242
	ds_read_b128 v[136:139], v242 offset:1024
	ds_read_b128 v[140:143], v242 offset:2048
	ds_read_b128 v[144:147], v242 offset:3072
	ds_read_b128 v[148:151], v242 offset:4096
	ds_read_b128 v[190:193], v242 offset:5120
	ds_read_b128 v[194:197], v242 offset:6144
	ds_read_b128 v[198:201], v242 offset:7168
	global_load_lds_dwordx4 v[2:3], off
	v_lshl_add_u64 v[2:3], s[0:1], 0, v[4:5]
	s_mov_b32 m0, s18
	s_nop 0
	global_load_lds_dwordx4 v[2:3], off
	s_barrier
	s_waitcnt lgkmcnt(0)
	s_waitcnt lgkmcnt(0)
	v_mfma_f32_16x16x32_bf16 v[2:5], v[132:135], v[108:111], v[14:17]
	v_mfma_f32_16x16x32_bf16 v[14:17], v[132:135], v[124:127], v[72:75]
	v_mfma_f32_16x16x32_bf16 v[70:73], v[140:143], v[108:111], v[76:79]
	v_mfma_f32_16x16x32_bf16 v[74:77], v[140:143], v[124:127], v[80:83]
	v_mfma_f32_16x16x32_bf16 v[78:81], v[148:151], v[108:111], v[84:87]
	v_mfma_f32_16x16x32_bf16 v[82:85], v[148:151], v[124:127], v[88:91]
	v_mfma_f32_16x16x32_bf16 v[86:89], v[194:197], v[108:111], v[92:95]
	v_mfma_f32_16x16x32_bf16 v[90:93], v[194:197], v[124:127], v[96:99]
	v_mfma_f32_16x16x32_bf16 v[2:5], v[136:139], v[116:119], v[2:5]
	v_mfma_f32_16x16x32_bf16 v[14:17], v[136:139], v[128:131], v[14:17]
	v_mfma_f32_16x16x32_bf16 v[70:73], v[144:147], v[116:119], v[70:73]
	v_mfma_f32_16x16x32_bf16 v[74:77], v[144:147], v[128:131], v[74:77]
	v_mfma_f32_16x16x32_bf16 v[78:81], v[190:193], v[116:119], v[78:81]
	v_mfma_f32_16x16x32_bf16 v[82:85], v[190:193], v[128:131], v[82:85]
	v_mfma_f32_16x16x32_bf16 v[86:89], v[198:201], v[116:119], v[86:89]
	v_mfma_f32_16x16x32_bf16 v[90:93], v[198:201], v[128:131], v[90:93]
	s_barrier
; #define G_LDA(dst, b, h)                                                                                                  \
;   _Pragma("unroll") for (int m = 0; m < 4; ++m) _Pragma("unroll") for (int k = 0; k < 2; ++k)                             \
;       dst[m][k] = *(const bf16x8*)((const char*)G_SA(b, h) + ((wr * 4 + m) * 2 + k) * 1024 + rdo)
; #define G_LDB(dst, b, h)                                                                                                  \
;   _Pragma("unroll") for (int n = 0; n < 2; ++n) _Pragma("unroll") for (int k = 0; k < 2; ++k)                             \
;       dst[n][k] = *(const bf16x8*)((const char*)G_SB(b, h) + ((wc * 2 + n) * 2 + k) * 1024 + rdo)
; #define G_WAIT_V(n) asm volatile("s_waitcnt vmcnt(" #n ")" ::: "memory")
; #define G_WAIT_L(n) asm volatile("s_waitcnt lgkmcnt(" #n ")" ::: "memory")
; #define G_BAR __builtin_amdgcn_s_barrier()
;     ...
;     G_BAR; G_WAIT_L(0); G_MMA(0, 0, At, B0); G_BAR;
;     G_LDB(B1, 0, 1); G_BAR; G_WAIT_L(0); G_MMA(0, 1, At, B1); G_BAR;
;     G_LDA(At, 0, 1); G_WAIT_V(4); G_BAR; G_WAIT_L(0); G_MMA(1, 0, At, B0); G_MMA(1, 1, At, B1); G_BAR;
;   }
;   {
;     G_LDB(B0, 1, 0); G_LDA(At, 1, 0); G_WAIT_V(2); G_BAR; G_WAIT_L(0); G_MMA(0, 0, At, B0); G_BAR;
	ds_read_b128 v[94:97], v234
	ds_read_b128 v[202:205], v235
	ds_read_b128 v[206:209], v236
	ds_read_b128 v[210:213], v237
	s_barrier
	s_waitcnt lgkmcnt(0)
	s_waitcnt lgkmcnt(0)
	v_mfma_f32_16x16x32_bf16 v[38:41], v[132:135], v[206:209], v[38:41]
	v_mfma_f32_16x16x32_bf16 v[42:45], v[140:143], v[94:97], v[42:45]
	v_mfma_f32_16x16x32_bf16 v[46:49], v[140:143], v[206:209], v[46:49]
	v_mfma_f32_16x16x32_bf16 v[50:53], v[148:151], v[94:97], v[50:53]
	v_mfma_f32_16x16x32_bf16 v[54:57], v[148:151], v[206:209], v[54:57]
	v_mfma_f32_16x16x32_bf16 v[58:61], v[194:197], v[94:97], v[58:61]
	v_mfma_f32_16x16x32_bf16 v[62:65], v[194:197], v[206:209], v[62:65]
	v_mfma_f32_16x16x32_bf16 v[120:123], v[132:135], v[94:97], v[120:123]
	v_mfma_f32_16x16x32_bf16 v[38:41], v[136:139], v[210:213], v[38:41]
	v_mfma_f32_16x16x32_bf16 v[42:45], v[144:147], v[202:205], v[42:45]
	v_mfma_f32_16x16x32_bf16 v[46:49], v[144:147], v[210:213], v[46:49]
	v_mfma_f32_16x16x32_bf16 v[50:53], v[190:193], v[202:205], v[50:53]
	v_mfma_f32_16x16x32_bf16 v[54:57], v[190:193], v[210:213], v[54:57]
	v_mfma_f32_16x16x32_bf16 v[58:61], v[198:201], v[202:205], v[58:61]
	v_mfma_f32_16x16x32_bf16 v[62:65], v[198:201], v[210:213], v[62:65]
	v_mfma_f32_16x16x32_bf16 v[214:217], v[136:139], v[202:205], v[120:123]
	s_barrier
	s_nop 0
	ds_read_b128 v[120:123], v242 offset:16384
	ds_read_b128 v[132:135], v242 offset:17408
	ds_read_b128 v[136:139], v242 offset:18432
	ds_read_b128 v[140:143], v242 offset:19456
	ds_read_b128 v[144:147], v242 offset:20480
	ds_read_b128 v[148:151], v242 offset:21504
	ds_read_b128 v[190:193], v242 offset:22528
	ds_read_b128 v[194:197], v242 offset:23552
	s_waitcnt vmcnt(4)
	s_barrier
	s_waitcnt lgkmcnt(0)
	s_waitcnt lgkmcnt(0)
	v_mfma_f32_16x16x32_bf16 v[10:13], v[120:123], v[108:111], v[10:13]
	v_mfma_f32_16x16x32_bf16 v[22:25], v[190:193], v[108:111], v[22:25]
	v_mfma_f32_16x16x32_bf16 v[26:29], v[190:193], v[124:127], v[26:29]
	v_mfma_f32_16x16x32_bf16 v[10:13], v[132:135], v[116:119], v[10:13]
	v_mfma_f32_16x16x32_bf16 v[152:155], v[120:123], v[124:127], v[152:155]
	v_mfma_f32_16x16x32_bf16 v[156:159], v[136:139], v[108:111], v[156:159]
	v_mfma_f32_16x16x32_bf16 v[164:167], v[136:139], v[124:127], v[164:167]
	v_mfma_f32_16x16x32_bf16 v[182:185], v[144:147], v[108:111], v[182:185]
	v_mfma_f32_16x16x32_bf16 v[186:189], v[144:147], v[124:127], v[186:189]
	v_mfma_f32_16x16x32_bf16 v[22:25], v[194:197], v[116:119], v[22:25]
	v_mfma_f32_16x16x32_bf16 v[26:29], v[194:197], v[128:131], v[26:29]
	v_mfma_f32_16x16x32_bf16 v[152:155], v[132:135], v[128:131], v[152:155]
	v_mfma_f32_16x16x32_bf16 v[156:159], v[140:143], v[116:119], v[156:159]
	v_mfma_f32_16x16x32_bf16 v[164:167], v[140:143], v[128:131], v[164:167]
	v_mfma_f32_16x16x32_bf16 v[182:185], v[148:151], v[116:119], v[182:185]
	v_mfma_f32_16x16x32_bf16 v[186:189], v[148:151], v[128:131], v[186:189]
	v_mfma_f32_16x16x32_bf16 v[30:33], v[136:139], v[94:97], v[30:33]
	v_mfma_f32_16x16x32_bf16 v[6:9], v[120:123], v[94:97], v[6:9]
	v_mfma_f32_16x16x32_bf16 v[18:21], v[120:123], v[206:209], v[18:21]
	v_mfma_f32_16x16x32_bf16 v[118:121], v[140:143], v[202:205], v[30:33]
	v_mfma_f32_16x16x32_bf16 v[30:33], v[136:139], v[206:209], v[34:37]
	v_mfma_f32_16x16x32_bf16 v[138:141], v[140:143], v[210:213], v[30:33]
	v_mfma_f32_16x16x32_bf16 v[30:33], v[144:147], v[94:97], v[66:69]
	v_mfma_f32_16x16x32_bf16 v[198:201], v[148:151], v[202:205], v[30:33]
	v_mfma_f32_16x16x32_bf16 v[30:33], v[144:147], v[206:209], v[112:115]
	v_mfma_f32_16x16x32_bf16 v[142:145], v[148:151], v[210:213], v[30:33]
	v_mfma_f32_16x16x32_bf16 v[30:33], v[190:193], v[94:97], v[100:103]
	v_mfma_f32_16x16x32_bf16 v[6:9], v[132:135], v[202:205], v[6:9]
	v_mfma_f32_16x16x32_bf16 v[18:21], v[132:135], v[210:213], v[18:21]
	v_mfma_f32_16x16x32_bf16 v[98:101], v[194:197], v[202:205], v[30:33]
	v_mfma_f32_16x16x32_bf16 v[30:33], v[190:193], v[206:209], v[104:107]
	v_mfma_f32_16x16x32_bf16 v[146:149], v[194:197], v[210:213], v[30:33]
	s_barrier
	s_nop 4
	s_nop 0
	ds_read_b128 v[30:33], v160
	ds_read_b128 v[34:37], v161
	ds_read_b128 v[190:193], v238
	ds_read_b128 v[194:197], v239
	ds_read_b128 v[66:69], v242 offset:32768
	ds_read_b128 v[94:97], v242 offset:33792
	ds_read_b128 v[202:205], v242 offset:34816
	ds_read_b128 v[206:209], v242 offset:35840
	ds_read_b128 v[210:213], v242 offset:36864
	ds_read_b128 v[218:221], v242 offset:37888
	ds_read_b128 v[222:225], v242 offset:38912
	ds_read_b128 v[226:229], v242 offset:39936
	s_waitcnt vmcnt(2)
	s_barrier
; #define G_LDA(dst, b, h)                                                                                                  \
;   _Pragma("unroll") for (int m = 0; m < 4; ++m) _Pragma("unroll") for (int k = 0; k < 2; ++k)                             \
;       dst[m][k] = *(const bf16x8*)((const char*)G_SA(b, h) + ((wr * 4 + m) * 2 + k) * 1024 + rdo)
; #define G_LDB(dst, b, h)                                                                                                  \
;   _Pragma("unroll") for (int n = 0; n < 2; ++n) _Pragma("unroll") for (int k = 0; k < 2; ++k)                             \
;       dst[n][k] = *(const bf16x8*)((const char*)G_SB(b, h) + ((wc * 2 + n) * 2 + k) * 1024 + rdo)
; #define G_WAIT_V(n) asm volatile("s_waitcnt vmcnt(" #n ")" ::: "memory")
; #define G_WAIT_L(n) asm volatile("s_waitcnt lgkmcnt(" #n ")" ::: "memory")
; #define G_BAR __builtin_amdgcn_s_barrier()
;     ...
;     G_LDB(B0, 1, 0); G_LDA(At, 1, 0); G_WAIT_V(2); G_BAR; G_WAIT_L(0); G_MMA(0, 0, At, B0); G_BAR;
;     G_LDB(B1, 1, 1); G_WAIT_V(0); G_BAR; G_WAIT_L(0); G_MMA(0, 1, At, B1); G_BAR;
;     G_LDA(At, 1, 1); G_BAR; G_WAIT_L(0); G_MMA(1, 0, At, B0); G_MMA(1, 1, At, B1); G_BAR;
;   }
;   if (wr == 0) G_BAR;
	s_waitcnt lgkmcnt(0)
	s_waitcnt lgkmcnt(0)
	v_mfma_f32_16x16x32_bf16 v[2:5], v[66:69], v[30:33], v[2:5]
	v_mfma_f32_16x16x32_bf16 v[126:129], v[94:97], v[34:37], v[2:5]
	v_mfma_f32_16x16x32_bf16 v[2:5], v[66:69], v[190:193], v[14:17]
	v_mfma_f32_16x16x32_bf16 v[134:137], v[94:97], v[194:197], v[2:5]
	v_mfma_f32_16x16x32_bf16 v[2:5], v[202:205], v[30:33], v[70:73]
	v_mfma_f32_16x16x32_bf16 v[122:125], v[206:209], v[34:37], v[2:5]
	v_mfma_f32_16x16x32_bf16 v[2:5], v[202:205], v[190:193], v[74:77]
	v_mfma_f32_16x16x32_bf16 v[130:133], v[206:209], v[194:197], v[2:5]
	v_mfma_f32_16x16x32_bf16 v[2:5], v[210:213], v[30:33], v[78:81]
	v_mfma_f32_16x16x32_bf16 v[110:113], v[218:221], v[34:37], v[2:5]
	v_mfma_f32_16x16x32_bf16 v[2:5], v[210:213], v[190:193], v[82:85]
	v_mfma_f32_16x16x32_bf16 v[114:117], v[218:221], v[194:197], v[2:5]
	v_mfma_f32_16x16x32_bf16 v[2:5], v[222:225], v[30:33], v[86:89]
	v_mfma_f32_16x16x32_bf16 v[102:105], v[226:229], v[34:37], v[2:5]
	v_mfma_f32_16x16x32_bf16 v[2:5], v[222:225], v[190:193], v[90:93]
	v_mfma_f32_16x16x32_bf16 v[106:109], v[226:229], v[194:197], v[2:5]
	s_barrier
	s_nop 4
	s_nop 0
	ds_read_b128 v[2:5], v240
	ds_read_b128 v[230:233], v241
	ds_read_b128 v[234:237], v243
	ds_read_b128 v[238:241], v162
	s_waitcnt vmcnt(0)
	s_barrier
	s_waitcnt lgkmcnt(0)
	s_waitcnt lgkmcnt(0)
	v_mfma_f32_16x16x32_bf16 v[14:17], v[66:69], v[2:5], v[214:217]
	v_mfma_f32_16x16x32_bf16 v[86:89], v[94:97], v[230:233], v[14:17]
	v_mfma_f32_16x16x32_bf16 v[14:17], v[66:69], v[234:237], v[38:41]
	v_mfma_f32_16x16x32_bf16 v[94:97], v[94:97], v[238:241], v[14:17]
	v_mfma_f32_16x16x32_bf16 v[14:17], v[202:205], v[2:5], v[42:45]
	v_mfma_f32_16x16x32_bf16 v[82:85], v[206:209], v[230:233], v[14:17]
	v_mfma_f32_16x16x32_bf16 v[14:17], v[202:205], v[234:237], v[46:49]
	v_mfma_f32_16x16x32_bf16 v[90:93], v[206:209], v[238:241], v[14:17]
	v_mfma_f32_16x16x32_bf16 v[14:17], v[210:213], v[2:5], v[50:53]
	v_mfma_f32_16x16x32_bf16 v[74:77], v[218:221], v[230:233], v[14:17]
	v_mfma_f32_16x16x32_bf16 v[14:17], v[210:213], v[234:237], v[54:57]
	v_mfma_f32_16x16x32_bf16 v[78:81], v[218:221], v[238:241], v[14:17]
	v_mfma_f32_16x16x32_bf16 v[14:17], v[222:225], v[2:5], v[58:61]
	v_mfma_f32_16x16x32_bf16 v[66:69], v[226:229], v[230:233], v[14:17]
	v_mfma_f32_16x16x32_bf16 v[14:17], v[222:225], v[234:237], v[62:65]
	v_mfma_f32_16x16x32_bf16 v[70:73], v[226:229], v[238:241], v[14:17]
	s_barrier
	s_nop 4
	s_nop 0
	ds_read_b128 v[14:17], v242 offset:49152
	ds_read_b128 v[202:205], v242 offset:50176
	ds_read_b128 v[206:209], v242 offset:51200
	ds_read_b128 v[210:213], v242 offset:52224
	ds_read_b128 v[214:217], v242 offset:53248
	ds_read_b128 v[218:221], v242 offset:54272
	ds_read_b128 v[222:225], v242 offset:55296
	ds_read_b128 v[226:229], v242 offset:56320
	s_barrier
	s_waitcnt lgkmcnt(0)
	s_waitcnt lgkmcnt(0)
	v_mfma_f32_16x16x32_bf16 v[10:13], v[14:17], v[30:33], v[10:13]
	v_mfma_f32_16x16x32_bf16 v[54:57], v[202:205], v[34:37], v[10:13]
	v_mfma_f32_16x16x32_bf16 v[10:13], v[14:17], v[190:193], v[152:155]
	v_mfma_f32_16x16x32_bf16 v[62:65], v[202:205], v[194:197], v[10:13]
	v_mfma_f32_16x16x32_bf16 v[10:13], v[206:209], v[30:33], v[156:159]
	v_mfma_f32_16x16x32_bf16 v[50:53], v[210:213], v[34:37], v[10:13]
	v_mfma_f32_16x16x32_bf16 v[10:13], v[206:209], v[190:193], v[164:167]
	v_mfma_f32_16x16x32_bf16 v[58:61], v[210:213], v[194:197], v[10:13]
	v_mfma_f32_16x16x32_bf16 v[10:13], v[214:217], v[30:33], v[182:185]
	v_mfma_f32_16x16x32_bf16 v[42:45], v[218:221], v[34:37], v[10:13]
	v_mfma_f32_16x16x32_bf16 v[10:13], v[214:217], v[190:193], v[186:189]
	v_mfma_f32_16x16x32_bf16 v[46:49], v[218:221], v[194:197], v[10:13]
	v_mfma_f32_16x16x32_bf16 v[10:13], v[222:225], v[30:33], v[22:25]
	v_mfma_f32_16x16x32_bf16 v[34:37], v[226:229], v[34:37], v[10:13]
	v_mfma_f32_16x16x32_bf16 v[10:13], v[222:225], v[190:193], v[26:29]
	v_mfma_f32_16x16x32_bf16 v[38:41], v[226:229], v[194:197], v[10:13]
	v_mfma_f32_16x16x32_bf16 v[6:9], v[14:17], v[2:5], v[6:9]
	v_mfma_f32_16x16x32_bf16 v[22:25], v[202:205], v[230:233], v[6:9]
	v_mfma_f32_16x16x32_bf16 v[6:9], v[14:17], v[234:237], v[18:21]
	v_mfma_f32_16x16x32_bf16 v[30:33], v[202:205], v[238:241], v[6:9]
	v_mfma_f32_16x16x32_bf16 v[6:9], v[206:209], v[2:5], v[118:121]
	v_mfma_f32_16x16x32_bf16 v[18:21], v[210:213], v[230:233], v[6:9]
	v_mfma_f32_16x16x32_bf16 v[6:9], v[206:209], v[234:237], v[138:141]
	v_mfma_f32_16x16x32_bf16 v[26:29], v[210:213], v[238:241], v[6:9]
	v_mfma_f32_16x16x32_bf16 v[6:9], v[214:217], v[2:5], v[198:201]
	v_mfma_f32_16x16x32_bf16 v[10:13], v[218:221], v[230:233], v[6:9]
	v_mfma_f32_16x16x32_bf16 v[6:9], v[214:217], v[234:237], v[142:145]
	v_mfma_f32_16x16x32_bf16 v[14:17], v[218:221], v[238:241], v[6:9]
	v_mfma_f32_16x16x32_bf16 v[2:5], v[222:225], v[2:5], v[98:101]
	v_mfma_f32_16x16x32_bf16 v[6:9], v[222:225], v[234:237], v[146:149]
	v_mfma_f32_16x16x32_bf16 v[2:5], v[226:229], v[230:233], v[2:5]
	v_mfma_f32_16x16x32_bf16 v[6:9], v[226:229], v[238:241], v[6:9]
	v_cmp_gt_u32_e32 vcc, s67, v0
	s_barrier
	s_and_saveexec_b64 s[16:17], vcc
	s_cbranch_execz .LBB0_214
	s_barrier
	s_branch .LBB0_214

; #define GM_LOAD(RA, RB, KT)                                                                 \
;   _Pragma("unroll") for (int i = 0; i < 4; ++i) {                                           \
;     RA[i] = *(const u32x4*)(ag + (size_t)(32 * i) * lda + (KT) * 64);                       \
;     RB[i] = *(const u32x4*)(bg + (size_t)(32 * i) * ldb + (KT) * 64);                       \
;   }
; template <bool DEEP = true>
; DI void gemm_main(f32x4 (&acc)[4][4], const u16* __restrict__ A, int lda, const u16* __restrict__ B, int ldb, int K, u16* lds) {
;     ...
;   if (DEEP) {
;     u32x4 ra0[4], rb0[4], ra1[4], rb1[4];
;     GM_LOAD(ra0, rb0, 0)
;     GM_LOAD(ra1, rb1, 1)
;     __syncthreads();
;     GM_STORE(ra0, rb0, 0)
;     __syncthreads();
;     for (int kt = 0; kt < nk; kt += 2) {
;       if (kt + 2 < nk) { GM_LOAD(ra0, rb0, kt + 2) }
;       GM_COMPUTE(0)
.LBB0_265:
	s_and_b32 s14, s20, 0xffffff80
	v_mov_b32_e32 v82, v169
	s_ashr_i32 s15, s14, 31
	v_mov_b32_e32 v83, v169
	s_and_b32 s21, s19, 0x80
	s_lshl_b64 s[0:1], s[14:15], 9
	s_add_u32 s0, s12, s0
	v_ashrrev_i32_e32 v34, 3, v83
	v_ashrrev_i32_e32 v35, 31, v34
	s_addc_u32 s1, s13, s1
	s_lshl_b32 s15, s21, 9
	v_lshlrev_b64 v[2:3], 9, v[34:35]
	v_lshlrev_b32_e32 v0, 4, v83
	s_add_u32 s22, s17, s15
	v_lshl_add_u64 v[4:5], s[0:1], 0, v[2:3]
	v_and_b32_e32 v0, 0x70, v0
	s_addc_u32 s23, s18, 0
	v_lshl_add_u64 v[66:67], v[4:5], 0, v[0:1]
	v_lshl_add_u64 v[2:3], s[22:23], 0, v[2:3]
	v_add_co_u32_e32 v70, vcc, s35, v66
	v_lshl_add_u64 v[68:69], v[2:3], 0, v[0:1]
	s_nop 0
	v_addc_co_u32_e32 v71, vcc, 0, v67, vcc
	v_add_co_u32_e32 v72, vcc, s35, v68
	global_load_dwordx4 v[2:5], v[66:67], off
	global_load_dwordx4 v[6:9], v[68:69], off
	v_addc_co_u32_e32 v73, vcc, 0, v69, vcc
	v_add_co_u32_e32 v74, vcc, s37, v66
	global_load_dwordx4 v[10:13], v[70:71], off
	s_nop 0
	v_addc_co_u32_e32 v75, vcc, 0, v67, vcc
	v_add_co_u32_e32 v76, vcc, s37, v68
	global_load_dwordx4 v[18:21], v[74:75], off
	s_nop 0
	v_addc_co_u32_e32 v77, vcc, 0, v69, vcc
	v_add_co_u32_e32 v78, vcc, s40, v66
	global_load_dwordx4 v[14:17], v[72:73], off
	s_nop 0
	v_addc_co_u32_e32 v79, vcc, 0, v67, vcc
	global_load_dwordx4 v[26:29], v[78:79], off
	v_add_co_u32_e32 v80, vcc, s40, v68
	global_load_dwordx4 v[22:25], v[76:77], off
	s_nop 0
	v_addc_co_u32_e32 v81, vcc, 0, v69, vcc
	global_load_dwordx4 v[30:33], v[80:81], off
	v_xor_b32_e32 v0, v34, v83
	v_lshlrev_b32_e32 v0, 4, v0
	v_lshlrev_b32_e32 v34, 7, v34
	v_and_b32_e32 v0, 0x70, v0
	v_add3_u32 v85, s33, v0, v34
	global_load_dwordx4 v[46:49], v[66:67], off offset:128
	global_load_dwordx4 v[42:45], v[70:71], off offset:128
	global_load_dwordx4 v[38:41], v[74:75], off offset:128
	global_load_dwordx4 v[34:37], v[78:79], off offset:128
	global_load_dwordx4 v[62:65], v[68:69], off offset:128
	global_load_dwordx4 v[58:61], v[72:73], off offset:128
	global_load_dwordx4 v[54:57], v[76:77], off offset:128
	global_load_dwordx4 v[50:53], v[80:81], off offset:128
	s_barrier
	v_and_b32_e32 v84, 15, v83
	v_lshrrev_b32_e32 v86, 1, v83
	v_and_or_b32 v84, v86, s41, v84
	v_lshrrev_b32_e32 v0, 4, v83
	v_bfe_u32 v87, v83, 4, 2
	v_lshl_add_u32 v88, v84, 7, s33
	v_lshlrev_b32_e32 v84, 7, v83
	v_and_b32_e32 v83, 7, v83
	v_and_b32_e32 v84, 0x2780, v84
	v_bitop3_b32 v0, v0, v83, 3 bitop3:0x6c
	v_add_u32_e32 v89, s33, v84
	v_lshlrev_b32_e32 v0, 4, v0
	v_add_u32_e32 v86, v88, v0
	v_add_u32_e32 v84, v89, v0
	v_bitop3_b32 v0, v87, v83, 4 bitop3:0x36
	v_lshlrev_b32_e32 v0, 4, v0
	v_add_u32_e32 v83, v88, v0
	v_add_u32_e32 v0, v89, v0
	s_waitcnt vmcnt(15)
	ds_write_b128 v85, v[2:5]
	s_waitcnt vmcnt(13)
	ds_write_b128 v85, v[10:13] offset:4096
	s_waitcnt vmcnt(12)
	ds_write_b128 v85, v[18:21] offset:8192
	s_waitcnt vmcnt(10)
	ds_write_b128 v85, v[26:29] offset:12288
	ds_write_b128 v85, v[6:9] offset:16384
	ds_write_b128 v85, v[14:17] offset:20480
	s_waitcnt vmcnt(9)
	ds_write_b128 v85, v[22:25] offset:24576
	s_waitcnt vmcnt(8)
	ds_write_b128 v85, v[30:33] offset:28672
	s_waitcnt lgkmcnt(0)
	s_barrier
	global_load_dwordx4 v[2:5], v[66:67], off offset:256
	global_load_dwordx4 v[6:9], v[68:69], off offset:256
	global_load_dwordx4 v[10:13], v[70:71], off offset:256
	global_load_dwordx4 v[14:17], v[72:73], off offset:256
	global_load_dwordx4 v[18:21], v[74:75], off offset:256
	global_load_dwordx4 v[22:25], v[76:77], off offset:256
	global_load_dwordx4 v[26:29], v[78:79], off offset:256
	global_load_dwordx4 v[30:33], v[80:81], off offset:256
	ds_read_b128 v[88:91], v86
	ds_read_b128 v[92:95], v86 offset:2048
	ds_read_b128 v[96:99], v86 offset:4096
	ds_read_b128 v[100:103], v86 offset:6144
	ds_read_b128 v[104:107], v84 offset:16384
	ds_read_b128 v[120:123], v84 offset:18432
	ds_read_b128 v[136:139], v84 offset:20480
	ds_read_b128 v[152:155], v84 offset:22528
	s_waitcnt lgkmcnt(3)
	v_mfma_f32_16x16x32_bf16 v[108:111], v[88:91], v[104:107], 0
	v_mfma_f32_16x16x32_bf16 v[112:115], v[92:95], v[104:107], 0
	v_mfma_f32_16x16x32_bf16 v[116:119], v[96:99], v[104:107], 0
	v_mfma_f32_16x16x32_bf16 v[104:107], v[100:103], v[104:107], 0
	s_waitcnt lgkmcnt(2)
	v_mfma_f32_16x16x32_bf16 v[124:127], v[88:91], v[120:123], 0
	v_mfma_f32_16x16x32_bf16 v[128:131], v[92:95], v[120:123], 0
	v_mfma_f32_16x16x32_bf16 v[132:135], v[96:99], v[120:123], 0
	v_mfma_f32_16x16x32_bf16 v[120:123], v[100:103], v[120:123], 0
	s_waitcnt lgkmcnt(1)
	v_mfma_f32_16x16x32_bf16 v[140:143], v[88:91], v[136:139], 0
	v_mfma_f32_16x16x32_bf16 v[144:147], v[92:95], v[136:139], 0
	v_mfma_f32_16x16x32_bf16 v[148:151], v[96:99], v[136:139], 0
	v_mfma_f32_16x16x32_bf16 v[136:139], v[100:103], v[136:139], 0
	s_waitcnt lgkmcnt(0)
	v_mfma_f32_16x16x32_bf16 v[88:91], v[88:91], v[152:155], 0
	v_mfma_f32_16x16x32_bf16 v[92:95], v[92:95], v[152:155], 0
	v_mfma_f32_16x16x32_bf16 v[96:99], v[96:99], v[152:155], 0
	v_mfma_f32_16x16x32_bf16 v[100:103], v[100:103], v[152:155], 0
	ds_read_b128 v[152:155], v83
	ds_read_b128 v[156:159], v83 offset:2048
	ds_read_b128 v[164:167], v83 offset:4096
	ds_read_b128 v[182:185], v83 offset:6144
	ds_read_b128 v[186:189], v0 offset:16384
	s_waitcnt lgkmcnt(0)
	v_mfma_f32_16x16x32_bf16 v[108:111], v[152:155], v[186:189], v[108:111]
	v_mfma_f32_16x16x32_bf16 v[112:115], v[156:159], v[186:189], v[112:115]
	v_mfma_f32_16x16x32_bf16 v[116:119], v[164:167], v[186:189], v[116:119]
	v_mfma_f32_16x16x32_bf16 v[104:107], v[182:185], v[186:189], v[104:107]
	ds_read_b128 v[186:189], v0 offset:18432
	s_waitcnt lgkmcnt(0)
	v_mfma_f32_16x16x32_bf16 v[124:127], v[152:155], v[186:189], v[124:127]
	v_mfma_f32_16x16x32_bf16 v[128:131], v[156:159], v[186:189], v[128:131]
	v_mfma_f32_16x16x32_bf16 v[132:135], v[164:167], v[186:189], v[132:135]
	v_mfma_f32_16x16x32_bf16 v[120:123], v[182:185], v[186:189], v[120:123]
	ds_read_b128 v[186:189], v0 offset:20480
	s_waitcnt lgkmcnt(0)
	v_mfma_f32_16x16x32_bf16 v[140:143], v[152:155], v[186:189], v[140:143]
	v_mfma_f32_16x16x32_bf16 v[144:147], v[156:159], v[186:189], v[144:147]
	v_mfma_f32_16x16x32_bf16 v[148:151], v[164:167], v[186:189], v[148:151]
	v_mfma_f32_16x16x32_bf16 v[136:139], v[182:185], v[186:189], v[136:139]
	ds_read_b128 v[186:189], v0 offset:22528
	s_waitcnt lgkmcnt(0)
	v_mfma_f32_16x16x32_bf16 v[88:91], v[152:155], v[186:189], v[88:91]
	v_mfma_f32_16x16x32_bf16 v[92:95], v[156:159], v[186:189], v[92:95]
	v_mfma_f32_16x16x32_bf16 v[96:99], v[164:167], v[186:189], v[96:99]
	v_mfma_f32_16x16x32_bf16 v[100:103], v[182:185], v[186:189], v[100:103]
	s_waitcnt vmcnt(15)
	ds_write_b128 v85, v[46:49] offset:32768
	s_waitcnt vmcnt(11)
	ds_write_b128 v85, v[62:65] offset:49152
	ds_write_b128 v85, v[42:45] offset:36864
	s_waitcnt vmcnt(10)
	ds_write_b128 v85, v[58:61] offset:53248
	ds_write_b128 v85, v[38:41] offset:40960
	s_waitcnt vmcnt(9)
	ds_write_b128 v85, v[54:57] offset:57344
	ds_write_b128 v85, v[34:37] offset:45056
	s_waitcnt vmcnt(8)
	ds_write_b128 v85, v[50:53] offset:61440
	s_waitcnt lgkmcnt(0)
	s_barrier
; #define GM_LOAD(RA, RB, KT)                                                                 \
;   _Pragma("unroll") for (int i = 0; i < 4; ++i) {                                           \
;     RA[i] = *(const u32x4*)(ag + (size_t)(32 * i) * lda + (KT) * 64);                       \
;     RB[i] = *(const u32x4*)(bg + (size_t)(32 * i) * ldb + (KT) * 64);                       \
;   }
; template <bool DEEP = true>
; DI void gemm_main(f32x4 (&acc)[4][4], const u16* __restrict__ A, int lda, const u16* __restrict__ B, int ldb, int K, u16* lds) {
;     ...
;     for (int kt = 0; kt < nk; kt += 2) {
;       if (kt + 2 < nk) { GM_LOAD(ra0, rb0, kt + 2) }
;       GM_COMPUTE(0)
;       __builtin_amdgcn_sched_barrier(0);
;       GM_STORE(ra1, rb1, 1)
;       __syncthreads();
;       if (kt + 3 < nk) { GM_LOAD(ra1, rb1, kt + 3) }
;       GM_COMPUTE(1)
;       __builtin_amdgcn_sched_barrier(0);
;       if (kt + 2 < nk) { GM_STORE(ra0, rb0, 0) }
	global_load_dwordx4 v[34:37], v[66:67], off offset:384
	global_load_dwordx4 v[38:41], v[68:69], off offset:384
	global_load_dwordx4 v[42:45], v[70:71], off offset:384
	global_load_dwordx4 v[46:49], v[72:73], off offset:384
	global_load_dwordx4 v[50:53], v[74:75], off offset:384
	global_load_dwordx4 v[54:57], v[76:77], off offset:384
	global_load_dwordx4 v[58:61], v[78:79], off offset:384
	global_load_dwordx4 v[62:65], v[80:81], off offset:384
	ds_read_b128 v[66:69], v86 offset:32768
	ds_read_b128 v[70:73], v86 offset:34816
	ds_read_b128 v[74:77], v86 offset:36864
	ds_read_b128 v[78:81], v86 offset:38912
	ds_read_b128 v[152:155], v84 offset:49152
	s_waitcnt lgkmcnt(0)
	v_mfma_f32_16x16x32_bf16 v[108:111], v[66:69], v[152:155], v[108:111]
	v_mfma_f32_16x16x32_bf16 v[112:115], v[70:73], v[152:155], v[112:115]
	v_mfma_f32_16x16x32_bf16 v[116:119], v[74:77], v[152:155], v[116:119]
	v_mfma_f32_16x16x32_bf16 v[104:107], v[78:81], v[152:155], v[104:107]
	ds_read_b128 v[152:155], v84 offset:51200
	s_waitcnt lgkmcnt(0)
	v_mfma_f32_16x16x32_bf16 v[124:127], v[66:69], v[152:155], v[124:127]
	v_mfma_f32_16x16x32_bf16 v[128:131], v[70:73], v[152:155], v[128:131]
	v_mfma_f32_16x16x32_bf16 v[132:135], v[74:77], v[152:155], v[132:135]
	v_mfma_f32_16x16x32_bf16 v[120:123], v[78:81], v[152:155], v[120:123]
	ds_read_b128 v[152:155], v84 offset:53248
	s_waitcnt lgkmcnt(0)
	v_mfma_f32_16x16x32_bf16 v[140:143], v[66:69], v[152:155], v[140:143]
	v_mfma_f32_16x16x32_bf16 v[144:147], v[70:73], v[152:155], v[144:147]
	v_mfma_f32_16x16x32_bf16 v[148:151], v[74:77], v[152:155], v[148:151]
	v_mfma_f32_16x16x32_bf16 v[136:139], v[78:81], v[152:155], v[136:139]
	ds_read_b128 v[152:155], v84 offset:55296
	s_waitcnt lgkmcnt(0)
	v_mfma_f32_16x16x32_bf16 v[66:69], v[66:69], v[152:155], v[88:91]
	v_mfma_f32_16x16x32_bf16 v[70:73], v[70:73], v[152:155], v[92:95]
	v_mfma_f32_16x16x32_bf16 v[74:77], v[74:77], v[152:155], v[96:99]
	v_mfma_f32_16x16x32_bf16 v[78:81], v[78:81], v[152:155], v[100:103]
	ds_read_b128 v[88:91], v83 offset:32768
	ds_read_b128 v[92:95], v83 offset:34816
	ds_read_b128 v[96:99], v83 offset:36864
	ds_read_b128 v[100:103], v83 offset:38912
	ds_read_b128 v[152:155], v0 offset:49152
	s_waitcnt lgkmcnt(0)
	v_mfma_f32_16x16x32_bf16 v[108:111], v[88:91], v[152:155], v[108:111]
	v_mfma_f32_16x16x32_bf16 v[112:115], v[92:95], v[152:155], v[112:115]
	v_mfma_f32_16x16x32_bf16 v[116:119], v[96:99], v[152:155], v[116:119]
	v_mfma_f32_16x16x32_bf16 v[104:107], v[100:103], v[152:155], v[104:107]
	ds_read_b128 v[152:155], v0 offset:51200
	s_waitcnt lgkmcnt(0)
	v_mfma_f32_16x16x32_bf16 v[124:127], v[88:91], v[152:155], v[124:127]
	v_mfma_f32_16x16x32_bf16 v[128:131], v[92:95], v[152:155], v[128:131]
	v_mfma_f32_16x16x32_bf16 v[132:135], v[96:99], v[152:155], v[132:135]
	v_mfma_f32_16x16x32_bf16 v[120:123], v[100:103], v[152:155], v[120:123]
	ds_read_b128 v[152:155], v0 offset:53248
	s_waitcnt lgkmcnt(0)
	v_mfma_f32_16x16x32_bf16 v[140:143], v[88:91], v[152:155], v[140:143]
	v_mfma_f32_16x16x32_bf16 v[144:147], v[92:95], v[152:155], v[144:147]
	v_mfma_f32_16x16x32_bf16 v[148:151], v[96:99], v[152:155], v[148:151]
	v_mfma_f32_16x16x32_bf16 v[136:139], v[100:103], v[152:155], v[136:139]
	ds_read_b128 v[152:155], v0 offset:55296
	s_waitcnt lgkmcnt(0)
	v_mfma_f32_16x16x32_bf16 v[66:69], v[88:91], v[152:155], v[66:69]
	v_mfma_f32_16x16x32_bf16 v[70:73], v[92:95], v[152:155], v[70:73]
	v_mfma_f32_16x16x32_bf16 v[74:77], v[96:99], v[152:155], v[74:77]
	v_mfma_f32_16x16x32_bf16 v[78:81], v[100:103], v[152:155], v[78:81]
	s_waitcnt vmcnt(15)
	ds_write_b128 v85, v[2:5]
	s_waitcnt vmcnt(14)
	ds_write_b128 v85, v[6:9] offset:16384
	s_waitcnt vmcnt(13)
	ds_write_b128 v85, v[10:13] offset:4096
	s_waitcnt vmcnt(12)
	ds_write_b128 v85, v[14:17] offset:20480
	s_waitcnt vmcnt(11)
	ds_write_b128 v85, v[18:21] offset:8192
	s_waitcnt vmcnt(10)
	ds_write_b128 v85, v[22:25] offset:24576
	s_waitcnt vmcnt(9)
	ds_write_b128 v85, v[26:29] offset:12288
	s_waitcnt vmcnt(8)
	ds_write_b128 v85, v[30:33] offset:28672
	s_waitcnt lgkmcnt(0)
	s_barrier
	ds_read_b128 v[2:5], v86
	ds_read_b128 v[6:9], v86 offset:2048
	ds_read_b128 v[10:13], v86 offset:4096
	ds_read_b128 v[14:17], v86 offset:6144
	ds_read_b128 v[18:21], v84 offset:16384
	ds_read_b128 v[88:91], v84 offset:18432
	s_waitcnt lgkmcnt(1)
	v_mfma_f32_16x16x32_bf16 v[22:25], v[2:5], v[18:21], v[108:111]
	v_mfma_f32_16x16x32_bf16 v[26:29], v[6:9], v[18:21], v[112:115]
	v_mfma_f32_16x16x32_bf16 v[30:33], v[10:13], v[18:21], v[116:119]
	v_mfma_f32_16x16x32_bf16 v[18:21], v[14:17], v[18:21], v[104:107]
	s_nop 2
	ds_read_b128 v[104:107], v84 offset:20480
	s_waitcnt lgkmcnt(1)
	v_mfma_f32_16x16x32_bf16 v[92:95], v[2:5], v[88:91], v[124:127]
	v_mfma_f32_16x16x32_bf16 v[96:99], v[6:9], v[88:91], v[128:131]
	v_mfma_f32_16x16x32_bf16 v[100:103], v[10:13], v[88:91], v[132:135]
	v_mfma_f32_16x16x32_bf16 v[88:91], v[14:17], v[88:91], v[120:123]
	s_nop 2
	ds_read_b128 v[120:123], v84 offset:22528
	s_waitcnt lgkmcnt(1)
	v_mfma_f32_16x16x32_bf16 v[108:111], v[2:5], v[104:107], v[140:143]
	v_mfma_f32_16x16x32_bf16 v[112:115], v[6:9], v[104:107], v[144:147]
	v_mfma_f32_16x16x32_bf16 v[116:119], v[10:13], v[104:107], v[148:151]
	v_mfma_f32_16x16x32_bf16 v[104:107], v[14:17], v[104:107], v[136:139]
	s_waitcnt lgkmcnt(0)
	v_mfma_f32_16x16x32_bf16 v[2:5], v[2:5], v[120:123], v[66:69]
	v_mfma_f32_16x16x32_bf16 v[6:9], v[6:9], v[120:123], v[70:73]
	v_mfma_f32_16x16x32_bf16 v[10:13], v[10:13], v[120:123], v[74:77]
	v_mfma_f32_16x16x32_bf16 v[14:17], v[14:17], v[120:123], v[78:81]
	ds_read_b128 v[66:69], v83
	ds_read_b128 v[70:73], v83 offset:2048
	ds_read_b128 v[74:77], v83 offset:4096
	ds_read_b128 v[78:81], v83 offset:6144
	ds_read_b128 v[120:123], v0 offset:16384
	s_waitcnt lgkmcnt(0)
; #define GM_LOAD(RA, RB, KT)                                                                 \
;   _Pragma("unroll") for (int i = 0; i < 4; ++i) {                                           \
;     RA[i] = *(const u32x4*)(ag + (size_t)(32 * i) * lda + (KT) * 64);                       \
;     RB[i] = *(const u32x4*)(bg + (size_t)(32 * i) * ldb + (KT) * 64);                       \
;   }
; template <bool DEEP = true>
; DI void gemm_main(f32x4 (&acc)[4][4], const u16* __restrict__ A, int lda, const u16* __restrict__ B, int ldb, int K, u16* lds) {
;     ...
;     for (int kt = 0; kt < nk; kt += 2) {
;       if (kt + 2 < nk) { GM_LOAD(ra0, rb0, kt + 2) }
;       GM_COMPUTE(0)
;       __builtin_amdgcn_sched_barrier(0);
;       GM_STORE(ra1, rb1, 1)
;       __syncthreads();
;       if (kt + 3 < nk) { GM_LOAD(ra1, rb1, kt + 3) }
;       GM_COMPUTE(1)
;       __builtin_amdgcn_sched_barrier(0);
;       if (kt + 2 < nk) { GM_STORE(ra0, rb0, 0) }
;       __syncthreads();
	v_mfma_f32_16x16x32_bf16 v[22:25], v[66:69], v[120:123], v[22:25]
	v_mfma_f32_16x16x32_bf16 v[26:29], v[70:73], v[120:123], v[26:29]
	v_mfma_f32_16x16x32_bf16 v[30:33], v[74:77], v[120:123], v[30:33]
	v_mfma_f32_16x16x32_bf16 v[18:21], v[78:81], v[120:123], v[18:21]
	ds_read_b128 v[120:123], v0 offset:18432
	s_waitcnt lgkmcnt(0)
	v_mfma_f32_16x16x32_bf16 v[92:95], v[66:69], v[120:123], v[92:95]
	v_mfma_f32_16x16x32_bf16 v[96:99], v[70:73], v[120:123], v[96:99]
	v_mfma_f32_16x16x32_bf16 v[100:103], v[74:77], v[120:123], v[100:103]
	v_mfma_f32_16x16x32_bf16 v[88:91], v[78:81], v[120:123], v[88:91]
	ds_read_b128 v[120:123], v0 offset:20480
	s_waitcnt lgkmcnt(0)
	v_mfma_f32_16x16x32_bf16 v[108:111], v[66:69], v[120:123], v[108:111]
	v_mfma_f32_16x16x32_bf16 v[112:115], v[70:73], v[120:123], v[112:115]
	v_mfma_f32_16x16x32_bf16 v[116:119], v[74:77], v[120:123], v[116:119]
	v_mfma_f32_16x16x32_bf16 v[104:107], v[78:81], v[120:123], v[104:107]
	ds_read_b128 v[120:123], v0 offset:22528
	s_waitcnt lgkmcnt(0)
	v_mfma_f32_16x16x32_bf16 v[2:5], v[66:69], v[120:123], v[2:5]
	v_mfma_f32_16x16x32_bf16 v[6:9], v[70:73], v[120:123], v[6:9]
	v_mfma_f32_16x16x32_bf16 v[10:13], v[74:77], v[120:123], v[10:13]
	v_mfma_f32_16x16x32_bf16 v[14:17], v[78:81], v[120:123], v[14:17]
	s_waitcnt vmcnt(7)
	ds_write_b128 v85, v[34:37] offset:32768
	s_waitcnt vmcnt(6)
	ds_write_b128 v85, v[38:41] offset:49152
	s_waitcnt vmcnt(5)
	ds_write_b128 v85, v[42:45] offset:36864
	s_waitcnt vmcnt(4)
	ds_write_b128 v85, v[46:49] offset:53248
	s_waitcnt vmcnt(3)
	ds_write_b128 v85, v[50:53] offset:40960
	s_waitcnt vmcnt(2)
	ds_write_b128 v85, v[54:57] offset:57344
	s_waitcnt vmcnt(1)
	ds_write_b128 v85, v[58:61] offset:45056
	s_waitcnt vmcnt(0)
	ds_write_b128 v85, v[62:65] offset:61440
	s_waitcnt lgkmcnt(0)
	s_barrier
	ds_read_b128 v[34:37], v86 offset:32768
	ds_read_b128 v[38:41], v86 offset:34816
	ds_read_b128 v[42:45], v86 offset:36864
	ds_read_b128 v[46:49], v86 offset:38912
	ds_read_b128 v[50:53], v84 offset:49152
	s_waitcnt lgkmcnt(0)
	v_mfma_f32_16x16x32_bf16 v[22:25], v[34:37], v[50:53], v[22:25]
	ds_read_b128 v[66:69], v84 offset:53248
	v_mfma_f32_16x16x32_bf16 v[26:29], v[38:41], v[50:53], v[26:29]
	v_mfma_f32_16x16x32_bf16 v[30:33], v[42:45], v[50:53], v[30:33]
	v_mfma_f32_16x16x32_bf16 v[18:21], v[46:49], v[50:53], v[18:21]
	ds_read_b128 v[50:53], v84 offset:51200
	ds_read_b128 v[84:87], v84 offset:55296
	s_waitcnt lgkmcnt(1)
	v_mfma_f32_16x16x32_bf16 v[54:57], v[34:37], v[50:53], v[92:95]
	v_mfma_f32_16x16x32_bf16 v[58:61], v[38:41], v[50:53], v[96:99]
	v_mfma_f32_16x16x32_bf16 v[62:65], v[42:45], v[50:53], v[100:103]
	v_mfma_f32_16x16x32_bf16 v[50:53], v[46:49], v[50:53], v[88:91]
	v_mfma_f32_16x16x32_bf16 v[70:73], v[34:37], v[66:69], v[108:111]
	v_mfma_f32_16x16x32_bf16 v[74:77], v[38:41], v[66:69], v[112:115]
	v_mfma_f32_16x16x32_bf16 v[78:81], v[42:45], v[66:69], v[116:119]
	v_mfma_f32_16x16x32_bf16 v[66:69], v[46:49], v[66:69], v[104:107]
	s_waitcnt lgkmcnt(0)
	v_mfma_f32_16x16x32_bf16 v[2:5], v[34:37], v[84:87], v[2:5]
	v_mfma_f32_16x16x32_bf16 v[6:9], v[38:41], v[84:87], v[6:9]
	v_mfma_f32_16x16x32_bf16 v[10:13], v[42:45], v[84:87], v[10:13]
	v_mfma_f32_16x16x32_bf16 v[14:17], v[46:49], v[84:87], v[14:17]
	ds_read_b128 v[34:37], v83 offset:32768
	ds_read_b128 v[38:41], v83 offset:34816
	ds_read_b128 v[42:45], v83 offset:36864
	ds_read_b128 v[46:49], v83 offset:38912
	ds_read_b128 v[84:87], v0 offset:49152
	s_waitcnt lgkmcnt(0)
	v_mfma_f32_16x16x32_bf16 v[22:25], v[34:37], v[84:87], v[22:25]
	v_mfma_f32_16x16x32_bf16 v[26:29], v[38:41], v[84:87], v[26:29]
	v_mfma_f32_16x16x32_bf16 v[30:33], v[42:45], v[84:87], v[30:33]
	v_mfma_f32_16x16x32_bf16 v[18:21], v[46:49], v[84:87], v[18:21]
	ds_read_b128 v[84:87], v0 offset:51200
	s_waitcnt lgkmcnt(0)
	v_mfma_f32_16x16x32_bf16 v[54:57], v[34:37], v[84:87], v[54:57]
	v_mfma_f32_16x16x32_bf16 v[58:61], v[38:41], v[84:87], v[58:61]
	v_mfma_f32_16x16x32_bf16 v[62:65], v[42:45], v[84:87], v[62:65]
	v_mfma_f32_16x16x32_bf16 v[50:53], v[46:49], v[84:87], v[50:53]
	ds_read_b128 v[84:87], v0 offset:53248
	s_waitcnt lgkmcnt(0)
	v_mfma_f32_16x16x32_bf16 v[70:73], v[34:37], v[84:87], v[70:73]
	v_mfma_f32_16x16x32_bf16 v[74:77], v[38:41], v[84:87], v[74:77]
	v_mfma_f32_16x16x32_bf16 v[78:81], v[42:45], v[84:87], v[78:81]
	v_mfma_f32_16x16x32_bf16 v[66:69], v[46:49], v[84:87], v[66:69]
	ds_read_b128 v[84:87], v0 offset:55296
	s_waitcnt lgkmcnt(0)
	v_mfma_f32_16x16x32_bf16 v[2:5], v[34:37], v[84:87], v[2:5]
	v_mfma_f32_16x16x32_bf16 v[6:9], v[38:41], v[84:87], v[6:9]
	v_mfma_f32_16x16x32_bf16 v[10:13], v[42:45], v[84:87], v[10:13]
	v_mfma_f32_16x16x32_bf16 v[14:17], v[46:49], v[84:87], v[14:17]
	v_mov_b32_e32 v0, v169
	s_barrier
; DI int tidx() { int t = threadIdx.x & 255; asm volatile("" : "+v"(t)); return t; }
; DI float silu(float x) { return x / (1.f + __expf(-x)); }
; DI u32x4 pack8(const float* f) { u32x4 o; o.x = pack2(f[0], f[1]); o.y = pack2(f[2], f[3]); o.z = pack2(f[4], f[5]); o.w = pack2(f[6], f[7]); return o; }
; DI void stage_c(const f32x4 (&acc)[4][4], float* Cs) {
;   const int tid = tidx(), lane = tid & 63, w = tid >> 6;
;   const int wm = w >> 1, wn = w & 1, fr = lane & 15, fq = lane >> 4;
; #pragma unroll
;   for (int m = 0; m < 4; ++m)
; #pragma unroll
;     for (int n = 0; n < 4; ++n)
; #pragma unroll
;       for (int j = 0; j < 4; ++j) Cs[(wm * 64 + m * 16 + fq * 4 + j) * CST + wn * 64 + n * 16 + fr] = acc[m][n][j];
;   __syncthreads();
; }
; DI void pw2_tile(PREF p, int l, int idx, unsigned char* ldsb) {
;     ...
;   u32x4 zr[8];
; #pragma unroll
;   for (int q = 0; q < 8; ++q) zr[q] = *(const u32x4*)(p.hb + (size_t)(row0 + (tid >> 4) + 16 * q) * HW + OFF_AZ + col0 + (tid & 15) * 8);
; #pragma unroll
;   for (int q = 0; q < 8; ++q) {
;     int r = (tid >> 4) + 16 * q, c = (tid & 15) * 8;
;     float v[8]; ld8(Cs + r * CST + c, v);
;     float z[8]; unpack8(zr[q], z);
; #pragma unroll
;     for (int j = 0; j < 8; ++j) v[j] *= silu(z[j]);
;     *(u32x4*)(p.ys + (size_t)(row0 + r) * 1024 + col0 + c) = pack8(v);
	s_lshl_b32 s52, s21, 1
	v_lshrrev_b32_e32 v35, 2, v0
	v_lshrrev_b32_e32 v34, 1, v0
	v_and_b32_e32 v35, 12, v35
	v_and_or_b32 v34, v34, s42, v35
	v_and_b32_e32 v0, 0x4f, v0
	v_mul_lo_u32 v34, v34, s92
	v_lshlrev_b32_e32 v0, 2, v0
	v_add3_u32 v0, s33, v34, v0
	ds_write2_b32 v0, v22, v54 offset1:16
	ds_write2_b32 v0, v23, v55 offset0:132 offset1:148
	v_add_u32_e32 v22, 0x400, v0
	ds_write2_b32 v22, v24, v56 offset0:8 offset1:24
	ds_write2_b32 v22, v25, v57 offset0:140 offset1:156
	ds_write2_b32 v0, v70, v2 offset0:32 offset1:48
	ds_write2_b32 v0, v71, v3 offset0:164 offset1:180
	ds_write2_b32 v22, v72, v4 offset0:40 offset1:56
	ds_write2_b32 v22, v73, v5 offset0:172 offset1:188
	v_add_u32_e32 v2, 0x2000, v0
	v_add_u32_e32 v3, 0x2400, v0
	ds_write2_b32 v2, v26, v58 offset0:64 offset1:80
	ds_write2_b32 v2, v27, v59 offset0:196 offset1:212
	ds_write2_b32 v3, v28, v60 offset0:72 offset1:88
	ds_write2_b32 v3, v29, v61 offset0:204 offset1:220
	ds_write2_b32 v2, v74, v6 offset0:96 offset1:112
	ds_write2_b32 v2, v75, v7 offset0:228 offset1:244
	ds_write2_b32 v3, v76, v8 offset0:104 offset1:120
	ds_write2_b32 v3, v77, v9 offset0:236 offset1:252
	v_add_u32_e32 v2, 0x4000, v0
	v_add_u32_e32 v3, 0x4400, v0
	v_add_u32_e32 v4, 0x4800, v0
	ds_write2_b32 v2, v30, v62 offset0:128 offset1:144
	ds_write2_b32 v3, v31, v63 offset0:4 offset1:20
	ds_write2_b32 v3, v32, v64 offset0:136 offset1:152
	ds_write2_b32 v4, v33, v65 offset0:12 offset1:28
	ds_write2_b32 v2, v78, v10 offset0:160 offset1:176
	ds_write2_b32 v3, v79, v11 offset0:36 offset1:52
	ds_write2_b32 v3, v80, v12 offset0:168 offset1:184
	ds_write2_b32 v4, v81, v13 offset0:44 offset1:60
	v_add_u32_e32 v2, 0x6000, v0
	v_add_u32_e32 v3, 0x6400, v0
	v_add_u32_e32 v0, 0x6800, v0
	v_ashrrev_i32_e32 v30, 4, v82
	ds_write2_b32 v2, v18, v50 offset0:192 offset1:208
	ds_write2_b32 v3, v19, v51 offset0:68 offset1:84
	ds_write2_b32 v3, v20, v52 offset0:200 offset1:216
	ds_write2_b32 v0, v21, v53 offset0:76 offset1:92
	ds_write2_b32 v2, v66, v14 offset0:224 offset1:240
	ds_write2_b32 v3, v67, v15 offset0:100 offset1:116
	ds_write2_b32 v3, v68, v16 offset0:232 offset1:248
	ds_write2_b32 v0, v69, v17 offset0:108 offset1:124
	v_add_u32_e32 v54, s14, v30
	v_lshlrev_b32_e32 v0, 3, v82
	v_mov_b64_e32 v[2:3], s[8:9]
	v_and_b32_e32 v31, 0x78, v0
	v_mad_i64_i32 v[4:5], s[0:1], v54, s60, v[2:3]
	v_lshl_add_u64 v[4:5], v[4:5], 0, s[52:53]
	v_lshlrev_b32_e32 v0, 1, v31
	v_lshl_add_u64 v[4:5], v[4:5], 0, v[0:1]
	s_waitcnt lgkmcnt(0)
	s_barrier
	global_load_dwordx4 v[56:59], v[4:5], off offset:1024
	v_add_u32_e32 v52, 16, v54
	v_mad_i64_i32 v[4:5], s[0:1], v52, s60, v[2:3]
	v_lshl_add_u64 v[4:5], v[4:5], 0, s[52:53]
	v_lshl_add_u64 v[4:5], v[4:5], 0, v[0:1]
	v_add_u32_e32 v50, 32, v54
	global_load_dwordx4 v[26:29], v[4:5], off offset:1024
	v_mad_i64_i32 v[4:5], s[0:1], v50, s60, v[2:3]
	v_lshl_add_u64 v[4:5], v[4:5], 0, s[52:53]
	v_lshl_add_u64 v[4:5], v[4:5], 0, v[0:1]
	v_add_u32_e32 v48, 48, v54
	global_load_dwordx4 v[22:25], v[4:5], off offset:1024
	v_mad_i64_i32 v[4:5], s[0:1], v48, s60, v[2:3]
	v_lshl_add_u64 v[4:5], v[4:5], 0, s[52:53]
	v_lshl_add_u64 v[4:5], v[4:5], 0, v[0:1]
	v_add_u32_e32 v46, 64, v54
	global_load_dwordx4 v[18:21], v[4:5], off offset:1024
	v_mad_i64_i32 v[4:5], s[0:1], v46, s60, v[2:3]
	v_lshl_add_u64 v[4:5], v[4:5], 0, s[52:53]
	v_lshl_add_u64 v[4:5], v[4:5], 0, v[0:1]
	v_add_u32_e32 v44, 0x50, v54
	global_load_dwordx4 v[14:17], v[4:5], off offset:1024
	v_mad_i64_i32 v[4:5], s[0:1], v44, s60, v[2:3]
	v_lshl_add_u64 v[4:5], v[4:5], 0, s[52:53]
	v_lshl_add_u64 v[4:5], v[4:5], 0, v[0:1]
	v_add_u32_e32 v42, 0x60, v54
	v_add_u32_e32 v38, 0x70, v54
	global_load_dwordx4 v[10:13], v[4:5], off offset:1024
	v_mad_i64_i32 v[4:5], s[0:1], v42, s60, v[2:3]
	v_mad_i64_i32 v[2:3], s[0:1], v38, s60, v[2:3]
	s_add_u32 s0, s10, s52
	s_addc_u32 s1, s11, 0
	v_lshl_add_u64 v[40:41], s[0:1], 0, v[0:1]
	v_lshl_add_u64 v[4:5], v[4:5], 0, s[52:53]
	v_lshl_add_u64 v[2:3], v[2:3], 0, s[52:53]
	v_lshl_add_u64 v[4:5], v[4:5], 0, v[0:1]
	v_lshl_add_u64 v[2:3], v[2:3], 0, v[0:1]
	v_lshlrev_b32_e32 v31, 2, v31
	v_mul_lo_u32 v0, v30, s92
	v_add3_u32 v0, s33, v31, v0
	global_load_dwordx4 v[6:9], v[4:5], off offset:1024
	v_ashrrev_i32_e32 v55, 31, v54
	global_load_dwordx4 v[2:5], v[2:3], off offset:1024
	ds_read_b128 v[34:37], v0
	ds_read_b128 v[30:33], v0 offset:16
	v_ashrrev_i32_e32 v53, 31, v52
	v_ashrrev_i32_e32 v51, 31, v50
	v_ashrrev_i32_e32 v49, 31, v48
	v_ashrrev_i32_e32 v47, 31, v46
	v_ashrrev_i32_e32 v45, 31, v44
	v_ashrrev_i32_e32 v43, 31, v42
	v_ashrrev_i32_e32 v39, 31, v38
	s_add_i32 s16, s16, s71
	s_add_i32 s19, s19, s36
	s_add_i32 s20, s20, s84
	s_cmpk_gt_i32 s16, 0x1ff
	s_waitcnt vmcnt(7)
	v_lshlrev_b32_e32 v60, 16, v56
	v_and_b32_e32 v61, 0xffff0000, v56
	v_lshlrev_b32_e32 v64, 16, v59
	v_and_b32_e32 v56, 0xffff0000, v59
	v_mul_f32_e32 v59, 0xbfb8aa3b, v60
	v_exp_f32_e32 v59, v59
	v_lshlrev_b32_e32 v62, 16, v57
	v_and_b32_e32 v57, 0xffff0000, v57
	v_lshlrev_b32_e32 v63, 16, v58
	v_add_f32_e32 v59, 1.0, v59
	v_and_b32_e32 v58, 0xffff0000, v58
	v_rcp_f32_e32 v65, v59
	s_nop 0
	v_mul_f32_e32 v59, v60, v65
	s_waitcnt lgkmcnt(1)
	v_mul_f32_e32 v34, v59, v34
	v_mul_f32_e32 v59, 0xbfb8aa3b, v61
	v_exp_f32_e32 v59, v59
	s_nop 0
	v_add_f32_e32 v59, 1.0, v59
	v_rcp_f32_e32 v60, v59
	s_nop 0
	v_mul_f32_e32 v59, v61, v60
	v_mul_f32_e32 v35, v59, v35
	v_mul_f32_e32 v59, 0xbfb8aa3b, v62
	v_exp_f32_e32 v59, v59
	s_nop 0
	v_add_f32_e32 v59, 1.0, v59
	v_rcp_f32_e32 v60, v59
	s_nop 0
	v_mul_f32_e32 v59, v62, v60
	v_mul_f32_e32 v36, v59, v36
	v_mul_f32_e32 v59, 0xbfb8aa3b, v57
	v_exp_f32_e32 v59, v59
	s_nop 0
	v_add_f32_e32 v59, 1.0, v59
	v_rcp_f32_e32 v60, v59
	s_nop 0
	v_mul_f32_e32 v57, v57, v60
	v_mul_f32_e32 v37, v57, v37
	v_mul_f32_e32 v57, 0xbfb8aa3b, v63
	v_exp_f32_e32 v57, v57
	s_nop 0
	v_add_f32_e32 v57, 1.0, v57
	v_rcp_f32_e32 v59, v57
	s_nop 0
	v_mul_f32_e32 v57, v63, v59
	s_waitcnt lgkmcnt(0)
; DI float silu(float x) { return x / (1.f + __expf(-x)); }
; DI u32x4 pack8(const float* f) { u32x4 o; o.x = pack2(f[0], f[1]); o.y = pack2(f[2], f[3]); o.z = pack2(f[4], f[5]); o.w = pack2(f[6], f[7]); return o; }
; DI void pw2_tile(PREF p, int l, int idx, unsigned char* ldsb) {
;     ...
;   u32x4 zr[8];
; #pragma unroll
;   for (int q = 0; q < 8; ++q) zr[q] = *(const u32x4*)(p.hb + (size_t)(row0 + (tid >> 4) + 16 * q) * HW + OFF_AZ + col0 + (tid & 15) * 8);
; #pragma unroll
;   for (int q = 0; q < 8; ++q) {
;     int r = (tid >> 4) + 16 * q, c = (tid & 15) * 8;
;     float v[8]; ld8(Cs + r * CST + c, v);
;     float z[8]; unpack8(zr[q], z);
; #pragma unroll
;     for (int j = 0; j < 8; ++j) v[j] *= silu(z[j]);
;     *(u32x4*)(p.ys + (size_t)(row0 + r) * 1024 + col0 + c) = pack8(v);
;   }
	v_mul_f32_e32 v57, v57, v30
	v_mul_f32_e32 v30, 0xbfb8aa3b, v58
	v_exp_f32_e32 v30, v30
	s_nop 0
	v_add_f32_e32 v30, 1.0, v30
	v_rcp_f32_e32 v59, v30
	s_nop 0
	v_mul_f32_e32 v30, v58, v59
	v_mul_f32_e32 v58, v30, v31
	v_mul_f32_e32 v30, 0xbfb8aa3b, v64
	v_exp_f32_e32 v30, v30
	s_nop 0
	v_add_f32_e32 v30, 1.0, v30
	v_rcp_f32_e32 v31, v30
	s_nop 0
	v_mul_f32_e32 v30, v64, v31
	v_mul_f32_e32 v59, v30, v32
	v_mul_f32_e32 v30, 0xbfb8aa3b, v56
	v_exp_f32_e32 v30, v30
	s_nop 0
	v_add_f32_e32 v30, 1.0, v30
	v_rcp_f32_e32 v31, v30
	s_nop 0
	v_mul_f32_e32 v30, v56, v31
	v_mul_f32_e32 v33, v30, v33
	v_cvt_pk_bf16_f32 v30, v34, v35
	v_lshlrev_b64 v[34:35], 11, v[54:55]
	s_waitcnt vmcnt(6)
	v_lshlrev_b32_e32 v54, 16, v26
	v_cvt_pk_bf16_f32 v32, v57, v58
	v_lshlrev_b32_e32 v56, 16, v27
	v_and_b32_e32 v57, 0xffff0000, v27
	v_mul_f32_e32 v27, 0xbfb8aa3b, v54
	v_exp_f32_e32 v27, v27
	v_cvt_pk_bf16_f32 v33, v59, v33
	v_and_b32_e32 v55, 0xffff0000, v26
	v_lshlrev_b32_e32 v59, 16, v29
	v_add_f32_e32 v27, 1.0, v27
	v_and_b32_e32 v26, 0xffff0000, v29
	v_lshl_add_u64 v[34:35], v[40:41], 0, v[34:35]
	v_cvt_pk_bf16_f32 v31, v36, v37
	global_store_dwordx4 v[34:35], v[30:33], off
	v_rcp_f32_e32 v29, v27
	s_nop 0
	v_mul_f32_e32 v27, v54, v29
	v_mul_f32_e32 v29, 0xbfb8aa3b, v55
	v_exp_f32_e32 v29, v29
	ds_read_b128 v[34:37], v0 offset:8448
	ds_read_b128 v[30:33], v0 offset:8464
	v_lshlrev_b32_e32 v58, 16, v28
	v_and_b32_e32 v28, 0xffff0000, v28
	v_add_f32_e32 v29, 1.0, v29
	s_waitcnt lgkmcnt(1)
	v_mul_f32_e32 v27, v27, v34
	v_rcp_f32_e32 v34, v29
	s_nop 0
	v_mul_f32_e32 v29, v55, v34
	v_mul_f32_e32 v34, 0xbfb8aa3b, v56
	v_exp_f32_e32 v34, v34
	v_mul_f32_e32 v29, v29, v35
	v_add_f32_e32 v34, 1.0, v34
	v_rcp_f32_e32 v35, v34
	s_nop 0
	v_mul_f32_e32 v34, v56, v35
	v_mul_f32_e32 v35, 0xbfb8aa3b, v57
	v_exp_f32_e32 v35, v35
	v_mul_f32_e32 v34, v34, v36
	v_add_f32_e32 v35, 1.0, v35
	v_rcp_f32_e32 v36, v35
	s_nop 0
	v_mul_f32_e32 v35, v57, v36
	v_mul_f32_e32 v36, 0xbfb8aa3b, v58
	v_exp_f32_e32 v36, v36
	v_mul_f32_e32 v35, v35, v37
	v_add_f32_e32 v36, 1.0, v36
	v_rcp_f32_e32 v37, v36
	s_nop 0
	v_mul_f32_e32 v36, v58, v37
	s_waitcnt lgkmcnt(0)
	v_mul_f32_e32 v30, v36, v30
	v_mul_f32_e32 v36, 0xbfb8aa3b, v28
	v_exp_f32_e32 v36, v36
	s_nop 0
	v_add_f32_e32 v36, 1.0, v36
	v_rcp_f32_e32 v37, v36
	s_nop 0
	v_mul_f32_e32 v28, v28, v37
	v_mul_f32_e32 v28, v28, v31
	v_mul_f32_e32 v31, 0xbfb8aa3b, v59
	v_exp_f32_e32 v31, v31
	v_cvt_pk_bf16_f32 v28, v30, v28
	s_nop 0
	v_add_f32_e32 v31, 1.0, v31
	v_rcp_f32_e32 v36, v31
	s_nop 0
	v_mul_f32_e32 v31, v59, v36
	v_mul_f32_e32 v31, v31, v32
	v_mul_f32_e32 v32, 0xbfb8aa3b, v26
	v_exp_f32_e32 v32, v32
	s_nop 0
	v_add_f32_e32 v32, 1.0, v32
	v_rcp_f32_e32 v36, v32
	s_nop 0
	v_mul_f32_e32 v26, v26, v36
	v_mul_f32_e32 v32, v26, v33
	v_cvt_pk_bf16_f32 v26, v27, v29
	v_cvt_pk_bf16_f32 v27, v34, v35
	s_waitcnt vmcnt(6)
	v_lshlrev_b32_e32 v34, 16, v22
	v_lshlrev_b32_e32 v36, 16, v23
	v_and_b32_e32 v37, 0xffff0000, v23
	v_mul_f32_e32 v23, 0xbfb8aa3b, v34
	v_exp_f32_e32 v23, v23
	v_cvt_pk_bf16_f32 v29, v31, v32
	v_lshlrev_b64 v[30:31], 11, v[52:53]
	v_and_b32_e32 v35, 0xffff0000, v22
	v_add_f32_e32 v23, 1.0, v23
	v_lshlrev_b32_e32 v53, 16, v25
	v_and_b32_e32 v22, 0xffff0000, v25
	v_lshl_add_u64 v[30:31], v[40:41], 0, v[30:31]
	global_store_dwordx4 v[30:31], v[26:29], off
	ds_read_b128 v[30:33], v0 offset:16896
	ds_read_b128 v[26:29], v0 offset:16912
	v_rcp_f32_e32 v25, v23
	s_nop 0
	v_mul_f32_e32 v23, v34, v25
	v_mul_f32_e32 v25, 0xbfb8aa3b, v35
	v_exp_f32_e32 v25, v25
	s_waitcnt lgkmcnt(1)
	v_mul_f32_e32 v23, v23, v30
	v_lshlrev_b32_e32 v52, 16, v24
	v_and_b32_e32 v24, 0xffff0000, v24
	v_add_f32_e32 v25, 1.0, v25
	v_rcp_f32_e32 v30, v25
	s_nop 0
	v_mul_f32_e32 v25, v35, v30
	v_mul_f32_e32 v30, 0xbfb8aa3b, v36
	v_exp_f32_e32 v30, v30
	v_mul_f32_e32 v25, v25, v31
	v_add_f32_e32 v30, 1.0, v30
	v_rcp_f32_e32 v31, v30
	s_nop 0
	v_mul_f32_e32 v30, v36, v31
	v_mul_f32_e32 v31, 0xbfb8aa3b, v37
	v_exp_f32_e32 v31, v31
	v_mul_f32_e32 v30, v30, v32
	v_add_f32_e32 v31, 1.0, v31
	v_rcp_f32_e32 v32, v31
	s_nop 0
	v_mul_f32_e32 v31, v37, v32
	v_mul_f32_e32 v32, 0xbfb8aa3b, v52
	v_exp_f32_e32 v32, v32
	v_mul_f32_e32 v31, v31, v33
	v_add_f32_e32 v32, 1.0, v32
	v_rcp_f32_e32 v33, v32
	s_nop 0
	v_mul_f32_e32 v32, v52, v33
	s_waitcnt lgkmcnt(0)
	v_mul_f32_e32 v26, v32, v26
	v_mul_f32_e32 v32, 0xbfb8aa3b, v24
	v_exp_f32_e32 v32, v32
	s_nop 0
	v_add_f32_e32 v32, 1.0, v32
	v_rcp_f32_e32 v33, v32
	s_nop 0
	v_mul_f32_e32 v24, v24, v33
	v_mul_f32_e32 v24, v24, v27
	v_mul_f32_e32 v27, 0xbfb8aa3b, v53
	v_exp_f32_e32 v27, v27
	v_cvt_pk_bf16_f32 v24, v26, v24
	s_nop 0
	v_add_f32_e32 v27, 1.0, v27
	v_rcp_f32_e32 v32, v27
	s_nop 0
	v_mul_f32_e32 v27, v53, v32
	v_mul_f32_e32 v27, v27, v28
	v_mul_f32_e32 v28, 0xbfb8aa3b, v22
	v_exp_f32_e32 v28, v28
	s_nop 0
	v_add_f32_e32 v28, 1.0, v28
	v_rcp_f32_e32 v32, v28
	s_nop 0
	v_mul_f32_e32 v22, v22, v32
	v_mul_f32_e32 v28, v22, v29
	v_cvt_pk_bf16_f32 v22, v23, v25
	v_cvt_pk_bf16_f32 v23, v30, v31
	s_waitcnt vmcnt(6)
	v_lshlrev_b32_e32 v30, 16, v18
	v_lshlrev_b32_e32 v32, 16, v19
	v_and_b32_e32 v33, 0xffff0000, v19
	v_mul_f32_e32 v19, 0xbfb8aa3b, v30
	v_exp_f32_e32 v19, v19
	v_and_b32_e32 v31, 0xffff0000, v18
	v_lshlrev_b32_e32 v35, 16, v21
	v_and_b32_e32 v18, 0xffff0000, v21
	v_add_f32_e32 v19, 1.0, v19
	v_cvt_pk_bf16_f32 v25, v27, v28
	v_lshlrev_b64 v[26:27], 11, v[50:51]
	v_lshl_add_u64 v[26:27], v[40:41], 0, v[26:27]
	v_rcp_f32_e32 v21, v19
	s_nop 0
	v_mul_f32_e32 v19, v30, v21
	v_mul_f32_e32 v21, 0xbfb8aa3b, v31
	global_store_dwordx4 v[26:27], v[22:25], off
	v_exp_f32_e32 v21, v21
	ds_read_b128 v[26:29], v0 offset:25344
	ds_read_b128 v[22:25], v0 offset:25360
	v_lshlrev_b32_e32 v34, 16, v20
	v_and_b32_e32 v20, 0xffff0000, v20
	v_add_f32_e32 v21, 1.0, v21
	s_waitcnt lgkmcnt(1)
; DI float silu(float x) { return x / (1.f + __expf(-x)); }
; DI u32x4 pack8(const float* f) { u32x4 o; o.x = pack2(f[0], f[1]); o.y = pack2(f[2], f[3]); o.z = pack2(f[4], f[5]); o.w = pack2(f[6], f[7]); return o; }
; DI void pw2_tile(PREF p, int l, int idx, unsigned char* ldsb) {
;     ...
;   for (int q = 0; q < 8; ++q) {
;     int r = (tid >> 4) + 16 * q, c = (tid & 15) * 8;
;     float v[8]; ld8(Cs + r * CST + c, v);
;     float z[8]; unpack8(zr[q], z);
; #pragma unroll
;     for (int j = 0; j < 8; ++j) v[j] *= silu(z[j]);
;     *(u32x4*)(p.ys + (size_t)(row0 + r) * 1024 + col0 + c) = pack8(v);
;   }
	v_mul_f32_e32 v19, v19, v26
	v_rcp_f32_e32 v26, v21
	s_nop 0
	v_mul_f32_e32 v21, v31, v26
	v_mul_f32_e32 v26, 0xbfb8aa3b, v32
	v_exp_f32_e32 v26, v26
	v_mul_f32_e32 v21, v21, v27
	v_add_f32_e32 v26, 1.0, v26
	v_rcp_f32_e32 v27, v26
	s_nop 0
	v_mul_f32_e32 v26, v32, v27
	v_mul_f32_e32 v27, 0xbfb8aa3b, v33
	v_exp_f32_e32 v27, v27
	v_mul_f32_e32 v26, v26, v28
	v_add_f32_e32 v27, 1.0, v27
	v_rcp_f32_e32 v28, v27
	s_nop 0
	v_mul_f32_e32 v27, v33, v28
	v_mul_f32_e32 v28, 0xbfb8aa3b, v34
	v_exp_f32_e32 v28, v28
	v_mul_f32_e32 v27, v27, v29
	v_add_f32_e32 v28, 1.0, v28
	v_rcp_f32_e32 v29, v28
	s_nop 0
	v_mul_f32_e32 v28, v34, v29
	s_waitcnt lgkmcnt(0)
	v_mul_f32_e32 v22, v28, v22
	v_mul_f32_e32 v28, 0xbfb8aa3b, v20
	v_exp_f32_e32 v28, v28
	s_nop 0
	v_add_f32_e32 v28, 1.0, v28
	v_rcp_f32_e32 v29, v28
	s_nop 0
	v_mul_f32_e32 v20, v20, v29
	v_mul_f32_e32 v20, v20, v23
	v_mul_f32_e32 v23, 0xbfb8aa3b, v35
	v_exp_f32_e32 v23, v23
	v_cvt_pk_bf16_f32 v20, v22, v20
	s_nop 0
	v_add_f32_e32 v23, 1.0, v23
	v_rcp_f32_e32 v28, v23
	s_nop 0
	v_mul_f32_e32 v23, v35, v28
	v_mul_f32_e32 v23, v23, v24
	v_mul_f32_e32 v24, 0xbfb8aa3b, v18
	v_exp_f32_e32 v24, v24
	s_nop 0
	v_add_f32_e32 v24, 1.0, v24
	v_rcp_f32_e32 v28, v24
	s_nop 0
	v_mul_f32_e32 v18, v18, v28
	v_mul_f32_e32 v24, v18, v25
	v_cvt_pk_bf16_f32 v18, v19, v21
	v_cvt_pk_bf16_f32 v19, v26, v27
	s_waitcnt vmcnt(6)
	v_lshlrev_b32_e32 v26, 16, v14
	v_lshlrev_b32_e32 v28, 16, v15
	v_and_b32_e32 v29, 0xffff0000, v15
	v_mul_f32_e32 v15, 0xbfb8aa3b, v26
	v_exp_f32_e32 v15, v15
	v_and_b32_e32 v27, 0xffff0000, v14
	v_lshlrev_b32_e32 v31, 16, v17
	v_and_b32_e32 v14, 0xffff0000, v17
	v_add_f32_e32 v15, 1.0, v15
	v_cvt_pk_bf16_f32 v21, v23, v24
	v_lshlrev_b64 v[22:23], 11, v[48:49]
	v_lshl_add_u64 v[22:23], v[40:41], 0, v[22:23]
	v_rcp_f32_e32 v17, v15
	s_nop 0
	v_mul_f32_e32 v15, v26, v17
	v_mul_f32_e32 v17, 0xbfb8aa3b, v27
	global_store_dwordx4 v[22:23], v[18:21], off
	v_exp_f32_e32 v17, v17
	ds_read_b128 v[22:25], v0 offset:33792
	ds_read_b128 v[18:21], v0 offset:33808
	v_lshlrev_b32_e32 v30, 16, v16
	v_and_b32_e32 v16, 0xffff0000, v16
	v_add_f32_e32 v17, 1.0, v17
	s_waitcnt lgkmcnt(1)
	v_mul_f32_e32 v15, v15, v22
	v_rcp_f32_e32 v22, v17
	s_nop 0
	v_mul_f32_e32 v17, v27, v22
	v_mul_f32_e32 v22, 0xbfb8aa3b, v28
	v_exp_f32_e32 v22, v22
	v_mul_f32_e32 v17, v17, v23
	v_add_f32_e32 v22, 1.0, v22
	v_rcp_f32_e32 v23, v22
	s_nop 0
	v_mul_f32_e32 v22, v28, v23
	v_mul_f32_e32 v23, 0xbfb8aa3b, v29
	v_exp_f32_e32 v23, v23
	v_mul_f32_e32 v22, v22, v24
	v_add_f32_e32 v23, 1.0, v23
	v_rcp_f32_e32 v24, v23
	s_nop 0
	v_mul_f32_e32 v23, v29, v24
	v_mul_f32_e32 v24, 0xbfb8aa3b, v30
	v_exp_f32_e32 v24, v24
	v_mul_f32_e32 v23, v23, v25
	v_add_f32_e32 v24, 1.0, v24
	v_rcp_f32_e32 v25, v24
	s_nop 0
	v_mul_f32_e32 v24, v30, v25
	s_waitcnt lgkmcnt(0)
	v_mul_f32_e32 v18, v24, v18
	v_mul_f32_e32 v24, 0xbfb8aa3b, v16
	v_exp_f32_e32 v24, v24
	s_nop 0
	v_add_f32_e32 v24, 1.0, v24
	v_rcp_f32_e32 v25, v24
	s_nop 0
	v_mul_f32_e32 v16, v16, v25
	v_mul_f32_e32 v16, v16, v19
	v_mul_f32_e32 v19, 0xbfb8aa3b, v31
	v_exp_f32_e32 v19, v19
	v_cvt_pk_bf16_f32 v16, v18, v16
	s_nop 0
	v_add_f32_e32 v19, 1.0, v19
	v_rcp_f32_e32 v24, v19
	s_nop 0
	v_mul_f32_e32 v19, v31, v24
	v_mul_f32_e32 v19, v19, v20
	v_mul_f32_e32 v20, 0xbfb8aa3b, v14
	v_exp_f32_e32 v20, v20
	s_nop 0
	v_add_f32_e32 v20, 1.0, v20
	v_rcp_f32_e32 v24, v20
	s_nop 0
	v_mul_f32_e32 v14, v14, v24
	v_mul_f32_e32 v20, v14, v21
	v_cvt_pk_bf16_f32 v14, v15, v17
	v_cvt_pk_bf16_f32 v15, v22, v23
	s_waitcnt vmcnt(6)
	v_lshlrev_b32_e32 v22, 16, v10
	v_lshlrev_b32_e32 v24, 16, v11
	v_and_b32_e32 v25, 0xffff0000, v11
	v_mul_f32_e32 v11, 0xbfb8aa3b, v22
	v_exp_f32_e32 v11, v11
	v_and_b32_e32 v23, 0xffff0000, v10
	v_lshlrev_b32_e32 v27, 16, v13
	v_and_b32_e32 v10, 0xffff0000, v13
	v_add_f32_e32 v11, 1.0, v11
	v_cvt_pk_bf16_f32 v17, v19, v20
	v_lshlrev_b64 v[18:19], 11, v[46:47]
	v_lshl_add_u64 v[18:19], v[40:41], 0, v[18:19]
	v_rcp_f32_e32 v13, v11
	s_nop 0
	v_mul_f32_e32 v11, v22, v13
	v_mul_f32_e32 v13, 0xbfb8aa3b, v23
	global_store_dwordx4 v[18:19], v[14:17], off
	v_exp_f32_e32 v13, v13
	ds_read_b128 v[18:21], v0 offset:42240
	ds_read_b128 v[14:17], v0 offset:42256
	v_lshlrev_b32_e32 v26, 16, v12
	v_and_b32_e32 v12, 0xffff0000, v12
	v_add_f32_e32 v13, 1.0, v13
	s_waitcnt lgkmcnt(1)
	v_mul_f32_e32 v11, v11, v18
	v_rcp_f32_e32 v18, v13
	s_nop 0
	v_mul_f32_e32 v13, v23, v18
	v_mul_f32_e32 v18, 0xbfb8aa3b, v24
	v_exp_f32_e32 v18, v18
	v_mul_f32_e32 v13, v13, v19
	v_add_f32_e32 v18, 1.0, v18
	v_rcp_f32_e32 v19, v18
	s_nop 0
	v_mul_f32_e32 v18, v24, v19
	v_mul_f32_e32 v19, 0xbfb8aa3b, v25
	v_exp_f32_e32 v19, v19
	v_mul_f32_e32 v18, v18, v20
	v_add_f32_e32 v19, 1.0, v19
	v_rcp_f32_e32 v20, v19
	s_nop 0
	v_mul_f32_e32 v19, v25, v20
	v_mul_f32_e32 v20, 0xbfb8aa3b, v26
	v_exp_f32_e32 v20, v20
	v_mul_f32_e32 v19, v19, v21
	v_add_f32_e32 v20, 1.0, v20
	v_rcp_f32_e32 v21, v20
	s_nop 0
	v_mul_f32_e32 v20, v26, v21
	s_waitcnt lgkmcnt(0)
; DI float silu(float x) { return x / (1.f + __expf(-x)); }
; DI u32x4 pack8(const float* f) { u32x4 o; o.x = pack2(f[0], f[1]); o.y = pack2(f[2], f[3]); o.z = pack2(f[4], f[5]); o.w = pack2(f[6], f[7]); return o; }
; DI void pw2_tile(PREF p, int l, int idx, unsigned char* ldsb) {
;     ...
;   for (int q = 0; q < 8; ++q) {
;     int r = (tid >> 4) + 16 * q, c = (tid & 15) * 8;
;     float v[8]; ld8(Cs + r * CST + c, v);
;     float z[8]; unpack8(zr[q], z);
; #pragma unroll
;     for (int j = 0; j < 8; ++j) v[j] *= silu(z[j]);
;     *(u32x4*)(p.ys + (size_t)(row0 + r) * 1024 + col0 + c) = pack8(v);
;   }
	v_mul_f32_e32 v14, v20, v14
	v_mul_f32_e32 v20, 0xbfb8aa3b, v12
	v_exp_f32_e32 v20, v20
	s_nop 0
	v_add_f32_e32 v20, 1.0, v20
	v_rcp_f32_e32 v21, v20
	s_nop 0
	v_mul_f32_e32 v12, v12, v21
	v_mul_f32_e32 v12, v12, v15
	v_mul_f32_e32 v15, 0xbfb8aa3b, v27
	v_exp_f32_e32 v15, v15
	v_cvt_pk_bf16_f32 v12, v14, v12
	s_nop 0
	v_add_f32_e32 v15, 1.0, v15
	v_rcp_f32_e32 v20, v15
	s_nop 0
	v_mul_f32_e32 v15, v27, v20
	v_mul_f32_e32 v15, v15, v16
	v_mul_f32_e32 v16, 0xbfb8aa3b, v10
	v_exp_f32_e32 v16, v16
	s_nop 0
	v_add_f32_e32 v16, 1.0, v16
	v_rcp_f32_e32 v20, v16
	s_nop 0
	v_mul_f32_e32 v10, v10, v20
	v_mul_f32_e32 v16, v10, v17
	v_cvt_pk_bf16_f32 v10, v11, v13
	v_cvt_pk_bf16_f32 v11, v18, v19
	s_waitcnt vmcnt(6)
	v_lshlrev_b32_e32 v18, 16, v6
	v_lshlrev_b32_e32 v20, 16, v7
	v_and_b32_e32 v21, 0xffff0000, v7
	v_mul_f32_e32 v7, 0xbfb8aa3b, v18
	v_exp_f32_e32 v7, v7
	v_and_b32_e32 v19, 0xffff0000, v6
	v_lshlrev_b32_e32 v23, 16, v9
	v_and_b32_e32 v6, 0xffff0000, v9
	v_add_f32_e32 v7, 1.0, v7
	v_cvt_pk_bf16_f32 v13, v15, v16
	v_lshlrev_b64 v[14:15], 11, v[44:45]
	v_lshl_add_u64 v[14:15], v[40:41], 0, v[14:15]
	v_rcp_f32_e32 v9, v7
	s_nop 0
	v_mul_f32_e32 v7, v18, v9
	v_mul_f32_e32 v9, 0xbfb8aa3b, v19
	global_store_dwordx4 v[14:15], v[10:13], off
	v_exp_f32_e32 v9, v9
	ds_read_b128 v[14:17], v0 offset:50688
	ds_read_b128 v[10:13], v0 offset:50704
	v_lshlrev_b32_e32 v22, 16, v8
	v_and_b32_e32 v8, 0xffff0000, v8
	v_add_f32_e32 v9, 1.0, v9
	s_waitcnt lgkmcnt(1)
	v_mul_f32_e32 v7, v7, v14
	v_rcp_f32_e32 v14, v9
	s_nop 0
	v_mul_f32_e32 v9, v19, v14
	v_mul_f32_e32 v14, 0xbfb8aa3b, v20
	v_exp_f32_e32 v14, v14
	v_mul_f32_e32 v9, v9, v15
	v_add_f32_e32 v14, 1.0, v14
	v_rcp_f32_e32 v15, v14
	s_nop 0
	v_mul_f32_e32 v14, v20, v15
	v_mul_f32_e32 v15, 0xbfb8aa3b, v21
	v_exp_f32_e32 v15, v15
	v_mul_f32_e32 v14, v14, v16
	v_add_f32_e32 v15, 1.0, v15
	v_rcp_f32_e32 v16, v15
	s_nop 0
	v_mul_f32_e32 v15, v21, v16
	v_mul_f32_e32 v16, 0xbfb8aa3b, v22
	v_exp_f32_e32 v16, v16
	v_mul_f32_e32 v15, v15, v17
	v_add_f32_e32 v16, 1.0, v16
	v_rcp_f32_e32 v17, v16
	s_nop 0
	v_mul_f32_e32 v16, v22, v17
	s_waitcnt lgkmcnt(0)
	v_mul_f32_e32 v10, v16, v10
	v_mul_f32_e32 v16, 0xbfb8aa3b, v8
	v_exp_f32_e32 v16, v16
	s_nop 0
	v_add_f32_e32 v16, 1.0, v16
	v_rcp_f32_e32 v17, v16
	s_nop 0
	v_mul_f32_e32 v8, v8, v17
	v_mul_f32_e32 v8, v8, v11
	v_mul_f32_e32 v11, 0xbfb8aa3b, v23
	v_exp_f32_e32 v11, v11
	v_cvt_pk_bf16_f32 v8, v10, v8
	s_nop 0
	v_add_f32_e32 v11, 1.0, v11
	v_rcp_f32_e32 v16, v11
	s_nop 0
	v_mul_f32_e32 v11, v23, v16
	v_mul_f32_e32 v11, v11, v12
	v_mul_f32_e32 v12, 0xbfb8aa3b, v6
	v_exp_f32_e32 v12, v12
	s_nop 0
	v_add_f32_e32 v12, 1.0, v12
	v_rcp_f32_e32 v16, v12
	s_nop 0
	v_mul_f32_e32 v6, v6, v16
	v_mul_f32_e32 v12, v6, v13
	v_cvt_pk_bf16_f32 v6, v7, v9
	v_cvt_pk_bf16_f32 v7, v14, v15
	s_waitcnt vmcnt(6)
	v_lshlrev_b32_e32 v14, 16, v2
	v_and_b32_e32 v15, 0xffff0000, v2
	v_mul_f32_e32 v2, 0xbfb8aa3b, v14
	v_exp_f32_e32 v2, v2
	v_cvt_pk_bf16_f32 v9, v11, v12
	v_lshlrev_b64 v[10:11], 11, v[42:43]
	v_lshl_add_u64 v[10:11], v[40:41], 0, v[10:11]
	global_store_dwordx4 v[10:11], v[6:9], off
	v_add_f32_e32 v2, 1.0, v2
	ds_read_b128 v[10:13], v0 offset:59136
	ds_read_b128 v[6:9], v0 offset:59152
	v_lshlrev_b32_e32 v18, 16, v5
	v_and_b32_e32 v0, 0xffff0000, v5
	v_lshlrev_b32_e32 v16, 16, v3
	v_and_b32_e32 v3, 0xffff0000, v3
	v_lshlrev_b32_e32 v17, 16, v4
	v_rcp_f32_e32 v5, v2
	s_nop 0
	v_mul_f32_e32 v2, v14, v5
	v_mul_f32_e32 v5, 0xbfb8aa3b, v15
	v_exp_f32_e32 v5, v5
	s_waitcnt lgkmcnt(1)
	v_mul_f32_e32 v2, v2, v10
	v_and_b32_e32 v4, 0xffff0000, v4
	v_add_f32_e32 v5, 1.0, v5
	v_rcp_f32_e32 v10, v5
	s_nop 0
	v_mul_f32_e32 v5, v15, v10
	v_mul_f32_e32 v10, 0xbfb8aa3b, v16
	v_exp_f32_e32 v10, v10
	v_mul_f32_e32 v5, v5, v11
	v_cvt_pk_bf16_f32 v2, v2, v5
	v_add_f32_e32 v10, 1.0, v10
	v_rcp_f32_e32 v11, v10
	s_nop 0
	v_mul_f32_e32 v10, v16, v11
	v_mul_f32_e32 v11, 0xbfb8aa3b, v3
	v_exp_f32_e32 v11, v11
	v_mul_f32_e32 v10, v10, v12
	v_add_f32_e32 v11, 1.0, v11
	v_rcp_f32_e32 v12, v11
	s_nop 0
	v_mul_f32_e32 v3, v3, v12
	v_mul_f32_e32 v11, 0xbfb8aa3b, v17
	v_exp_f32_e32 v11, v11
	v_mul_f32_e32 v3, v3, v13
	v_cvt_pk_bf16_f32 v3, v10, v3
	v_add_f32_e32 v11, 1.0, v11
	v_rcp_f32_e32 v12, v11
	s_nop 0
	v_mul_f32_e32 v11, v17, v12
	s_waitcnt lgkmcnt(0)
	v_mul_f32_e32 v6, v11, v6
	v_mul_f32_e32 v11, 0xbfb8aa3b, v4
	v_exp_f32_e32 v11, v11
	s_nop 0
	v_add_f32_e32 v11, 1.0, v11
	v_rcp_f32_e32 v12, v11
	s_nop 0
	v_mul_f32_e32 v4, v4, v12
	v_mul_f32_e32 v4, v4, v7
	v_mul_f32_e32 v7, 0xbfb8aa3b, v18
	v_exp_f32_e32 v7, v7
	v_cvt_pk_bf16_f32 v4, v6, v4
	s_nop 0
	v_add_f32_e32 v7, 1.0, v7
	v_rcp_f32_e32 v11, v7
	s_nop 0
	v_mul_f32_e32 v7, v18, v11
	v_mul_f32_e32 v7, v7, v8
	v_mul_f32_e32 v8, 0xbfb8aa3b, v0
	v_exp_f32_e32 v8, v8
	s_nop 0
	v_add_f32_e32 v8, 1.0, v8
	v_rcp_f32_e32 v11, v8
	s_nop 0
	v_mul_f32_e32 v0, v0, v11
	v_mul_f32_e32 v0, v0, v9
	v_cvt_pk_bf16_f32 v5, v7, v0
	v_lshlrev_b64 v[6:7], 11, v[38:39]
	v_lshl_add_u64 v[6:7], v[40:41], 0, v[6:7]
	global_store_dwordx4 v[6:7], v[2:5], off
	s_cbranch_scc0 .LBB0_265

; #define GM_LOAD(RA, RB, KT)                                                                 \
;   _Pragma("unroll") for (int i = 0; i < 4; ++i) {                                           \
;     RA[i] = *(const u32x4*)(ag + (size_t)(32 * i) * lda + (KT) * 64);                       \
;     RB[i] = *(const u32x4*)(bg + (size_t)(32 * i) * ldb + (KT) * 64);                       \
;   }
; template <bool DEEP = true>
; DI void gemm_main(f32x4 (&acc)[4][4], const u16* __restrict__ A, int lda, const u16* __restrict__ B, int ldb, int K, u16* lds) {
;     ...
;   if (DEEP) {
;     u32x4 ra0[4], rb0[4], ra1[4], rb1[4];
;     GM_LOAD(ra0, rb0, 0)
;     GM_LOAD(ra1, rb1, 1)
;     __syncthreads();
;     GM_STORE(ra0, rb0, 0)
;     __syncthreads();
;     for (int kt = 0; kt < nk; kt += 2) {
;       if (kt + 2 < nk) { GM_LOAD(ra0, rb0, kt + 2) }
;       GM_COMPUTE(0)
;       __builtin_amdgcn_sched_barrier(0);
;       GM_STORE(ra1, rb1, 1)
.LBB0_337:
	s_or_b64 exec, exec, s[18:19]
	s_and_b32 s18, s20, 3
	s_mul_i32 s0, s24, 0x1540
	s_mul_hi_i32 s1, s24, 0x1540
	s_add_u32 s0, s16, s0
	s_addc_u32 s1, s17, s1
	v_mov_b32_e32 v35, v169
	s_lshl_b32 s19, s18, 15
	v_mov_b64_e32 v[2:3], s[0:1]
	v_ashrrev_i32_e32 v68, 3, v35
	v_lshlrev_b32_e32 v0, 4, v35
	s_add_u32 s26, s21, s19
	v_ashrrev_i32_e32 v69, 31, v68
	v_mad_i64_i32 v[2:3], s[0:1], v68, s60, v[2:3]
	v_and_b32_e32 v0, 0x70, v0
	s_addc_u32 s27, s22, 0
	v_lshl_add_u64 v[2:3], v[2:3], 0, v[0:1]
	v_lshlrev_b64 v[4:5], 8, v[68:69]
	s_mov_b32 s0, 0x2b000
	v_lshl_add_u64 v[4:5], s[26:27], 0, v[4:5]
	v_add_co_u32_e32 v10, vcc, s0, v2
	v_lshl_add_u64 v[6:7], v[4:5], 0, v[0:1]
	s_nop 0
	v_addc_co_u32_e32 v11, vcc, 0, v3, vcc
	s_movk_i32 s0, 0x2000
	v_add_co_u32_e32 v14, vcc, s0, v6
	global_load_dwordx4 v[36:39], v[2:3], off offset:2048
	global_load_dwordx4 v[40:43], v[6:7], off
	v_addc_co_u32_e32 v15, vcc, 0, v7, vcc
	v_add_co_u32_e32 v18, vcc, s28, v2
	s_movk_i32 s0, 0x4000
	s_nop 0
	v_addc_co_u32_e32 v19, vcc, 0, v3, vcc
	global_load_dwordx4 v[44:47], v[10:11], off
	v_add_co_u32_e32 v22, vcc, s0, v6
	global_load_dwordx4 v[48:51], v[14:15], off
	s_nop 0
	v_addc_co_u32_e32 v23, vcc, 0, v7, vcc
	s_mov_b32 s0, 0x80000
	global_load_dwordx4 v[52:55], v[18:19], off offset:2048
	v_add_co_u32_e32 v26, vcc, s0, v2
	global_load_dwordx4 v[56:59], v[22:23], off
	s_nop 0
	v_addc_co_u32_e32 v27, vcc, 0, v3, vcc
	s_movk_i32 s0, 0x6000
	global_load_dwordx4 v[60:63], v[26:27], off
	v_add_co_u32_e32 v30, vcc, s0, v6
	v_xor_b32_e32 v71, v68, v35
	s_nop 0
	v_addc_co_u32_e32 v31, vcc, 0, v7, vcc
	global_load_dwordx4 v[64:67], v[30:31], off
	s_nop 0
	global_load_dwordx4 v[2:5], v[2:3], off offset:2176
	s_nop 0
	global_load_dwordx4 v[6:9], v[6:7], off offset:128
	s_nop 0
	global_load_dwordx4 v[10:13], v[10:11], off offset:128
	s_nop 0
	global_load_dwordx4 v[14:17], v[14:15], off offset:128
	s_nop 0
	global_load_dwordx4 v[18:21], v[18:19], off offset:2176
	s_nop 0
	global_load_dwordx4 v[22:25], v[22:23], off offset:128
	s_nop 0
	global_load_dwordx4 v[26:29], v[26:27], off offset:128
	s_nop 0
	global_load_dwordx4 v[30:33], v[30:31], off offset:128
	v_lshlrev_b32_e32 v69, 4, v71
	v_and_b32_e32 v69, 0x70, v69
	v_lshlrev_b32_e32 v68, 7, v68
	v_add3_u32 v120, s33, v69, v68
	s_waitcnt lgkmcnt(0)
	s_barrier
	s_mov_b32 s0, 0x1ffffc0
	v_lshrrev_b32_e32 v70, 4, v35
	v_bfe_u32 v0, v35, 4, 2
	s_waitcnt vmcnt(15)
	ds_write_b128 v120, v[36:39]
	s_waitcnt vmcnt(14)
	ds_write_b128 v120, v[40:43] offset:16384
	s_waitcnt vmcnt(13)
	ds_write_b128 v120, v[44:47] offset:4096
	s_waitcnt vmcnt(12)
	ds_write_b128 v120, v[48:51] offset:20480
	s_waitcnt vmcnt(11)
	ds_write_b128 v120, v[52:55] offset:8192
	s_waitcnt vmcnt(10)
	ds_write_b128 v120, v[56:59] offset:24576
	s_waitcnt vmcnt(9)
	ds_write_b128 v120, v[60:63] offset:12288
	s_waitcnt vmcnt(8)
	ds_write_b128 v120, v[64:67] offset:28672
	v_and_b32_e32 v36, 15, v35
	v_lshrrev_b32_e32 v37, 1, v35
	v_and_or_b32 v36, v37, s0, v36
	v_lshlrev_b32_e32 v37, 7, v35
	v_and_b32_e32 v35, 7, v35
	v_and_b32_e32 v37, 0x2780, v37
	v_bitop3_b32 v38, v70, v35, 3 bitop3:0x6c
	v_bitop3_b32 v0, v0, v35, 4 bitop3:0x36
	v_lshl_add_u32 v36, v36, 7, s33
	v_add_u32_e32 v37, s33, v37
	v_lshlrev_b32_e32 v38, 4, v38
	v_lshlrev_b32_e32 v0, 4, v0
	s_waitcnt lgkmcnt(0)
	s_barrier
	v_add_u32_e32 v121, v36, v38
	v_add_u32_e32 v122, v37, v38
	v_add_u32_e32 v35, v36, v0
	v_add_u32_e32 v0, v37, v0
	ds_read_b128 v[36:39], v121
	ds_read_b128 v[40:43], v121 offset:2048
	ds_read_b128 v[44:47], v121 offset:4096
	ds_read_b128 v[48:51], v121 offset:6144
	ds_read_b128 v[52:55], v122 offset:16384
	ds_read_b128 v[68:71], v122 offset:18432
	ds_read_b128 v[84:87], v122 offset:20480
	ds_read_b128 v[100:103], v122 offset:22528
	s_waitcnt lgkmcnt(3)
	v_mfma_f32_16x16x32_bf16 v[56:59], v[36:39], v[52:55], 0
	v_mfma_f32_16x16x32_bf16 v[60:63], v[40:43], v[52:55], 0
	v_mfma_f32_16x16x32_bf16 v[64:67], v[44:47], v[52:55], 0
	v_mfma_f32_16x16x32_bf16 v[52:55], v[48:51], v[52:55], 0
	s_waitcnt lgkmcnt(2)
	v_mfma_f32_16x16x32_bf16 v[72:75], v[36:39], v[68:71], 0
	v_mfma_f32_16x16x32_bf16 v[76:79], v[40:43], v[68:71], 0
	v_mfma_f32_16x16x32_bf16 v[80:83], v[44:47], v[68:71], 0
	v_mfma_f32_16x16x32_bf16 v[68:71], v[48:51], v[68:71], 0
	s_waitcnt lgkmcnt(1)
	v_mfma_f32_16x16x32_bf16 v[88:91], v[36:39], v[84:87], 0
	v_mfma_f32_16x16x32_bf16 v[92:95], v[40:43], v[84:87], 0
	v_mfma_f32_16x16x32_bf16 v[96:99], v[44:47], v[84:87], 0
	v_mfma_f32_16x16x32_bf16 v[84:87], v[48:51], v[84:87], 0
	s_waitcnt lgkmcnt(0)
	v_mfma_f32_16x16x32_bf16 v[36:39], v[36:39], v[100:103], 0
	v_mfma_f32_16x16x32_bf16 v[40:43], v[40:43], v[100:103], 0
	v_mfma_f32_16x16x32_bf16 v[44:47], v[44:47], v[100:103], 0
	v_mfma_f32_16x16x32_bf16 v[48:51], v[48:51], v[100:103], 0
	ds_read_b128 v[100:103], v35
	ds_read_b128 v[104:107], v35 offset:2048
	ds_read_b128 v[108:111], v35 offset:4096
	ds_read_b128 v[112:115], v35 offset:6144
	ds_read_b128 v[116:119], v0 offset:16384
	s_waitcnt lgkmcnt(0)
	v_mfma_f32_16x16x32_bf16 v[56:59], v[100:103], v[116:119], v[56:59]
	v_mfma_f32_16x16x32_bf16 v[60:63], v[104:107], v[116:119], v[60:63]
	v_mfma_f32_16x16x32_bf16 v[64:67], v[108:111], v[116:119], v[64:67]
	v_mfma_f32_16x16x32_bf16 v[52:55], v[112:115], v[116:119], v[52:55]
	ds_read_b128 v[116:119], v0 offset:18432
	s_waitcnt lgkmcnt(0)
	v_mfma_f32_16x16x32_bf16 v[72:75], v[100:103], v[116:119], v[72:75]
	v_mfma_f32_16x16x32_bf16 v[76:79], v[104:107], v[116:119], v[76:79]
	v_mfma_f32_16x16x32_bf16 v[80:83], v[108:111], v[116:119], v[80:83]
	v_mfma_f32_16x16x32_bf16 v[68:71], v[112:115], v[116:119], v[68:71]
	ds_read_b128 v[116:119], v0 offset:20480
	s_waitcnt lgkmcnt(0)
	v_mfma_f32_16x16x32_bf16 v[88:91], v[100:103], v[116:119], v[88:91]
	v_mfma_f32_16x16x32_bf16 v[92:95], v[104:107], v[116:119], v[92:95]
	v_mfma_f32_16x16x32_bf16 v[96:99], v[108:111], v[116:119], v[96:99]
	v_mfma_f32_16x16x32_bf16 v[84:87], v[112:115], v[116:119], v[84:87]
	ds_read_b128 v[116:119], v0 offset:22528
	s_waitcnt lgkmcnt(0)
	v_mfma_f32_16x16x32_bf16 v[36:39], v[100:103], v[116:119], v[36:39]
	v_mfma_f32_16x16x32_bf16 v[40:43], v[104:107], v[116:119], v[40:43]
	v_mfma_f32_16x16x32_bf16 v[44:47], v[108:111], v[116:119], v[44:47]
	v_mfma_f32_16x16x32_bf16 v[48:51], v[112:115], v[116:119], v[48:51]
	s_waitcnt vmcnt(7)
	ds_write_b128 v120, v[2:5] offset:32768
	s_waitcnt vmcnt(6)
	ds_write_b128 v120, v[6:9] offset:49152
	s_waitcnt vmcnt(5)
	ds_write_b128 v120, v[10:13] offset:36864
	s_waitcnt vmcnt(4)
	ds_write_b128 v120, v[14:17] offset:53248
	s_waitcnt vmcnt(3)
	ds_write_b128 v120, v[18:21] offset:40960
	s_waitcnt vmcnt(2)
	ds_write_b128 v120, v[22:25] offset:57344
	s_waitcnt vmcnt(1)
	ds_write_b128 v120, v[26:29] offset:45056
	s_waitcnt vmcnt(0)
	ds_write_b128 v120, v[30:33] offset:61440
	s_waitcnt lgkmcnt(0)
	s_barrier
; DI int tidx() { int t = threadIdx.x & 255; asm volatile("" : "+v"(t)); return t; }
; #define GM_LOAD(RA, RB, KT)                                                                 \
;   _Pragma("unroll") for (int i = 0; i < 4; ++i) {                                           \
;     RA[i] = *(const u32x4*)(ag + (size_t)(32 * i) * lda + (KT) * 64);                       \
;     RB[i] = *(const u32x4*)(bg + (size_t)(32 * i) * ldb + (KT) * 64);                       \
;   }
; template <bool DEEP = true>
; DI void gemm_main(f32x4 (&acc)[4][4], const u16* __restrict__ A, int lda, const u16* __restrict__ B, int ldb, int K, u16* lds) {
;     ...
;     for (int kt = 0; kt < nk; kt += 2) {
;       if (kt + 2 < nk) { GM_LOAD(ra0, rb0, kt + 2) }
;       GM_COMPUTE(0)
;       __builtin_amdgcn_sched_barrier(0);
;       GM_STORE(ra1, rb1, 1)
;       __syncthreads();
;       if (kt + 3 < nk) { GM_LOAD(ra1, rb1, kt + 3) }
;       GM_COMPUTE(1)
;       __builtin_amdgcn_sched_barrier(0);
;       if (kt + 2 < nk) { GM_STORE(ra0, rb0, 0) }
;       __syncthreads();
; DI void stage_c(const f32x4 (&acc)[4][4], float* Cs) {
;   const int tid = tidx(), lane = tid & 63, w = tid >> 6;
;   const int wm = w >> 1, wn = w & 1, fr = lane & 15, fq = lane >> 4;
; #pragma unroll
;   for (int m = 0; m < 4; ++m)
; #pragma unroll
;     for (int n = 0; n < 4; ++n)
; #pragma unroll
;       for (int j = 0; j < 4; ++j) Cs[(wm * 64 + m * 16 + fq * 4 + j) * CST + wn * 64 + n * 16 + fr] = acc[m][n][j];
;   __syncthreads();
; }
	ds_read_b128 v[2:5], v121 offset:32768
	ds_read_b128 v[6:9], v121 offset:34816
	ds_read_b128 v[10:13], v121 offset:36864
	ds_read_b128 v[14:17], v121 offset:38912
	ds_read_b128 v[18:21], v122 offset:49152
	s_waitcnt lgkmcnt(0)
	v_mfma_f32_16x16x32_bf16 v[22:25], v[2:5], v[18:21], v[56:59]
	v_mfma_f32_16x16x32_bf16 v[26:29], v[6:9], v[18:21], v[60:63]
	v_mfma_f32_16x16x32_bf16 v[30:33], v[10:13], v[18:21], v[64:67]
	v_mfma_f32_16x16x32_bf16 v[18:21], v[14:17], v[18:21], v[52:55]
	s_nop 2
	ds_read_b128 v[52:55], v122 offset:51200
	s_waitcnt lgkmcnt(0)
	v_mfma_f32_16x16x32_bf16 v[56:59], v[2:5], v[52:55], v[72:75]
	v_mfma_f32_16x16x32_bf16 v[60:63], v[6:9], v[52:55], v[76:79]
	v_mfma_f32_16x16x32_bf16 v[64:67], v[10:13], v[52:55], v[80:83]
	v_mfma_f32_16x16x32_bf16 v[52:55], v[14:17], v[52:55], v[68:71]
	s_nop 2
	ds_read_b128 v[68:71], v122 offset:53248
	s_waitcnt lgkmcnt(0)
	v_mfma_f32_16x16x32_bf16 v[72:75], v[2:5], v[68:71], v[88:91]
	v_mfma_f32_16x16x32_bf16 v[76:79], v[6:9], v[68:71], v[92:95]
	v_mfma_f32_16x16x32_bf16 v[80:83], v[10:13], v[68:71], v[96:99]
	v_mfma_f32_16x16x32_bf16 v[68:71], v[14:17], v[68:71], v[84:87]
	s_nop 2
	ds_read_b128 v[84:87], v122 offset:55296
	s_waitcnt lgkmcnt(0)
	v_mfma_f32_16x16x32_bf16 v[2:5], v[2:5], v[84:87], v[36:39]
	v_mfma_f32_16x16x32_bf16 v[6:9], v[6:9], v[84:87], v[40:43]
	v_mfma_f32_16x16x32_bf16 v[10:13], v[10:13], v[84:87], v[44:47]
	v_mfma_f32_16x16x32_bf16 v[14:17], v[14:17], v[84:87], v[48:51]
	ds_read_b128 v[36:39], v35 offset:32768
	ds_read_b128 v[40:43], v35 offset:34816
	ds_read_b128 v[44:47], v35 offset:36864
	ds_read_b128 v[48:51], v35 offset:38912
	ds_read_b128 v[84:87], v0 offset:49152
	s_waitcnt lgkmcnt(0)
	v_mfma_f32_16x16x32_bf16 v[22:25], v[36:39], v[84:87], v[22:25]
	v_mfma_f32_16x16x32_bf16 v[26:29], v[40:43], v[84:87], v[26:29]
	v_mfma_f32_16x16x32_bf16 v[30:33], v[44:47], v[84:87], v[30:33]
	v_mfma_f32_16x16x32_bf16 v[18:21], v[48:51], v[84:87], v[18:21]
	ds_read_b128 v[84:87], v0 offset:51200
	s_waitcnt lgkmcnt(0)
	v_mfma_f32_16x16x32_bf16 v[56:59], v[36:39], v[84:87], v[56:59]
	v_mfma_f32_16x16x32_bf16 v[60:63], v[40:43], v[84:87], v[60:63]
	v_mfma_f32_16x16x32_bf16 v[64:67], v[44:47], v[84:87], v[64:67]
	v_mfma_f32_16x16x32_bf16 v[52:55], v[48:51], v[84:87], v[52:55]
	ds_read_b128 v[84:87], v0 offset:53248
	s_waitcnt lgkmcnt(0)
	v_mfma_f32_16x16x32_bf16 v[72:75], v[36:39], v[84:87], v[72:75]
	v_mfma_f32_16x16x32_bf16 v[76:79], v[40:43], v[84:87], v[76:79]
	v_mfma_f32_16x16x32_bf16 v[80:83], v[44:47], v[84:87], v[80:83]
	v_mfma_f32_16x16x32_bf16 v[68:71], v[48:51], v[84:87], v[68:71]
	ds_read_b128 v[84:87], v0 offset:55296
	s_waitcnt lgkmcnt(0)
	v_mfma_f32_16x16x32_bf16 v[2:5], v[36:39], v[84:87], v[2:5]
	v_mfma_f32_16x16x32_bf16 v[6:9], v[40:43], v[84:87], v[6:9]
	v_mfma_f32_16x16x32_bf16 v[10:13], v[44:47], v[84:87], v[10:13]
	v_mfma_f32_16x16x32_bf16 v[14:17], v[48:51], v[84:87], v[14:17]
	v_mov_b32_e32 v0, v169
	s_barrier
	s_mov_b32 s0, 0xfffffc0
	v_lshrrev_b32_e32 v36, 2, v0
	v_lshrrev_b32_e32 v35, 1, v0
	v_and_b32_e32 v36, 12, v36
	v_and_or_b32 v35, v35, s0, v36
	v_and_b32_e32 v0, 0x4f, v0
	v_mul_lo_u32 v35, v35, s92
	v_lshlrev_b32_e32 v0, 2, v0
	v_add3_u32 v0, s33, v35, v0
	ds_write2_b32 v0, v22, v56 offset1:16
	ds_write2_b32 v0, v23, v57 offset0:132 offset1:148
	v_add_u32_e32 v22, 0x400, v0
	ds_write2_b32 v22, v24, v58 offset0:8 offset1:24
	ds_write2_b32 v22, v25, v59 offset0:140 offset1:156
	ds_write2_b32 v0, v72, v2 offset0:32 offset1:48
	ds_write2_b32 v0, v73, v3 offset0:164 offset1:180
	ds_write2_b32 v22, v74, v4 offset0:40 offset1:56
	ds_write2_b32 v22, v75, v5 offset0:172 offset1:188
	v_add_u32_e32 v2, 0x2000, v0
	v_add_u32_e32 v3, 0x2400, v0
	ds_write2_b32 v2, v26, v60 offset0:64 offset1:80
	ds_write2_b32 v2, v27, v61 offset0:196 offset1:212
	ds_write2_b32 v3, v28, v62 offset0:72 offset1:88
	ds_write2_b32 v3, v29, v63 offset0:204 offset1:220
	ds_write2_b32 v2, v76, v6 offset0:96 offset1:112
	ds_write2_b32 v2, v77, v7 offset0:228 offset1:244
	ds_write2_b32 v3, v78, v8 offset0:104 offset1:120
	ds_write2_b32 v3, v79, v9 offset0:236 offset1:252
	v_add_u32_e32 v2, 0x4000, v0
	v_add_u32_e32 v3, 0x4400, v0
	v_add_u32_e32 v4, 0x4800, v0
	ds_write2_b32 v2, v30, v64 offset0:128 offset1:144
	ds_write2_b32 v3, v31, v65 offset0:4 offset1:20
	ds_write2_b32 v3, v32, v66 offset0:136 offset1:152
	ds_write2_b32 v4, v33, v67 offset0:12 offset1:28
	ds_write2_b32 v2, v80, v10 offset0:160 offset1:176
	ds_write2_b32 v3, v81, v11 offset0:36 offset1:52
	ds_write2_b32 v3, v82, v12 offset0:168 offset1:184
	ds_write2_b32 v4, v83, v13 offset0:44 offset1:60
	v_add_u32_e32 v2, 0x6000, v0
	v_add_u32_e32 v3, 0x6400, v0
	v_add_u32_e32 v0, 0x6800, v0
	ds_write2_b32 v2, v18, v52 offset0:192 offset1:208
	ds_write2_b32 v3, v19, v53 offset0:68 offset1:84
	ds_write2_b32 v3, v20, v54 offset0:200 offset1:216
	ds_write2_b32 v0, v21, v55 offset0:76 offset1:92
	ds_write2_b32 v2, v68, v14 offset0:224 offset1:240
	ds_write2_b32 v3, v69, v15 offset0:100 offset1:116
	ds_write2_b32 v3, v70, v16 offset0:232 offset1:248
	ds_write2_b32 v0, v71, v17 offset0:108 offset1:124
	v_lshlrev_b32_e32 v0, 3, v34
	v_ashrrev_i32_e32 v18, 3, v34
	v_and_b32_e32 v0, 56, v0
	v_lshlrev_b32_e32 v2, 2, v0
	v_readlane_b32 s25, v254, 16
	v_mul_lo_u32 v3, v18, s92
	v_add3_u32 v17, s33, v2, v3
	v_lshl_add_u32 v16, v18, 2, s25
	s_waitcnt lgkmcnt(0)
	s_barrier
; DI u32x4 pack8(const float* f) { u32x4 o; o.x = pack2(f[0], f[1]); o.y = pack2(f[2], f[3]); o.z = pack2(f[4], f[5]); o.w = pack2(f[6], f[7]); return o; }
; DI void kv_tile(PREF p, int l, int idx, unsigned char* ldsb) {
;     ...
; #pragma unroll
;   for (int q = 0; q < 4; ++q) {
;     int r = (tid >> 3) + 32 * q, c = (tid & 7) * 8;
;     float rs = aux[r];
;     float v[8]; ld8(Cs + r * CST + c, v);
; #pragma unroll
;     for (int j = 0; j < 8; ++j) v[j] *= rs;
;     *(u32x4*)(p.Km + (size_t)(row0 + r) * 384 + head * 96 + c) = pack8(v);
;   }
;   {
;     int b = row0 >> 12, s0 = row0 & 4095;
; #pragma unroll
;     for (int q = 0; q < 4; ++q) {
;       int item = tid + 256 * q; int c = item & 63, rg = item >> 6;
;       float v[8];
; #pragma unroll
;       for (int j = 0; j < 8; ++j) v[j] = Cs[(rg * 8 + j) * CST + 64 + c] * aux[rg * 8 + j];
;       *(u32x4*)(p.Vmt + ((size_t)(b * 4 + head) * 64 + c) * S_ + s0 + rg * 8) = pack8(v);
;     }
	ds_read2_b32 v[10:11], v16 offset1:32
	ds_read_b128 v[2:5], v17
	ds_read_b128 v[6:9], v17 offset:16
	s_mul_i32 s52, s18, 0xc0
	s_add_u32 s0, s12, s52
	s_addc_u32 s1, s13, 0
	v_lshlrev_b32_e32 v0, 1, v0
	v_lshl_add_u64 v[12:13], s[0:1], 0, v[0:1]
	s_waitcnt lgkmcnt(1)
	v_mul_f32_e32 v0, v10, v2
	v_mul_f32_e32 v2, v10, v3
	v_mul_f32_e32 v3, v10, v4
	v_mul_f32_e32 v4, v10, v5
	s_waitcnt lgkmcnt(0)
	v_mul_f32_e32 v5, v10, v6
	v_cvt_pk_bf16_f32 v2, v0, v2
	v_add_u32_e32 v0, s24, v18
	v_mul_f32_e32 v6, v10, v7
	v_mul_f32_e32 v7, v10, v8
	v_mul_f32_e32 v8, v10, v9
	v_cvt_pk_bf16_f32 v3, v3, v4
	v_cvt_pk_bf16_f32 v4, v5, v6
	v_cvt_pk_bf16_f32 v5, v7, v8
	v_mad_i64_i32 v[14:15], s[0:1], v0, s96, v[12:13]
	ds_read_b128 v[6:9], v17 offset:16896
	global_store_dwordx4 v[14:15], v[2:5], off
	ds_read_b128 v[2:5], v17 offset:16912
	s_and_b32 s19, s23, 0xf80
	v_and_b32_e32 v54, 1, v34
	s_waitcnt lgkmcnt(1)
	v_mul_f32_e32 v6, v11, v6
	v_mul_f32_e32 v7, v11, v7
	s_waitcnt lgkmcnt(0)
	v_mul_f32_e32 v14, v11, v3
	v_mul_f32_e32 v10, v11, v2
	v_mul_f32_e32 v15, v11, v4
	v_mul_f32_e32 v5, v11, v5
	v_cvt_pk_bf16_f32 v4, v10, v14
	v_add_u32_e32 v14, 32, v0
	v_mul_f32_e32 v8, v11, v8
	v_mul_f32_e32 v9, v11, v9
	v_cvt_pk_bf16_f32 v2, v6, v7
	v_cvt_pk_bf16_f32 v3, v8, v9
	v_cvt_pk_bf16_f32 v5, v15, v5
	v_mad_i64_i32 v[14:15], s[0:1], v14, s96, v[12:13]
	ds_read2_b32 v[10:11], v16 offset0:64 offset1:96
	ds_read_b128 v[6:9], v17 offset:33792
	global_store_dwordx4 v[14:15], v[2:5], off
	ds_read_b128 v[2:5], v17 offset:33808
	v_cmp_eq_u32_e32 vcc, 0, v54
	s_waitcnt lgkmcnt(1)
	v_mul_f32_e32 v6, v10, v6
	v_mul_f32_e32 v7, v10, v7
	v_mul_f32_e32 v8, v10, v8
	v_mul_f32_e32 v9, v10, v9
	s_waitcnt lgkmcnt(0)
	v_mul_f32_e32 v14, v10, v2
	v_mul_f32_e32 v15, v10, v3
	v_mul_f32_e32 v16, v10, v4
	v_mul_f32_e32 v5, v10, v5
	v_add_u32_e32 v10, 64, v0
	v_cvt_pk_bf16_f32 v2, v6, v7
	v_cvt_pk_bf16_f32 v3, v8, v9
	v_cvt_pk_bf16_f32 v4, v14, v15
	v_cvt_pk_bf16_f32 v5, v16, v5
	ds_read_b128 v[6:9], v17 offset:50688
	v_mad_i64_i32 v[14:15], s[0:1], v10, s96, v[12:13]
	global_store_dwordx4 v[14:15], v[2:5], off
	ds_read_b128 v[2:5], v17 offset:50704
	s_waitcnt lgkmcnt(1)
	v_mul_f32_e32 v6, v11, v6
	v_mul_f32_e32 v7, v11, v7
	v_add_u32_e32 v0, 0x60, v0
	v_mul_f32_e32 v8, v11, v8
	s_waitcnt lgkmcnt(0)
	v_mul_f32_e32 v10, v11, v2
	v_cvt_pk_bf16_f32 v2, v6, v7
	v_mad_i64_i32 v[6:7], s[0:1], v0, s96, v[12:13]
	s_ashr_i32 s0, s20, 5
	s_and_b32 s0, s0, -4
	s_or_b32 s0, s0, s18
	s_ashr_i32 s1, s0, 31
	v_mul_f32_e32 v14, v11, v3
	v_mul_f32_e32 v15, v11, v4
	v_mul_f32_e32 v5, v11, v5
	v_cvt_pk_bf16_f32 v4, v10, v14
	s_lshl_b64 s[0:1], s[0:1], 19
	v_mul_f32_e32 v9, v11, v9
	v_cvt_pk_bf16_f32 v3, v8, v9
	v_cvt_pk_bf16_f32 v5, v15, v5
	global_store_dwordx4 v[6:7], v[2:5], off
	s_add_u32 s0, s14, s0
	s_addc_u32 s1, s15, s1
	v_and_b32_e32 v4, 63, v34
	v_lshlrev_b32_e32 v0, 13, v4
	v_and_b32_e32 v12, -8, v18
	v_lshl_add_u64 v[2:3], s[0:1], 0, v[0:1]
	v_mul_lo_u32 v0, v12, s92
	v_lshlrev_b32_e32 v20, 2, v4
	s_lshl_b32 s0, s19, 1
	s_mov_b32 s1, s53
	v_add3_u32 v0, s33, v0, v20
	v_lshl_add_u32 v6, v12, 2, s25
	v_lshl_add_u64 v[10:11], v[2:3], 0, s[0:1]
	ds_read2_b32 v[14:15], v0 offset0:64 offset1:196
	ds_read_b128 v[2:5], v6
	v_add_u32_e32 v7, 0x400, v0
	ds_read2_b32 v[16:17], v7 offset0:72 offset1:204
	ds_read_b96 v[6:8], v6 offset:16
	ds_read_b32 v9, v0 offset:3424
	v_add_u32_e32 v0, 0x800, v0
	v_ashrrev_i32_e32 v13, 31, v12
	s_waitcnt lgkmcnt(3)
	v_mul_f32_e32 v19, v14, v2
	v_mul_f32_e32 v15, v15, v3
	ds_read2_b32 v[2:3], v0 offset0:80 offset1:212
	v_or_b32_e32 v0, 7, v18
	v_mul_lo_u32 v14, v0, s92
	s_waitcnt lgkmcnt(3)
	v_mul_f32_e32 v4, v16, v4
	v_add3_u32 v16, s33, v14, v20
	v_add_u32_e32 v14, 0x100, v34
	v_ashrrev_i32_e32 v21, 3, v14
	v_and_b32_e32 v14, -8, v21
	v_mul_f32_e32 v5, v17, v5
	v_lshl_add_u32 v0, v0, 2, s25
	v_mul_lo_u32 v17, v14, s92
	v_add3_u32 v18, s33, v17, v20
	ds_read_b32 v16, v16 offset:256
	ds_read_b32 v0, v0
	ds_read_b32 v22, v18 offset:3424
	s_waitcnt lgkmcnt(3)
	v_mul_f32_e32 v6, v2, v6
	v_mul_f32_e32 v7, v3, v7
	v_cvt_pk_bf16_f32 v3, v4, v5
	s_waitcnt lgkmcnt(1)
	v_mul_f32_e32 v0, v16, v0
	v_cvt_pk_bf16_f32 v4, v6, v7
	v_lshl_add_u64 v[6:7], v[12:13], 1, v[10:11]
	v_mul_f32_e32 v8, v9, v8
	v_cvt_pk_bf16_f32 v2, v19, v15
	v_cvt_pk_bf16_f32 v5, v8, v0
	global_store_dwordx4 v[6:7], v[2:5], off
	ds_read2_b32 v[12:13], v18 offset0:64 offset1:196
	v_lshl_add_u32 v0, v14, 2, s25
	ds_read_b128 v[2:5], v0
	ds_read_b96 v[6:8], v0 offset:16
	v_add_u32_e32 v0, 0x400, v18
	ds_read2_b32 v[16:17], v0 offset0:72 offset1:204
	v_add_u32_e32 v0, 0x800, v18
	ds_read2_b32 v[18:19], v0 offset0:80 offset1:212
	s_waitcnt lgkmcnt(3)
	v_mul_f32_e32 v0, v12, v2
	v_or_b32_e32 v2, 7, v21
	v_mul_f32_e32 v9, v13, v3
	v_mul_lo_u32 v3, v2, s92
	v_add3_u32 v3, s33, v3, v20
	v_lshl_add_u32 v2, v2, 2, s25
	s_waitcnt lgkmcnt(1)
	v_mul_f32_e32 v13, v16, v4
	v_mul_f32_e32 v16, v17, v5
	s_waitcnt lgkmcnt(0)
	v_mul_f32_e32 v17, v18, v6
	v_mul_f32_e32 v18, v19, v7
	ds_read_b32 v6, v3 offset:256
	ds_read_b32 v7, v2
	v_add_u32_e32 v2, 0x200, v34
	v_ashrrev_i32_e32 v21, 3, v2
	v_and_b32_e32 v12, -8, v21
	v_ashrrev_i32_e32 v15, 31, v14
	v_mul_lo_u32 v2, v12, s92
	v_mul_f32_e32 v19, v22, v8
	v_add3_u32 v22, s33, v2, v20
	v_lshl_add_u32 v23, v12, 2, s25
	v_lshl_add_u64 v[14:15], v[14:15], 1, v[10:11]
	ds_read_b128 v[2:5], v23
	ds_read_b32 v24, v22 offset:3424
	s_waitcnt lgkmcnt(2)
	v_mul_f32_e32 v25, v6, v7
	v_cvt_pk_bf16_f32 v6, v0, v9
	v_cvt_pk_bf16_f32 v7, v13, v16
	v_cvt_pk_bf16_f32 v8, v17, v18
	v_cvt_pk_bf16_f32 v9, v19, v25
	global_store_dwordx4 v[14:15], v[6:9], off
	ds_read2_b32 v[14:15], v22 offset0:64 offset1:196
	v_add_u32_e32 v0, 0x400, v22
	ds_read2_b32 v[16:17], v0 offset0:72 offset1:204
	ds_read_b96 v[6:8], v23 offset:16
	v_ashrrev_i32_e32 v13, 31, v12
	s_waitcnt lgkmcnt(2)
; DI u32x4 pack8(const float* f) { u32x4 o; o.x = pack2(f[0], f[1]); o.y = pack2(f[2], f[3]); o.z = pack2(f[4], f[5]); o.w = pack2(f[6], f[7]); return o; }
; DI void kv_tile(PREF p, int l, int idx, unsigned char* ldsb) {
;     ...
;   {
;     int b = row0 >> 12, s0 = row0 & 4095;
; #pragma unroll
;     for (int q = 0; q < 4; ++q) {
;       int item = tid + 256 * q; int c = item & 63, rg = item >> 6;
;       float v[8];
; #pragma unroll
;       for (int j = 0; j < 8; ++j) v[j] = Cs[(rg * 8 + j) * CST + 64 + c] * aux[rg * 8 + j];
;       *(u32x4*)(p.Vmt + ((size_t)(b * 4 + head) * 64 + c) * S_ + s0 + rg * 8) = pack8(v);
;     }
;   }
;   {
;     int r = tid >> 1, half = tid & 1;
;     int t = row0 + r, s = t & 4095;
;     const u16* src = p.hb + (size_t)t * HW + OFF_KR;
;     float x1[16], x2[16];
;     unpack8(*(const u32x4*)(src), x1); unpack8(*(const u32x4*)(src + 8), x1 + 8);
;     unpack8(*(const u32x4*)(src + 16), x2); unpack8(*(const u32x4*)(src + 24), x2 + 8);
;     const float* cs = p.rcos + s * 16; const float* sn = p.rsin + s * 16;
	v_mul_f32_e32 v0, v14, v2
	v_or_b32_e32 v14, 7, v21
	v_mul_f32_e32 v9, v15, v3
	s_waitcnt lgkmcnt(1)
	v_mul_f32_e32 v4, v16, v4
	v_mul_lo_u32 v15, v14, s92
	v_lshl_add_u32 v16, v14, 2, s25
	v_add_u32_e32 v14, 0x300, v34
	v_add_u32_e32 v2, 0x800, v22
	v_ashrrev_i32_e32 v18, 3, v14
	ds_read2_b32 v[2:3], v2 offset0:80 offset1:212
	v_and_b32_e32 v14, -8, v18
	v_mul_f32_e32 v5, v17, v5
	v_add3_u32 v15, s33, v15, v20
	v_mul_lo_u32 v17, v14, s92
	v_add3_u32 v19, s33, v17, v20
	ds_read_b32 v15, v15 offset:256
	ds_read_b32 v16, v16
	ds_read_b32 v21, v19 offset:3424
	s_waitcnt lgkmcnt(3)
	v_mul_f32_e32 v6, v2, v6
	v_mul_f32_e32 v7, v3, v7
	v_mul_f32_e32 v8, v24, v8
	s_waitcnt lgkmcnt(1)
	v_mul_f32_e32 v15, v15, v16
	v_cvt_pk_bf16_f32 v2, v0, v9
	v_cvt_pk_bf16_f32 v3, v4, v5
	v_cvt_pk_bf16_f32 v4, v6, v7
	v_cvt_pk_bf16_f32 v5, v8, v15
	v_lshl_add_u64 v[6:7], v[12:13], 1, v[10:11]
	v_lshl_add_u32 v0, v14, 2, s25
	global_store_dwordx4 v[6:7], v[2:5], off
	ds_read2_b32 v[12:13], v19 offset0:64 offset1:196
	ds_read_b128 v[2:5], v0
	v_add_u32_e32 v6, 0x400, v19
	ds_read2_b32 v[16:17], v6 offset0:72 offset1:204
	ds_read_b96 v[6:8], v0 offset:16
	v_ashrrev_i32_e32 v15, 31, v14
	s_waitcnt lgkmcnt(2)
	v_mul_f32_e32 v0, v12, v2
	v_add_u32_e32 v2, 0x800, v19
	v_or_b32_e32 v12, 7, v18
	v_mul_f32_e32 v9, v13, v3
	ds_read2_b32 v[2:3], v2 offset0:80 offset1:212
	v_mul_lo_u32 v13, v12, s92
	v_add3_u32 v13, s33, v13, v20
	v_lshl_add_u32 v12, v12, 2, s25
	ds_read_b32 v13, v13 offset:256
	ds_read_b32 v12, v12
	s_waitcnt lgkmcnt(4)
	v_mul_f32_e32 v4, v16, v4
	s_waitcnt lgkmcnt(2)
	v_mul_f32_e32 v6, v2, v6
	v_mul_f32_e32 v7, v3, v7
	v_mul_f32_e32 v5, v17, v5
	v_cvt_pk_bf16_f32 v2, v0, v9
	v_cvt_pk_bf16_f32 v3, v4, v5
	v_cvt_pk_bf16_f32 v4, v6, v7
	v_lshl_add_u64 v[6:7], v[14:15], 1, v[10:11]
	v_ashrrev_i32_e32 v0, 1, v34
	v_mul_f32_e32 v8, v21, v8
	s_waitcnt lgkmcnt(0)
	v_mul_f32_e32 v12, v13, v12
	v_cvt_pk_bf16_f32 v5, v8, v12
	global_store_dwordx4 v[6:7], v[2:5], off
	v_add_u32_e32 v0, s24, v0
	v_lshlrev_b32_e32 v10, 6, v0
	v_mov_b64_e32 v[2:3], s[16:17]
	v_mad_i64_i32 v[30:31], s[0:1], v0, s60, v[2:3]
	global_load_dwordx4 v[2:5], v[30:31], off offset:2304
	global_load_dwordx4 v[6:9], v[30:31], off offset:2336
	v_and_b32_e32 v46, 0x3ffc0, v10
	global_load_dwordx4 v[10:13], v46, s[10:11]
	global_load_dwordx4 v[14:17], v46, s[8:9]
	global_load_dwordx4 v[18:21], v46, s[10:11] offset:16
	global_load_dwordx4 v[22:25], v46, s[8:9] offset:16
	global_load_dwordx4 v[26:29], v[30:31], off offset:2320
	s_nop 0
	global_load_dwordx4 v[30:33], v[30:31], off offset:2352
	s_nop 0
	global_load_dwordx4 v[34:37], v46, s[8:9] offset:48
	global_load_dwordx4 v[38:41], v46, s[10:11] offset:48
	global_load_dwordx4 v[42:45], v46, s[8:9] offset:32
	s_nop 0
	global_load_dwordx4 v[46:49], v46, s[10:11] offset:32
	s_add_i32 s20, s20, s71
	s_add_i32 s23, s23, s85
	s_cmpk_gt_i32 s20, 0x3ff
	s_waitcnt vmcnt(9)
	v_mov_b32_e32 v52, v10
	s_waitcnt vmcnt(8)
	v_mov_b32_e32 v53, v14
	v_lshlrev_b32_e32 v50, 16, v2
	v_lshlrev_b32_e32 v51, 16, v6
	v_pk_mul_f32 v[52:53], v[52:53], v[50:51]
	s_nop 0
	v_add_f32_e32 v55, v53, v52
	v_mov_b32_e32 v52, v14
	v_mov_b32_e32 v53, v10
	v_pk_mul_f32 v[50:51], v[52:53], v[50:51]
	v_mov_b32_e32 v14, v11
	v_sub_f32_e32 v10, v50, v51
	v_cndmask_b32_e32 v55, v55, v10, vcc
	v_and_b32_e32 v51, 0xffff0000, v6
	v_and_b32_e32 v50, 0xffff0000, v2
	v_mov_b32_e32 v10, v15
	v_pk_mul_f32 v[10:11], v[10:11], v[50:51]
	v_pk_mul_f32 v[52:53], v[14:15], v[50:51]
	v_sub_f32_e32 v6, v10, v11
	v_lshlrev_b32_e32 v11, 16, v7
	v_lshlrev_b32_e32 v10, 16, v3
	v_mov_b32_e32 v14, v12
	v_mov_b32_e32 v15, v16
	v_add_f32_e32 v2, v53, v52
	v_pk_mul_f32 v[14:15], v[14:15], v[10:11]
	v_cndmask_b32_e32 v50, v2, v6, vcc
	v_add_f32_e32 v2, v15, v14
	v_mov_b32_e32 v14, v16
	v_mov_b32_e32 v15, v12
	v_pk_mul_f32 v[10:11], v[14:15], v[10:11]
	v_and_b32_e32 v7, 0xffff0000, v7
	v_sub_f32_e32 v6, v10, v11
	v_cndmask_b32_e32 v10, v2, v6, vcc
	v_and_b32_e32 v6, 0xffff0000, v3
	v_mov_b32_e32 v16, v13
	v_pk_mul_f32 v[2:3], v[16:17], v[6:7]
	v_mov_b32_e32 v12, v17
	v_add_f32_e32 v11, v3, v2
	v_pk_mul_f32 v[2:3], v[12:13], v[6:7]
	s_waitcnt vmcnt(7)
	v_mov_b32_e32 v6, v18
	v_sub_f32_e32 v2, v2, v3
	v_cndmask_b32_e32 v11, v11, v2, vcc
	v_lshlrev_b32_e32 v3, 16, v8
	v_lshlrev_b32_e32 v2, 16, v4
	s_waitcnt vmcnt(6)
; DI u32x4 pack8(const float* f) { u32x4 o; o.x = pack2(f[0], f[1]); o.y = pack2(f[2], f[3]); o.z = pack2(f[4], f[5]); o.w = pack2(f[6], f[7]); return o; }
; DI void kv_tile(PREF p, int l, int idx, unsigned char* ldsb) {
;     ...
;   {
;     int r = tid >> 1, half = tid & 1;
;     int t = row0 + r, s = t & 4095;
;     const u16* src = p.hb + (size_t)t * HW + OFF_KR;
;     float x1[16], x2[16];
;     unpack8(*(const u32x4*)(src), x1); unpack8(*(const u32x4*)(src + 8), x1 + 8);
;     unpack8(*(const u32x4*)(src + 16), x2); unpack8(*(const u32x4*)(src + 24), x2 + 8);
;     const float* cs = p.rcos + s * 16; const float* sn = p.rsin + s * 16;
;     float ov[16];
; #pragma unroll
;     for (int i = 0; i < 16; ++i) ov[i] = half ? (x2[i] * cs[i] + x1[i] * sn[i]) : (x1[i] * cs[i] - x2[i] * sn[i]);
;     u16* dst = p.Km + (size_t)t * 384 + head * 96 + 64 + half * 16;
;     *(u32x4*)dst = pack8(ov); *(u32x4*)(dst + 8) = pack8(ov + 8);
;   }
	v_mov_b32_e32 v7, v22
	v_pk_mul_f32 v[6:7], v[6:7], v[2:3]
	s_nop 0
	v_add_f32_e32 v12, v7, v6
	v_mov_b32_e32 v6, v22
	v_mov_b32_e32 v7, v18
	v_pk_mul_f32 v[2:3], v[6:7], v[2:3]
	v_mov_b32_e32 v22, v19
	v_sub_f32_e32 v2, v2, v3
	v_cndmask_b32_e32 v12, v12, v2, vcc
	v_and_b32_e32 v3, 0xffff0000, v8
	v_and_b32_e32 v2, 0xffff0000, v4
	v_mov_b32_e32 v18, v23
	v_pk_mul_f32 v[6:7], v[22:23], v[2:3]
	v_pk_mul_f32 v[2:3], v[18:19], v[2:3]
	v_add_f32_e32 v4, v7, v6
	v_sub_f32_e32 v2, v2, v3
	v_cndmask_b32_e32 v8, v4, v2, vcc
	v_lshlrev_b32_e32 v3, 16, v9
	v_lshlrev_b32_e32 v2, 16, v5
	v_mov_b32_e32 v6, v20
	v_mov_b32_e32 v7, v24
	v_pk_mul_f32 v[6:7], v[6:7], v[2:3]
	s_nop 0
	v_add_f32_e32 v4, v7, v6
	v_mov_b32_e32 v6, v24
	v_mov_b32_e32 v7, v20
	v_pk_mul_f32 v[2:3], v[6:7], v[2:3]
	v_mov_b32_e32 v24, v21
	v_sub_f32_e32 v2, v2, v3
	v_cndmask_b32_e32 v13, v4, v2, vcc
	v_and_b32_e32 v3, 0xffff0000, v9
	v_and_b32_e32 v2, 0xffff0000, v5
	v_mov_b32_e32 v20, v25
	v_pk_mul_f32 v[4:5], v[24:25], v[2:3]
	v_pk_mul_f32 v[2:3], v[20:21], v[2:3]
	v_add_f32_e32 v4, v5, v4
	v_sub_f32_e32 v2, v2, v3
	v_cndmask_b32_e32 v9, v4, v2, vcc
	s_waitcnt vmcnt(4)
	v_lshlrev_b32_e32 v3, 16, v30
	v_lshlrev_b32_e32 v2, 16, v26
	s_waitcnt vmcnt(0)
	v_mov_b32_e32 v4, v46
	v_mov_b32_e32 v5, v42
	v_pk_mul_f32 v[4:5], v[4:5], v[2:3]
	s_nop 0
	v_add_f32_e32 v6, v5, v4
	v_mov_b32_e32 v4, v42
	v_mov_b32_e32 v5, v46
	v_pk_mul_f32 v[2:3], v[4:5], v[2:3]
	v_mov_b32_e32 v42, v47
	v_sub_f32_e32 v2, v2, v3
	v_cndmask_b32_e32 v14, v6, v2, vcc
	v_and_b32_e32 v3, 0xffff0000, v30
	v_and_b32_e32 v2, 0xffff0000, v26
	v_mov_b32_e32 v46, v43
	v_pk_mul_f32 v[4:5], v[42:43], v[2:3]
	v_pk_mul_f32 v[2:3], v[46:47], v[2:3]
	v_add_f32_e32 v4, v5, v4
	v_sub_f32_e32 v2, v2, v3
	v_cndmask_b32_e32 v15, v4, v2, vcc
	v_lshlrev_b32_e32 v3, 16, v31
	v_lshlrev_b32_e32 v2, 16, v27
	v_mov_b32_e32 v4, v48
	v_mov_b32_e32 v5, v44
	v_pk_mul_f32 v[4:5], v[4:5], v[2:3]
	s_nop 0
	v_add_f32_e32 v6, v5, v4
	v_mov_b32_e32 v4, v44
	v_mov_b32_e32 v5, v48
	v_pk_mul_f32 v[2:3], v[4:5], v[2:3]
	v_mov_b32_e32 v44, v49
	v_sub_f32_e32 v2, v2, v3
	v_cndmask_b32_e32 v16, v6, v2, vcc
	v_and_b32_e32 v3, 0xffff0000, v31
	v_and_b32_e32 v2, 0xffff0000, v27
	v_mov_b32_e32 v48, v45
	v_pk_mul_f32 v[4:5], v[44:45], v[2:3]
	v_pk_mul_f32 v[2:3], v[48:49], v[2:3]
	v_add_f32_e32 v4, v5, v4
	v_sub_f32_e32 v2, v2, v3
	v_cndmask_b32_e32 v17, v4, v2, vcc
	v_lshlrev_b32_e32 v3, 16, v32
	v_lshlrev_b32_e32 v2, 16, v28
	v_mov_b32_e32 v4, v38
	v_mov_b32_e32 v5, v34
	v_pk_mul_f32 v[4:5], v[4:5], v[2:3]
	s_nop 0
	v_add_f32_e32 v6, v5, v4
	v_mov_b32_e32 v4, v34
	v_mov_b32_e32 v5, v38
	v_pk_mul_f32 v[2:3], v[4:5], v[2:3]
	v_mov_b32_e32 v34, v39
	v_sub_f32_e32 v2, v2, v3
	v_cndmask_b32_e32 v18, v6, v2, vcc
	v_and_b32_e32 v3, 0xffff0000, v32
	v_and_b32_e32 v2, 0xffff0000, v28
	v_mov_b32_e32 v38, v35
	v_pk_mul_f32 v[4:5], v[34:35], v[2:3]
	v_pk_mul_f32 v[2:3], v[38:39], v[2:3]
	v_add_f32_e32 v4, v5, v4
	v_sub_f32_e32 v2, v2, v3
	v_cndmask_b32_e32 v19, v4, v2, vcc
	v_lshlrev_b32_e32 v3, 16, v33
	v_lshlrev_b32_e32 v2, 16, v29
	v_mov_b32_e32 v4, v40
	v_mov_b32_e32 v5, v36
	v_pk_mul_f32 v[4:5], v[4:5], v[2:3]
	s_nop 0
	v_add_f32_e32 v6, v5, v4
	v_mov_b32_e32 v4, v36
	v_mov_b32_e32 v5, v40
	v_pk_mul_f32 v[2:3], v[4:5], v[2:3]
	v_mov_b32_e32 v36, v41
	v_sub_f32_e32 v2, v2, v3
	v_cndmask_b32_e32 v20, v6, v2, vcc
	v_and_b32_e32 v3, 0xffff0000, v33
	v_and_b32_e32 v2, 0xffff0000, v29
	v_mov_b32_e32 v40, v37
	v_pk_mul_f32 v[4:5], v[36:37], v[2:3]
	v_pk_mul_f32 v[2:3], v[40:41], v[2:3]
	v_add_f32_e32 v4, v5, v4
	v_sub_f32_e32 v2, v2, v3
	v_cndmask_b32_e32 v21, v4, v2, vcc
	v_mov_b64_e32 v[2:3], s[12:13]
	v_mad_i64_i32 v[2:3], s[0:1], v0, s96, v[2:3]
	v_lshl_add_u64 v[2:3], v[2:3], 0, s[52:53]
	v_lshlrev_b32_e32 v0, 5, v54
	v_lshl_add_u64 v[6:7], v[2:3], 0, v[0:1]
	v_cvt_pk_bf16_f32 v2, v55, v50
	v_cvt_pk_bf16_f32 v3, v10, v11
	v_cvt_pk_bf16_f32 v4, v12, v8
	v_cvt_pk_bf16_f32 v5, v13, v9
	global_store_dwordx4 v[6:7], v[2:5], off offset:128
	s_nop 1
	v_cvt_pk_bf16_f32 v2, v14, v15
	v_cvt_pk_bf16_f32 v3, v16, v17
	v_cvt_pk_bf16_f32 v4, v18, v19
	v_cvt_pk_bf16_f32 v5, v20, v21
	global_store_dwordx4 v[6:7], v[2:5], off offset:144
	s_cbranch_scc1 .LBB0_340

; #define GM_LOAD(RA, RB, KT)                                                                 \
;   _Pragma("unroll") for (int i = 0; i < 4; ++i) {                                           \
;     RA[i] = *(const u32x4*)(ag + (size_t)(32 * i) * lda + (KT) * 64);                       \
;     RB[i] = *(const u32x4*)(bg + (size_t)(32 * i) * ldb + (KT) * 64);                       \
;   }
; template <bool DEEP = true>
; DI void gemm_main(f32x4 (&acc)[4][4], const u16* __restrict__ A, int lda, const u16* __restrict__ B, int ldb, int K, u16* lds) {
;     ...
;   if (DEEP) {
;     u32x4 ra0[4], rb0[4], ra1[4], rb1[4];
;     GM_LOAD(ra0, rb0, 0)
;     GM_LOAD(ra1, rb1, 1)
;     __syncthreads();
;     GM_STORE(ra0, rb0, 0)
;     __syncthreads();
;     for (int kt = 0; kt < nk; kt += 2) {
;       if (kt + 2 < nk) { GM_LOAD(ra0, rb0, kt + 2) }
;       GM_COMPUTE(0)
.LBB0_348:
	s_or_b64 exec, exec, s[8:9]
	s_mul_i32 s19, s19, 3
	s_sub_i32 s0, s20, s19
	s_lshl_b32 s8, s0, 7
	s_mul_i32 s0, s18, 0x1540
	s_mul_hi_i32 s1, s18, 0x1540
	s_add_u32 s0, s10, s0
	s_addc_u32 s1, s11, s1
	s_ashr_i32 s9, s8, 31
	v_mov_b32_e32 v83, v169
	s_lshl_b64 s[16:17], s[8:9], 9
	v_mov_b64_e32 v[2:3], s[0:1]
	v_ashrrev_i32_e32 v34, 3, v83
	v_lshlrev_b32_e32 v0, 4, v83
	s_add_u32 s16, s21, s16
	v_ashrrev_i32_e32 v35, 31, v34
	v_mad_i64_i32 v[2:3], s[0:1], v34, s60, v[2:3]
	v_and_b32_e32 v0, 0x70, v0
	s_addc_u32 s17, s22, s17
	v_lshl_add_u64 v[66:67], v[2:3], 0, v[0:1]
	v_lshlrev_b64 v[2:3], 9, v[34:35]
	s_mov_b32 s0, 0x2a000
	v_lshl_add_u64 v[2:3], s[16:17], 0, v[2:3]
	v_add_co_u32_e32 v70, vcc, s0, v66
	v_lshl_add_u64 v[68:69], v[2:3], 0, v[0:1]
	s_nop 0
	v_addc_co_u32_e32 v71, vcc, 0, v67, vcc
	s_movk_i32 s0, 0x4000
	v_add_co_u32_e32 v72, vcc, s0, v68
	s_mov_b32 s0, 0x8000
	s_nop 0
	v_addc_co_u32_e32 v73, vcc, 0, v69, vcc
	v_add_co_u32_e32 v74, vcc, s28, v66
	global_load_dwordx4 v[2:5], v[66:67], off offset:1536
	global_load_dwordx4 v[6:9], v[68:69], off
	v_addc_co_u32_e32 v75, vcc, 0, v67, vcc
	v_add_co_u32_e32 v76, vcc, s0, v68
	s_mov_b32 s0, 0x7f000
	s_nop 0
	v_addc_co_u32_e32 v77, vcc, 0, v69, vcc
	global_load_dwordx4 v[10:13], v[70:71], off offset:3584
	v_add_co_u32_e32 v78, vcc, s0, v66
	global_load_dwordx4 v[18:21], v[74:75], off offset:1536
	s_nop 0
	v_addc_co_u32_e32 v79, vcc, 0, v67, vcc
	global_load_dwordx4 v[26:29], v[78:79], off offset:3584
	s_mov_b32 s0, 0xc000
	global_load_dwordx4 v[14:17], v[72:73], off
	v_add_co_u32_e32 v80, vcc, s0, v68
	global_load_dwordx4 v[22:25], v[76:77], off
	s_nop 0
	v_addc_co_u32_e32 v81, vcc, 0, v69, vcc
	global_load_dwordx4 v[30:33], v[80:81], off
	v_xor_b32_e32 v0, v34, v83
	v_lshlrev_b32_e32 v0, 4, v0
	v_lshlrev_b32_e32 v34, 7, v34
	v_and_b32_e32 v0, 0x70, v0
	v_add3_u32 v85, s33, v0, v34
	global_load_dwordx4 v[46:49], v[66:67], off offset:1664
	global_load_dwordx4 v[42:45], v[70:71], off offset:3712
	global_load_dwordx4 v[38:41], v[74:75], off offset:1664
	global_load_dwordx4 v[34:37], v[78:79], off offset:3712
	global_load_dwordx4 v[62:65], v[68:69], off offset:128
	global_load_dwordx4 v[58:61], v[72:73], off offset:128
	global_load_dwordx4 v[54:57], v[76:77], off offset:128
	global_load_dwordx4 v[50:53], v[80:81], off offset:128
	s_waitcnt lgkmcnt(0)
	s_barrier
	v_and_b32_e32 v84, 15, v83
	v_lshrrev_b32_e32 v86, 1, v83
	s_mov_b32 s0, 0x1ffffc0
	v_and_or_b32 v84, v86, s0, v84
	v_lshrrev_b32_e32 v0, 4, v83
	v_bfe_u32 v87, v83, 4, 2
	v_lshl_add_u32 v88, v84, 7, s33
	v_lshlrev_b32_e32 v84, 7, v83
	v_and_b32_e32 v83, 7, v83
	v_and_b32_e32 v84, 0x2780, v84
	v_bitop3_b32 v0, v0, v83, 3 bitop3:0x6c
	v_add_u32_e32 v89, s33, v84
	v_lshlrev_b32_e32 v0, 4, v0
	v_add_u32_e32 v86, v88, v0
	v_add_u32_e32 v84, v89, v0
	v_bitop3_b32 v0, v87, v83, 4 bitop3:0x36
	v_lshlrev_b32_e32 v0, 4, v0
	v_add_u32_e32 v83, v88, v0
	v_add_u32_e32 v0, v89, v0
	s_waitcnt vmcnt(15)
	ds_write_b128 v85, v[2:5]
	s_waitcnt vmcnt(13)
	ds_write_b128 v85, v[10:13] offset:4096
	s_waitcnt vmcnt(12)
	ds_write_b128 v85, v[18:21] offset:8192
	s_waitcnt vmcnt(11)
	ds_write_b128 v85, v[26:29] offset:12288
	ds_write_b128 v85, v[6:9] offset:16384
	s_waitcnt vmcnt(10)
	ds_write_b128 v85, v[14:17] offset:20480
	s_waitcnt vmcnt(9)
	ds_write_b128 v85, v[22:25] offset:24576
	s_waitcnt vmcnt(8)
	ds_write_b128 v85, v[30:33] offset:28672
	s_waitcnt lgkmcnt(0)
	s_barrier
	global_load_dwordx4 v[2:5], v[66:67], off offset:1792
	global_load_dwordx4 v[6:9], v[68:69], off offset:256
	global_load_dwordx4 v[10:13], v[70:71], off offset:3840
	global_load_dwordx4 v[14:17], v[72:73], off offset:256
	global_load_dwordx4 v[18:21], v[74:75], off offset:1792
	global_load_dwordx4 v[22:25], v[76:77], off offset:256
	global_load_dwordx4 v[26:29], v[78:79], off offset:3840
	global_load_dwordx4 v[30:33], v[80:81], off offset:256
	ds_read_b128 v[88:91], v86
	ds_read_b128 v[92:95], v86 offset:2048
	ds_read_b128 v[96:99], v86 offset:4096
	ds_read_b128 v[100:103], v86 offset:6144
	ds_read_b128 v[104:107], v84 offset:16384
	ds_read_b128 v[120:123], v84 offset:18432
	ds_read_b128 v[136:139], v84 offset:20480
	ds_read_b128 v[152:155], v84 offset:22528
	s_waitcnt lgkmcnt(3)
	v_mfma_f32_16x16x32_bf16 v[108:111], v[88:91], v[104:107], 0
	v_mfma_f32_16x16x32_bf16 v[112:115], v[92:95], v[104:107], 0
	v_mfma_f32_16x16x32_bf16 v[116:119], v[96:99], v[104:107], 0
	v_mfma_f32_16x16x32_bf16 v[104:107], v[100:103], v[104:107], 0
	s_waitcnt lgkmcnt(2)
	v_mfma_f32_16x16x32_bf16 v[124:127], v[88:91], v[120:123], 0
	v_mfma_f32_16x16x32_bf16 v[128:131], v[92:95], v[120:123], 0
	v_mfma_f32_16x16x32_bf16 v[132:135], v[96:99], v[120:123], 0
	v_mfma_f32_16x16x32_bf16 v[120:123], v[100:103], v[120:123], 0
	s_waitcnt lgkmcnt(1)
	v_mfma_f32_16x16x32_bf16 v[140:143], v[88:91], v[136:139], 0
	v_mfma_f32_16x16x32_bf16 v[144:147], v[92:95], v[136:139], 0
	v_mfma_f32_16x16x32_bf16 v[148:151], v[96:99], v[136:139], 0
	v_mfma_f32_16x16x32_bf16 v[136:139], v[100:103], v[136:139], 0
	s_waitcnt lgkmcnt(0)
	v_mfma_f32_16x16x32_bf16 v[88:91], v[88:91], v[152:155], 0
	v_mfma_f32_16x16x32_bf16 v[92:95], v[92:95], v[152:155], 0
	v_mfma_f32_16x16x32_bf16 v[96:99], v[96:99], v[152:155], 0
	v_mfma_f32_16x16x32_bf16 v[100:103], v[100:103], v[152:155], 0
	ds_read_b128 v[152:155], v83
	ds_read_b128 v[156:159], v83 offset:2048
	ds_read_b128 v[164:167], v83 offset:4096
	ds_read_b128 v[182:185], v83 offset:6144
	ds_read_b128 v[186:189], v0 offset:16384
	s_waitcnt lgkmcnt(0)
; #define GM_LOAD(RA, RB, KT)                                                                 \
;   _Pragma("unroll") for (int i = 0; i < 4; ++i) {                                           \
;     RA[i] = *(const u32x4*)(ag + (size_t)(32 * i) * lda + (KT) * 64);                       \
;     RB[i] = *(const u32x4*)(bg + (size_t)(32 * i) * ldb + (KT) * 64);                       \
;   }
; template <bool DEEP = true>
; DI void gemm_main(f32x4 (&acc)[4][4], const u16* __restrict__ A, int lda, const u16* __restrict__ B, int ldb, int K, u16* lds) {
;     ...
;     for (int kt = 0; kt < nk; kt += 2) {
;       if (kt + 2 < nk) { GM_LOAD(ra0, rb0, kt + 2) }
;       GM_COMPUTE(0)
;       __builtin_amdgcn_sched_barrier(0);
;       GM_STORE(ra1, rb1, 1)
;       __syncthreads();
;       if (kt + 3 < nk) { GM_LOAD(ra1, rb1, kt + 3) }
;       GM_COMPUTE(1)
;       __builtin_amdgcn_sched_barrier(0);
;       if (kt + 2 < nk) { GM_STORE(ra0, rb0, 0) }
	v_mfma_f32_16x16x32_bf16 v[108:111], v[152:155], v[186:189], v[108:111]
	v_mfma_f32_16x16x32_bf16 v[112:115], v[156:159], v[186:189], v[112:115]
	v_mfma_f32_16x16x32_bf16 v[116:119], v[164:167], v[186:189], v[116:119]
	v_mfma_f32_16x16x32_bf16 v[104:107], v[182:185], v[186:189], v[104:107]
	ds_read_b128 v[186:189], v0 offset:18432
	s_waitcnt lgkmcnt(0)
	v_mfma_f32_16x16x32_bf16 v[124:127], v[152:155], v[186:189], v[124:127]
	v_mfma_f32_16x16x32_bf16 v[128:131], v[156:159], v[186:189], v[128:131]
	v_mfma_f32_16x16x32_bf16 v[132:135], v[164:167], v[186:189], v[132:135]
	v_mfma_f32_16x16x32_bf16 v[120:123], v[182:185], v[186:189], v[120:123]
	ds_read_b128 v[186:189], v0 offset:20480
	s_waitcnt lgkmcnt(0)
	v_mfma_f32_16x16x32_bf16 v[140:143], v[152:155], v[186:189], v[140:143]
	v_mfma_f32_16x16x32_bf16 v[144:147], v[156:159], v[186:189], v[144:147]
	v_mfma_f32_16x16x32_bf16 v[148:151], v[164:167], v[186:189], v[148:151]
	v_mfma_f32_16x16x32_bf16 v[136:139], v[182:185], v[186:189], v[136:139]
	ds_read_b128 v[186:189], v0 offset:22528
	s_waitcnt lgkmcnt(0)
	v_mfma_f32_16x16x32_bf16 v[88:91], v[152:155], v[186:189], v[88:91]
	v_mfma_f32_16x16x32_bf16 v[92:95], v[156:159], v[186:189], v[92:95]
	v_mfma_f32_16x16x32_bf16 v[96:99], v[164:167], v[186:189], v[96:99]
	v_mfma_f32_16x16x32_bf16 v[100:103], v[182:185], v[186:189], v[100:103]
	s_waitcnt vmcnt(15)
	ds_write_b128 v85, v[46:49] offset:32768
	s_waitcnt vmcnt(11)
	ds_write_b128 v85, v[62:65] offset:49152
	ds_write_b128 v85, v[42:45] offset:36864
	s_waitcnt vmcnt(10)
	ds_write_b128 v85, v[58:61] offset:53248
	ds_write_b128 v85, v[38:41] offset:40960
	s_waitcnt vmcnt(9)
	ds_write_b128 v85, v[54:57] offset:57344
	ds_write_b128 v85, v[34:37] offset:45056
	s_waitcnt vmcnt(8)
	ds_write_b128 v85, v[50:53] offset:61440
	s_waitcnt lgkmcnt(0)
	s_barrier
	global_load_dwordx4 v[34:37], v[66:67], off offset:1920
	global_load_dwordx4 v[38:41], v[68:69], off offset:384
	global_load_dwordx4 v[42:45], v[70:71], off offset:3968
	global_load_dwordx4 v[46:49], v[72:73], off offset:384
	global_load_dwordx4 v[50:53], v[74:75], off offset:1920
	global_load_dwordx4 v[54:57], v[76:77], off offset:384
	global_load_dwordx4 v[58:61], v[78:79], off offset:3968
	global_load_dwordx4 v[62:65], v[80:81], off offset:384
	ds_read_b128 v[66:69], v86 offset:32768
	ds_read_b128 v[70:73], v86 offset:34816
	ds_read_b128 v[74:77], v86 offset:36864
	ds_read_b128 v[78:81], v86 offset:38912
	ds_read_b128 v[152:155], v84 offset:49152
	s_waitcnt lgkmcnt(0)
	v_mfma_f32_16x16x32_bf16 v[108:111], v[66:69], v[152:155], v[108:111]
	v_mfma_f32_16x16x32_bf16 v[112:115], v[70:73], v[152:155], v[112:115]
	v_mfma_f32_16x16x32_bf16 v[116:119], v[74:77], v[152:155], v[116:119]
	v_mfma_f32_16x16x32_bf16 v[104:107], v[78:81], v[152:155], v[104:107]
	ds_read_b128 v[152:155], v84 offset:51200
	s_waitcnt lgkmcnt(0)
	v_mfma_f32_16x16x32_bf16 v[124:127], v[66:69], v[152:155], v[124:127]
	v_mfma_f32_16x16x32_bf16 v[128:131], v[70:73], v[152:155], v[128:131]
	v_mfma_f32_16x16x32_bf16 v[132:135], v[74:77], v[152:155], v[132:135]
	v_mfma_f32_16x16x32_bf16 v[120:123], v[78:81], v[152:155], v[120:123]
	ds_read_b128 v[152:155], v84 offset:53248
	s_waitcnt lgkmcnt(0)
	v_mfma_f32_16x16x32_bf16 v[140:143], v[66:69], v[152:155], v[140:143]
	v_mfma_f32_16x16x32_bf16 v[144:147], v[70:73], v[152:155], v[144:147]
	v_mfma_f32_16x16x32_bf16 v[148:151], v[74:77], v[152:155], v[148:151]
	v_mfma_f32_16x16x32_bf16 v[136:139], v[78:81], v[152:155], v[136:139]
	ds_read_b128 v[152:155], v84 offset:55296
	s_waitcnt lgkmcnt(0)
	v_mfma_f32_16x16x32_bf16 v[66:69], v[66:69], v[152:155], v[88:91]
	v_mfma_f32_16x16x32_bf16 v[70:73], v[70:73], v[152:155], v[92:95]
	v_mfma_f32_16x16x32_bf16 v[74:77], v[74:77], v[152:155], v[96:99]
	v_mfma_f32_16x16x32_bf16 v[78:81], v[78:81], v[152:155], v[100:103]
	ds_read_b128 v[88:91], v83 offset:32768
	ds_read_b128 v[92:95], v83 offset:34816
	ds_read_b128 v[96:99], v83 offset:36864
	ds_read_b128 v[100:103], v83 offset:38912
	ds_read_b128 v[152:155], v0 offset:49152
	s_waitcnt lgkmcnt(0)
	v_mfma_f32_16x16x32_bf16 v[108:111], v[88:91], v[152:155], v[108:111]
	v_mfma_f32_16x16x32_bf16 v[112:115], v[92:95], v[152:155], v[112:115]
	v_mfma_f32_16x16x32_bf16 v[116:119], v[96:99], v[152:155], v[116:119]
	v_mfma_f32_16x16x32_bf16 v[104:107], v[100:103], v[152:155], v[104:107]
	ds_read_b128 v[152:155], v0 offset:51200
	s_waitcnt lgkmcnt(0)
	v_mfma_f32_16x16x32_bf16 v[124:127], v[88:91], v[152:155], v[124:127]
	v_mfma_f32_16x16x32_bf16 v[128:131], v[92:95], v[152:155], v[128:131]
	v_mfma_f32_16x16x32_bf16 v[132:135], v[96:99], v[152:155], v[132:135]
	v_mfma_f32_16x16x32_bf16 v[120:123], v[100:103], v[152:155], v[120:123]
	ds_read_b128 v[152:155], v0 offset:53248
	s_waitcnt lgkmcnt(0)
	v_mfma_f32_16x16x32_bf16 v[140:143], v[88:91], v[152:155], v[140:143]
	v_mfma_f32_16x16x32_bf16 v[144:147], v[92:95], v[152:155], v[144:147]
	v_mfma_f32_16x16x32_bf16 v[148:151], v[96:99], v[152:155], v[148:151]
	v_mfma_f32_16x16x32_bf16 v[136:139], v[100:103], v[152:155], v[136:139]
	ds_read_b128 v[152:155], v0 offset:55296
	s_waitcnt lgkmcnt(0)
	v_mfma_f32_16x16x32_bf16 v[66:69], v[88:91], v[152:155], v[66:69]
	v_mfma_f32_16x16x32_bf16 v[70:73], v[92:95], v[152:155], v[70:73]
	v_mfma_f32_16x16x32_bf16 v[74:77], v[96:99], v[152:155], v[74:77]
	v_mfma_f32_16x16x32_bf16 v[78:81], v[100:103], v[152:155], v[78:81]
	s_waitcnt vmcnt(15)
	ds_write_b128 v85, v[2:5]
	s_waitcnt vmcnt(14)
	ds_write_b128 v85, v[6:9] offset:16384
	s_waitcnt vmcnt(13)
	ds_write_b128 v85, v[10:13] offset:4096
	s_waitcnt vmcnt(12)
	ds_write_b128 v85, v[14:17] offset:20480
	s_waitcnt vmcnt(11)
	ds_write_b128 v85, v[18:21] offset:8192
	s_waitcnt vmcnt(10)
	ds_write_b128 v85, v[22:25] offset:24576
	s_waitcnt vmcnt(9)
	ds_write_b128 v85, v[26:29] offset:12288
	s_waitcnt vmcnt(8)
	ds_write_b128 v85, v[30:33] offset:28672
	s_waitcnt lgkmcnt(0)
	s_barrier
; #define GM_LOAD(RA, RB, KT)                                                                 \
;   _Pragma("unroll") for (int i = 0; i < 4; ++i) {                                           \
;     RA[i] = *(const u32x4*)(ag + (size_t)(32 * i) * lda + (KT) * 64);                       \
;     RB[i] = *(const u32x4*)(bg + (size_t)(32 * i) * ldb + (KT) * 64);                       \
;   }
; template <bool DEEP = true>
; DI void gemm_main(f32x4 (&acc)[4][4], const u16* __restrict__ A, int lda, const u16* __restrict__ B, int ldb, int K, u16* lds) {
;     ...
;     for (int kt = 0; kt < nk; kt += 2) {
;       if (kt + 2 < nk) { GM_LOAD(ra0, rb0, kt + 2) }
;       GM_COMPUTE(0)
;       __builtin_amdgcn_sched_barrier(0);
;       GM_STORE(ra1, rb1, 1)
;       __syncthreads();
;       if (kt + 3 < nk) { GM_LOAD(ra1, rb1, kt + 3) }
;       GM_COMPUTE(1)
;       __builtin_amdgcn_sched_barrier(0);
;       if (kt + 2 < nk) { GM_STORE(ra0, rb0, 0) }
;       __syncthreads();
	ds_read_b128 v[2:5], v86
	ds_read_b128 v[6:9], v86 offset:2048
	ds_read_b128 v[10:13], v86 offset:4096
	ds_read_b128 v[14:17], v86 offset:6144
	ds_read_b128 v[18:21], v84 offset:16384
	ds_read_b128 v[88:91], v84 offset:18432
	s_waitcnt lgkmcnt(1)
	v_mfma_f32_16x16x32_bf16 v[22:25], v[2:5], v[18:21], v[108:111]
	v_mfma_f32_16x16x32_bf16 v[26:29], v[6:9], v[18:21], v[112:115]
	v_mfma_f32_16x16x32_bf16 v[30:33], v[10:13], v[18:21], v[116:119]
	v_mfma_f32_16x16x32_bf16 v[18:21], v[14:17], v[18:21], v[104:107]
	s_nop 2
	ds_read_b128 v[104:107], v84 offset:20480
	s_waitcnt lgkmcnt(1)
	v_mfma_f32_16x16x32_bf16 v[92:95], v[2:5], v[88:91], v[124:127]
	v_mfma_f32_16x16x32_bf16 v[96:99], v[6:9], v[88:91], v[128:131]
	v_mfma_f32_16x16x32_bf16 v[100:103], v[10:13], v[88:91], v[132:135]
	v_mfma_f32_16x16x32_bf16 v[88:91], v[14:17], v[88:91], v[120:123]
	s_nop 2
	ds_read_b128 v[120:123], v84 offset:22528
	s_waitcnt lgkmcnt(1)
	v_mfma_f32_16x16x32_bf16 v[108:111], v[2:5], v[104:107], v[140:143]
	v_mfma_f32_16x16x32_bf16 v[112:115], v[6:9], v[104:107], v[144:147]
	v_mfma_f32_16x16x32_bf16 v[116:119], v[10:13], v[104:107], v[148:151]
	v_mfma_f32_16x16x32_bf16 v[104:107], v[14:17], v[104:107], v[136:139]
	s_waitcnt lgkmcnt(0)
	v_mfma_f32_16x16x32_bf16 v[2:5], v[2:5], v[120:123], v[66:69]
	v_mfma_f32_16x16x32_bf16 v[6:9], v[6:9], v[120:123], v[70:73]
	v_mfma_f32_16x16x32_bf16 v[10:13], v[10:13], v[120:123], v[74:77]
	v_mfma_f32_16x16x32_bf16 v[14:17], v[14:17], v[120:123], v[78:81]
	ds_read_b128 v[66:69], v83
	ds_read_b128 v[70:73], v83 offset:2048
	ds_read_b128 v[74:77], v83 offset:4096
	ds_read_b128 v[78:81], v83 offset:6144
	ds_read_b128 v[120:123], v0 offset:16384
	s_waitcnt lgkmcnt(0)
	v_mfma_f32_16x16x32_bf16 v[22:25], v[66:69], v[120:123], v[22:25]
	v_mfma_f32_16x16x32_bf16 v[26:29], v[70:73], v[120:123], v[26:29]
	v_mfma_f32_16x16x32_bf16 v[30:33], v[74:77], v[120:123], v[30:33]
	v_mfma_f32_16x16x32_bf16 v[18:21], v[78:81], v[120:123], v[18:21]
	ds_read_b128 v[120:123], v0 offset:18432
	s_waitcnt lgkmcnt(0)
	v_mfma_f32_16x16x32_bf16 v[92:95], v[66:69], v[120:123], v[92:95]
	v_mfma_f32_16x16x32_bf16 v[96:99], v[70:73], v[120:123], v[96:99]
	v_mfma_f32_16x16x32_bf16 v[100:103], v[74:77], v[120:123], v[100:103]
	v_mfma_f32_16x16x32_bf16 v[88:91], v[78:81], v[120:123], v[88:91]
	ds_read_b128 v[120:123], v0 offset:20480
	s_waitcnt lgkmcnt(0)
	v_mfma_f32_16x16x32_bf16 v[108:111], v[66:69], v[120:123], v[108:111]
	v_mfma_f32_16x16x32_bf16 v[112:115], v[70:73], v[120:123], v[112:115]
	v_mfma_f32_16x16x32_bf16 v[116:119], v[74:77], v[120:123], v[116:119]
	v_mfma_f32_16x16x32_bf16 v[104:107], v[78:81], v[120:123], v[104:107]
	ds_read_b128 v[120:123], v0 offset:22528
	s_waitcnt lgkmcnt(0)
	v_mfma_f32_16x16x32_bf16 v[2:5], v[66:69], v[120:123], v[2:5]
	v_mfma_f32_16x16x32_bf16 v[6:9], v[70:73], v[120:123], v[6:9]
	v_mfma_f32_16x16x32_bf16 v[10:13], v[74:77], v[120:123], v[10:13]
	v_mfma_f32_16x16x32_bf16 v[14:17], v[78:81], v[120:123], v[14:17]
	s_waitcnt vmcnt(7)
	ds_write_b128 v85, v[34:37] offset:32768
	s_waitcnt vmcnt(6)
	ds_write_b128 v85, v[38:41] offset:49152
	s_waitcnt vmcnt(5)
	ds_write_b128 v85, v[42:45] offset:36864
	s_waitcnt vmcnt(4)
	ds_write_b128 v85, v[46:49] offset:53248
	s_waitcnt vmcnt(3)
	ds_write_b128 v85, v[50:53] offset:40960
	s_waitcnt vmcnt(2)
	ds_write_b128 v85, v[54:57] offset:57344
	s_waitcnt vmcnt(1)
	ds_write_b128 v85, v[58:61] offset:45056
	s_waitcnt vmcnt(0)
	ds_write_b128 v85, v[62:65] offset:61440
	s_waitcnt lgkmcnt(0)
	s_barrier
	ds_read_b128 v[34:37], v86 offset:32768
	ds_read_b128 v[38:41], v86 offset:34816
	ds_read_b128 v[42:45], v86 offset:36864
	ds_read_b128 v[46:49], v86 offset:38912
	ds_read_b128 v[50:53], v84 offset:49152
	s_waitcnt lgkmcnt(0)
	v_mfma_f32_16x16x32_bf16 v[22:25], v[34:37], v[50:53], v[22:25]
	ds_read_b128 v[66:69], v84 offset:53248
	v_mfma_f32_16x16x32_bf16 v[26:29], v[38:41], v[50:53], v[26:29]
	v_mfma_f32_16x16x32_bf16 v[30:33], v[42:45], v[50:53], v[30:33]
	v_mfma_f32_16x16x32_bf16 v[18:21], v[46:49], v[50:53], v[18:21]
	ds_read_b128 v[50:53], v84 offset:51200
	ds_read_b128 v[84:87], v84 offset:55296
	s_waitcnt lgkmcnt(1)
	v_mfma_f32_16x16x32_bf16 v[54:57], v[34:37], v[50:53], v[92:95]
	v_mfma_f32_16x16x32_bf16 v[58:61], v[38:41], v[50:53], v[96:99]
	v_mfma_f32_16x16x32_bf16 v[62:65], v[42:45], v[50:53], v[100:103]
	v_mfma_f32_16x16x32_bf16 v[50:53], v[46:49], v[50:53], v[88:91]
	v_mfma_f32_16x16x32_bf16 v[70:73], v[34:37], v[66:69], v[108:111]
	v_mfma_f32_16x16x32_bf16 v[74:77], v[38:41], v[66:69], v[112:115]
	v_mfma_f32_16x16x32_bf16 v[78:81], v[42:45], v[66:69], v[116:119]
	v_mfma_f32_16x16x32_bf16 v[66:69], v[46:49], v[66:69], v[104:107]
	s_waitcnt lgkmcnt(0)
	v_mfma_f32_16x16x32_bf16 v[2:5], v[34:37], v[84:87], v[2:5]
	v_mfma_f32_16x16x32_bf16 v[6:9], v[38:41], v[84:87], v[6:9]
	v_mfma_f32_16x16x32_bf16 v[10:13], v[42:45], v[84:87], v[10:13]
	v_mfma_f32_16x16x32_bf16 v[14:17], v[46:49], v[84:87], v[14:17]
	ds_read_b128 v[34:37], v83 offset:32768
	ds_read_b128 v[38:41], v83 offset:34816
	ds_read_b128 v[42:45], v83 offset:36864
	ds_read_b128 v[46:49], v83 offset:38912
	ds_read_b128 v[84:87], v0 offset:49152
	s_waitcnt lgkmcnt(0)
	v_mfma_f32_16x16x32_bf16 v[22:25], v[34:37], v[84:87], v[22:25]
	v_mfma_f32_16x16x32_bf16 v[26:29], v[38:41], v[84:87], v[26:29]
	v_mfma_f32_16x16x32_bf16 v[30:33], v[42:45], v[84:87], v[30:33]
	v_mfma_f32_16x16x32_bf16 v[18:21], v[46:49], v[84:87], v[18:21]
	ds_read_b128 v[84:87], v0 offset:51200
	s_waitcnt lgkmcnt(0)
	v_mfma_f32_16x16x32_bf16 v[54:57], v[34:37], v[84:87], v[54:57]
	v_mfma_f32_16x16x32_bf16 v[58:61], v[38:41], v[84:87], v[58:61]
	v_mfma_f32_16x16x32_bf16 v[62:65], v[42:45], v[84:87], v[62:65]
	v_mfma_f32_16x16x32_bf16 v[50:53], v[46:49], v[84:87], v[50:53]
	ds_read_b128 v[84:87], v0 offset:53248
	s_waitcnt lgkmcnt(0)
	v_mfma_f32_16x16x32_bf16 v[70:73], v[34:37], v[84:87], v[70:73]
	v_mfma_f32_16x16x32_bf16 v[74:77], v[38:41], v[84:87], v[74:77]
	v_mfma_f32_16x16x32_bf16 v[78:81], v[42:45], v[84:87], v[78:81]
	v_mfma_f32_16x16x32_bf16 v[66:69], v[46:49], v[84:87], v[66:69]
	ds_read_b128 v[84:87], v0 offset:55296
	s_waitcnt lgkmcnt(0)
	v_mfma_f32_16x16x32_bf16 v[2:5], v[34:37], v[84:87], v[2:5]
	v_mfma_f32_16x16x32_bf16 v[6:9], v[38:41], v[84:87], v[6:9]
	v_mfma_f32_16x16x32_bf16 v[10:13], v[42:45], v[84:87], v[10:13]
	v_mfma_f32_16x16x32_bf16 v[14:17], v[46:49], v[84:87], v[14:17]
	v_mov_b32_e32 v0, v169
	s_barrier
; DI int tidx() { int t = threadIdx.x & 255; asm volatile("" : "+v"(t)); return t; }
; DI void stage_c(const f32x4 (&acc)[4][4], float* Cs) {
;   const int tid = tidx(), lane = tid & 63, w = tid >> 6;
;   const int wm = w >> 1, wn = w & 1, fr = lane & 15, fq = lane >> 4;
; #pragma unroll
;   for (int m = 0; m < 4; ++m)
; #pragma unroll
;     for (int n = 0; n < 4; ++n)
; #pragma unroll
;       for (int j = 0; j < 4; ++j) Cs[(wm * 64 + m * 16 + fq * 4 + j) * CST + wn * 64 + n * 16 + fr] = acc[m][n][j];
;   __syncthreads();
; }
; DI void q_tile(PREF p, int l, int idx, unsigned char* ldsb) {
;     ...
;   stage_c(acc, Cs);
; #pragma unroll
;   for (int q = 0; q < 8; ++q) {
;     int r = (tid >> 4) + 16 * q, c = (tid & 15) * 8;
;     int n = col0 + c; int dd = n % 96;
;     float rs = aux[r];
;     float v[8]; ld8(Cs + r * CST + c, v);
; #pragma unroll
;     for (int j = 0; j < 8; ++j) v[j] *= rs;
;     if (dd >= 64) {
;       int ri0 = dd - 64; int s = (row0 + r) & 4095;
;       float pv[8];
;       if (ri0 < 16) {
;         ld8(Cs + r * CST + c + 16, pv);
;         const float* cs = p.rcos + s * 16 + ri0; const float* sn = p.rsin + s * 16 + ri0;
; #pragma unroll
;         for (int j = 0; j < 8; ++j) v[j] = v[j] * cs[j] - pv[j] * rs * sn[j];
;       } else {
;         ld8(Cs + r * CST + c - 16, pv);
;         const float* cs = p.rcos + s * 16 + ri0 - 16; const float* sn = p.rsin + s * 16 + ri0 - 16;
; #pragma unroll
;         for (int j = 0; j < 8; ++j) v[j] = v[j] * cs[j] + pv[j] * rs * sn[j];
;       }
;     }
	s_mov_b32 s0, 0xfffffc0
	v_lshrrev_b32_e32 v35, 2, v0
	v_lshrrev_b32_e32 v34, 1, v0
	v_and_b32_e32 v35, 12, v35
	v_and_or_b32 v34, v34, s0, v35
	v_and_b32_e32 v0, 0x4f, v0
	v_mul_lo_u32 v34, v34, s92
	v_lshlrev_b32_e32 v0, 2, v0
	v_add3_u32 v0, s33, v34, v0
	ds_write2_b32 v0, v22, v54 offset1:16
	ds_write2_b32 v0, v23, v55 offset0:132 offset1:148
	v_add_u32_e32 v22, 0x400, v0
	ds_write2_b32 v22, v24, v56 offset0:8 offset1:24
	ds_write2_b32 v22, v25, v57 offset0:140 offset1:156
	ds_write2_b32 v0, v70, v2 offset0:32 offset1:48
	ds_write2_b32 v0, v71, v3 offset0:164 offset1:180
	ds_write2_b32 v22, v72, v4 offset0:40 offset1:56
	ds_write2_b32 v22, v73, v5 offset0:172 offset1:188
	v_add_u32_e32 v2, 0x2000, v0
	v_add_u32_e32 v3, 0x2400, v0
	ds_write2_b32 v2, v26, v58 offset0:64 offset1:80
	ds_write2_b32 v2, v27, v59 offset0:196 offset1:212
	ds_write2_b32 v3, v28, v60 offset0:72 offset1:88
	ds_write2_b32 v3, v29, v61 offset0:204 offset1:220
	ds_write2_b32 v2, v74, v6 offset0:96 offset1:112
	ds_write2_b32 v2, v75, v7 offset0:228 offset1:244
	ds_write2_b32 v3, v76, v8 offset0:104 offset1:120
	ds_write2_b32 v3, v77, v9 offset0:236 offset1:252
	v_add_u32_e32 v2, 0x4000, v0
	v_add_u32_e32 v3, 0x4400, v0
	v_add_u32_e32 v4, 0x4800, v0
	ds_write2_b32 v2, v30, v62 offset0:128 offset1:144
	ds_write2_b32 v3, v31, v63 offset0:4 offset1:20
	ds_write2_b32 v3, v32, v64 offset0:136 offset1:152
	ds_write2_b32 v4, v33, v65 offset0:12 offset1:28
	ds_write2_b32 v2, v78, v10 offset0:160 offset1:176
	ds_write2_b32 v3, v79, v11 offset0:36 offset1:52
	ds_write2_b32 v3, v80, v12 offset0:168 offset1:184
	ds_write2_b32 v4, v81, v13 offset0:44 offset1:60
	v_add_u32_e32 v2, 0x6000, v0
	v_add_u32_e32 v3, 0x6400, v0
	v_add_u32_e32 v0, 0x6800, v0
	ds_write2_b32 v2, v18, v50 offset0:192 offset1:208
	ds_write2_b32 v3, v19, v51 offset0:68 offset1:84
	ds_write2_b32 v3, v20, v52 offset0:200 offset1:216
	ds_write2_b32 v0, v21, v53 offset0:76 offset1:92
	ds_write2_b32 v2, v66, v14 offset0:224 offset1:240
	ds_write2_b32 v3, v67, v15 offset0:100 offset1:116
	ds_write2_b32 v3, v68, v16 offset0:232 offset1:248
	ds_write2_b32 v0, v69, v17 offset0:108 offset1:124
	v_lshlrev_b32_e32 v0, 3, v82
	v_and_b32_e32 v0, 0x78, v0
	v_or_b32_e32 v6, s8, v0
	s_mov_b32 s0, 0x2aaaaaab
	v_mul_hi_i32 v2, v6, s0
	v_lshrrev_b32_e32 v3, 31, v2
	v_lshrrev_b32_e32 v2, 4, v2
	v_add_u32_e32 v2, v2, v3
	s_movk_i32 s0, 0x60
	v_mul_lo_u32 v2, v2, s0
	v_ashrrev_i32_e32 v17, 4, v82
	v_sub_u32_e32 v2, v6, v2
	s_movk_i32 s0, 0x4f
	v_lshl_add_u32 v22, v0, 2, s33
	v_cmp_lt_u32_e32 vcc, s0, v2
	v_readlane_b32 s0, v254, 16
	v_mul_lo_u32 v23, v17, s92
	v_add_u32_e32 v7, v22, v23
	v_lshl_add_u32 v21, v17, 2, s0
	s_waitcnt lgkmcnt(0)
	s_barrier
	ds_read_b32 v16, v21
	ds_read_b128 v[8:11], v7
	ds_read_b128 v[24:27], v7 offset:16
	v_subrev_u32_e32 v0, 64, v2
	v_cmp_lt_i32_e64 s[8:9], 63, v2
	v_lshlrev_b64 v[2:3], 2, v[0:1]
	v_lshl_add_u64 v[4:5], s[12:13], 0, v[2:3]
	v_lshl_add_u64 v[2:3], s[14:15], 0, v[2:3]
	s_waitcnt lgkmcnt(1)
	v_pk_mul_f32 v[14:15], v[16:17], v[8:9] op_sel_hi:[0,1]
	v_pk_mul_f32 v[12:13], v[16:17], v[10:11] op_sel_hi:[0,1]
	s_waitcnt lgkmcnt(0)
	v_pk_mul_f32 v[10:11], v[16:17], v[24:25] op_sel_hi:[0,1]
	v_pk_mul_f32 v[8:9], v[16:17], v[26:27] op_sel_hi:[0,1]
	v_add_u32_e32 v20, s18, v17
	s_and_saveexec_b64 s[16:17], s[8:9]
	s_cbranch_execz .LBB0_354
	v_lshlrev_b32_e32 v0, 4, v20
	v_and_b32_e32 v0, 0xfff0, v0
	v_lshlrev_b32_e32 v0, 2, v0
	v_mov_b32_e32 v17, v16
	v_lshl_add_u64 v[18:19], v[4:5], 0, v[0:1]
	s_and_saveexec_b64 s[0:1], vcc
	s_xor_b64 s[18:19], exec, s[0:1]
	s_cbranch_execz .LBB0_351
	v_subrev_u32_e32 v24, 64, v7
	v_lshl_add_u64 v[40:41], v[2:3], 0, v[0:1]
	ds_read_b128 v[24:27], v24
	global_load_dwordx4 v[28:31], v[18:19], off offset:-48
	global_load_dwordx4 v[32:35], v[18:19], off offset:-64
	global_load_dwordx4 v[36:39], v[40:41], off offset:-48
	s_nop 0
	global_load_dwordx4 v[40:43], v[40:41], off offset:-64
	v_subrev_u32_e32 v7, 48, v7
	s_waitcnt lgkmcnt(0)
	v_pk_mul_f32 v[18:19], v[16:17], v[24:25]
	s_waitcnt vmcnt(0)
	v_pk_mul_f32 v[18:19], v[18:19], v[40:41]
	s_nop 0
	v_pk_fma_f32 v[14:15], v[14:15], v[32:33], v[18:19]
	v_pk_mul_f32 v[18:19], v[16:17], v[26:27]
	ds_read_b128 v[24:27], v7
	v_pk_mul_f32 v[18:19], v[18:19], v[42:43]
	s_nop 0
	v_pk_fma_f32 v[12:13], v[12:13], v[34:35], v[18:19]
	s_waitcnt lgkmcnt(0)
	v_pk_mul_f32 v[18:19], v[16:17], v[24:25]
	v_pk_mul_f32 v[16:17], v[16:17], v[26:27]
	v_pk_mul_f32 v[18:19], v[18:19], v[36:37]
	v_pk_mul_f32 v[16:17], v[16:17], v[38:39]
	v_pk_fma_f32 v[10:11], v[10:11], v[28:29], v[18:19]
	v_pk_fma_f32 v[8:9], v[8:9], v[30:31], v[16:17]

; #define G_LDA(dst, b, h)                                                                                                  \
;   _Pragma("unroll") for (int m = 0; m < 4; ++m) _Pragma("unroll") for (int k = 0; k < 2; ++k)                             \
;       dst[m][k] = *(const bf16x8*)((const char*)G_SA(b, h) + ((wr * 4 + m) * 2 + k) * 1024 + rdo)
; #define G_LDB(dst, b, h)                                                                                                  \
;   _Pragma("unroll") for (int n = 0; n < 2; ++n) _Pragma("unroll") for (int k = 0; k < 2; ++k)                             \
;       dst[n][k] = *(const bf16x8*)((const char*)G_SB(b, h) + ((wc * 2 + n) * 2 + k) * 1024 + rdo)
; #define G_WAIT_L(n) asm volatile("s_waitcnt lgkmcnt(" #n ")" ::: "memory")
; #define G_BAR __builtin_amdgcn_s_barrier()
; #define G_SCHED __builtin_amdgcn_sched_barrier(0)
;     ...
;   for (int tt = 0; tt < nt - 2; tt += 2) {
;     G_LDB(B0, 0, 0); G_SCHED; G_LDA(At, 0, 0); G_STAGE(G_SA(1, 1), A, oa0, oa1, LDA, 128, KA(tt + 1));
;     G_WAIT_L(8); G_BAR; G_WAIT_L(0); G_MMA(0, 0, At, B0); G_BAR; G_SCHED;
;     G_LDB(B1, 0, 1); G_STAGE(G_SB(0, 0), B, ob0, ob1, LDB, 0, KB(tt + 2));
;     G_BAR; G_WAIT_L(0); G_MMA(0, 1, At, B1); G_BAR;
;     G_LDA(At, 0, 1); G_STAGE(G_SA(0, 0), A, oa0, oa1, LDA, 0, KA(tt + 2));
;     G_BAR; G_WAIT_L(0); G_MMA(1, 0, At, B0); G_BAR; G_SCHED;
.LBB0_453:
	ds_read_b128 v[182:185], v161
	ds_read_b128 v[186:189], v161 offset:1024
	ds_read_b128 v[190:193], v161 offset:2048
	ds_read_b128 v[194:197], v161 offset:3072
	v_add_u32_e32 v162, 0xc000, v144
	v_lshl_add_u64 v[166:167], v[136:137], 0, s[20:21]
	v_readfirstlane_b32 s0, v162
	v_lshl_add_u64 v[164:165], v[166:167], 0, s[78:79]
	s_mov_b32 m0, s0
	ds_read_b128 v[198:201], v143
	ds_read_b128 v[202:205], v143 offset:1024
	ds_read_b128 v[206:209], v143 offset:2048
	ds_read_b128 v[210:213], v143 offset:3072
	ds_read_b128 v[214:217], v143 offset:4096
	ds_read_b128 v[218:221], v143 offset:5120
	ds_read_b128 v[222:225], v143 offset:6144
	ds_read_b128 v[226:229], v143 offset:7168
	global_load_lds_dwordx4 v[164:165], off
	v_add_u32_e32 v164, 0xe000, v144
	v_lshl_add_u64 v[246:247], v[134:135], 0, s[20:21]
	v_readfirstlane_b32 s0, v164
	v_lshl_add_u64 v[230:231], v[246:247], 0, s[78:79]
	s_mov_b32 m0, s0
	s_nop 0
	global_load_lds_dwordx4 v[230:231], off
	s_waitcnt lgkmcnt(8)
	s_barrier
	s_waitcnt lgkmcnt(0)
	s_waitcnt lgkmcnt(0)
	v_mfma_f32_16x16x32_bf16 v[126:129], v[198:201], v[182:185], v[126:129]
	v_mfma_f32_16x16x32_bf16 v[122:125], v[198:201], v[190:193], v[122:125]
	v_mfma_f32_16x16x32_bf16 v[118:121], v[206:209], v[182:185], v[118:121]
	v_mfma_f32_16x16x32_bf16 v[114:117], v[206:209], v[190:193], v[114:117]
	v_mfma_f32_16x16x32_bf16 v[110:113], v[214:217], v[182:185], v[110:113]
	v_mfma_f32_16x16x32_bf16 v[106:109], v[214:217], v[190:193], v[106:109]
	v_mfma_f32_16x16x32_bf16 v[102:105], v[222:225], v[182:185], v[102:105]
	v_mfma_f32_16x16x32_bf16 v[98:101], v[222:225], v[190:193], v[98:101]
	v_mfma_f32_16x16x32_bf16 v[126:129], v[202:205], v[186:189], v[126:129]
	v_mfma_f32_16x16x32_bf16 v[122:125], v[202:205], v[194:197], v[122:125]
	v_mfma_f32_16x16x32_bf16 v[118:121], v[210:213], v[186:189], v[118:121]
	v_mfma_f32_16x16x32_bf16 v[114:117], v[210:213], v[194:197], v[114:117]
	v_mfma_f32_16x16x32_bf16 v[110:113], v[218:221], v[186:189], v[110:113]
	v_mfma_f32_16x16x32_bf16 v[106:109], v[218:221], v[194:197], v[106:109]
	v_mfma_f32_16x16x32_bf16 v[102:105], v[226:229], v[186:189], v[102:105]
	v_mfma_f32_16x16x32_bf16 v[98:101], v[226:229], v[194:197], v[98:101]
	s_barrier
	v_lshl_add_u64 v[248:249], v[140:141], 0, s[20:21]
	v_readfirstlane_b32 s0, v147
	v_lshl_add_u64 v[250:251], v[248:249], 0, s[82:83]
	s_mov_b32 m0, s0
	ds_read_b128 v[230:233], v159
	ds_read_b128 v[234:237], v159 offset:1024
	ds_read_b128 v[238:241], v159 offset:2048
	ds_read_b128 v[242:245], v159 offset:3072
	global_load_lds_dwordx4 v[250:251], off
	v_lshl_add_u64 v[250:251], v[138:139], 0, s[20:21]
	v_readfirstlane_b32 s0, v148
	v_lshl_add_u64 v[252:253], v[250:251], 0, s[82:83]
	s_mov_b32 m0, s0
	s_nop 0
	global_load_lds_dwordx4 v[252:253], off
	s_barrier
	s_waitcnt lgkmcnt(0)
	s_waitcnt lgkmcnt(0)
	v_mfma_f32_16x16x32_bf16 v[94:97], v[198:201], v[230:233], v[94:97]
	v_mfma_f32_16x16x32_bf16 v[86:89], v[198:201], v[238:241], v[86:89]
	v_mfma_f32_16x16x32_bf16 v[70:73], v[206:209], v[230:233], v[70:73]
	v_mfma_f32_16x16x32_bf16 v[58:61], v[206:209], v[238:241], v[58:61]
	v_mfma_f32_16x16x32_bf16 v[54:57], v[214:217], v[230:233], v[54:57]
	v_mfma_f32_16x16x32_bf16 v[50:53], v[214:217], v[238:241], v[50:53]
	v_mfma_f32_16x16x32_bf16 v[46:49], v[222:225], v[230:233], v[46:49]
	v_mfma_f32_16x16x32_bf16 v[42:45], v[222:225], v[238:241], v[42:45]
	v_mfma_f32_16x16x32_bf16 v[94:97], v[202:205], v[234:237], v[94:97]
	v_mfma_f32_16x16x32_bf16 v[86:89], v[202:205], v[242:245], v[86:89]
	v_mfma_f32_16x16x32_bf16 v[70:73], v[210:213], v[234:237], v[70:73]
	v_mfma_f32_16x16x32_bf16 v[58:61], v[210:213], v[242:245], v[58:61]
	v_mfma_f32_16x16x32_bf16 v[54:57], v[218:221], v[234:237], v[54:57]
	v_mfma_f32_16x16x32_bf16 v[50:53], v[218:221], v[242:245], v[50:53]
	v_mfma_f32_16x16x32_bf16 v[46:49], v[226:229], v[234:237], v[46:49]
	v_mfma_f32_16x16x32_bf16 v[42:45], v[226:229], v[242:245], v[42:45]
	v_readfirstlane_b32 s0, v144
	v_lshl_add_u64 v[252:253], v[166:167], 0, s[82:83]
	s_mov_b32 m0, s0
	v_readfirstlane_b32 s0, v145
	s_barrier
	ds_read_b128 v[198:201], v143 offset:16384
	ds_read_b128 v[202:205], v143 offset:17408
	ds_read_b128 v[206:209], v143 offset:18432
	ds_read_b128 v[210:213], v143 offset:19456
	ds_read_b128 v[214:217], v143 offset:20480
	ds_read_b128 v[218:221], v143 offset:21504
	ds_read_b128 v[222:225], v143 offset:22528
	ds_read_b128 v[226:229], v143 offset:23552
	global_load_lds_dwordx4 v[252:253], off
	v_lshl_add_u64 v[252:253], v[246:247], 0, s[82:83]
	s_mov_b32 m0, s0
	s_nop 0
	global_load_lds_dwordx4 v[252:253], off
	s_barrier
	s_waitcnt lgkmcnt(0)
	s_waitcnt lgkmcnt(0)
	v_mfma_f32_16x16x32_bf16 v[38:41], v[198:201], v[182:185], v[38:41]
	v_mfma_f32_16x16x32_bf16 v[34:37], v[198:201], v[190:193], v[34:37]
	v_mfma_f32_16x16x32_bf16 v[30:33], v[206:209], v[182:185], v[30:33]
	v_mfma_f32_16x16x32_bf16 v[26:29], v[206:209], v[190:193], v[26:29]
	v_mfma_f32_16x16x32_bf16 v[22:25], v[214:217], v[182:185], v[22:25]
	v_mfma_f32_16x16x32_bf16 v[18:21], v[214:217], v[190:193], v[18:21]
	v_mfma_f32_16x16x32_bf16 v[14:17], v[222:225], v[182:185], v[14:17]
	v_mfma_f32_16x16x32_bf16 v[10:13], v[222:225], v[190:193], v[10:13]
	v_mfma_f32_16x16x32_bf16 v[38:41], v[202:205], v[186:189], v[38:41]
	v_mfma_f32_16x16x32_bf16 v[34:37], v[202:205], v[194:197], v[34:37]
	v_mfma_f32_16x16x32_bf16 v[30:33], v[210:213], v[186:189], v[30:33]
	v_mfma_f32_16x16x32_bf16 v[26:29], v[210:213], v[194:197], v[26:29]
	v_mfma_f32_16x16x32_bf16 v[22:25], v[218:221], v[186:189], v[22:25]
	v_mfma_f32_16x16x32_bf16 v[18:21], v[218:221], v[194:197], v[18:21]
	v_mfma_f32_16x16x32_bf16 v[14:17], v[226:229], v[186:189], v[14:17]
	v_mfma_f32_16x16x32_bf16 v[10:13], v[226:229], v[194:197], v[10:13]
	s_barrier
; #define G_LDA(dst, b, h)                                                                                                  \
;   _Pragma("unroll") for (int m = 0; m < 4; ++m) _Pragma("unroll") for (int k = 0; k < 2; ++k)                             \
;       dst[m][k] = *(const bf16x8*)((const char*)G_SA(b, h) + ((wr * 4 + m) * 2 + k) * 1024 + rdo)
; #define G_LDB(dst, b, h)                                                                                                  \
;   _Pragma("unroll") for (int n = 0; n < 2; ++n) _Pragma("unroll") for (int k = 0; k < 2; ++k)                             \
;       dst[n][k] = *(const bf16x8*)((const char*)G_SB(b, h) + ((wc * 2 + n) * 2 + k) * 1024 + rdo)
; #define G_WAIT_V(n) asm volatile("s_waitcnt vmcnt(" #n ")" ::: "memory")
; #define G_WAIT_L(n) asm volatile("s_waitcnt lgkmcnt(" #n ")" ::: "memory")
; #define G_BAR __builtin_amdgcn_s_barrier()
; #define G_SCHED __builtin_amdgcn_sched_barrier(0)
;     ...
;     G_STAGE(G_SB(0, 1), B, ob0, ob1, LDB, 128, KB(tt + 2));
;     G_WAIT_V(6); G_BAR; G_MMA(1, 1, At, B1); G_BAR;
;     G_LDB(B0, 1, 0); G_SCHED; G_LDA(At, 1, 0); G_STAGE(G_SA(0, 1), A, oa0, oa1, LDA, 128, KA(tt + 2));
;     G_WAIT_L(8); G_BAR; G_WAIT_L(0); G_MMA(0, 0, At, B0); G_BAR; G_SCHED;
;     G_LDB(B1, 1, 1); G_STAGE(G_SB(1, 0), B, ob0, ob1, LDB, 0, KB(tt + 3));
;     G_BAR; G_WAIT_L(0); G_MMA(0, 1, At, B1); G_BAR;
	v_readfirstlane_b32 s0, v149
	v_lshl_add_u64 v[182:183], v[248:249], 0, s[86:87]
	s_mov_b32 m0, s0
	v_readfirstlane_b32 s0, v151
	global_load_lds_dwordx4 v[182:183], off
	v_lshl_add_u64 v[182:183], v[250:251], 0, s[86:87]
	s_mov_b32 m0, s0
	s_nop 0
	global_load_lds_dwordx4 v[182:183], off
	s_waitcnt vmcnt(6)
	s_barrier
	v_mfma_f32_16x16x32_bf16 v[6:9], v[198:201], v[230:233], v[6:9]
	v_mfma_f32_16x16x32_bf16 v[2:5], v[198:201], v[238:241], v[2:5]
	v_mfma_f32_16x16x32_bf16 v[62:65], v[206:209], v[230:233], v[62:65]
	v_mfma_f32_16x16x32_bf16 v[66:69], v[206:209], v[238:241], v[66:69]
	v_mfma_f32_16x16x32_bf16 v[74:77], v[214:217], v[230:233], v[74:77]
	v_mfma_f32_16x16x32_bf16 v[78:81], v[214:217], v[238:241], v[78:81]
	v_mfma_f32_16x16x32_bf16 v[82:85], v[222:225], v[230:233], v[82:85]
	v_mfma_f32_16x16x32_bf16 v[90:93], v[222:225], v[238:241], v[90:93]
	v_mfma_f32_16x16x32_bf16 v[6:9], v[202:205], v[234:237], v[6:9]
	v_mfma_f32_16x16x32_bf16 v[2:5], v[202:205], v[242:245], v[2:5]
	v_mfma_f32_16x16x32_bf16 v[62:65], v[210:213], v[234:237], v[62:65]
	v_mfma_f32_16x16x32_bf16 v[66:69], v[210:213], v[242:245], v[66:69]
	v_mfma_f32_16x16x32_bf16 v[74:77], v[218:221], v[234:237], v[74:77]
	v_mfma_f32_16x16x32_bf16 v[78:81], v[218:221], v[242:245], v[78:81]
	v_mfma_f32_16x16x32_bf16 v[82:85], v[226:229], v[234:237], v[82:85]
	v_mfma_f32_16x16x32_bf16 v[90:93], v[226:229], v[242:245], v[90:93]
	s_barrier
	ds_read_b128 v[182:185], v150
	ds_read_b128 v[186:189], v150 offset:1024
	ds_read_b128 v[190:193], v150 offset:2048
	ds_read_b128 v[194:197], v150 offset:3072
	v_readfirstlane_b32 s0, v152
	v_lshl_add_u64 v[230:231], v[166:167], 0, s[86:87]
	s_mov_b32 m0, s0
	v_readfirstlane_b32 s0, v153
	ds_read_b128 v[198:201], v143 offset:32768
	ds_read_b128 v[202:205], v143 offset:33792
	ds_read_b128 v[206:209], v143 offset:34816
	ds_read_b128 v[210:213], v143 offset:35840
	ds_read_b128 v[214:217], v143 offset:36864
	ds_read_b128 v[218:221], v143 offset:37888
	ds_read_b128 v[222:225], v143 offset:38912
	ds_read_b128 v[226:229], v143 offset:39936
	global_load_lds_dwordx4 v[230:231], off
	v_lshl_add_u64 v[230:231], v[246:247], 0, s[86:87]
	s_mov_b32 m0, s0
	s_nop 0
	global_load_lds_dwordx4 v[230:231], off
	s_waitcnt lgkmcnt(8)
	s_barrier
	s_waitcnt lgkmcnt(0)
	s_waitcnt lgkmcnt(0)
	v_mfma_f32_16x16x32_bf16 v[126:129], v[198:201], v[182:185], v[126:129]
	v_mfma_f32_16x16x32_bf16 v[122:125], v[198:201], v[190:193], v[122:125]
	v_mfma_f32_16x16x32_bf16 v[118:121], v[206:209], v[182:185], v[118:121]
	v_mfma_f32_16x16x32_bf16 v[114:117], v[206:209], v[190:193], v[114:117]
	v_mfma_f32_16x16x32_bf16 v[110:113], v[214:217], v[182:185], v[110:113]
	v_mfma_f32_16x16x32_bf16 v[106:109], v[214:217], v[190:193], v[106:109]
	v_mfma_f32_16x16x32_bf16 v[102:105], v[222:225], v[182:185], v[102:105]
	v_mfma_f32_16x16x32_bf16 v[98:101], v[222:225], v[190:193], v[98:101]
	v_mfma_f32_16x16x32_bf16 v[126:129], v[202:205], v[186:189], v[126:129]
	v_mfma_f32_16x16x32_bf16 v[122:125], v[202:205], v[194:197], v[122:125]
	v_mfma_f32_16x16x32_bf16 v[118:121], v[210:213], v[186:189], v[118:121]
	v_mfma_f32_16x16x32_bf16 v[114:117], v[210:213], v[194:197], v[114:117]
	v_mfma_f32_16x16x32_bf16 v[110:113], v[218:221], v[186:189], v[110:113]
	v_mfma_f32_16x16x32_bf16 v[106:109], v[218:221], v[194:197], v[106:109]
	v_mfma_f32_16x16x32_bf16 v[102:105], v[226:229], v[186:189], v[102:105]
	v_mfma_f32_16x16x32_bf16 v[98:101], v[226:229], v[194:197], v[98:101]
	s_barrier
	v_readfirstlane_b32 s0, v154
	v_lshl_add_u64 v[252:253], v[248:249], 0, s[90:91]
	s_mov_b32 m0, s0
	v_readfirstlane_b32 s0, v155
	ds_read_b128 v[230:233], v146
	ds_read_b128 v[234:237], v146 offset:1024
	ds_read_b128 v[238:241], v146 offset:2048
	ds_read_b128 v[242:245], v146 offset:3072
	global_load_lds_dwordx4 v[252:253], off
	v_lshl_add_u64 v[252:253], v[250:251], 0, s[90:91]
	s_mov_b32 m0, s0
	s_nop 0
	global_load_lds_dwordx4 v[252:253], off
	s_barrier
	s_waitcnt lgkmcnt(0)
	s_waitcnt lgkmcnt(0)
	v_mfma_f32_16x16x32_bf16 v[94:97], v[198:201], v[230:233], v[94:97]
	v_mfma_f32_16x16x32_bf16 v[86:89], v[198:201], v[238:241], v[86:89]
	v_mfma_f32_16x16x32_bf16 v[70:73], v[206:209], v[230:233], v[70:73]
	v_mfma_f32_16x16x32_bf16 v[58:61], v[206:209], v[238:241], v[58:61]
	v_mfma_f32_16x16x32_bf16 v[54:57], v[214:217], v[230:233], v[54:57]
	v_mfma_f32_16x16x32_bf16 v[50:53], v[214:217], v[238:241], v[50:53]
	v_mfma_f32_16x16x32_bf16 v[46:49], v[222:225], v[230:233], v[46:49]
	v_mfma_f32_16x16x32_bf16 v[42:45], v[222:225], v[238:241], v[42:45]
	v_mfma_f32_16x16x32_bf16 v[94:97], v[202:205], v[234:237], v[94:97]
	v_mfma_f32_16x16x32_bf16 v[86:89], v[202:205], v[242:245], v[86:89]
	v_mfma_f32_16x16x32_bf16 v[70:73], v[210:213], v[234:237], v[70:73]
	v_mfma_f32_16x16x32_bf16 v[58:61], v[210:213], v[242:245], v[58:61]
	v_mfma_f32_16x16x32_bf16 v[54:57], v[218:221], v[234:237], v[54:57]
	v_mfma_f32_16x16x32_bf16 v[50:53], v[218:221], v[242:245], v[50:53]
	v_mfma_f32_16x16x32_bf16 v[46:49], v[226:229], v[234:237], v[46:49]
	v_mfma_f32_16x16x32_bf16 v[42:45], v[226:229], v[242:245], v[42:45]
	v_readfirstlane_b32 s0, v156
	v_lshl_add_u64 v[166:167], v[166:167], 0, s[90:91]
	s_mov_b32 m0, s0
	v_readfirstlane_b32 s0, v157
	s_barrier
	ds_read_b128 v[198:201], v143 offset:49152
	ds_read_b128 v[202:205], v143 offset:50176
	ds_read_b128 v[206:209], v143 offset:51200
	ds_read_b128 v[210:213], v143 offset:52224
	ds_read_b128 v[214:217], v143 offset:53248
	ds_read_b128 v[218:221], v143 offset:54272
	ds_read_b128 v[222:225], v143 offset:55296
	ds_read_b128 v[226:229], v143 offset:56320
	global_load_lds_dwordx4 v[166:167], off
	v_lshl_add_u64 v[166:167], v[246:247], 0, s[90:91]
	s_mov_b32 m0, s0
	s_nop 0
	global_load_lds_dwordx4 v[166:167], off
	s_barrier
; #define G_LDA(dst, b, h)                                                                                                  \
;   _Pragma("unroll") for (int m = 0; m < 4; ++m) _Pragma("unroll") for (int k = 0; k < 2; ++k)                             \
;       dst[m][k] = *(const bf16x8*)((const char*)G_SA(b, h) + ((wr * 4 + m) * 2 + k) * 1024 + rdo)
; #define G_LDB(dst, b, h)                                                                                                  \
;   _Pragma("unroll") for (int n = 0; n < 2; ++n) _Pragma("unroll") for (int k = 0; k < 2; ++k)                             \
;       dst[n][k] = *(const bf16x8*)((const char*)G_SB(b, h) + ((wc * 2 + n) * 2 + k) * 1024 + rdo)
; #define G_WAIT_V(n) asm volatile("s_waitcnt vmcnt(" #n ")" ::: "memory")
; #define G_WAIT_L(n) asm volatile("s_waitcnt lgkmcnt(" #n ")" ::: "memory")
; #define G_BAR __builtin_amdgcn_s_barrier()
; #define G_SCHED __builtin_amdgcn_sched_barrier(0)
; DI void br_flush(PREF p, f32x4 (&acc)[2][2][4][2], int slot) { br_store(p, acc, slot); zero_acc256(acc); }
;     ...
;     G_LDA(At, 1, 1); G_STAGE(G_SA(1, 0), A, oa0, oa1, LDA, 0, KA(tt + 3));
;     G_BAR; G_WAIT_L(0); G_MMA(1, 0, At, B0); G_BAR; G_SCHED;
;     G_STAGE(G_SB(1, 1), B, ob0, ob1, LDB, 128, KB(tt + 3));
;     G_WAIT_V(6); G_BAR; G_MMA(1, 1, At, B1); G_BAR;
;     if (MODE && ((tt + 1) & 3) == 3) br_flush(p, acc, (tt + 1) >> 2);
;   }
;   {
;     G_LDB(B0, 0, 0); G_LDA(At, 0, 0); G_STAGE(G_SA(1, 1), A, oa0, oa1, LDA, 128, KA(nt - 1));
;     G_BAR; G_WAIT_L(0); G_MMA(0, 0, At, B0); G_BAR;
;     G_LDB(B1, 0, 1); G_BAR; G_WAIT_L(0); G_MMA(0, 1, At, B1); G_BAR;
	s_waitcnt lgkmcnt(0)
	s_waitcnt lgkmcnt(0)
	v_mfma_f32_16x16x32_bf16 v[38:41], v[198:201], v[182:185], v[38:41]
	v_mfma_f32_16x16x32_bf16 v[34:37], v[198:201], v[190:193], v[34:37]
	v_mfma_f32_16x16x32_bf16 v[30:33], v[206:209], v[182:185], v[30:33]
	v_mfma_f32_16x16x32_bf16 v[26:29], v[206:209], v[190:193], v[26:29]
	v_mfma_f32_16x16x32_bf16 v[22:25], v[214:217], v[182:185], v[22:25]
	v_mfma_f32_16x16x32_bf16 v[18:21], v[214:217], v[190:193], v[18:21]
	v_mfma_f32_16x16x32_bf16 v[14:17], v[222:225], v[182:185], v[14:17]
	v_mfma_f32_16x16x32_bf16 v[10:13], v[222:225], v[190:193], v[10:13]
	v_mfma_f32_16x16x32_bf16 v[38:41], v[202:205], v[186:189], v[38:41]
	v_mfma_f32_16x16x32_bf16 v[34:37], v[202:205], v[194:197], v[34:37]
	v_mfma_f32_16x16x32_bf16 v[30:33], v[210:213], v[186:189], v[30:33]
	v_mfma_f32_16x16x32_bf16 v[26:29], v[210:213], v[194:197], v[26:29]
	v_mfma_f32_16x16x32_bf16 v[22:25], v[218:221], v[186:189], v[22:25]
	v_mfma_f32_16x16x32_bf16 v[18:21], v[218:221], v[194:197], v[18:21]
	v_mfma_f32_16x16x32_bf16 v[14:17], v[226:229], v[186:189], v[14:17]
	v_mfma_f32_16x16x32_bf16 v[10:13], v[226:229], v[194:197], v[10:13]
	s_barrier
	v_readfirstlane_b32 s0, v158
	v_lshl_add_u64 v[166:167], v[248:249], 0, s[6:7]
	s_mov_b32 m0, s0
	v_readfirstlane_b32 s0, v160
	global_load_lds_dwordx4 v[166:167], off
	v_lshl_add_u64 v[166:167], v[250:251], 0, s[6:7]
	s_mov_b32 m0, s0
	s_nop 0
	global_load_lds_dwordx4 v[166:167], off
	s_waitcnt vmcnt(6)
	s_barrier
	v_mfma_f32_16x16x32_bf16 v[6:9], v[198:201], v[230:233], v[6:9]
	v_mfma_f32_16x16x32_bf16 v[2:5], v[198:201], v[238:241], v[2:5]
	v_mfma_f32_16x16x32_bf16 v[62:65], v[206:209], v[230:233], v[62:65]
	v_mfma_f32_16x16x32_bf16 v[66:69], v[206:209], v[238:241], v[66:69]
	v_mfma_f32_16x16x32_bf16 v[74:77], v[214:217], v[230:233], v[74:77]
	v_mfma_f32_16x16x32_bf16 v[78:81], v[214:217], v[238:241], v[78:81]
	v_mfma_f32_16x16x32_bf16 v[82:85], v[222:225], v[230:233], v[82:85]
	v_mfma_f32_16x16x32_bf16 v[90:93], v[222:225], v[238:241], v[90:93]
	v_mfma_f32_16x16x32_bf16 v[6:9], v[202:205], v[234:237], v[6:9]
	v_mfma_f32_16x16x32_bf16 v[2:5], v[202:205], v[242:245], v[2:5]
	v_mfma_f32_16x16x32_bf16 v[62:65], v[210:213], v[234:237], v[62:65]
	v_mfma_f32_16x16x32_bf16 v[66:69], v[210:213], v[242:245], v[66:69]
	v_mfma_f32_16x16x32_bf16 v[74:77], v[218:221], v[234:237], v[74:77]
	v_mfma_f32_16x16x32_bf16 v[78:81], v[218:221], v[242:245], v[78:81]
	v_mfma_f32_16x16x32_bf16 v[82:85], v[226:229], v[234:237], v[82:85]
	v_mfma_f32_16x16x32_bf16 v[90:93], v[226:229], v[242:245], v[90:93]
	s_add_i32 s15, s15, 2
	s_add_u32 s20, s20, 0x100
	s_addc_u32 s21, s21, 0
	s_cmp_lt_u32 s15, 12
	s_barrier
	s_cbranch_scc1 .LBB0_453
	s_add_u32 s0, s18, 0x40780
	s_addc_u32 s1, s19, 0
	v_readfirstlane_b32 s15, v162
	v_lshl_add_u64 v[132:133], v[132:133], 1, s[0:1]
	s_mov_b32 m0, s15
	v_lshl_add_u64 v[130:131], v[130:131], 1, s[0:1]
	v_readfirstlane_b32 s0, v164
	ds_read_b128 v[134:137], v161
	ds_read_b128 v[138:141], v161 offset:1024
	ds_read_b128 v[152:155], v161 offset:2048
	ds_read_b128 v[182:185], v161 offset:3072
	ds_read_b128 v[186:189], v143
	ds_read_b128 v[190:193], v143 offset:1024
	ds_read_b128 v[194:197], v143 offset:2048
	ds_read_b128 v[198:201], v143 offset:3072
	ds_read_b128 v[202:205], v143 offset:4096
	ds_read_b128 v[206:209], v143 offset:5120
	ds_read_b128 v[210:213], v143 offset:6144
	ds_read_b128 v[214:217], v143 offset:7168
	global_load_lds_dwordx4 v[132:133], off
	s_mov_b32 m0, s0
	s_nop 0
	global_load_lds_dwordx4 v[130:131], off
	s_barrier
	s_waitcnt lgkmcnt(0)
	s_waitcnt lgkmcnt(0)
	v_mfma_f32_16x16x32_bf16 v[126:129], v[186:189], v[134:137], v[126:129]
	v_mfma_f32_16x16x32_bf16 v[122:125], v[186:189], v[152:155], v[122:125]
	v_mfma_f32_16x16x32_bf16 v[110:113], v[202:205], v[134:137], v[110:113]
	v_mfma_f32_16x16x32_bf16 v[102:105], v[210:213], v[134:137], v[102:105]
	v_mfma_f32_16x16x32_bf16 v[126:129], v[190:193], v[138:141], v[126:129]
	v_mfma_f32_16x16x32_bf16 v[122:125], v[190:193], v[182:185], v[122:125]
	v_mfma_f32_16x16x32_bf16 v[118:121], v[194:197], v[134:137], v[118:121]
	v_mfma_f32_16x16x32_bf16 v[114:117], v[194:197], v[152:155], v[114:117]
	v_mfma_f32_16x16x32_bf16 v[110:113], v[206:209], v[138:141], v[110:113]
	v_mfma_f32_16x16x32_bf16 v[106:109], v[202:205], v[152:155], v[106:109]
	v_mfma_f32_16x16x32_bf16 v[102:105], v[214:217], v[138:141], v[102:105]
	v_mfma_f32_16x16x32_bf16 v[98:101], v[210:213], v[152:155], v[98:101]
	v_mfma_f32_16x16x32_bf16 v[130:133], v[198:201], v[138:141], v[118:121]
	v_mfma_f32_16x16x32_bf16 v[164:167], v[198:201], v[182:185], v[114:117]
	v_mfma_f32_16x16x32_bf16 v[218:221], v[206:209], v[182:185], v[106:109]
	v_mfma_f32_16x16x32_bf16 v[222:225], v[214:217], v[182:185], v[98:101]
	s_barrier
	s_nop 1
	s_nop 0
	ds_read_b128 v[98:101], v159
	ds_read_b128 v[106:109], v159 offset:1024
	ds_read_b128 v[114:117], v159 offset:2048
	ds_read_b128 v[118:121], v159 offset:3072
	s_barrier
	s_waitcnt lgkmcnt(0)
	s_waitcnt lgkmcnt(0)
	v_mfma_f32_16x16x32_bf16 v[94:97], v[186:189], v[98:101], v[94:97]
	v_mfma_f32_16x16x32_bf16 v[70:73], v[194:197], v[98:101], v[70:73]
	v_mfma_f32_16x16x32_bf16 v[58:61], v[194:197], v[114:117], v[58:61]
	v_mfma_f32_16x16x32_bf16 v[54:57], v[202:205], v[98:101], v[54:57]
	v_mfma_f32_16x16x32_bf16 v[50:53], v[202:205], v[114:117], v[50:53]
	v_mfma_f32_16x16x32_bf16 v[46:49], v[210:213], v[98:101], v[46:49]
	v_mfma_f32_16x16x32_bf16 v[42:45], v[210:213], v[114:117], v[42:45]
	v_mfma_f32_16x16x32_bf16 v[94:97], v[190:193], v[106:109], v[94:97]
	v_mfma_f32_16x16x32_bf16 v[86:89], v[186:189], v[114:117], v[86:89]
	v_mfma_f32_16x16x32_bf16 v[70:73], v[198:201], v[106:109], v[70:73]
	v_mfma_f32_16x16x32_bf16 v[58:61], v[198:201], v[118:121], v[58:61]
	v_mfma_f32_16x16x32_bf16 v[54:57], v[206:209], v[106:109], v[54:57]
	v_mfma_f32_16x16x32_bf16 v[50:53], v[206:209], v[118:121], v[50:53]
	v_mfma_f32_16x16x32_bf16 v[46:49], v[214:217], v[106:109], v[46:49]
	v_mfma_f32_16x16x32_bf16 v[42:45], v[214:217], v[118:121], v[42:45]
	v_mfma_f32_16x16x32_bf16 v[156:159], v[190:193], v[118:121], v[86:89]
	s_barrier
; #define G_LDA(dst, b, h)                                                                                                  \
;   _Pragma("unroll") for (int m = 0; m < 4; ++m) _Pragma("unroll") for (int k = 0; k < 2; ++k)                             \
;       dst[m][k] = *(const bf16x8*)((const char*)G_SA(b, h) + ((wr * 4 + m) * 2 + k) * 1024 + rdo)
; #define G_LDB(dst, b, h)                                                                                                  \
;   _Pragma("unroll") for (int n = 0; n < 2; ++n) _Pragma("unroll") for (int k = 0; k < 2; ++k)                             \
;       dst[n][k] = *(const bf16x8*)((const char*)G_SB(b, h) + ((wc * 2 + n) * 2 + k) * 1024 + rdo)
; #define G_WAIT_V(n) asm volatile("s_waitcnt vmcnt(" #n ")" ::: "memory")
; #define G_WAIT_L(n) asm volatile("s_waitcnt lgkmcnt(" #n ")" ::: "memory")
; #define G_BAR __builtin_amdgcn_s_barrier()
;     ...
;     G_LDB(B1, 0, 1); G_BAR; G_WAIT_L(0); G_MMA(0, 1, At, B1); G_BAR;
;     G_LDA(At, 0, 1); G_WAIT_V(4); G_BAR; G_WAIT_L(0); G_MMA(1, 0, At, B0); G_MMA(1, 1, At, B1); G_BAR;
;   }
;   {
;     G_LDB(B0, 1, 0); G_LDA(At, 1, 0); G_WAIT_V(2); G_BAR; G_WAIT_L(0); G_MMA(0, 0, At, B0); G_BAR;
	s_nop 0
	ds_read_b128 v[86:89], v143 offset:16384
	ds_read_b128 v[186:189], v143 offset:17408
	ds_read_b128 v[190:193], v143 offset:18432
	ds_read_b128 v[194:197], v143 offset:19456
	ds_read_b128 v[198:201], v143 offset:20480
	ds_read_b128 v[202:205], v143 offset:21504
	ds_read_b128 v[206:209], v143 offset:22528
	ds_read_b128 v[210:213], v143 offset:23552
	s_waitcnt vmcnt(4)
	s_barrier
	s_waitcnt lgkmcnt(0)
	s_waitcnt lgkmcnt(0)
	v_mfma_f32_16x16x32_bf16 v[38:41], v[86:89], v[134:137], v[38:41]
	v_mfma_f32_16x16x32_bf16 v[34:37], v[86:89], v[152:155], v[34:37]
	v_mfma_f32_16x16x32_bf16 v[30:33], v[190:193], v[134:137], v[30:33]
	v_mfma_f32_16x16x32_bf16 v[26:29], v[190:193], v[152:155], v[26:29]
	v_mfma_f32_16x16x32_bf16 v[22:25], v[198:201], v[134:137], v[22:25]
	v_mfma_f32_16x16x32_bf16 v[18:21], v[198:201], v[152:155], v[18:21]
	v_mfma_f32_16x16x32_bf16 v[14:17], v[206:209], v[134:137], v[14:17]
	v_mfma_f32_16x16x32_bf16 v[10:13], v[206:209], v[152:155], v[10:13]
	v_mfma_f32_16x16x32_bf16 v[38:41], v[186:189], v[138:141], v[38:41]
	v_mfma_f32_16x16x32_bf16 v[34:37], v[186:189], v[182:185], v[34:37]
	v_mfma_f32_16x16x32_bf16 v[30:33], v[194:197], v[138:141], v[30:33]
	v_mfma_f32_16x16x32_bf16 v[26:29], v[194:197], v[182:185], v[26:29]
	v_mfma_f32_16x16x32_bf16 v[22:25], v[202:205], v[138:141], v[22:25]
	v_mfma_f32_16x16x32_bf16 v[18:21], v[202:205], v[182:185], v[18:21]
	v_mfma_f32_16x16x32_bf16 v[14:17], v[210:213], v[138:141], v[14:17]
	v_mfma_f32_16x16x32_bf16 v[10:13], v[210:213], v[182:185], v[10:13]
	v_mfma_f32_16x16x32_bf16 v[62:65], v[190:193], v[98:101], v[62:65]
	v_mfma_f32_16x16x32_bf16 v[134:137], v[194:197], v[106:109], v[62:65]
	v_mfma_f32_16x16x32_bf16 v[62:65], v[190:193], v[114:117], v[66:69]
	v_mfma_f32_16x16x32_bf16 v[138:141], v[194:197], v[118:121], v[62:65]
	v_mfma_f32_16x16x32_bf16 v[62:65], v[198:201], v[98:101], v[74:77]
	v_mfma_f32_16x16x32_bf16 v[152:155], v[202:205], v[106:109], v[62:65]
	v_mfma_f32_16x16x32_bf16 v[62:65], v[198:201], v[114:117], v[78:81]
	v_mfma_f32_16x16x32_bf16 v[6:9], v[86:89], v[98:101], v[6:9]
	v_mfma_f32_16x16x32_bf16 v[2:5], v[86:89], v[114:117], v[2:5]
	v_mfma_f32_16x16x32_bf16 v[182:185], v[202:205], v[118:121], v[62:65]
	v_mfma_f32_16x16x32_bf16 v[62:65], v[206:209], v[98:101], v[82:85]
	v_mfma_f32_16x16x32_bf16 v[6:9], v[186:189], v[106:109], v[6:9]
	v_mfma_f32_16x16x32_bf16 v[2:5], v[186:189], v[118:121], v[2:5]
	v_mfma_f32_16x16x32_bf16 v[186:189], v[210:213], v[106:109], v[62:65]
	v_mfma_f32_16x16x32_bf16 v[62:65], v[206:209], v[114:117], v[90:93]
	v_mfma_f32_16x16x32_bf16 v[190:193], v[210:213], v[118:121], v[62:65]
	s_barrier
	ds_read_b128 v[194:197], v150
	ds_read_b128 v[198:201], v150 offset:1024
	ds_read_b128 v[202:205], v150 offset:2048
	ds_read_b128 v[148:151], v150 offset:3072
	s_nop 0
	s_nop 0
	ds_read_b128 v[62:65], v143 offset:32768
	ds_read_b128 v[66:69], v143 offset:33792
	ds_read_b128 v[74:77], v143 offset:34816
	ds_read_b128 v[78:81], v143 offset:35840
	ds_read_b128 v[206:209], v143 offset:36864
	ds_read_b128 v[210:213], v143 offset:37888
	ds_read_b128 v[214:217], v143 offset:38912
	ds_read_b128 v[226:229], v143 offset:39936
	s_waitcnt vmcnt(2)
	s_barrier
	s_waitcnt lgkmcnt(0)
	s_waitcnt lgkmcnt(0)
	v_mfma_f32_16x16x32_bf16 v[82:85], v[62:65], v[194:197], v[126:129]
	v_mfma_f32_16x16x32_bf16 v[118:121], v[66:69], v[198:201], v[82:85]
	v_mfma_f32_16x16x32_bf16 v[82:85], v[62:65], v[202:205], v[122:125]
	v_mfma_f32_16x16x32_bf16 v[126:129], v[66:69], v[148:151], v[82:85]
	v_mfma_f32_16x16x32_bf16 v[82:85], v[74:77], v[194:197], v[130:133]
	v_mfma_f32_16x16x32_bf16 v[114:117], v[78:81], v[198:201], v[82:85]
	v_mfma_f32_16x16x32_bf16 v[82:85], v[74:77], v[202:205], v[164:167]
	v_mfma_f32_16x16x32_bf16 v[122:125], v[78:81], v[148:151], v[82:85]
	v_mfma_f32_16x16x32_bf16 v[82:85], v[206:209], v[194:197], v[110:113]
	v_mfma_f32_16x16x32_bf16 v[106:109], v[210:213], v[198:201], v[82:85]
	v_mfma_f32_16x16x32_bf16 v[82:85], v[206:209], v[202:205], v[218:221]
	v_mfma_f32_16x16x32_bf16 v[110:113], v[210:213], v[148:151], v[82:85]
	v_mfma_f32_16x16x32_bf16 v[82:85], v[214:217], v[194:197], v[102:105]
	v_mfma_f32_16x16x32_bf16 v[98:101], v[226:229], v[198:201], v[82:85]
	v_mfma_f32_16x16x32_bf16 v[82:85], v[214:217], v[202:205], v[222:225]
	v_mfma_f32_16x16x32_bf16 v[102:105], v[226:229], v[148:151], v[82:85]
	s_barrier
; #define G_LDA(dst, b, h)                                                                                                  \
;   _Pragma("unroll") for (int m = 0; m < 4; ++m) _Pragma("unroll") for (int k = 0; k < 2; ++k)                             \
;       dst[m][k] = *(const bf16x8*)((const char*)G_SA(b, h) + ((wr * 4 + m) * 2 + k) * 1024 + rdo)
; #define G_LDB(dst, b, h)                                                                                                  \
;   _Pragma("unroll") for (int n = 0; n < 2; ++n) _Pragma("unroll") for (int k = 0; k < 2; ++k)                             \
;       dst[n][k] = *(const bf16x8*)((const char*)G_SB(b, h) + ((wc * 2 + n) * 2 + k) * 1024 + rdo)
; #define G_WAIT_V(n) asm volatile("s_waitcnt vmcnt(" #n ")" ::: "memory")
; #define G_WAIT_L(n) asm volatile("s_waitcnt lgkmcnt(" #n ")" ::: "memory")
; #define G_BAR __builtin_amdgcn_s_barrier()
;     ...
;     G_LDB(B1, 1, 1); G_WAIT_V(0); G_BAR; G_WAIT_L(0); G_MMA(0, 1, At, B1); G_BAR;
;     G_LDA(At, 1, 1); G_BAR; G_WAIT_L(0); G_MMA(1, 0, At, B0); G_MMA(1, 1, At, B1); G_BAR;
;   }
;   if (wr == 0) G_BAR;
	ds_read_b128 v[130:133], v146
	ds_read_b128 v[164:167], v146 offset:1024
	ds_read_b128 v[218:221], v146 offset:2048
	ds_read_b128 v[144:147], v146 offset:3072
	s_waitcnt vmcnt(0)
	s_barrier
	s_waitcnt lgkmcnt(0)
	s_waitcnt lgkmcnt(0)
	v_mfma_f32_16x16x32_bf16 v[82:85], v[62:65], v[130:133], v[94:97]
	v_mfma_f32_16x16x32_bf16 v[62:65], v[62:65], v[218:221], v[156:159]
	v_mfma_f32_16x16x32_bf16 v[94:97], v[66:69], v[144:147], v[62:65]
	v_mfma_f32_16x16x32_bf16 v[62:65], v[74:77], v[130:133], v[70:73]
	v_mfma_f32_16x16x32_bf16 v[58:61], v[74:77], v[218:221], v[58:61]
	v_mfma_f32_16x16x32_bf16 v[54:57], v[206:209], v[130:133], v[54:57]
	v_mfma_f32_16x16x32_bf16 v[50:53], v[206:209], v[218:221], v[50:53]
	v_mfma_f32_16x16x32_bf16 v[46:49], v[214:217], v[130:133], v[46:49]
	v_mfma_f32_16x16x32_bf16 v[42:45], v[214:217], v[218:221], v[42:45]
	v_mfma_f32_16x16x32_bf16 v[86:89], v[66:69], v[164:167], v[82:85]
	v_mfma_f32_16x16x32_bf16 v[82:85], v[78:81], v[164:167], v[62:65]
	v_mfma_f32_16x16x32_bf16 v[90:93], v[78:81], v[144:147], v[58:61]
	v_mfma_f32_16x16x32_bf16 v[74:77], v[210:213], v[164:167], v[54:57]
	v_mfma_f32_16x16x32_bf16 v[78:81], v[210:213], v[144:147], v[50:53]
	v_mfma_f32_16x16x32_bf16 v[66:69], v[226:229], v[164:167], v[46:49]
	v_mfma_f32_16x16x32_bf16 v[70:73], v[226:229], v[144:147], v[42:45]
	s_barrier
	ds_read_b128 v[156:159], v143 offset:49152
	ds_read_b128 v[206:209], v143 offset:50176
	ds_read_b128 v[210:213], v143 offset:51200
	ds_read_b128 v[214:217], v143 offset:52224
	ds_read_b128 v[222:225], v143 offset:53248
	ds_read_b128 v[226:229], v143 offset:54272
	ds_read_b128 v[230:233], v143 offset:55296
	ds_read_b128 v[234:237], v143 offset:56320
	s_barrier
	s_waitcnt lgkmcnt(0)
	s_waitcnt lgkmcnt(0)
	v_mfma_f32_16x16x32_bf16 v[38:41], v[156:159], v[194:197], v[38:41]
	v_mfma_f32_16x16x32_bf16 v[34:37], v[156:159], v[202:205], v[34:37]
	v_mfma_f32_16x16x32_bf16 v[30:33], v[210:213], v[194:197], v[30:33]
	v_mfma_f32_16x16x32_bf16 v[26:29], v[210:213], v[202:205], v[26:29]
	v_mfma_f32_16x16x32_bf16 v[22:25], v[222:225], v[194:197], v[22:25]
	v_mfma_f32_16x16x32_bf16 v[18:21], v[222:225], v[202:205], v[18:21]
	v_mfma_f32_16x16x32_bf16 v[14:17], v[230:233], v[194:197], v[14:17]
	v_mfma_f32_16x16x32_bf16 v[10:13], v[230:233], v[202:205], v[10:13]
	v_mfma_f32_16x16x32_bf16 v[54:57], v[206:209], v[198:201], v[38:41]
	v_mfma_f32_16x16x32_bf16 v[62:65], v[206:209], v[148:151], v[34:37]
	v_mfma_f32_16x16x32_bf16 v[50:53], v[214:217], v[198:201], v[30:33]
	v_mfma_f32_16x16x32_bf16 v[58:61], v[214:217], v[148:151], v[26:29]
	v_mfma_f32_16x16x32_bf16 v[42:45], v[226:229], v[198:201], v[22:25]
	v_mfma_f32_16x16x32_bf16 v[46:49], v[226:229], v[148:151], v[18:21]
	v_mfma_f32_16x16x32_bf16 v[34:37], v[234:237], v[198:201], v[14:17]
	v_mfma_f32_16x16x32_bf16 v[38:41], v[234:237], v[148:151], v[10:13]
	v_mfma_f32_16x16x32_bf16 v[2:5], v[156:159], v[218:221], v[2:5]
	v_mfma_f32_16x16x32_bf16 v[30:33], v[206:209], v[144:147], v[2:5]
	v_mfma_f32_16x16x32_bf16 v[2:5], v[210:213], v[130:133], v[134:137]
	v_mfma_f32_16x16x32_bf16 v[18:21], v[214:217], v[164:167], v[2:5]
	v_mfma_f32_16x16x32_bf16 v[2:5], v[210:213], v[218:221], v[138:141]
	v_mfma_f32_16x16x32_bf16 v[26:29], v[214:217], v[144:147], v[2:5]
	v_mfma_f32_16x16x32_bf16 v[2:5], v[222:225], v[130:133], v[152:155]
	v_mfma_f32_16x16x32_bf16 v[6:9], v[156:159], v[130:133], v[6:9]
	v_mfma_f32_16x16x32_bf16 v[10:13], v[226:229], v[164:167], v[2:5]
	v_mfma_f32_16x16x32_bf16 v[2:5], v[222:225], v[218:221], v[182:185]
	v_mfma_f32_16x16x32_bf16 v[22:25], v[206:209], v[164:167], v[6:9]
	v_mfma_f32_16x16x32_bf16 v[14:17], v[226:229], v[144:147], v[2:5]
	v_mfma_f32_16x16x32_bf16 v[2:5], v[230:233], v[130:133], v[186:189]
	v_mfma_f32_16x16x32_bf16 v[6:9], v[230:233], v[218:221], v[190:193]
	v_mfma_f32_16x16x32_bf16 v[2:5], v[234:237], v[164:167], v[2:5]
	v_mfma_f32_16x16x32_bf16 v[6:9], v[234:237], v[144:147], v[6:9]
	v_cmp_gt_u32_e32 vcc, s67, v0
	s_barrier
	s_and_saveexec_b64 s[18:19], vcc
	s_cbranch_execz .LBB0_456
	s_barrier
